# row-pair-interleaved H and W_in layout (full-128B-line LDS-DMA pieces) in all 4 in-proj GEMM layers + k-loop DMA/MFMA interleave with counted lgkmcnt
# speedup vs baseline: 1.0573x; 1.0573x over previous
.LBB0_16:
	s_cmpk_lt_i32 s18, 0x310
	s_cselect_b64 s[2:3], -1, 0
	v_writelane_b32 v254, s2, 50
	v_mov_b32_e32 v0, v190
	s_cmpk_gt_i32 s18, 0x30f
	v_writelane_b32 v254, s3, 51
	s_cbranch_scc1 .LBB0_51
	v_and_b32_e32 v20, 63, v0
	v_ashrrev_i32_e32 v21, 6, v0
	v_ashrrev_i32_e32 v22, 3, v0
	v_lshlrev_b32_e32 v0, 3, v0
	s_load_dword s6, s[0:1], 0x108
	v_and_b32_e32 v3, 56, v0
	v_bfe_u32 v0, v190, 2, 1
	v_lshlrev_b32_e32 v0, 7, v0
	v_bfe_u32 v200, v190, 3, 1
	v_lshl_or_b32 v0, v200, 6, v0
	v_and_b32_e32 v200, 3, v190
	v_lshl_or_b32 v0, v200, 4, v0
	v_mov_b32_e32 v1, 0
	v_lshl_add_u64 v[16:17], s[52:53], 0, v[0:1]
	v_lshlrev_b32_e32 v0, 2, v22
	s_movk_i32 s2, 0x104
	v_lshlrev_b32_e32 v2, 2, v20
	v_mad_u32_u24 v23, v3, s2, v0
	v_mul_lo_u32 v0, v21, s2
	s_lshl_b32 s7, s18, 6
	s_waitcnt lgkmcnt(0)
	s_lshl_b32 s8, s6, 6
	s_mov_b32 s9, 0
	s_movk_i32 s10, 0xc10
	s_movk_i32 s11, 0x3040
	v_add_u32_e32 v24, v2, v0
	s_movk_i32 s12, 0x7fff
	v_mov_b32_e32 v25, 1
	s_mov_b32 s13, s18
	s_branch .LBB0_19
.LBB0_18:
	s_or_b64 exec, exec, s[4:5]
	s_barrier
	s_waitcnt vmcnt(0)
	ds_write_b32 v24, v0
	ds_write_b32 v24, v1 offset:1040
	ds_write_b32 v24, v2 offset:2080
	ds_write_b32 v24, v3 offset:3120
	ds_write_b32 v24, v4 offset:4160
	ds_write_b32 v24, v5 offset:5200
	ds_write_b32 v24, v6 offset:6240
	ds_write_b32 v24, v7 offset:7280
	ds_write_b32 v24, v8 offset:8320
	ds_write_b32 v24, v9 offset:9360
	ds_write_b32 v24, v10 offset:10400
	ds_write_b32 v24, v11 offset:11440
	ds_write_b32 v24, v12 offset:12480
	ds_write_b32 v24, v13 offset:13520
	ds_write_b32 v24, v14 offset:14560
	ds_write_b32 v24, v15 offset:15600
	s_waitcnt lgkmcnt(0)
	s_barrier
	ds_read2_b32 v[6:7], v23 offset1:32
	ds_read2_b32 v[8:9], v23 offset0:65 offset1:97
	ds_read2_b32 v[10:11], v23 offset0:130 offset1:162
	ds_read2_b32 v[12:13], v23 offset0:195 offset1:227
	v_add_u32_e32 v30, s14, v22
	v_and_b32_e32 v30, -2, v30
	s_ashr_i32 s3, s2, 31
	v_add_u32_e32 v0, 0x400, v23
	v_ashrrev_i32_e32 v31, 31, v30
	v_lshl_add_u64 v[4:5], s[2:3], 2, v[16:17]
	ds_read2_b32 v[14:15], v0 offset0:4 offset1:36
	ds_read2_b32 v[18:19], v0 offset0:69 offset1:101
	ds_read2_b32 v[26:27], v0 offset0:134 offset1:166
	ds_read2_b32 v[28:29], v0 offset0:199 offset1:231
	v_lshlrev_b64 v[0:1], 11, v[30:31]
	v_lshl_add_u64 v[32:33], v[4:5], 0, v[0:1]
	s_waitcnt lgkmcnt(7)
	v_and_b32_sdwa v1, v6, v25 dst_sel:DWORD dst_unused:UNUSED_PAD src0_sel:WORD_1 src1_sel:DWORD
	v_add3_u32 v2, v6, v1, s12
	s_waitcnt lgkmcnt(4)
	v_and_b32_sdwa v1, v12, v25 dst_sel:DWORD dst_unused:UNUSED_PAD src0_sel:WORD_1 src1_sel:DWORD
	v_and_b32_sdwa v3, v8, v25 dst_sel:DWORD dst_unused:UNUSED_PAD src0_sel:WORD_1 src1_sel:DWORD
	v_and_b32_sdwa v0, v10, v25 dst_sel:DWORD dst_unused:UNUSED_PAD src0_sel:WORD_1 src1_sel:DWORD
	v_add3_u32 v1, v12, v1, s12
	v_add3_u32 v3, v8, v3, s12
	v_add3_u32 v0, v10, v0, s12
	v_and_b32_e32 v1, 0xffff0000, v1
	v_and_b32_e32 v3, 0xffff0000, v3
	v_or_b32_sdwa v1, v1, v0 dst_sel:DWORD dst_unused:UNUSED_PAD src0_sel:DWORD src1_sel:WORD_1
	v_or_b32_sdwa v0, v3, v2 dst_sel:DWORD dst_unused:UNUSED_PAD src0_sel:DWORD src1_sel:WORD_1
	s_waitcnt lgkmcnt(3)
	v_and_b32_sdwa v3, v14, v25 dst_sel:DWORD dst_unused:UNUSED_PAD src0_sel:WORD_1 src1_sel:DWORD
	v_add3_u32 v6, v14, v3, s12
	s_waitcnt lgkmcnt(0)
	v_and_b32_sdwa v3, v28, v25 dst_sel:DWORD dst_unused:UNUSED_PAD src0_sel:WORD_1 src1_sel:DWORD
	v_and_b32_sdwa v8, v18, v25 dst_sel:DWORD dst_unused:UNUSED_PAD src0_sel:WORD_1 src1_sel:DWORD
	v_and_b32_sdwa v2, v26, v25 dst_sel:DWORD dst_unused:UNUSED_PAD src0_sel:WORD_1 src1_sel:DWORD
	v_add3_u32 v3, v28, v3, s12
	v_add3_u32 v8, v18, v8, s12
	v_add3_u32 v2, v26, v2, s12
	v_and_b32_e32 v3, 0xffff0000, v3
	v_and_b32_e32 v8, 0xffff0000, v8
	v_or_b32_sdwa v3, v3, v2 dst_sel:DWORD dst_unused:UNUSED_PAD src0_sel:DWORD src1_sel:WORD_1
	v_or_b32_sdwa v2, v8, v6 dst_sel:DWORD dst_unused:UNUSED_PAD src0_sel:DWORD src1_sel:WORD_1
	global_store_dwordx4 v[32:33], v[0:3], off
	s_add_i32 s13, s13, s6
	s_add_i32 s7, s7, s8
	v_add_u32_e32 v0, 32, v30
	v_ashrrev_i32_e32 v1, 31, v0
	v_lshlrev_b64 v[0:1], 11, v[0:1]
	v_lshl_add_u64 v[4:5], v[4:5], 0, v[0:1]
	v_and_b32_sdwa v1, v7, v25 dst_sel:DWORD dst_unused:UNUSED_PAD src0_sel:WORD_1 src1_sel:DWORD
	v_add3_u32 v2, v7, v1, s12
	v_and_b32_sdwa v1, v13, v25 dst_sel:DWORD dst_unused:UNUSED_PAD src0_sel:WORD_1 src1_sel:DWORD
	v_and_b32_sdwa v3, v9, v25 dst_sel:DWORD dst_unused:UNUSED_PAD src0_sel:WORD_1 src1_sel:DWORD
	v_and_b32_sdwa v0, v11, v25 dst_sel:DWORD dst_unused:UNUSED_PAD src0_sel:WORD_1 src1_sel:DWORD
	v_add3_u32 v1, v13, v1, s12
	v_add3_u32 v3, v9, v3, s12
	v_add3_u32 v0, v11, v0, s12
	v_and_b32_e32 v1, 0xffff0000, v1
	v_and_b32_e32 v3, 0xffff0000, v3
	v_or_b32_sdwa v1, v1, v0 dst_sel:DWORD dst_unused:UNUSED_PAD src0_sel:DWORD src1_sel:WORD_1
	v_or_b32_sdwa v0, v3, v2 dst_sel:DWORD dst_unused:UNUSED_PAD src0_sel:DWORD src1_sel:WORD_1
	v_and_b32_sdwa v3, v15, v25 dst_sel:DWORD dst_unused:UNUSED_PAD src0_sel:WORD_1 src1_sel:DWORD
	v_add3_u32 v6, v15, v3, s12
	v_and_b32_sdwa v3, v29, v25 dst_sel:DWORD dst_unused:UNUSED_PAD src0_sel:WORD_1 src1_sel:DWORD
	v_and_b32_sdwa v7, v19, v25 dst_sel:DWORD dst_unused:UNUSED_PAD src0_sel:WORD_1 src1_sel:DWORD
	v_and_b32_sdwa v2, v27, v25 dst_sel:DWORD dst_unused:UNUSED_PAD src0_sel:WORD_1 src1_sel:DWORD
	v_add3_u32 v3, v29, v3, s12
	v_add3_u32 v7, v19, v7, s12
	v_add3_u32 v2, v27, v2, s12
	v_and_b32_e32 v3, 0xffff0000, v3
	v_and_b32_e32 v7, 0xffff0000, v7
	v_or_b32_sdwa v3, v3, v2 dst_sel:DWORD dst_unused:UNUSED_PAD src0_sel:DWORD src1_sel:WORD_1
	v_or_b32_sdwa v2, v7, v6 dst_sel:DWORD dst_unused:UNUSED_PAD src0_sel:DWORD src1_sel:WORD_1
	s_cmpk_lt_i32 s13, 0x310
	global_store_dwordx4 v[4:5], v[0:3], off
	s_cbranch_scc0 .LBB0_51

.LBB0_86:
	s_nop 0
	v_mov_b32_e32 v0, v190
	v_mov_b32_e32 v1, v190
	s_add_u32 s88, s52, 0x12d0000
	s_addc_u32 s89, s53, 0
	v_ashrrev_i32_e32 v1, 6, v1
	v_writelane_b32 v254, s18, 56
	s_lshl_b32 s2, s18, 2
	v_writelane_b32 v254, s2, 57
	v_add_u32_e32 v30, s2, v1
	s_movk_i32 s2, 0x4080
	v_cmp_gt_i32_e32 vcc, s2, v30
	v_mbcnt_lo_u32_b32 v191, -1, 0
	s_and_saveexec_b64 s[2:3], vcc
	s_cbranch_execz .LBB0_91
	s_load_dwordx16 s[12:27], s[0:1], 0x0
	v_lshlrev_b32_e32 v0, 2, v0
	v_and_b32_e32 v16, 0xfc, v0
	v_lshlrev_b32_e32 v32, 2, v16
	v_mbcnt_hi_u32_b32 v17, -1, v191
	s_waitcnt lgkmcnt(0)
	global_load_dwordx4 v[0:3], v32, s[26:27]
	global_load_dwordx4 v[4:7], v32, s[26:27] offset:1024
	global_load_dwordx4 v[8:11], v32, s[26:27] offset:2048
	global_load_dwordx4 v[12:15], v32, s[26:27] offset:3072
	v_and_b32_e32 v18, 64, v17
	v_mov_b32_e32 v33, 0
	v_xor_b32_e32 v20, 32, v17
	v_add_u32_e32 v26, 64, v18
	v_mov_b32_e32 v19, v33
	v_xor_b32_e32 v21, 16, v17
	v_lshrrev_b32_e32 v18, 5, v16
	v_lshlrev_b32_e32 v18, 7, v18
	v_and_b32_e32 v200, 28, v16
	v_lshl_or_b32 v18, v200, 1, v18
	v_cmp_lt_i32_e32 vcc, v20, v26
	s_load_dwordx16 s[16:31], s[0:1], 0xc0
	v_xor_b32_e32 v22, 8, v17
	v_lshl_add_u64 v[36:37], s[88:89], 0, v[18:19]
	v_cndmask_b32_e32 v18, v17, v20, vcc
	v_cmp_lt_i32_e32 vcc, v21, v26
	s_load_dword s8, s[0:1], 0x108
	v_xor_b32_e32 v23, 4, v17
	v_cndmask_b32_e32 v19, v17, v21, vcc
	v_cmp_lt_i32_e32 vcc, v22, v26
	v_xor_b32_e32 v24, 2, v17
	v_xor_b32_e32 v25, 1, v17
	v_cndmask_b32_e32 v20, v17, v22, vcc
	v_cmp_lt_i32_e32 vcc, v23, v26
	s_waitcnt lgkmcnt(0)
	s_cmp_lg_u64 s[30:31], 0
	s_mov_b64 s[4:5], 0
	v_cndmask_b32_e32 v21, v17, v23, vcc
	v_cmp_lt_i32_e32 vcc, v24, v26
	s_movk_i32 s10, 0x4000
	v_mov_b32_e32 v46, s15
	v_cndmask_b32_e32 v22, v17, v24, vcc
	v_cmp_lt_i32_e32 vcc, v25, v26
	v_mov_b32_e32 v47, s13
	v_mov_b32_e32 v48, s14
	v_cndmask_b32_e32 v17, v17, v25, vcc
	v_mov_b32_e32 v49, s12
	s_movk_i32 s11, 0x3fff
	v_mov_b32_e32 v50, 0x358637bd
	s_mov_b32 s12, 0x800000
	s_movk_i32 s13, 0x7fff
	s_movk_i32 s14, 0x407f
	s_cselect_b64 s[6:7], -1, 0
	v_lshl_add_u64 v[34:35], s[30:31], 0, v[32:33]
	v_lshlrev_b32_e32 v32, 2, v16
	v_lshlrev_b32_e32 v51, 2, v18
	v_lshlrev_b32_e32 v52, 2, v19
	v_lshlrev_b32_e32 v53, 2, v20
	v_lshlrev_b32_e32 v54, 2, v21
	v_lshlrev_b32_e32 v55, 2, v22
	v_lshlrev_b32_e32 v56, 2, v17
	s_lshl_b32 s15, s8, 2
	v_mov_b32_e32 v57, 1
	s_waitcnt vmcnt(3)
	v_mov_b32_e32 v38, v1
	v_mov_b32_e32 v39, v3
	v_mov_b32_e32 v1, v2
	s_waitcnt vmcnt(2)
	v_mov_b32_e32 v2, v5
	v_mov_b32_e32 v3, v7
	v_mov_b32_e32 v5, v6
	s_waitcnt vmcnt(1)
	v_mov_b32_e32 v6, v9
	v_mov_b32_e32 v7, v11
	v_mov_b32_e32 v9, v10
	s_waitcnt vmcnt(0)
	v_mov_b32_e32 v10, v13
	v_mov_b32_e32 v11, v15
	v_mov_b32_e32 v13, v14
	s_branch .LBB0_89
.LBB0_88:
	s_or_b64 exec, exec, s[8:9]
	s_waitcnt lgkmcnt(0)
	v_add_f32_e32 v14, v15, v23
	v_fmamk_f32 v14, v14, 0x3a800000, v50
	v_mul_f32_e32 v15, 0x4b800000, v14
	v_cmp_gt_f32_e32 vcc, s12, v14
	s_nop 1
	v_cndmask_b32_e32 v14, v14, v15, vcc
	v_rsq_f32_e32 v22, v14
	v_and_b32_e32 v14, -2, v30
	v_mov_b32_e32 v15, v31
	v_lshlrev_b64 v[14:15], 11, v[14:15]
	v_and_b32_e32 v200, 1, v30
	v_lshl_or_b32 v14, v200, 6, v14
	v_lshl_add_u64 v[14:15], v[36:37], 0, v[14:15]
	v_add_u32_e32 v30, s15, v30
	v_mul_f32_e32 v23, 0x45800000, v22
	v_cndmask_b32_e32 v22, v22, v23, vcc
	v_pk_mul_f32 v[26:27], v[44:45], v[22:23] op_sel_hi:[1,0]
	v_pk_mul_f32 v[28:29], v[28:29], v[22:23] op_sel_hi:[1,0]
	v_pk_mul_f32 v[26:27], v[0:1], v[26:27]
	v_pk_mul_f32 v[28:29], v[38:39], v[28:29]
	v_and_b32_sdwa v23, v27, v57 dst_sel:DWORD dst_unused:UNUSED_PAD src0_sel:WORD_1 src1_sel:DWORD
	v_and_b32_sdwa v31, v26, v57 dst_sel:DWORD dst_unused:UNUSED_PAD src0_sel:WORD_1 src1_sel:DWORD
	v_add3_u32 v26, v26, v31, s13
	v_add3_u32 v23, v27, v23, s13
	v_and_b32_sdwa v27, v29, v57 dst_sel:DWORD dst_unused:UNUSED_PAD src0_sel:WORD_1 src1_sel:DWORD
	v_and_b32_sdwa v31, v28, v57 dst_sel:DWORD dst_unused:UNUSED_PAD src0_sel:WORD_1 src1_sel:DWORD
	v_add3_u32 v27, v29, v27, s13
	v_add3_u32 v28, v28, v31, s13
	v_and_b32_e32 v27, 0xffff0000, v27
	v_and_b32_e32 v28, 0xffff0000, v28
	v_or_b32_sdwa v27, v27, v23 dst_sel:DWORD dst_unused:UNUSED_PAD src0_sel:DWORD src1_sel:WORD_1
	v_or_b32_sdwa v26, v28, v26 dst_sel:DWORD dst_unused:UNUSED_PAD src0_sel:DWORD src1_sel:WORD_1
	global_store_dwordx2 v[14:15], v[26:27], off
	v_pk_mul_f32 v[26:27], v[42:43], v[22:23] op_sel_hi:[1,0]
	v_pk_mul_f32 v[20:21], v[20:21], v[22:23] op_sel_hi:[1,0]
	v_pk_mul_f32 v[26:27], v[4:5], v[26:27]
	v_pk_mul_f32 v[20:21], v[2:3], v[20:21]
	v_and_b32_sdwa v23, v27, v57 dst_sel:DWORD dst_unused:UNUSED_PAD src0_sel:WORD_1 src1_sel:DWORD
	v_and_b32_sdwa v28, v26, v57 dst_sel:DWORD dst_unused:UNUSED_PAD src0_sel:WORD_1 src1_sel:DWORD
	v_add3_u32 v26, v26, v28, s13
	v_add3_u32 v23, v27, v23, s13
	v_and_b32_sdwa v27, v21, v57 dst_sel:DWORD dst_unused:UNUSED_PAD src0_sel:WORD_1 src1_sel:DWORD
	v_and_b32_sdwa v28, v20, v57 dst_sel:DWORD dst_unused:UNUSED_PAD src0_sel:WORD_1 src1_sel:DWORD
	v_add3_u32 v21, v21, v27, s13
	v_add3_u32 v20, v20, v28, s13
	v_and_b32_e32 v21, 0xffff0000, v21
	v_and_b32_e32 v20, 0xffff0000, v20
	v_or_b32_sdwa v21, v21, v23 dst_sel:DWORD dst_unused:UNUSED_PAD src0_sel:DWORD src1_sel:WORD_1
	v_or_b32_sdwa v20, v20, v26 dst_sel:DWORD dst_unused:UNUSED_PAD src0_sel:DWORD src1_sel:WORD_1
	global_store_dwordx2 v[14:15], v[20:21], off offset:1024
	v_pk_mul_f32 v[20:21], v[40:41], v[22:23] op_sel_hi:[1,0]
	v_pk_mul_f32 v[24:25], v[24:25], v[22:23] op_sel_hi:[1,0]
	v_pk_mul_f32 v[20:21], v[8:9], v[20:21]
	v_pk_mul_f32 v[24:25], v[6:7], v[24:25]
	v_and_b32_sdwa v23, v21, v57 dst_sel:DWORD dst_unused:UNUSED_PAD src0_sel:WORD_1 src1_sel:DWORD
	v_and_b32_sdwa v26, v20, v57 dst_sel:DWORD dst_unused:UNUSED_PAD src0_sel:WORD_1 src1_sel:DWORD
	v_add3_u32 v21, v21, v23, s13
	v_and_b32_sdwa v23, v25, v57 dst_sel:DWORD dst_unused:UNUSED_PAD src0_sel:WORD_1 src1_sel:DWORD
	v_add3_u32 v20, v20, v26, s13
	v_and_b32_sdwa v26, v24, v57 dst_sel:DWORD dst_unused:UNUSED_PAD src0_sel:WORD_1 src1_sel:DWORD
	v_add3_u32 v23, v25, v23, s13
	v_add3_u32 v24, v24, v26, s13
	v_and_b32_e32 v23, 0xffff0000, v23
	v_and_b32_e32 v24, 0xffff0000, v24
	v_pk_mul_f32 v[18:19], v[18:19], v[22:23] op_sel_hi:[1,0]
	v_or_b32_sdwa v21, v23, v21 dst_sel:DWORD dst_unused:UNUSED_PAD src0_sel:DWORD src1_sel:WORD_1
	v_or_b32_sdwa v20, v24, v20 dst_sel:DWORD dst_unused:UNUSED_PAD src0_sel:DWORD src1_sel:WORD_1
	v_pk_mul_f32 v[16:17], v[16:17], v[22:23] op_sel_hi:[1,0]
	v_pk_mul_f32 v[18:19], v[12:13], v[18:19]
	global_store_dwordx2 v[14:15], v[20:21], off offset:2048
	v_pk_mul_f32 v[16:17], v[10:11], v[16:17]
	v_and_b32_sdwa v20, v19, v57 dst_sel:DWORD dst_unused:UNUSED_PAD src0_sel:WORD_1 src1_sel:DWORD
	v_and_b32_sdwa v21, v18, v57 dst_sel:DWORD dst_unused:UNUSED_PAD src0_sel:WORD_1 src1_sel:DWORD
	v_add3_u32 v18, v18, v21, s13
	v_add3_u32 v19, v19, v20, s13
	v_and_b32_sdwa v20, v17, v57 dst_sel:DWORD dst_unused:UNUSED_PAD src0_sel:WORD_1 src1_sel:DWORD
	v_and_b32_sdwa v21, v16, v57 dst_sel:DWORD dst_unused:UNUSED_PAD src0_sel:WORD_1 src1_sel:DWORD
	v_add3_u32 v17, v17, v20, s13
	v_add3_u32 v16, v16, v21, s13
	v_and_b32_e32 v17, 0xffff0000, v17
	v_and_b32_e32 v16, 0xffff0000, v16
	v_cmp_lt_i32_e32 vcc, s14, v30
	v_or_b32_sdwa v17, v17, v19 dst_sel:DWORD dst_unused:UNUSED_PAD src0_sel:DWORD src1_sel:WORD_1
	v_or_b32_sdwa v16, v16, v18 dst_sel:DWORD dst_unused:UNUSED_PAD src0_sel:DWORD src1_sel:WORD_1
	s_or_b64 s[4:5], vcc, s[4:5]
	global_store_dwordx2 v[14:15], v[16:17], off offset:3072
	s_andn2_b64 exec, exec, s[4:5]
	s_cbranch_execz .LBB0_91

.LBB0_116:
	s_or_b64 exec, exec, s[38:39]
	s_waitcnt lgkmcnt(0)
	s_add_u32 s94, s52, 0x3310000
	s_addc_u32 s95, s53, 0
	s_add_u32 s96, s52, 0x4330000
	s_addc_u32 s97, s53, 0
	s_add_u32 s2, s52, 0x63d0000
	s_addc_u32 s3, s53, 0
	v_writelane_b32 v254, s2, 60
	s_barrier
	s_nop 0
	v_writelane_b32 v254, s3, 61
	s_add_u32 s2, s52, 0x84d0000
	s_addc_u32 s3, s53, 0
	v_writelane_b32 v254, s2, 62
	s_nop 1
	v_writelane_b32 v254, s3, 63
	s_nop 0
	v_readlane_b32 s49, v254, 56
	s_cmpk_lt_i32 s49, 0x600
	s_cselect_b64 s[2:3], -1, 0
	v_writelane_b32 v255, s2, 0
	s_cmpk_gt_i32 s49, 0x5ff
	s_nop 0
	v_writelane_b32 v255, s3, 1
	s_cbranch_scc1 .LBB0_248
	s_add_u32 s6, s0, 0x108
	s_movk_i32 s34, 0xf000
	s_movk_i32 s36, 0xfc00
	s_movk_i32 s38, 0xf040
	s_movk_i32 s40, 0xfc40
	s_addc_u32 s7, s1, 0
	v_mov_b32_e32 v129, 0
	s_mov_b64 s[8:9], 0x20000
	s_mov_b64 s[10:11], 0x40000
	s_mov_b64 s[12:13], 0x60000
	s_mov_b64 s[14:15], 0x20080
	s_mov_b64 s[16:17], 0x40080
	s_mov_b64 s[18:19], 0x60080
	s_mov_b64 s[20:21], 0x12d0100
	s_mov_b64 s[22:23], 0x12f0100
	s_mov_b64 s[24:25], 0x1310100
	s_mov_b64 s[26:27], 0x1330100
	s_mov_b64 s[28:29], 0x100
	s_mov_b64 s[30:31], 0x20100
	s_mov_b64 s[62:63], 0x80
	s_movk_i32 s46, 0x7fff
	s_mov_b32 s47, 0xffff0000
	s_movk_i32 s48, 0x1ff
	s_mov_b32 s35, -1
	s_mov_b32 s37, -1
	s_mov_b32 s39, -1
	s_mov_b32 s41, -1
	v_mov_b32_e32 v142, 1
	s_branch .LBB0_120

.LBB0_122:
	v_mov_b32_e32 v134, v190
	s_lshl_b32 s43, s42, 8
	v_ashrrev_i32_e32 v4, 2, v134
	v_and_b32_e32 v4, -2, v4
	v_lshlrev_b32_e32 v0, 6, v134
	v_and_b32_e32 v141, 0xffffe000, v0
	v_add_u32_e32 v0, s43, v4
	v_ashrrev_i32_e32 v1, 31, v0
	v_add_u32_e32 v2, s4, v4
	v_lshlrev_b32_e32 v140, 4, v134
	v_lshlrev_b64 v[0:1], 11, v[0:1]
	v_ashrrev_i32_e32 v3, 31, v2
	v_lshl_add_u64 v[0:1], s[88:89], 0, v[0:1]
	v_and_b32_e32 v128, 0x70, v140
	v_lshlrev_b64 v[2:3], 11, v[2:3]
	v_readfirstlane_b32 s2, v140
	v_add_u32_e32 v5, 0x1000, v140
	v_lshl_add_u64 v[0:1], v[0:1], 0, v[128:129]
	v_lshl_add_u64 v[2:3], s[52:53], 0, v[2:3]
	s_waitcnt vmcnt(0)
	s_mov_b32 m0, s2
	v_readfirstlane_b32 s2, v5
	v_add_u32_e32 v5, 0x2000, v140
	v_lshl_add_u64 v[130:131], v[2:3], 0, v[128:129]
	global_load_lds_dwordx4 v[0:1], off
	v_lshl_add_u64 v[2:3], v[0:1], 0, s[8:9]
	s_mov_b32 m0, s2
	v_readfirstlane_b32 s2, v5
	v_add_u32_e32 v5, 0x3000, v140
	global_load_lds_dwordx4 v[2:3], off
	v_lshl_add_u64 v[2:3], v[0:1], 0, s[10:11]
	s_mov_b32 m0, s2
	v_readfirstlane_b32 s2, v5
	global_load_lds_dwordx4 v[2:3], off
	v_lshl_add_u64 v[2:3], v[0:1], 0, s[12:13]
	s_mov_b32 m0, s2
	v_add_u32_e32 v5, 0x5000, v140
	global_load_lds_dwordx4 v[2:3], off
	v_add_u32_e32 v2, 0x4000, v140
	s_lshl_b32 s3, s5, 8
	v_readfirstlane_b32 s2, v2
	s_mov_b32 m0, s2
	v_readfirstlane_b32 s2, v5
	v_add_u32_e32 v5, 0x6000, v140
	global_load_lds_dwordx4 v[130:131], off
	v_lshl_add_u64 v[2:3], v[130:131], 0, s[8:9]
	s_mov_b32 m0, s2
	v_readfirstlane_b32 s2, v5
	v_add_u32_e32 v5, 0x7000, v140
	global_load_lds_dwordx4 v[2:3], off
	v_lshl_add_u64 v[2:3], v[0:1], 0, s[62:63]
	s_mov_b32 m0, s2
	v_readfirstlane_b32 s2, v5
	v_add_u32_e32 v5, 0x8000, v140
	global_load_lds_dwordx4 v[2:3], off
	v_lshl_add_u64 v[2:3], v[0:1], 0, s[14:15]
	s_mov_b32 m0, s2
	v_readfirstlane_b32 s2, v5
	global_load_lds_dwordx4 v[2:3], off
	v_lshl_add_u64 v[2:3], v[0:1], 0, s[16:17]
	s_mov_b32 m0, s2
	v_lshl_add_u64 v[0:1], v[0:1], 0, s[18:19]
	global_load_lds_dwordx4 v[2:3], off
	v_add_u32_e32 v2, 0x9000, v140
	v_and_b32_e32 v135, 15, v134
	v_readfirstlane_b32 s2, v2
	v_add_u32_e32 v2, 0xa000, v140
	s_mov_b32 m0, s2
	v_readfirstlane_b32 s2, v2
	v_add_u32_e32 v2, 0xb000, v140
	global_load_lds_dwordx4 v[0:1], off
	v_lshl_add_u64 v[0:1], v[130:131], 0, s[62:63]
	s_mov_b32 m0, s2
	v_readfirstlane_b32 s2, v2
	global_load_lds_dwordx4 v[0:1], off
	v_lshl_add_u64 v[0:1], v[130:131], 0, s[14:15]
	s_mov_b32 m0, s2
	s_and_b32 s2, s49, 7
	global_load_lds_dwordx4 v[0:1], off
	s_lshl_b32 s2, s2, 11
	s_or_b32 s2, s3, s2
	v_add_u32_e32 v0, s2, v4
	v_ashrrev_i32_e32 v1, 31, v0
	v_lshlrev_b64 v[0:1], 11, v[0:1]
	v_and_b32_e32 v2, 7, v134
	v_lshl_or_b32 v0, v2, 4, v0
	v_bfe_u32 v136, v134, 6, 1
	v_lshl_add_u64 v[132:133], s[52:53], 0, v[0:1]
	v_mov_b32_e32 v0, 0
	v_lshlrev_b32_e32 v137, 6, v135
	v_and_b32_e32 v138, 48, v134
	v_lshlrev_b32_e32 v139, 12, v136
	s_mov_b32 s44, 0
	s_mov_b64 s[2:3], 0
	v_mov_b32_e32 v1, v0
	v_mov_b32_e32 v2, v0
	v_mov_b32_e32 v3, v0
	v_mov_b32_e32 v4, v0
	v_mov_b32_e32 v5, v0
	v_mov_b32_e32 v6, v0
	v_mov_b32_e32 v7, v0
	v_mov_b32_e32 v8, v0
	v_mov_b32_e32 v9, v0
	v_mov_b32_e32 v10, v0
	v_mov_b32_e32 v11, v0
	v_mov_b32_e32 v12, v0
	v_mov_b32_e32 v13, v0
	v_mov_b32_e32 v14, v0
	v_mov_b32_e32 v15, v0
	v_mov_b32_e32 v16, v0
	v_mov_b32_e32 v17, v0
	v_mov_b32_e32 v18, v0
	v_mov_b32_e32 v19, v0
	v_mov_b32_e32 v20, v0
	v_mov_b32_e32 v21, v0
	v_mov_b32_e32 v22, v0
	v_mov_b32_e32 v23, v0
	v_mov_b32_e32 v24, v0
	v_mov_b32_e32 v25, v0
	v_mov_b32_e32 v26, v0
	v_mov_b32_e32 v27, v0
	v_mov_b32_e32 v28, v0
	v_mov_b32_e32 v29, v0
	v_mov_b32_e32 v30, v0
	v_mov_b32_e32 v31, v0
	v_mov_b32_e32 v32, v0
	v_mov_b32_e32 v33, v0
	v_mov_b32_e32 v34, v0
	v_mov_b32_e32 v35, v0
	v_mov_b32_e32 v36, v0
	v_mov_b32_e32 v37, v0
	v_mov_b32_e32 v38, v0
	v_mov_b32_e32 v39, v0
	v_mov_b32_e32 v40, v0
	v_mov_b32_e32 v41, v0
	v_mov_b32_e32 v42, v0
	v_mov_b32_e32 v43, v0
	v_mov_b32_e32 v44, v0
	v_mov_b32_e32 v45, v0
	v_mov_b32_e32 v46, v0
	v_mov_b32_e32 v47, v0
	v_mov_b32_e32 v48, v0
	v_mov_b32_e32 v49, v0
	v_mov_b32_e32 v50, v0
	v_mov_b32_e32 v51, v0
	v_mov_b32_e32 v52, v0
	v_mov_b32_e32 v53, v0
	v_mov_b32_e32 v54, v0
	v_mov_b32_e32 v55, v0
	v_mov_b32_e32 v56, v0
	v_mov_b32_e32 v57, v0
	v_mov_b32_e32 v58, v0
	v_mov_b32_e32 v59, v0
	v_mov_b32_e32 v60, v0
	v_mov_b32_e32 v61, v0
	v_mov_b32_e32 v62, v0
	v_mov_b32_e32 v63, v0
	v_mov_b32_e32 v64, v0
	v_mov_b32_e32 v65, v0
	v_mov_b32_e32 v66, v0
	v_mov_b32_e32 v67, v0
	v_mov_b32_e32 v68, v0
	v_mov_b32_e32 v69, v0
	v_mov_b32_e32 v70, v0
	v_mov_b32_e32 v71, v0
	v_mov_b32_e32 v72, v0
	v_mov_b32_e32 v73, v0
	v_mov_b32_e32 v74, v0
	v_mov_b32_e32 v75, v0
	v_mov_b32_e32 v76, v0
	v_mov_b32_e32 v77, v0
	v_mov_b32_e32 v78, v0
	v_mov_b32_e32 v79, v0
	v_mov_b32_e32 v80, v0
	v_mov_b32_e32 v81, v0
	v_mov_b32_e32 v82, v0
	v_mov_b32_e32 v83, v0
	v_mov_b32_e32 v84, v0
	v_mov_b32_e32 v85, v0
	v_mov_b32_e32 v86, v0
	v_mov_b32_e32 v87, v0
	v_mov_b32_e32 v88, v0
	v_mov_b32_e32 v89, v0
	v_mov_b32_e32 v90, v0
	v_mov_b32_e32 v91, v0
	v_mov_b32_e32 v92, v0
	v_mov_b32_e32 v93, v0
	v_mov_b32_e32 v94, v0
	v_mov_b32_e32 v95, v0
	v_mov_b32_e32 v96, v0
	v_mov_b32_e32 v97, v0
	v_mov_b32_e32 v98, v0
	v_mov_b32_e32 v99, v0
	v_mov_b32_e32 v100, v0
	v_mov_b32_e32 v101, v0
	v_mov_b32_e32 v102, v0
	v_mov_b32_e32 v103, v0
	v_mov_b32_e32 v104, v0
	v_mov_b32_e32 v105, v0
	v_mov_b32_e32 v106, v0
	v_mov_b32_e32 v107, v0
	v_mov_b32_e32 v108, v0
	v_mov_b32_e32 v109, v0
	v_mov_b32_e32 v110, v0
	v_mov_b32_e32 v111, v0
	v_mov_b32_e32 v112, v0
	v_mov_b32_e32 v113, v0
	v_mov_b32_e32 v114, v0
	v_mov_b32_e32 v115, v0
	v_mov_b32_e32 v116, v0
	v_mov_b32_e32 v117, v0
	v_mov_b32_e32 v118, v0
	v_mov_b32_e32 v119, v0
	v_mov_b32_e32 v120, v0
	v_mov_b32_e32 v121, v0
	v_mov_b32_e32 v122, v0
	v_mov_b32_e32 v123, v0
	v_mov_b32_e32 v124, v0
	v_mov_b32_e32 v125, v0
	v_mov_b32_e32 v126, v0
	v_mov_b32_e32 v127, v0
.LBB0_123:
	s_add_i32 s45, s44, 2
	s_mul_hi_i32 s50, s45, 0x55555556
	s_lshr_b32 s51, s50, 31
	s_add_i32 s50, s50, s51
	s_mul_i32 s50, s50, 3
	s_sub_i32 s45, s45, s50
	s_mulk_i32 s45, 0x6000
	s_mul_i32 s54, s44, 0x6000
	v_readfirstlane_b32 s55, v140
	v_lshl_add_u64 v[232:233], v[132:133], 0, s[2:3]
	v_lshl_add_u64 v[234:235], v[130:131], 0, s[2:3]
	s_add_u32 s55, s55, s45
	s_waitcnt vmcnt(6) lgkmcnt(0)
	s_barrier
	v_or_b32_e32 v128, s54, v139
	v_add3_u32 v128, v128, v137, v138
	ds_read_b128 v[176:179], v128 offset:16384
	ds_read_b128 v[180:183], v128 offset:17408
	ds_read_b128 v[184:187], v128 offset:18432
	ds_read_b128 v[192:195], v128 offset:19456
	v_add_u32_e32 v128, s54, v141
	v_add3_u32 v128, v128, v137, v138
	ds_read_b128 v[144:147], v128
	ds_read_b128 v[148:151], v128 offset:1024
	ds_read_b128 v[152:155], v128 offset:2048
	ds_read_b128 v[156:159], v128 offset:3072
	ds_read_b128 v[160:163], v128 offset:4096
	ds_read_b128 v[164:167], v128 offset:5120
	ds_read_b128 v[168:171], v128 offset:6144
	ds_read_b128 v[172:175], v128 offset:7168
	s_setprio 1
	s_waitcnt lgkmcnt(7)
	v_mfma_f32_16x16x32_bf16 v[124:127], v[144:147], v[176:179], v[124:127]
	v_mfma_f32_16x16x32_bf16 v[120:123], v[144:147], v[180:183], v[120:123]
	v_mfma_f32_16x16x32_bf16 v[116:119], v[144:147], v[184:187], v[116:119]
	v_mfma_f32_16x16x32_bf16 v[112:115], v[144:147], v[192:195], v[112:115]
	s_mov_b32 m0, s55
	v_lshl_add_u64 v[236:237], v[232:233], 0, s[20:21]
	global_load_lds_dwordx4 v[236:237], off
	s_waitcnt lgkmcnt(6)
	v_mfma_f32_16x16x32_bf16 v[108:111], v[148:151], v[176:179], v[108:111]
	v_mfma_f32_16x16x32_bf16 v[104:107], v[148:151], v[180:183], v[104:107]
	v_mfma_f32_16x16x32_bf16 v[100:103], v[148:151], v[184:187], v[100:103]
	v_mfma_f32_16x16x32_bf16 v[96:99], v[148:151], v[192:195], v[96:99]
	s_add_u32 m0, s55, 0x1000
	v_lshl_add_u64 v[236:237], v[232:233], 0, s[22:23]
	global_load_lds_dwordx4 v[236:237], off
	s_waitcnt lgkmcnt(5)
	v_mfma_f32_16x16x32_bf16 v[92:95], v[152:155], v[176:179], v[92:95]
	v_mfma_f32_16x16x32_bf16 v[88:91], v[152:155], v[180:183], v[88:91]
	v_mfma_f32_16x16x32_bf16 v[84:87], v[152:155], v[184:187], v[84:87]
	v_mfma_f32_16x16x32_bf16 v[80:83], v[152:155], v[192:195], v[80:83]
	s_add_u32 m0, s55, 0x2000
	v_lshl_add_u64 v[236:237], v[232:233], 0, s[24:25]
	global_load_lds_dwordx4 v[236:237], off
	s_waitcnt lgkmcnt(4)
	v_mfma_f32_16x16x32_bf16 v[76:79], v[156:159], v[176:179], v[76:79]
	v_mfma_f32_16x16x32_bf16 v[72:75], v[156:159], v[180:183], v[72:75]
	v_mfma_f32_16x16x32_bf16 v[68:71], v[156:159], v[184:187], v[68:71]
	v_mfma_f32_16x16x32_bf16 v[64:67], v[156:159], v[192:195], v[64:67]
	s_add_u32 m0, s55, 0x3000
	v_lshl_add_u64 v[236:237], v[232:233], 0, s[26:27]
	global_load_lds_dwordx4 v[236:237], off
	s_waitcnt lgkmcnt(3)
	v_mfma_f32_16x16x32_bf16 v[60:63], v[160:163], v[176:179], v[60:63]
	v_mfma_f32_16x16x32_bf16 v[56:59], v[160:163], v[180:183], v[56:59]
	v_mfma_f32_16x16x32_bf16 v[52:55], v[160:163], v[184:187], v[52:55]
	v_mfma_f32_16x16x32_bf16 v[48:51], v[160:163], v[192:195], v[48:51]
	s_add_u32 m0, s55, 0x4000
	v_lshl_add_u64 v[236:237], v[234:235], 0, s[28:29]
	global_load_lds_dwordx4 v[236:237], off
	s_waitcnt lgkmcnt(2)
	v_mfma_f32_16x16x32_bf16 v[44:47], v[164:167], v[176:179], v[44:47]
	v_mfma_f32_16x16x32_bf16 v[40:43], v[164:167], v[180:183], v[40:43]
	v_mfma_f32_16x16x32_bf16 v[36:39], v[164:167], v[184:187], v[36:39]
	v_mfma_f32_16x16x32_bf16 v[32:35], v[164:167], v[192:195], v[32:35]
	s_add_u32 m0, s55, 0x5000
	v_lshl_add_u64 v[236:237], v[234:235], 0, s[30:31]
	global_load_lds_dwordx4 v[236:237], off
	s_waitcnt lgkmcnt(1)
	v_mfma_f32_16x16x32_bf16 v[28:31], v[168:171], v[176:179], v[28:31]
	v_mfma_f32_16x16x32_bf16 v[24:27], v[168:171], v[180:183], v[24:27]
	v_mfma_f32_16x16x32_bf16 v[20:23], v[168:171], v[184:187], v[20:23]
	v_mfma_f32_16x16x32_bf16 v[16:19], v[168:171], v[192:195], v[16:19]
	s_waitcnt lgkmcnt(0)
	v_mfma_f32_16x16x32_bf16 v[12:15], v[172:175], v[176:179], v[12:15]
	v_mfma_f32_16x16x32_bf16 v[8:11], v[172:175], v[180:183], v[8:11]
	v_mfma_f32_16x16x32_bf16 v[4:7], v[172:175], v[184:187], v[4:7]
	v_mfma_f32_16x16x32_bf16 v[0:3], v[172:175], v[192:195], v[0:3]
	s_setprio 0
	s_add_i32 s45, s44, 1
	s_cmp_lg_u32 s44, 2
	s_cselect_b32 s44, s45, 0
	s_add_u32 s2, s2, 0x80
	s_addc_u32 s3, s3, 0
	s_cmpk_lg_i32 s2, 0xf00
	s_cbranch_scc1 .LBB0_123
	s_waitcnt vmcnt(6) lgkmcnt(0)
	s_barrier
	v_add3_u32 v128, v141, v137, v138
	ds_read_b128 v[130:133], v128
	ds_read_b128 v[144:147], v128 offset:1024
	ds_read_b128 v[148:151], v128 offset:2048
	ds_read_b128 v[152:155], v128 offset:3072
	ds_read_b128 v[156:159], v128 offset:4096
	ds_read_b128 v[160:163], v128 offset:5120
	ds_read_b128 v[164:167], v128 offset:6144
	ds_read_b128 v[168:171], v128 offset:7168
	v_add3_u32 v137, v139, v137, v138
	ds_read_b128 v[138:141], v137 offset:16384
	ds_read_b128 v[172:175], v137 offset:17408
	ds_read_b128 v[176:179], v137 offset:18432
	ds_read_b128 v[180:183], v137 offset:19456
	s_setprio 1
	s_waitcnt lgkmcnt(0)
	v_mfma_f32_16x16x32_bf16 v[124:127], v[130:133], v[138:141], v[124:127]
	v_mfma_f32_16x16x32_bf16 v[120:123], v[130:133], v[172:175], v[120:123]
	v_mfma_f32_16x16x32_bf16 v[116:119], v[130:133], v[176:179], v[116:119]
	v_mfma_f32_16x16x32_bf16 v[112:115], v[130:133], v[180:183], v[112:115]
	v_mfma_f32_16x16x32_bf16 v[108:111], v[144:147], v[138:141], v[108:111]
	v_mfma_f32_16x16x32_bf16 v[104:107], v[144:147], v[172:175], v[104:107]
	v_mfma_f32_16x16x32_bf16 v[100:103], v[144:147], v[176:179], v[100:103]
	v_mfma_f32_16x16x32_bf16 v[96:99], v[144:147], v[180:183], v[96:99]
	v_mfma_f32_16x16x32_bf16 v[92:95], v[148:151], v[138:141], v[92:95]
	v_mfma_f32_16x16x32_bf16 v[88:91], v[148:151], v[172:175], v[88:91]
	v_mfma_f32_16x16x32_bf16 v[84:87], v[148:151], v[176:179], v[84:87]
	v_mfma_f32_16x16x32_bf16 v[80:83], v[148:151], v[180:183], v[80:83]
	v_mfma_f32_16x16x32_bf16 v[76:79], v[152:155], v[138:141], v[76:79]
	v_mfma_f32_16x16x32_bf16 v[72:75], v[152:155], v[172:175], v[72:75]
	v_mfma_f32_16x16x32_bf16 v[68:71], v[152:155], v[176:179], v[68:71]
	v_mfma_f32_16x16x32_bf16 v[64:67], v[152:155], v[180:183], v[64:67]
	v_mfma_f32_16x16x32_bf16 v[60:63], v[156:159], v[138:141], v[60:63]
	v_mfma_f32_16x16x32_bf16 v[56:59], v[156:159], v[172:175], v[56:59]
	v_mfma_f32_16x16x32_bf16 v[52:55], v[156:159], v[176:179], v[52:55]
	v_mfma_f32_16x16x32_bf16 v[48:51], v[156:159], v[180:183], v[48:51]
	v_mfma_f32_16x16x32_bf16 v[44:47], v[160:163], v[138:141], v[44:47]
	v_mfma_f32_16x16x32_bf16 v[40:43], v[160:163], v[172:175], v[40:43]
	v_mfma_f32_16x16x32_bf16 v[36:39], v[160:163], v[176:179], v[36:39]
	v_mfma_f32_16x16x32_bf16 v[32:35], v[160:163], v[180:183], v[32:35]
	v_mfma_f32_16x16x32_bf16 v[28:31], v[164:167], v[138:141], v[28:31]
	v_mfma_f32_16x16x32_bf16 v[24:27], v[164:167], v[172:175], v[24:27]
	v_mfma_f32_16x16x32_bf16 v[20:23], v[164:167], v[176:179], v[20:23]
	v_mfma_f32_16x16x32_bf16 v[16:19], v[164:167], v[180:183], v[16:19]
	v_mfma_f32_16x16x32_bf16 v[12:15], v[168:171], v[138:141], v[12:15]
	v_mfma_f32_16x16x32_bf16 v[8:11], v[168:171], v[172:175], v[8:11]
	v_mfma_f32_16x16x32_bf16 v[4:7], v[168:171], v[176:179], v[4:7]
	v_mfma_f32_16x16x32_bf16 v[0:3], v[168:171], v[180:183], v[0:3]
	s_setprio 0
	s_waitcnt vmcnt(0) lgkmcnt(0)
	s_barrier
	ds_read_b128 v[130:133], v128 offset:24576
	ds_read_b128 v[138:141], v128 offset:25600
	ds_read_b128 v[144:147], v128 offset:26624
	ds_read_b128 v[148:151], v128 offset:27648
	ds_read_b128 v[152:155], v128 offset:28672
	ds_read_b128 v[156:159], v128 offset:29696
	ds_read_b128 v[160:163], v128 offset:30720
	ds_read_b128 v[164:167], v128 offset:31744
	ds_read_b128 v[168:171], v137 offset:40960
	ds_read_b128 v[172:175], v137 offset:41984
	ds_read_b128 v[176:179], v137 offset:43008
	ds_read_b128 v[180:183], v137 offset:44032
	s_setprio 1
	s_waitcnt lgkmcnt(0)
	v_mfma_f32_16x16x32_bf16 v[124:127], v[130:133], v[168:171], v[124:127]
	v_mfma_f32_16x16x32_bf16 v[120:123], v[130:133], v[172:175], v[120:123]
	v_mfma_f32_16x16x32_bf16 v[116:119], v[130:133], v[176:179], v[116:119]
	v_mfma_f32_16x16x32_bf16 v[112:115], v[130:133], v[180:183], v[112:115]
	v_mfma_f32_16x16x32_bf16 v[108:111], v[138:141], v[168:171], v[108:111]
	v_mfma_f32_16x16x32_bf16 v[104:107], v[138:141], v[172:175], v[104:107]
	v_mfma_f32_16x16x32_bf16 v[100:103], v[138:141], v[176:179], v[100:103]
	v_mfma_f32_16x16x32_bf16 v[96:99], v[138:141], v[180:183], v[96:99]
	v_mfma_f32_16x16x32_bf16 v[92:95], v[144:147], v[168:171], v[92:95]
	v_mfma_f32_16x16x32_bf16 v[88:91], v[144:147], v[172:175], v[88:91]
	v_mfma_f32_16x16x32_bf16 v[84:87], v[144:147], v[176:179], v[84:87]
	v_mfma_f32_16x16x32_bf16 v[130:133], v[144:147], v[180:183], v[80:83]
	v_mfma_f32_16x16x32_bf16 v[138:141], v[148:151], v[168:171], v[76:79]
	v_mfma_f32_16x16x32_bf16 v[72:75], v[148:151], v[172:175], v[72:75]
	v_mfma_f32_16x16x32_bf16 v[68:71], v[148:151], v[176:179], v[68:71]
	v_mfma_f32_16x16x32_bf16 v[64:67], v[148:151], v[180:183], v[64:67]
	v_mfma_f32_16x16x32_bf16 v[60:63], v[152:155], v[168:171], v[60:63]
	v_mfma_f32_16x16x32_bf16 v[56:59], v[152:155], v[172:175], v[56:59]
	v_mfma_f32_16x16x32_bf16 v[52:55], v[152:155], v[176:179], v[52:55]
	v_mfma_f32_16x16x32_bf16 v[48:51], v[152:155], v[180:183], v[48:51]
	v_mfma_f32_16x16x32_bf16 v[44:47], v[156:159], v[168:171], v[44:47]
	v_mfma_f32_16x16x32_bf16 v[40:43], v[156:159], v[172:175], v[40:43]
	v_mfma_f32_16x16x32_bf16 v[36:39], v[156:159], v[176:179], v[36:39]
	v_mfma_f32_16x16x32_bf16 v[32:35], v[156:159], v[180:183], v[32:35]
	v_mfma_f32_16x16x32_bf16 v[28:31], v[160:163], v[168:171], v[28:31]
	v_mfma_f32_16x16x32_bf16 v[24:27], v[160:163], v[172:175], v[24:27]
	v_mfma_f32_16x16x32_bf16 v[20:23], v[160:163], v[176:179], v[20:23]
	v_mfma_f32_16x16x32_bf16 v[16:19], v[160:163], v[180:183], v[16:19]
	v_mfma_f32_16x16x32_bf16 v[12:15], v[164:167], v[168:171], v[12:15]
	v_mfma_f32_16x16x32_bf16 v[8:11], v[164:167], v[172:175], v[8:11]
	v_mfma_f32_16x16x32_bf16 v[4:7], v[164:167], v[176:179], v[4:7]
	v_mfma_f32_16x16x32_bf16 v[0:3], v[164:167], v[180:183], v[0:3]
	s_setprio 0
	v_and_b32_e32 v76, 0xffffff80, v134
	v_add_u32_e32 v76, s43, v76
	v_lshlrev_b32_e32 v77, 6, v136
	s_add_i32 s2, s4, 0xfffffc00
	v_ashrrev_i32_e32 v76, 6, v76
	v_or3_b32 v136, v77, s2, v135
	v_ashrrev_i32_e32 v77, 31, v76
	v_lshlrev_b64 v[78:79], 17, v[76:77]
	v_readlane_b32 s2, v254, 60
	v_lshrrev_b32_e32 v77, 1, v134
	v_and_b32_sdwa v81, v127, v142 dst_sel:DWORD dst_unused:UNUSED_PAD src0_sel:WORD_1 src1_sel:DWORD
	v_and_b32_sdwa v82, v125, v142 dst_sel:DWORD dst_unused:UNUSED_PAD src0_sel:WORD_1 src1_sel:DWORD
	v_readlane_b32 s3, v254, 61
	v_and_b32_e32 v128, 24, v77
	v_and_b32_sdwa v77, v126, v142 dst_sel:DWORD dst_unused:UNUSED_PAD src0_sel:WORD_1 src1_sel:DWORD
	v_and_b32_sdwa v80, v124, v142 dst_sel:DWORD dst_unused:UNUSED_PAD src0_sel:WORD_1 src1_sel:DWORD
	v_add3_u32 v81, v127, v81, s46
	v_add3_u32 v82, v125, v82, s46
	v_lshl_add_u64 v[78:79], s[2:3], 0, v[78:79]
	v_mov_b32_e32 v137, v129
	v_add3_u32 v80, v124, v80, s46
	v_add3_u32 v77, v126, v77, s46
	v_and_b32_e32 v81, 0xffff0000, v81
	v_and_b32_e32 v82, 0xffff0000, v82
	v_and_b32_sdwa v83, v123, v142 dst_sel:DWORD dst_unused:UNUSED_PAD src0_sel:WORD_1 src1_sel:DWORD
	v_lshl_add_u64 v[134:135], v[78:79], 0, v[128:129]
	v_lshlrev_b64 v[78:79], 7, v[136:137]
	v_or_b32_sdwa v81, v81, v77 dst_sel:DWORD dst_unused:UNUSED_PAD src0_sel:DWORD src1_sel:WORD_1
	v_or_b32_sdwa v80, v82, v80 dst_sel:DWORD dst_unused:UNUSED_PAD src0_sel:DWORD src1_sel:WORD_1
	v_and_b32_sdwa v77, v122, v142 dst_sel:DWORD dst_unused:UNUSED_PAD src0_sel:WORD_1 src1_sel:DWORD
	v_and_b32_sdwa v82, v120, v142 dst_sel:DWORD dst_unused:UNUSED_PAD src0_sel:WORD_1 src1_sel:DWORD
	v_add3_u32 v83, v123, v83, s46
	v_lshl_add_u64 v[144:145], v[134:135], 0, v[78:79]
	v_add3_u32 v82, v120, v82, s46
	v_add3_u32 v77, v122, v77, s46
	v_and_b32_sdwa v120, v121, v142 dst_sel:DWORD dst_unused:UNUSED_PAD src0_sel:WORD_1 src1_sel:DWORD
	v_and_b32_e32 v83, 0xffff0000, v83
	global_store_dwordx2 v[144:145], v[80:81], off
	v_or_b32_e32 v80, 16, v136
	v_mov_b32_e32 v81, v129
	v_add3_u32 v120, v121, v120, s46
	v_or_b32_sdwa v83, v83, v77 dst_sel:DWORD dst_unused:UNUSED_PAD src0_sel:DWORD src1_sel:WORD_1
	v_and_b32_sdwa v77, v118, v142 dst_sel:DWORD dst_unused:UNUSED_PAD src0_sel:WORD_1 src1_sel:DWORD
	v_lshlrev_b64 v[80:81], 7, v[80:81]
	v_and_b32_e32 v120, 0xffff0000, v120
	v_and_b32_sdwa v122, v116, v142 dst_sel:DWORD dst_unused:UNUSED_PAD src0_sel:WORD_1 src1_sel:DWORD
	v_add3_u32 v77, v118, v77, s46
	v_and_b32_sdwa v118, v119, v142 dst_sel:DWORD dst_unused:UNUSED_PAD src0_sel:WORD_1 src1_sel:DWORD
	v_lshl_add_u64 v[124:125], v[134:135], 0, v[80:81]
	v_or_b32_sdwa v82, v120, v82 dst_sel:DWORD dst_unused:UNUSED_PAD src0_sel:DWORD src1_sel:WORD_1
	v_add3_u32 v116, v116, v122, s46
	v_and_b32_sdwa v122, v117, v142 dst_sel:DWORD dst_unused:UNUSED_PAD src0_sel:WORD_1 src1_sel:DWORD
	v_add3_u32 v118, v119, v118, s46
	global_store_dwordx2 v[124:125], v[82:83], off
	v_or_b32_e32 v82, 32, v136
	v_mov_b32_e32 v83, v129
	v_add3_u32 v117, v117, v122, s46
	v_and_b32_e32 v118, 0xffff0000, v118
	v_lshlrev_b64 v[82:83], 7, v[82:83]
	v_and_b32_e32 v119, 0xffff0000, v117
	v_or_b32_sdwa v117, v118, v77 dst_sel:DWORD dst_unused:UNUSED_PAD src0_sel:DWORD src1_sel:WORD_1
	v_and_b32_sdwa v77, v114, v142 dst_sel:DWORD dst_unused:UNUSED_PAD src0_sel:WORD_1 src1_sel:DWORD
	v_and_b32_sdwa v122, v112, v142 dst_sel:DWORD dst_unused:UNUSED_PAD src0_sel:WORD_1 src1_sel:DWORD
	v_lshl_add_u64 v[120:121], v[134:135], 0, v[82:83]
	v_or_b32_sdwa v116, v119, v116 dst_sel:DWORD dst_unused:UNUSED_PAD src0_sel:DWORD src1_sel:WORD_1
	v_add3_u32 v112, v112, v122, s46
	v_add3_u32 v77, v114, v77, s46
	v_and_b32_sdwa v114, v115, v142 dst_sel:DWORD dst_unused:UNUSED_PAD src0_sel:WORD_1 src1_sel:DWORD
	v_and_b32_sdwa v122, v113, v142 dst_sel:DWORD dst_unused:UNUSED_PAD src0_sel:WORD_1 src1_sel:DWORD
	global_store_dwordx2 v[120:121], v[116:117], off
	v_or_b32_e32 v116, 48, v136
	v_mov_b32_e32 v117, v129
	v_add3_u32 v114, v115, v114, s46
	v_add3_u32 v113, v113, v122, s46
	v_lshlrev_b64 v[116:117], 7, v[116:117]
	v_and_b32_e32 v114, 0xffff0000, v114
	v_and_b32_e32 v115, 0xffff0000, v113
	v_lshl_add_u64 v[118:119], v[134:135], 0, v[116:117]
	v_or_b32_sdwa v113, v114, v77 dst_sel:DWORD dst_unused:UNUSED_PAD src0_sel:DWORD src1_sel:WORD_1
	v_or_b32_sdwa v112, v115, v112 dst_sel:DWORD dst_unused:UNUSED_PAD src0_sel:DWORD src1_sel:WORD_1
	global_store_dwordx2 v[118:119], v[112:113], off
	v_and_b32_sdwa v77, v110, v142 dst_sel:DWORD dst_unused:UNUSED_PAD src0_sel:WORD_1 src1_sel:DWORD
	v_and_b32_sdwa v112, v108, v142 dst_sel:DWORD dst_unused:UNUSED_PAD src0_sel:WORD_1 src1_sel:DWORD
	v_add3_u32 v108, v108, v112, s46
	v_add3_u32 v77, v110, v77, s46
	v_and_b32_sdwa v110, v111, v142 dst_sel:DWORD dst_unused:UNUSED_PAD src0_sel:WORD_1 src1_sel:DWORD
	v_and_b32_sdwa v112, v109, v142 dst_sel:DWORD dst_unused:UNUSED_PAD src0_sel:WORD_1 src1_sel:DWORD
	v_add3_u32 v110, v111, v110, s46
	v_add3_u32 v109, v109, v112, s46
	v_and_b32_e32 v110, 0xffff0000, v110
	v_and_b32_e32 v111, 0xffff0000, v109
	v_or_b32_sdwa v109, v110, v77 dst_sel:DWORD dst_unused:UNUSED_PAD src0_sel:DWORD src1_sel:WORD_1
	v_or_b32_sdwa v108, v111, v108 dst_sel:DWORD dst_unused:UNUSED_PAD src0_sel:DWORD src1_sel:WORD_1
	global_store_dwordx2 v[144:145], v[108:109], off offset:32
	v_and_b32_sdwa v77, v106, v142 dst_sel:DWORD dst_unused:UNUSED_PAD src0_sel:WORD_1 src1_sel:DWORD
	v_and_b32_sdwa v108, v104, v142 dst_sel:DWORD dst_unused:UNUSED_PAD src0_sel:WORD_1 src1_sel:DWORD
	v_add3_u32 v104, v104, v108, s46
	v_add3_u32 v77, v106, v77, s46
	v_and_b32_sdwa v106, v107, v142 dst_sel:DWORD dst_unused:UNUSED_PAD src0_sel:WORD_1 src1_sel:DWORD
	v_and_b32_sdwa v108, v105, v142 dst_sel:DWORD dst_unused:UNUSED_PAD src0_sel:WORD_1 src1_sel:DWORD
	v_add3_u32 v106, v107, v106, s46
	v_add3_u32 v105, v105, v108, s46
	v_and_b32_e32 v106, 0xffff0000, v106
	v_and_b32_e32 v107, 0xffff0000, v105
	v_or_b32_sdwa v105, v106, v77 dst_sel:DWORD dst_unused:UNUSED_PAD src0_sel:DWORD src1_sel:WORD_1
	v_or_b32_sdwa v104, v107, v104 dst_sel:DWORD dst_unused:UNUSED_PAD src0_sel:DWORD src1_sel:WORD_1
	global_store_dwordx2 v[124:125], v[104:105], off offset:32
	v_and_b32_sdwa v77, v102, v142 dst_sel:DWORD dst_unused:UNUSED_PAD src0_sel:WORD_1 src1_sel:DWORD
	v_and_b32_sdwa v104, v100, v142 dst_sel:DWORD dst_unused:UNUSED_PAD src0_sel:WORD_1 src1_sel:DWORD
	v_add3_u32 v100, v100, v104, s46
	v_add3_u32 v77, v102, v77, s46
	v_and_b32_sdwa v102, v103, v142 dst_sel:DWORD dst_unused:UNUSED_PAD src0_sel:WORD_1 src1_sel:DWORD
	v_and_b32_sdwa v104, v101, v142 dst_sel:DWORD dst_unused:UNUSED_PAD src0_sel:WORD_1 src1_sel:DWORD
	v_add3_u32 v102, v103, v102, s46
	v_add3_u32 v101, v101, v104, s46
	v_and_b32_e32 v102, 0xffff0000, v102
	v_and_b32_e32 v103, 0xffff0000, v101
	v_or_b32_sdwa v101, v102, v77 dst_sel:DWORD dst_unused:UNUSED_PAD src0_sel:DWORD src1_sel:WORD_1
	v_or_b32_sdwa v100, v103, v100 dst_sel:DWORD dst_unused:UNUSED_PAD src0_sel:DWORD src1_sel:WORD_1
	global_store_dwordx2 v[120:121], v[100:101], off offset:32
	v_and_b32_sdwa v77, v98, v142 dst_sel:DWORD dst_unused:UNUSED_PAD src0_sel:WORD_1 src1_sel:DWORD
	v_and_b32_sdwa v100, v96, v142 dst_sel:DWORD dst_unused:UNUSED_PAD src0_sel:WORD_1 src1_sel:DWORD
	v_add3_u32 v96, v96, v100, s46
	v_add3_u32 v77, v98, v77, s46
	v_and_b32_sdwa v98, v99, v142 dst_sel:DWORD dst_unused:UNUSED_PAD src0_sel:WORD_1 src1_sel:DWORD
	v_and_b32_sdwa v100, v97, v142 dst_sel:DWORD dst_unused:UNUSED_PAD src0_sel:WORD_1 src1_sel:DWORD
	v_add3_u32 v98, v99, v98, s46
	v_add3_u32 v97, v97, v100, s46
	v_and_b32_e32 v98, 0xffff0000, v98
	v_and_b32_e32 v99, 0xffff0000, v97
	v_or_b32_sdwa v97, v98, v77 dst_sel:DWORD dst_unused:UNUSED_PAD src0_sel:DWORD src1_sel:WORD_1
	v_or_b32_sdwa v96, v99, v96 dst_sel:DWORD dst_unused:UNUSED_PAD src0_sel:DWORD src1_sel:WORD_1
	global_store_dwordx2 v[118:119], v[96:97], off offset:32
	v_and_b32_sdwa v77, v94, v142 dst_sel:DWORD dst_unused:UNUSED_PAD src0_sel:WORD_1 src1_sel:DWORD
	v_and_b32_sdwa v96, v92, v142 dst_sel:DWORD dst_unused:UNUSED_PAD src0_sel:WORD_1 src1_sel:DWORD
	v_add3_u32 v92, v92, v96, s46
	v_add3_u32 v77, v94, v77, s46
	v_and_b32_sdwa v94, v95, v142 dst_sel:DWORD dst_unused:UNUSED_PAD src0_sel:WORD_1 src1_sel:DWORD
	v_and_b32_sdwa v96, v93, v142 dst_sel:DWORD dst_unused:UNUSED_PAD src0_sel:WORD_1 src1_sel:DWORD
	v_add3_u32 v94, v95, v94, s46
	v_add3_u32 v93, v93, v96, s46
	v_and_b32_e32 v94, 0xffff0000, v94
	v_and_b32_e32 v95, 0xffff0000, v93
	v_or_b32_sdwa v93, v94, v77 dst_sel:DWORD dst_unused:UNUSED_PAD src0_sel:DWORD src1_sel:WORD_1
	v_or_b32_sdwa v92, v95, v92 dst_sel:DWORD dst_unused:UNUSED_PAD src0_sel:DWORD src1_sel:WORD_1
	global_store_dwordx2 v[144:145], v[92:93], off offset:64
	v_and_b32_sdwa v77, v90, v142 dst_sel:DWORD dst_unused:UNUSED_PAD src0_sel:WORD_1 src1_sel:DWORD
	v_and_b32_sdwa v92, v88, v142 dst_sel:DWORD dst_unused:UNUSED_PAD src0_sel:WORD_1 src1_sel:DWORD
	v_add3_u32 v88, v88, v92, s46
	v_add3_u32 v77, v90, v77, s46
	v_and_b32_sdwa v90, v91, v142 dst_sel:DWORD dst_unused:UNUSED_PAD src0_sel:WORD_1 src1_sel:DWORD
	v_and_b32_sdwa v92, v89, v142 dst_sel:DWORD dst_unused:UNUSED_PAD src0_sel:WORD_1 src1_sel:DWORD
	v_add3_u32 v90, v91, v90, s46
	v_add3_u32 v89, v89, v92, s46
	v_and_b32_e32 v90, 0xffff0000, v90
	v_and_b32_e32 v91, 0xffff0000, v89
	v_or_b32_sdwa v89, v90, v77 dst_sel:DWORD dst_unused:UNUSED_PAD src0_sel:DWORD src1_sel:WORD_1
	v_or_b32_sdwa v88, v91, v88 dst_sel:DWORD dst_unused:UNUSED_PAD src0_sel:DWORD src1_sel:WORD_1
	global_store_dwordx2 v[124:125], v[88:89], off offset:64
	v_and_b32_sdwa v77, v86, v142 dst_sel:DWORD dst_unused:UNUSED_PAD src0_sel:WORD_1 src1_sel:DWORD
	v_and_b32_sdwa v88, v84, v142 dst_sel:DWORD dst_unused:UNUSED_PAD src0_sel:WORD_1 src1_sel:DWORD
	v_add3_u32 v84, v84, v88, s46
	v_add3_u32 v77, v86, v77, s46
	v_and_b32_sdwa v86, v87, v142 dst_sel:DWORD dst_unused:UNUSED_PAD src0_sel:WORD_1 src1_sel:DWORD
	v_and_b32_sdwa v88, v85, v142 dst_sel:DWORD dst_unused:UNUSED_PAD src0_sel:WORD_1 src1_sel:DWORD
	v_add3_u32 v86, v87, v86, s46
	v_add3_u32 v85, v85, v88, s46
	v_and_b32_e32 v86, 0xffff0000, v86
	v_and_b32_e32 v87, 0xffff0000, v85
	v_or_b32_sdwa v85, v86, v77 dst_sel:DWORD dst_unused:UNUSED_PAD src0_sel:DWORD src1_sel:WORD_1
	v_or_b32_sdwa v84, v87, v84 dst_sel:DWORD dst_unused:UNUSED_PAD src0_sel:DWORD src1_sel:WORD_1
	global_store_dwordx2 v[120:121], v[84:85], off offset:64
	v_and_b32_sdwa v85, v133, v142 dst_sel:DWORD dst_unused:UNUSED_PAD src0_sel:WORD_1 src1_sel:DWORD
	v_and_b32_sdwa v86, v131, v142 dst_sel:DWORD dst_unused:UNUSED_PAD src0_sel:WORD_1 src1_sel:DWORD
	v_and_b32_sdwa v77, v132, v142 dst_sel:DWORD dst_unused:UNUSED_PAD src0_sel:WORD_1 src1_sel:DWORD
	v_and_b32_sdwa v84, v130, v142 dst_sel:DWORD dst_unused:UNUSED_PAD src0_sel:WORD_1 src1_sel:DWORD
	v_add3_u32 v85, v133, v85, s46
	v_add3_u32 v86, v131, v86, s46
	v_add3_u32 v84, v130, v84, s46
	v_add3_u32 v77, v132, v77, s46
	v_and_b32_e32 v85, 0xffff0000, v85
	v_and_b32_e32 v86, 0xffff0000, v86
	v_or_b32_sdwa v85, v85, v77 dst_sel:DWORD dst_unused:UNUSED_PAD src0_sel:DWORD src1_sel:WORD_1
	v_or_b32_sdwa v84, v86, v84 dst_sel:DWORD dst_unused:UNUSED_PAD src0_sel:DWORD src1_sel:WORD_1
	global_store_dwordx2 v[118:119], v[84:85], off offset:64
	v_and_b32_sdwa v85, v141, v142 dst_sel:DWORD dst_unused:UNUSED_PAD src0_sel:WORD_1 src1_sel:DWORD
	v_and_b32_sdwa v86, v139, v142 dst_sel:DWORD dst_unused:UNUSED_PAD src0_sel:WORD_1 src1_sel:DWORD
	v_and_b32_sdwa v77, v140, v142 dst_sel:DWORD dst_unused:UNUSED_PAD src0_sel:WORD_1 src1_sel:DWORD
	v_and_b32_sdwa v84, v138, v142 dst_sel:DWORD dst_unused:UNUSED_PAD src0_sel:WORD_1 src1_sel:DWORD
	v_add3_u32 v85, v141, v85, s46
	v_add3_u32 v86, v139, v86, s46
	v_add3_u32 v84, v138, v84, s46
	v_add3_u32 v77, v140, v77, s46
	v_and_b32_e32 v85, 0xffff0000, v85
	v_and_b32_e32 v86, 0xffff0000, v86
	v_or_b32_sdwa v85, v85, v77 dst_sel:DWORD dst_unused:UNUSED_PAD src0_sel:DWORD src1_sel:WORD_1
	v_or_b32_sdwa v84, v86, v84 dst_sel:DWORD dst_unused:UNUSED_PAD src0_sel:DWORD src1_sel:WORD_1
	global_store_dwordx2 v[144:145], v[84:85], off offset:96
	v_and_b32_sdwa v77, v74, v142 dst_sel:DWORD dst_unused:UNUSED_PAD src0_sel:WORD_1 src1_sel:DWORD
	v_and_b32_sdwa v84, v72, v142 dst_sel:DWORD dst_unused:UNUSED_PAD src0_sel:WORD_1 src1_sel:DWORD
	v_add3_u32 v72, v72, v84, s46
	v_add3_u32 v74, v74, v77, s46
	v_and_b32_sdwa v77, v75, v142 dst_sel:DWORD dst_unused:UNUSED_PAD src0_sel:WORD_1 src1_sel:DWORD
	v_and_b32_sdwa v84, v73, v142 dst_sel:DWORD dst_unused:UNUSED_PAD src0_sel:WORD_1 src1_sel:DWORD
	v_add3_u32 v75, v75, v77, s46
	v_add3_u32 v73, v73, v84, s46
	v_and_b32_e32 v75, 0xffff0000, v75
	v_and_b32_e32 v77, 0xffff0000, v73
	v_or_b32_sdwa v73, v75, v74 dst_sel:DWORD dst_unused:UNUSED_PAD src0_sel:DWORD src1_sel:WORD_1
	v_or_b32_sdwa v72, v77, v72 dst_sel:DWORD dst_unused:UNUSED_PAD src0_sel:DWORD src1_sel:WORD_1
	global_store_dwordx2 v[124:125], v[72:73], off offset:96
	v_and_b32_sdwa v72, v70, v142 dst_sel:DWORD dst_unused:UNUSED_PAD src0_sel:WORD_1 src1_sel:DWORD
	v_and_b32_sdwa v73, v68, v142 dst_sel:DWORD dst_unused:UNUSED_PAD src0_sel:WORD_1 src1_sel:DWORD
	v_add3_u32 v68, v68, v73, s46
	v_add3_u32 v70, v70, v72, s46
	v_and_b32_sdwa v72, v71, v142 dst_sel:DWORD dst_unused:UNUSED_PAD src0_sel:WORD_1 src1_sel:DWORD
	v_and_b32_sdwa v73, v69, v142 dst_sel:DWORD dst_unused:UNUSED_PAD src0_sel:WORD_1 src1_sel:DWORD
	v_add3_u32 v71, v71, v72, s46
	v_add3_u32 v69, v69, v73, s46
	v_and_b32_e32 v71, 0xffff0000, v71
	v_and_b32_e32 v72, 0xffff0000, v69
	v_or_b32_sdwa v69, v71, v70 dst_sel:DWORD dst_unused:UNUSED_PAD src0_sel:DWORD src1_sel:WORD_1
	v_or_b32_sdwa v68, v72, v68 dst_sel:DWORD dst_unused:UNUSED_PAD src0_sel:DWORD src1_sel:WORD_1
	global_store_dwordx2 v[120:121], v[68:69], off offset:96
	v_and_b32_sdwa v69, v64, v142 dst_sel:DWORD dst_unused:UNUSED_PAD src0_sel:WORD_1 src1_sel:DWORD
	v_and_b32_sdwa v68, v66, v142 dst_sel:DWORD dst_unused:UNUSED_PAD src0_sel:WORD_1 src1_sel:DWORD
	v_add3_u32 v64, v64, v69, s46
	v_and_b32_sdwa v69, v65, v142 dst_sel:DWORD dst_unused:UNUSED_PAD src0_sel:WORD_1 src1_sel:DWORD
	v_add3_u32 v66, v66, v68, s46
	v_and_b32_sdwa v68, v67, v142 dst_sel:DWORD dst_unused:UNUSED_PAD src0_sel:WORD_1 src1_sel:DWORD
	v_add3_u32 v65, v65, v69, s46
	v_add3_u32 v67, v67, v68, s46
	v_and_b32_e32 v68, 0xffff0000, v65
	v_or_b32_sdwa v64, v68, v64 dst_sel:DWORD dst_unused:UNUSED_PAD src0_sel:DWORD src1_sel:WORD_1
	v_and_b32_sdwa v68, v62, v142 dst_sel:DWORD dst_unused:UNUSED_PAD src0_sel:WORD_1 src1_sel:DWORD
	v_and_b32_sdwa v69, v60, v142 dst_sel:DWORD dst_unused:UNUSED_PAD src0_sel:WORD_1 src1_sel:DWORD
	v_add3_u32 v62, v62, v68, s46
	v_and_b32_sdwa v68, v63, v142 dst_sel:DWORD dst_unused:UNUSED_PAD src0_sel:WORD_1 src1_sel:DWORD
	v_add3_u32 v60, v60, v69, s46
	v_and_b32_sdwa v69, v61, v142 dst_sel:DWORD dst_unused:UNUSED_PAD src0_sel:WORD_1 src1_sel:DWORD
	v_add3_u32 v63, v63, v68, s46
	v_add3_u32 v61, v61, v69, s46
	v_and_b32_e32 v63, 0xffff0000, v63
	v_and_b32_e32 v68, 0xffff0000, v61
	v_or_b32_sdwa v61, v63, v62 dst_sel:DWORD dst_unused:UNUSED_PAD src0_sel:DWORD src1_sel:WORD_1
	v_and_b32_sdwa v62, v58, v142 dst_sel:DWORD dst_unused:UNUSED_PAD src0_sel:WORD_1 src1_sel:DWORD
	v_and_b32_sdwa v63, v56, v142 dst_sel:DWORD dst_unused:UNUSED_PAD src0_sel:WORD_1 src1_sel:DWORD
	v_add3_u32 v58, v58, v62, s46
	v_and_b32_sdwa v62, v59, v142 dst_sel:DWORD dst_unused:UNUSED_PAD src0_sel:WORD_1 src1_sel:DWORD
	v_and_b32_e32 v67, 0xffff0000, v67
	v_add3_u32 v56, v56, v63, s46
	v_and_b32_sdwa v63, v57, v142 dst_sel:DWORD dst_unused:UNUSED_PAD src0_sel:WORD_1 src1_sel:DWORD
	v_add3_u32 v59, v59, v62, s46
	v_or_b32_sdwa v65, v67, v66 dst_sel:DWORD dst_unused:UNUSED_PAD src0_sel:DWORD src1_sel:WORD_1
	v_add3_u32 v57, v57, v63, s46
	v_and_b32_e32 v59, 0xffff0000, v59
	global_store_dwordx2 v[118:119], v[64:65], off offset:96
	v_or_b32_e32 v64, 1, v76
	v_and_b32_e32 v62, 0xffff0000, v57
	v_or_b32_sdwa v57, v59, v58 dst_sel:DWORD dst_unused:UNUSED_PAD src0_sel:DWORD src1_sel:WORD_1
	v_and_b32_sdwa v58, v54, v142 dst_sel:DWORD dst_unused:UNUSED_PAD src0_sel:WORD_1 src1_sel:DWORD
	v_ashrrev_i32_e32 v65, 31, v64
	v_and_b32_sdwa v59, v52, v142 dst_sel:DWORD dst_unused:UNUSED_PAD src0_sel:WORD_1 src1_sel:DWORD
	v_add3_u32 v54, v54, v58, s46
	v_and_b32_sdwa v58, v55, v142 dst_sel:DWORD dst_unused:UNUSED_PAD src0_sel:WORD_1 src1_sel:DWORD
	v_lshlrev_b64 v[64:65], 17, v[64:65]
	v_add3_u32 v52, v52, v59, s46
	v_and_b32_sdwa v59, v53, v142 dst_sel:DWORD dst_unused:UNUSED_PAD src0_sel:WORD_1 src1_sel:DWORD
	v_add3_u32 v55, v55, v58, s46
	v_lshl_add_u64 v[64:65], s[2:3], 0, v[64:65]
	v_add3_u32 v53, v53, v59, s46
	v_and_b32_e32 v55, 0xffff0000, v55
	v_lshl_add_u64 v[64:65], v[64:65], 0, v[128:129]
	v_and_b32_e32 v58, 0xffff0000, v53
	v_or_b32_sdwa v53, v55, v54 dst_sel:DWORD dst_unused:UNUSED_PAD src0_sel:DWORD src1_sel:WORD_1
	v_and_b32_sdwa v54, v50, v142 dst_sel:DWORD dst_unused:UNUSED_PAD src0_sel:WORD_1 src1_sel:DWORD
	v_and_b32_sdwa v55, v48, v142 dst_sel:DWORD dst_unused:UNUSED_PAD src0_sel:WORD_1 src1_sel:DWORD
	v_lshl_add_u64 v[66:67], v[64:65], 0, v[78:79]
	v_or_b32_sdwa v60, v68, v60 dst_sel:DWORD dst_unused:UNUSED_PAD src0_sel:DWORD src1_sel:WORD_1
	v_add3_u32 v48, v48, v55, s46
	v_add3_u32 v50, v50, v54, s46
	v_and_b32_sdwa v54, v51, v142 dst_sel:DWORD dst_unused:UNUSED_PAD src0_sel:WORD_1 src1_sel:DWORD
	v_and_b32_sdwa v55, v49, v142 dst_sel:DWORD dst_unused:UNUSED_PAD src0_sel:WORD_1 src1_sel:DWORD
	global_store_dwordx2 v[66:67], v[60:61], off
	v_lshl_add_u64 v[60:61], v[64:65], 0, v[80:81]
	v_or_b32_sdwa v56, v62, v56 dst_sel:DWORD dst_unused:UNUSED_PAD src0_sel:DWORD src1_sel:WORD_1
	v_add3_u32 v51, v51, v54, s46
	v_add3_u32 v49, v49, v55, s46
	global_store_dwordx2 v[60:61], v[56:57], off
	v_lshl_add_u64 v[56:57], v[64:65], 0, v[82:83]
	v_or_b32_sdwa v52, v58, v52 dst_sel:DWORD dst_unused:UNUSED_PAD src0_sel:DWORD src1_sel:WORD_1
	v_and_b32_e32 v51, 0xffff0000, v51
	v_and_b32_e32 v54, 0xffff0000, v49
	global_store_dwordx2 v[56:57], v[52:53], off
	v_lshl_add_u64 v[52:53], v[64:65], 0, v[116:117]
	v_or_b32_sdwa v49, v51, v50 dst_sel:DWORD dst_unused:UNUSED_PAD src0_sel:DWORD src1_sel:WORD_1
	v_or_b32_sdwa v48, v54, v48 dst_sel:DWORD dst_unused:UNUSED_PAD src0_sel:DWORD src1_sel:WORD_1
	global_store_dwordx2 v[52:53], v[48:49], off
	v_and_b32_sdwa v48, v46, v142 dst_sel:DWORD dst_unused:UNUSED_PAD src0_sel:WORD_1 src1_sel:DWORD
	v_and_b32_sdwa v49, v44, v142 dst_sel:DWORD dst_unused:UNUSED_PAD src0_sel:WORD_1 src1_sel:DWORD
	v_add3_u32 v44, v44, v49, s46
	v_add3_u32 v46, v46, v48, s46
	v_and_b32_sdwa v48, v47, v142 dst_sel:DWORD dst_unused:UNUSED_PAD src0_sel:WORD_1 src1_sel:DWORD
	v_and_b32_sdwa v49, v45, v142 dst_sel:DWORD dst_unused:UNUSED_PAD src0_sel:WORD_1 src1_sel:DWORD
	v_add3_u32 v47, v47, v48, s46
	v_add3_u32 v45, v45, v49, s46
	v_and_b32_e32 v47, 0xffff0000, v47
	v_and_b32_e32 v48, 0xffff0000, v45
	v_or_b32_sdwa v45, v47, v46 dst_sel:DWORD dst_unused:UNUSED_PAD src0_sel:DWORD src1_sel:WORD_1
	v_or_b32_sdwa v44, v48, v44 dst_sel:DWORD dst_unused:UNUSED_PAD src0_sel:DWORD src1_sel:WORD_1
	global_store_dwordx2 v[66:67], v[44:45], off offset:32
	v_and_b32_sdwa v44, v42, v142 dst_sel:DWORD dst_unused:UNUSED_PAD src0_sel:WORD_1 src1_sel:DWORD
	v_and_b32_sdwa v45, v40, v142 dst_sel:DWORD dst_unused:UNUSED_PAD src0_sel:WORD_1 src1_sel:DWORD
	v_add3_u32 v40, v40, v45, s46
	v_add3_u32 v42, v42, v44, s46
	v_and_b32_sdwa v44, v43, v142 dst_sel:DWORD dst_unused:UNUSED_PAD src0_sel:WORD_1 src1_sel:DWORD
	v_and_b32_sdwa v45, v41, v142 dst_sel:DWORD dst_unused:UNUSED_PAD src0_sel:WORD_1 src1_sel:DWORD
	v_add3_u32 v43, v43, v44, s46
	v_add3_u32 v41, v41, v45, s46
	v_and_b32_e32 v43, 0xffff0000, v43
	v_and_b32_e32 v44, 0xffff0000, v41
	v_or_b32_sdwa v41, v43, v42 dst_sel:DWORD dst_unused:UNUSED_PAD src0_sel:DWORD src1_sel:WORD_1
	v_or_b32_sdwa v40, v44, v40 dst_sel:DWORD dst_unused:UNUSED_PAD src0_sel:DWORD src1_sel:WORD_1
	global_store_dwordx2 v[60:61], v[40:41], off offset:32
	v_and_b32_sdwa v40, v38, v142 dst_sel:DWORD dst_unused:UNUSED_PAD src0_sel:WORD_1 src1_sel:DWORD
	v_and_b32_sdwa v41, v36, v142 dst_sel:DWORD dst_unused:UNUSED_PAD src0_sel:WORD_1 src1_sel:DWORD
	v_add3_u32 v36, v36, v41, s46
	v_add3_u32 v38, v38, v40, s46
	v_and_b32_sdwa v40, v39, v142 dst_sel:DWORD dst_unused:UNUSED_PAD src0_sel:WORD_1 src1_sel:DWORD
	v_and_b32_sdwa v41, v37, v142 dst_sel:DWORD dst_unused:UNUSED_PAD src0_sel:WORD_1 src1_sel:DWORD
	v_add3_u32 v39, v39, v40, s46
	v_add3_u32 v37, v37, v41, s46
	v_and_b32_e32 v39, 0xffff0000, v39
	v_and_b32_e32 v40, 0xffff0000, v37
	v_or_b32_sdwa v37, v39, v38 dst_sel:DWORD dst_unused:UNUSED_PAD src0_sel:DWORD src1_sel:WORD_1
	v_or_b32_sdwa v36, v40, v36 dst_sel:DWORD dst_unused:UNUSED_PAD src0_sel:DWORD src1_sel:WORD_1
	global_store_dwordx2 v[56:57], v[36:37], off offset:32
	v_and_b32_sdwa v36, v34, v142 dst_sel:DWORD dst_unused:UNUSED_PAD src0_sel:WORD_1 src1_sel:DWORD
	v_and_b32_sdwa v37, v32, v142 dst_sel:DWORD dst_unused:UNUSED_PAD src0_sel:WORD_1 src1_sel:DWORD
	v_add3_u32 v32, v32, v37, s46
	v_add3_u32 v34, v34, v36, s46
	v_and_b32_sdwa v36, v35, v142 dst_sel:DWORD dst_unused:UNUSED_PAD src0_sel:WORD_1 src1_sel:DWORD
	v_and_b32_sdwa v37, v33, v142 dst_sel:DWORD dst_unused:UNUSED_PAD src0_sel:WORD_1 src1_sel:DWORD
	v_add3_u32 v35, v35, v36, s46
	v_add3_u32 v33, v33, v37, s46
	v_and_b32_e32 v35, 0xffff0000, v35
	v_and_b32_e32 v36, 0xffff0000, v33
	v_or_b32_sdwa v33, v35, v34 dst_sel:DWORD dst_unused:UNUSED_PAD src0_sel:DWORD src1_sel:WORD_1
	v_or_b32_sdwa v32, v36, v32 dst_sel:DWORD dst_unused:UNUSED_PAD src0_sel:DWORD src1_sel:WORD_1
	global_store_dwordx2 v[52:53], v[32:33], off offset:32
	v_and_b32_sdwa v32, v30, v142 dst_sel:DWORD dst_unused:UNUSED_PAD src0_sel:WORD_1 src1_sel:DWORD
	v_and_b32_sdwa v33, v28, v142 dst_sel:DWORD dst_unused:UNUSED_PAD src0_sel:WORD_1 src1_sel:DWORD
	v_add3_u32 v28, v28, v33, s46
	v_add3_u32 v30, v30, v32, s46
	v_and_b32_sdwa v32, v31, v142 dst_sel:DWORD dst_unused:UNUSED_PAD src0_sel:WORD_1 src1_sel:DWORD
	v_and_b32_sdwa v33, v29, v142 dst_sel:DWORD dst_unused:UNUSED_PAD src0_sel:WORD_1 src1_sel:DWORD
	v_add3_u32 v31, v31, v32, s46
	v_add3_u32 v29, v29, v33, s46
	v_and_b32_e32 v31, 0xffff0000, v31
	v_and_b32_e32 v32, 0xffff0000, v29
	v_or_b32_sdwa v29, v31, v30 dst_sel:DWORD dst_unused:UNUSED_PAD src0_sel:DWORD src1_sel:WORD_1
	v_or_b32_sdwa v28, v32, v28 dst_sel:DWORD dst_unused:UNUSED_PAD src0_sel:DWORD src1_sel:WORD_1
	global_store_dwordx2 v[66:67], v[28:29], off offset:64
	v_and_b32_sdwa v28, v26, v142 dst_sel:DWORD dst_unused:UNUSED_PAD src0_sel:WORD_1 src1_sel:DWORD
	v_and_b32_sdwa v29, v24, v142 dst_sel:DWORD dst_unused:UNUSED_PAD src0_sel:WORD_1 src1_sel:DWORD
	v_add3_u32 v24, v24, v29, s46
	v_add3_u32 v26, v26, v28, s46
	v_and_b32_sdwa v28, v27, v142 dst_sel:DWORD dst_unused:UNUSED_PAD src0_sel:WORD_1 src1_sel:DWORD
	v_and_b32_sdwa v29, v25, v142 dst_sel:DWORD dst_unused:UNUSED_PAD src0_sel:WORD_1 src1_sel:DWORD
	v_add3_u32 v27, v27, v28, s46
	v_add3_u32 v25, v25, v29, s46
	v_and_b32_e32 v27, 0xffff0000, v27
	v_and_b32_e32 v28, 0xffff0000, v25
	v_or_b32_sdwa v25, v27, v26 dst_sel:DWORD dst_unused:UNUSED_PAD src0_sel:DWORD src1_sel:WORD_1
	v_or_b32_sdwa v24, v28, v24 dst_sel:DWORD dst_unused:UNUSED_PAD src0_sel:DWORD src1_sel:WORD_1
	global_store_dwordx2 v[60:61], v[24:25], off offset:64
	v_and_b32_sdwa v24, v22, v142 dst_sel:DWORD dst_unused:UNUSED_PAD src0_sel:WORD_1 src1_sel:DWORD
	v_and_b32_sdwa v25, v20, v142 dst_sel:DWORD dst_unused:UNUSED_PAD src0_sel:WORD_1 src1_sel:DWORD
	v_add3_u32 v20, v20, v25, s46
	v_add3_u32 v22, v22, v24, s46
	v_and_b32_sdwa v24, v23, v142 dst_sel:DWORD dst_unused:UNUSED_PAD src0_sel:WORD_1 src1_sel:DWORD
	v_and_b32_sdwa v25, v21, v142 dst_sel:DWORD dst_unused:UNUSED_PAD src0_sel:WORD_1 src1_sel:DWORD
	v_add3_u32 v23, v23, v24, s46
	v_add3_u32 v21, v21, v25, s46
	v_and_b32_e32 v23, 0xffff0000, v23
	v_and_b32_e32 v24, 0xffff0000, v21
	v_or_b32_sdwa v21, v23, v22 dst_sel:DWORD dst_unused:UNUSED_PAD src0_sel:DWORD src1_sel:WORD_1
	v_or_b32_sdwa v20, v24, v20 dst_sel:DWORD dst_unused:UNUSED_PAD src0_sel:DWORD src1_sel:WORD_1
	global_store_dwordx2 v[56:57], v[20:21], off offset:64
	v_and_b32_sdwa v20, v18, v142 dst_sel:DWORD dst_unused:UNUSED_PAD src0_sel:WORD_1 src1_sel:DWORD
	v_and_b32_sdwa v21, v16, v142 dst_sel:DWORD dst_unused:UNUSED_PAD src0_sel:WORD_1 src1_sel:DWORD
	v_add3_u32 v16, v16, v21, s46
	v_add3_u32 v18, v18, v20, s46
	v_and_b32_sdwa v20, v19, v142 dst_sel:DWORD dst_unused:UNUSED_PAD src0_sel:WORD_1 src1_sel:DWORD
	v_and_b32_sdwa v21, v17, v142 dst_sel:DWORD dst_unused:UNUSED_PAD src0_sel:WORD_1 src1_sel:DWORD
	v_add3_u32 v19, v19, v20, s46
	v_add3_u32 v17, v17, v21, s46
	v_and_b32_e32 v19, 0xffff0000, v19
	v_and_b32_e32 v20, 0xffff0000, v17
	v_or_b32_sdwa v17, v19, v18 dst_sel:DWORD dst_unused:UNUSED_PAD src0_sel:DWORD src1_sel:WORD_1
	v_or_b32_sdwa v16, v20, v16 dst_sel:DWORD dst_unused:UNUSED_PAD src0_sel:DWORD src1_sel:WORD_1
	global_store_dwordx2 v[52:53], v[16:17], off offset:64
	v_and_b32_sdwa v16, v14, v142 dst_sel:DWORD dst_unused:UNUSED_PAD src0_sel:WORD_1 src1_sel:DWORD
	v_and_b32_sdwa v17, v12, v142 dst_sel:DWORD dst_unused:UNUSED_PAD src0_sel:WORD_1 src1_sel:DWORD
	v_add3_u32 v12, v12, v17, s46
	v_add3_u32 v14, v14, v16, s46
	v_and_b32_sdwa v16, v15, v142 dst_sel:DWORD dst_unused:UNUSED_PAD src0_sel:WORD_1 src1_sel:DWORD
	v_and_b32_sdwa v17, v13, v142 dst_sel:DWORD dst_unused:UNUSED_PAD src0_sel:WORD_1 src1_sel:DWORD
	v_add3_u32 v15, v15, v16, s46
	v_add3_u32 v13, v13, v17, s46
	v_and_b32_e32 v15, 0xffff0000, v15
	v_and_b32_e32 v16, 0xffff0000, v13
	v_or_b32_sdwa v13, v15, v14 dst_sel:DWORD dst_unused:UNUSED_PAD src0_sel:DWORD src1_sel:WORD_1
	v_or_b32_sdwa v12, v16, v12 dst_sel:DWORD dst_unused:UNUSED_PAD src0_sel:DWORD src1_sel:WORD_1
	global_store_dwordx2 v[66:67], v[12:13], off offset:96
	v_and_b32_sdwa v12, v10, v142 dst_sel:DWORD dst_unused:UNUSED_PAD src0_sel:WORD_1 src1_sel:DWORD
	v_and_b32_sdwa v13, v8, v142 dst_sel:DWORD dst_unused:UNUSED_PAD src0_sel:WORD_1 src1_sel:DWORD
	v_add3_u32 v8, v8, v13, s46
	v_add3_u32 v10, v10, v12, s46
	v_and_b32_sdwa v12, v11, v142 dst_sel:DWORD dst_unused:UNUSED_PAD src0_sel:WORD_1 src1_sel:DWORD
	v_and_b32_sdwa v13, v9, v142 dst_sel:DWORD dst_unused:UNUSED_PAD src0_sel:WORD_1 src1_sel:DWORD
	v_add3_u32 v11, v11, v12, s46
	v_add3_u32 v9, v9, v13, s46
	v_and_b32_e32 v11, 0xffff0000, v11
	v_and_b32_e32 v12, 0xffff0000, v9
	v_or_b32_sdwa v9, v11, v10 dst_sel:DWORD dst_unused:UNUSED_PAD src0_sel:DWORD src1_sel:WORD_1
	v_or_b32_sdwa v8, v12, v8 dst_sel:DWORD dst_unused:UNUSED_PAD src0_sel:DWORD src1_sel:WORD_1
	global_store_dwordx2 v[60:61], v[8:9], off offset:96
	v_and_b32_sdwa v8, v6, v142 dst_sel:DWORD dst_unused:UNUSED_PAD src0_sel:WORD_1 src1_sel:DWORD
	v_and_b32_sdwa v9, v4, v142 dst_sel:DWORD dst_unused:UNUSED_PAD src0_sel:WORD_1 src1_sel:DWORD
	v_add3_u32 v4, v4, v9, s46
	v_add3_u32 v6, v6, v8, s46
	v_and_b32_sdwa v8, v7, v142 dst_sel:DWORD dst_unused:UNUSED_PAD src0_sel:WORD_1 src1_sel:DWORD
	v_and_b32_sdwa v9, v5, v142 dst_sel:DWORD dst_unused:UNUSED_PAD src0_sel:WORD_1 src1_sel:DWORD
	v_add3_u32 v7, v7, v8, s46
	v_add3_u32 v5, v5, v9, s46
	v_and_b32_e32 v7, 0xffff0000, v7
	v_and_b32_e32 v8, 0xffff0000, v5
	v_or_b32_sdwa v5, v7, v6 dst_sel:DWORD dst_unused:UNUSED_PAD src0_sel:DWORD src1_sel:WORD_1
	v_or_b32_sdwa v4, v8, v4 dst_sel:DWORD dst_unused:UNUSED_PAD src0_sel:DWORD src1_sel:WORD_1
	global_store_dwordx2 v[56:57], v[4:5], off offset:96
	v_and_b32_sdwa v4, v2, v142 dst_sel:DWORD dst_unused:UNUSED_PAD src0_sel:WORD_1 src1_sel:DWORD
	v_and_b32_sdwa v5, v0, v142 dst_sel:DWORD dst_unused:UNUSED_PAD src0_sel:WORD_1 src1_sel:DWORD
	v_add3_u32 v0, v0, v5, s46
	v_add3_u32 v2, v2, v4, s46
	v_and_b32_sdwa v4, v3, v142 dst_sel:DWORD dst_unused:UNUSED_PAD src0_sel:WORD_1 src1_sel:DWORD
	v_and_b32_sdwa v5, v1, v142 dst_sel:DWORD dst_unused:UNUSED_PAD src0_sel:WORD_1 src1_sel:DWORD
	v_add3_u32 v3, v3, v4, s46
	v_add3_u32 v1, v1, v5, s46
	v_and_b32_e32 v3, 0xffff0000, v3
	v_and_b32_e32 v4, 0xffff0000, v1
	v_or_b32_sdwa v1, v3, v2 dst_sel:DWORD dst_unused:UNUSED_PAD src0_sel:DWORD src1_sel:WORD_1
	v_or_b32_sdwa v0, v4, v0 dst_sel:DWORD dst_unused:UNUSED_PAD src0_sel:DWORD src1_sel:WORD_1
	global_store_dwordx2 v[52:53], v[0:1], off offset:96
	s_branch .LBB0_119
.LBB0_125:
	v_mov_b32_e32 v134, v190
	s_lshl_b32 s42, s42, 8
	v_lshlrev_b32_e32 v0, 6, v134
	v_and_b32_e32 v141, 0xffffe3c0, v0
	v_lshlrev_b32_e32 v0, 1, v134
	v_and_b32_e32 v5, 3, v134
	v_ashrrev_i32_e32 v4, 2, v134
	v_and_b32_e32 v4, -2, v4
	v_and_or_b32 v0, v0, 24, v5
	v_lshlrev_b32_e32 v139, 6, v0
	v_add_u32_e32 v0, s42, v4
	v_ashrrev_i32_e32 v1, 31, v0
	v_add_u32_e32 v2, s4, v4
	v_lshlrev_b32_e32 v140, 4, v134
	v_lshlrev_b64 v[0:1], 11, v[0:1]
	v_ashrrev_i32_e32 v3, 31, v2
	v_lshl_add_u64 v[0:1], s[88:89], 0, v[0:1]
	v_and_b32_e32 v128, 0x70, v140
	v_lshlrev_b64 v[2:3], 11, v[2:3]
	v_readfirstlane_b32 s2, v140
	v_add_u32_e32 v6, 0x1000, v140
	v_lshl_add_u64 v[0:1], v[0:1], 0, v[128:129]
	v_lshl_add_u64 v[2:3], s[52:53], 0, v[2:3]
	s_waitcnt vmcnt(0)
	s_mov_b32 m0, s2
	v_readfirstlane_b32 s2, v6
	v_add_u32_e32 v6, 0x2000, v140
	v_lshl_add_u64 v[130:131], v[2:3], 0, v[128:129]
	global_load_lds_dwordx4 v[0:1], off
	v_lshl_add_u64 v[2:3], v[0:1], 0, s[8:9]
	s_mov_b32 m0, s2
	v_readfirstlane_b32 s2, v6
	v_add_u32_e32 v6, 0x3000, v140
	global_load_lds_dwordx4 v[2:3], off
	v_lshl_add_u64 v[2:3], v[0:1], 0, s[10:11]
	s_mov_b32 m0, s2
	v_readfirstlane_b32 s2, v6
	global_load_lds_dwordx4 v[2:3], off
	v_lshl_add_u64 v[2:3], v[0:1], 0, s[12:13]
	s_mov_b32 m0, s2
	v_add_u32_e32 v6, 0x5000, v140
	global_load_lds_dwordx4 v[2:3], off
	v_add_u32_e32 v2, 0x4000, v140
	s_lshl_b32 s3, s5, 8
	v_readfirstlane_b32 s2, v2
	s_mov_b32 m0, s2
	v_readfirstlane_b32 s2, v6
	v_add_u32_e32 v6, 0x6000, v140
	global_load_lds_dwordx4 v[130:131], off
	v_lshl_add_u64 v[2:3], v[130:131], 0, s[8:9]
	s_mov_b32 m0, s2
	v_readfirstlane_b32 s2, v6
	v_add_u32_e32 v6, 0x7000, v140
	global_load_lds_dwordx4 v[2:3], off
	v_lshl_add_u64 v[2:3], v[0:1], 0, s[62:63]
	s_mov_b32 m0, s2
	v_readfirstlane_b32 s2, v6
	v_add_u32_e32 v6, 0x8000, v140
	global_load_lds_dwordx4 v[2:3], off
	v_lshl_add_u64 v[2:3], v[0:1], 0, s[14:15]
	s_mov_b32 m0, s2
	v_readfirstlane_b32 s2, v6
	global_load_lds_dwordx4 v[2:3], off
	v_lshl_add_u64 v[2:3], v[0:1], 0, s[16:17]
	s_mov_b32 m0, s2
	v_lshl_add_u64 v[0:1], v[0:1], 0, s[18:19]
	global_load_lds_dwordx4 v[2:3], off
	v_add_u32_e32 v2, 0x9000, v140
	v_bfe_u32 v136, v134, 6, 1
	v_readfirstlane_b32 s2, v2
	v_add_u32_e32 v2, 0xa000, v140
	s_mov_b32 m0, s2
	v_readfirstlane_b32 s2, v2
	v_add_u32_e32 v2, 0xb000, v140
	global_load_lds_dwordx4 v[0:1], off
	v_lshl_add_u64 v[0:1], v[130:131], 0, s[62:63]
	s_mov_b32 m0, s2
	v_readfirstlane_b32 s2, v2
	global_load_lds_dwordx4 v[0:1], off
	v_lshl_add_u64 v[0:1], v[130:131], 0, s[14:15]
	s_mov_b32 m0, s2
	s_and_b32 s2, s49, 7
	global_load_lds_dwordx4 v[0:1], off
	s_lshl_b32 s2, s2, 11
	s_or_b32 s2, s3, s2
	v_add_u32_e32 v0, s2, v4
	v_ashrrev_i32_e32 v1, 31, v0
	v_lshlrev_b64 v[0:1], 11, v[0:1]
	v_and_b32_e32 v238, 7, v134
	v_lshl_or_b32 v0, v238, 4, v0
	v_lshl_add_u64 v[132:133], s[52:53], 0, v[0:1]
	v_mov_b32_e32 v0, 0
	v_and_b32_e32 v135, 15, v134
	v_and_b32_e32 v137, 48, v134
	v_lshlrev_b32_e32 v138, 12, v136
	s_mov_b32 s5, 0
	s_mov_b64 s[2:3], 0
	v_mov_b32_e32 v1, v0
	v_mov_b32_e32 v2, v0
	v_mov_b32_e32 v3, v0
	v_mov_b32_e32 v4, v0
	v_mov_b32_e32 v5, v0
	v_mov_b32_e32 v6, v0
	v_mov_b32_e32 v7, v0
	v_mov_b32_e32 v8, v0
	v_mov_b32_e32 v9, v0
	v_mov_b32_e32 v10, v0
	v_mov_b32_e32 v11, v0
	v_mov_b32_e32 v12, v0
	v_mov_b32_e32 v13, v0
	v_mov_b32_e32 v14, v0
	v_mov_b32_e32 v15, v0
	v_mov_b32_e32 v16, v0
	v_mov_b32_e32 v17, v0
	v_mov_b32_e32 v18, v0
	v_mov_b32_e32 v19, v0
	v_mov_b32_e32 v20, v0
	v_mov_b32_e32 v21, v0
	v_mov_b32_e32 v22, v0
	v_mov_b32_e32 v23, v0
	v_mov_b32_e32 v24, v0
	v_mov_b32_e32 v25, v0
	v_mov_b32_e32 v26, v0
	v_mov_b32_e32 v27, v0
	v_mov_b32_e32 v28, v0
	v_mov_b32_e32 v29, v0
	v_mov_b32_e32 v30, v0
	v_mov_b32_e32 v31, v0
	v_mov_b32_e32 v32, v0
	v_mov_b32_e32 v33, v0
	v_mov_b32_e32 v34, v0
	v_mov_b32_e32 v35, v0
	v_mov_b32_e32 v36, v0
	v_mov_b32_e32 v37, v0
	v_mov_b32_e32 v38, v0
	v_mov_b32_e32 v39, v0
	v_mov_b32_e32 v40, v0
	v_mov_b32_e32 v41, v0
	v_mov_b32_e32 v42, v0
	v_mov_b32_e32 v43, v0
	v_mov_b32_e32 v44, v0
	v_mov_b32_e32 v45, v0
	v_mov_b32_e32 v46, v0
	v_mov_b32_e32 v47, v0
	v_mov_b32_e32 v48, v0
	v_mov_b32_e32 v49, v0
	v_mov_b32_e32 v50, v0
	v_mov_b32_e32 v51, v0
	v_mov_b32_e32 v52, v0
	v_mov_b32_e32 v53, v0
	v_mov_b32_e32 v54, v0
	v_mov_b32_e32 v55, v0
	v_mov_b32_e32 v56, v0
	v_mov_b32_e32 v57, v0
	v_mov_b32_e32 v58, v0
	v_mov_b32_e32 v59, v0
	v_mov_b32_e32 v60, v0
	v_mov_b32_e32 v61, v0
	v_mov_b32_e32 v62, v0
	v_mov_b32_e32 v63, v0
	v_mov_b32_e32 v64, v0
	v_mov_b32_e32 v65, v0
	v_mov_b32_e32 v66, v0
	v_mov_b32_e32 v67, v0
	v_mov_b32_e32 v68, v0
	v_mov_b32_e32 v69, v0
	v_mov_b32_e32 v70, v0
	v_mov_b32_e32 v71, v0
	v_mov_b32_e32 v72, v0
	v_mov_b32_e32 v73, v0
	v_mov_b32_e32 v74, v0
	v_mov_b32_e32 v75, v0
	v_mov_b32_e32 v76, v0
	v_mov_b32_e32 v77, v0
	v_mov_b32_e32 v78, v0
	v_mov_b32_e32 v79, v0
	v_mov_b32_e32 v80, v0
	v_mov_b32_e32 v81, v0
	v_mov_b32_e32 v82, v0
	v_mov_b32_e32 v83, v0
	v_mov_b32_e32 v84, v0
	v_mov_b32_e32 v85, v0
	v_mov_b32_e32 v86, v0
	v_mov_b32_e32 v87, v0
	v_mov_b32_e32 v88, v0
	v_mov_b32_e32 v89, v0
	v_mov_b32_e32 v90, v0
	v_mov_b32_e32 v91, v0
	v_mov_b32_e32 v92, v0
	v_mov_b32_e32 v93, v0
	v_mov_b32_e32 v94, v0
	v_mov_b32_e32 v95, v0
	v_mov_b32_e32 v96, v0
	v_mov_b32_e32 v97, v0
	v_mov_b32_e32 v98, v0
	v_mov_b32_e32 v99, v0
	v_mov_b32_e32 v100, v0
	v_mov_b32_e32 v101, v0
	v_mov_b32_e32 v102, v0
	v_mov_b32_e32 v103, v0
	v_mov_b32_e32 v104, v0
	v_mov_b32_e32 v105, v0
	v_mov_b32_e32 v106, v0
	v_mov_b32_e32 v107, v0
	v_mov_b32_e32 v108, v0
	v_mov_b32_e32 v109, v0
	v_mov_b32_e32 v110, v0
	v_mov_b32_e32 v111, v0
	v_mov_b32_e32 v112, v0
	v_mov_b32_e32 v113, v0
	v_mov_b32_e32 v114, v0
	v_mov_b32_e32 v115, v0
	v_mov_b32_e32 v116, v0
	v_mov_b32_e32 v117, v0
	v_mov_b32_e32 v118, v0
	v_mov_b32_e32 v119, v0
	v_mov_b32_e32 v120, v0
	v_mov_b32_e32 v121, v0
	v_mov_b32_e32 v122, v0
	v_mov_b32_e32 v123, v0
	v_mov_b32_e32 v124, v0
	v_mov_b32_e32 v125, v0
	v_mov_b32_e32 v126, v0
	v_mov_b32_e32 v127, v0
.LBB0_126:
	s_add_i32 s43, s5, 2
	s_mul_hi_i32 s44, s43, 0x55555556
	s_lshr_b32 s45, s44, 31
	s_add_i32 s44, s44, s45
	s_mul_i32 s44, s44, 3
	s_sub_i32 s43, s43, s44
	s_mulk_i32 s43, 0x6000
	s_mul_i32 s54, s5, 0x6000
	v_readfirstlane_b32 s55, v140
	v_lshl_add_u64 v[232:233], v[132:133], 0, s[2:3]
	v_lshl_add_u64 v[234:235], v[130:131], 0, s[2:3]
	s_add_u32 s55, s55, s43
	s_waitcnt vmcnt(6) lgkmcnt(0)
	s_barrier
	v_or_b32_e32 v128, s54, v138
	v_add3_u32 v128, v128, v139, v137
	ds_read_b128 v[176:179], v128 offset:16384
	ds_read_b128 v[180:183], v128 offset:16640
	ds_read_b128 v[184:187], v128 offset:18432
	ds_read_b128 v[192:195], v128 offset:18688
	v_add3_u32 v128, s54, v141, v137
	ds_read_b128 v[144:147], v128
	ds_read_b128 v[148:151], v128 offset:1024
	ds_read_b128 v[152:155], v128 offset:2048
	ds_read_b128 v[156:159], v128 offset:3072
	ds_read_b128 v[160:163], v128 offset:4096
	ds_read_b128 v[164:167], v128 offset:5120
	ds_read_b128 v[168:171], v128 offset:6144
	ds_read_b128 v[172:175], v128 offset:7168
	s_setprio 1
	s_waitcnt lgkmcnt(7)
	v_mfma_f32_16x16x32_bf16 v[124:127], v[176:179], v[144:147], v[124:127]
	v_mfma_f32_16x16x32_bf16 v[120:123], v[180:183], v[144:147], v[120:123]
	v_mfma_f32_16x16x32_bf16 v[116:119], v[184:187], v[144:147], v[116:119]
	v_mfma_f32_16x16x32_bf16 v[112:115], v[192:195], v[144:147], v[112:115]
	s_mov_b32 m0, s55
	v_lshl_add_u64 v[236:237], v[232:233], 0, s[20:21]
	global_load_lds_dwordx4 v[236:237], off
	s_waitcnt lgkmcnt(6)
	v_mfma_f32_16x16x32_bf16 v[108:111], v[176:179], v[148:151], v[108:111]
	v_mfma_f32_16x16x32_bf16 v[104:107], v[180:183], v[148:151], v[104:107]
	v_mfma_f32_16x16x32_bf16 v[100:103], v[184:187], v[148:151], v[100:103]
	v_mfma_f32_16x16x32_bf16 v[96:99], v[192:195], v[148:151], v[96:99]
	s_add_u32 m0, s55, 0x1000
	v_lshl_add_u64 v[236:237], v[232:233], 0, s[22:23]
	global_load_lds_dwordx4 v[236:237], off
	s_waitcnt lgkmcnt(5)
	v_mfma_f32_16x16x32_bf16 v[92:95], v[176:179], v[152:155], v[92:95]
	v_mfma_f32_16x16x32_bf16 v[88:91], v[180:183], v[152:155], v[88:91]
	v_mfma_f32_16x16x32_bf16 v[84:87], v[184:187], v[152:155], v[84:87]
	v_mfma_f32_16x16x32_bf16 v[80:83], v[192:195], v[152:155], v[80:83]
	s_add_u32 m0, s55, 0x2000
	v_lshl_add_u64 v[236:237], v[232:233], 0, s[24:25]
	global_load_lds_dwordx4 v[236:237], off
	s_waitcnt lgkmcnt(4)
	v_mfma_f32_16x16x32_bf16 v[76:79], v[176:179], v[156:159], v[76:79]
	v_mfma_f32_16x16x32_bf16 v[72:75], v[180:183], v[156:159], v[72:75]
	v_mfma_f32_16x16x32_bf16 v[68:71], v[184:187], v[156:159], v[68:71]
	v_mfma_f32_16x16x32_bf16 v[64:67], v[192:195], v[156:159], v[64:67]
	s_add_u32 m0, s55, 0x3000
	v_lshl_add_u64 v[236:237], v[232:233], 0, s[26:27]
	global_load_lds_dwordx4 v[236:237], off
	s_waitcnt lgkmcnt(3)
	v_mfma_f32_16x16x32_bf16 v[60:63], v[176:179], v[160:163], v[60:63]
	v_mfma_f32_16x16x32_bf16 v[56:59], v[180:183], v[160:163], v[56:59]
	v_mfma_f32_16x16x32_bf16 v[52:55], v[184:187], v[160:163], v[52:55]
	v_mfma_f32_16x16x32_bf16 v[48:51], v[192:195], v[160:163], v[48:51]
	s_add_u32 m0, s55, 0x4000
	v_lshl_add_u64 v[236:237], v[234:235], 0, s[28:29]
	global_load_lds_dwordx4 v[236:237], off
	s_waitcnt lgkmcnt(2)
	v_mfma_f32_16x16x32_bf16 v[44:47], v[176:179], v[164:167], v[44:47]
	v_mfma_f32_16x16x32_bf16 v[40:43], v[180:183], v[164:167], v[40:43]
	v_mfma_f32_16x16x32_bf16 v[36:39], v[184:187], v[164:167], v[36:39]
	v_mfma_f32_16x16x32_bf16 v[32:35], v[192:195], v[164:167], v[32:35]
	s_add_u32 m0, s55, 0x5000
	v_lshl_add_u64 v[236:237], v[234:235], 0, s[30:31]
	global_load_lds_dwordx4 v[236:237], off
	s_waitcnt lgkmcnt(1)
	v_mfma_f32_16x16x32_bf16 v[28:31], v[176:179], v[168:171], v[28:31]
	v_mfma_f32_16x16x32_bf16 v[24:27], v[180:183], v[168:171], v[24:27]
	v_mfma_f32_16x16x32_bf16 v[20:23], v[184:187], v[168:171], v[20:23]
	v_mfma_f32_16x16x32_bf16 v[16:19], v[192:195], v[168:171], v[16:19]
	s_waitcnt lgkmcnt(0)
	v_mfma_f32_16x16x32_bf16 v[12:15], v[176:179], v[172:175], v[12:15]
	v_mfma_f32_16x16x32_bf16 v[8:11], v[180:183], v[172:175], v[8:11]
	v_mfma_f32_16x16x32_bf16 v[4:7], v[184:187], v[172:175], v[4:7]
	v_mfma_f32_16x16x32_bf16 v[0:3], v[192:195], v[172:175], v[0:3]
	s_setprio 0
	s_add_i32 s43, s5, 1
	s_cmp_lg_u32 s5, 2
	s_cselect_b32 s5, s43, 0
	s_add_u32 s2, s2, 0x80
	s_addc_u32 s3, s3, 0
	s_cmpk_eq_i32 s2, 0xf00
	s_cbranch_scc0 .LBB0_126
	s_waitcnt vmcnt(6) lgkmcnt(0)
	s_barrier
	v_add_u32_e32 v128, v141, v137
	ds_read_b128 v[130:133], v128
	ds_read_b128 v[144:147], v128 offset:1024
	ds_read_b128 v[148:151], v128 offset:2048
	ds_read_b128 v[152:155], v128 offset:3072
	ds_read_b128 v[156:159], v128 offset:4096
	ds_read_b128 v[160:163], v128 offset:5120
	ds_read_b128 v[164:167], v128 offset:6144
	ds_read_b128 v[168:171], v128 offset:7168
	v_add3_u32 v137, v138, v139, v137
	ds_read_b128 v[138:141], v137 offset:16384
	ds_read_b128 v[172:175], v137 offset:16640
	ds_read_b128 v[176:179], v137 offset:18432
	ds_read_b128 v[180:183], v137 offset:18688
	s_setprio 1
	s_waitcnt lgkmcnt(0)
	v_mfma_f32_16x16x32_bf16 v[124:127], v[138:141], v[130:133], v[124:127]
	v_mfma_f32_16x16x32_bf16 v[184:187], v[172:175], v[130:133], v[120:123]
	v_mfma_f32_16x16x32_bf16 v[116:119], v[176:179], v[130:133], v[116:119]
	v_mfma_f32_16x16x32_bf16 v[130:133], v[180:183], v[130:133], v[112:115]
	v_mfma_f32_16x16x32_bf16 v[108:111], v[138:141], v[144:147], v[108:111]
	v_mfma_f32_16x16x32_bf16 v[100:103], v[176:179], v[144:147], v[100:103]
	v_mfma_f32_16x16x32_bf16 v[92:95], v[138:141], v[148:151], v[92:95]
	v_mfma_f32_16x16x32_bf16 v[84:87], v[176:179], v[148:151], v[84:87]
	v_mfma_f32_16x16x32_bf16 v[76:79], v[138:141], v[152:155], v[76:79]
	v_mfma_f32_16x16x32_bf16 v[68:71], v[176:179], v[152:155], v[68:71]
	v_mfma_f32_16x16x32_bf16 v[60:63], v[138:141], v[156:159], v[60:63]
	v_mfma_f32_16x16x32_bf16 v[52:55], v[176:179], v[156:159], v[52:55]
	v_mfma_f32_16x16x32_bf16 v[44:47], v[138:141], v[160:163], v[44:47]
	v_mfma_f32_16x16x32_bf16 v[36:39], v[176:179], v[160:163], v[36:39]
	v_mfma_f32_16x16x32_bf16 v[28:31], v[138:141], v[164:167], v[28:31]
	v_mfma_f32_16x16x32_bf16 v[20:23], v[176:179], v[164:167], v[20:23]
	v_mfma_f32_16x16x32_bf16 v[12:15], v[138:141], v[168:171], v[12:15]
	v_mfma_f32_16x16x32_bf16 v[138:141], v[172:175], v[168:171], v[8:11]
	v_mfma_f32_16x16x32_bf16 v[4:7], v[176:179], v[168:171], v[4:7]
	v_mfma_f32_16x16x32_bf16 v[192:195], v[172:175], v[144:147], v[104:107]
	v_mfma_f32_16x16x32_bf16 v[144:147], v[180:183], v[144:147], v[96:99]
	v_mfma_f32_16x16x32_bf16 v[196:199], v[172:175], v[148:151], v[88:91]
	v_mfma_f32_16x16x32_bf16 v[148:151], v[180:183], v[148:151], v[80:83]
	v_mfma_f32_16x16x32_bf16 v[200:203], v[172:175], v[152:155], v[72:75]
	v_mfma_f32_16x16x32_bf16 v[152:155], v[180:183], v[152:155], v[64:67]
	v_mfma_f32_16x16x32_bf16 v[204:207], v[172:175], v[156:159], v[56:59]
	v_mfma_f32_16x16x32_bf16 v[156:159], v[180:183], v[156:159], v[48:51]
	v_mfma_f32_16x16x32_bf16 v[208:211], v[172:175], v[160:163], v[40:43]
	v_mfma_f32_16x16x32_bf16 v[160:163], v[180:183], v[160:163], v[32:35]
	v_mfma_f32_16x16x32_bf16 v[212:215], v[172:175], v[164:167], v[24:27]
	v_mfma_f32_16x16x32_bf16 v[164:167], v[180:183], v[164:167], v[16:19]
	v_mfma_f32_16x16x32_bf16 v[168:171], v[180:183], v[168:171], v[0:3]
	s_setprio 0
	s_waitcnt vmcnt(0) lgkmcnt(0)
	s_barrier
	s_nop 1
	ds_read_b128 v[0:3], v128 offset:24576
	ds_read_b128 v[8:11], v128 offset:25600
	ds_read_b128 v[16:19], v128 offset:26624
	ds_read_b128 v[24:27], v128 offset:27648
	ds_read_b128 v[32:35], v128 offset:28672
	ds_read_b128 v[172:175], v128 offset:29696
	ds_read_b128 v[176:179], v128 offset:30720
	ds_read_b128 v[180:183], v128 offset:31744
	ds_read_b128 v[216:219], v137 offset:40960
	ds_read_b128 v[220:223], v137 offset:41216
	ds_read_b128 v[224:227], v137 offset:43008
	ds_read_b128 v[228:231], v137 offset:43264
	s_setprio 1
	s_waitcnt lgkmcnt(0)
	v_mfma_f32_16x16x32_bf16 v[120:123], v[216:219], v[0:3], v[124:127]
	v_mfma_f32_16x16x32_bf16 v[124:127], v[220:223], v[0:3], v[184:187]
	v_mfma_f32_16x16x32_bf16 v[112:115], v[224:227], v[0:3], v[116:119]
	v_mfma_f32_16x16x32_bf16 v[116:119], v[228:231], v[0:3], v[130:133]
	v_mfma_f32_16x16x32_bf16 v[104:107], v[216:219], v[8:11], v[108:111]
	v_mfma_f32_16x16x32_bf16 v[108:111], v[220:223], v[8:11], v[192:195]
	v_mfma_f32_16x16x32_bf16 v[96:99], v[224:227], v[8:11], v[100:103]
	v_mfma_f32_16x16x32_bf16 v[100:103], v[228:231], v[8:11], v[144:147]
	v_mfma_f32_16x16x32_bf16 v[88:91], v[216:219], v[16:19], v[92:95]
	v_mfma_f32_16x16x32_bf16 v[92:95], v[220:223], v[16:19], v[196:199]
	v_mfma_f32_16x16x32_bf16 v[80:83], v[224:227], v[16:19], v[84:87]
	v_mfma_f32_16x16x32_bf16 v[84:87], v[228:231], v[16:19], v[148:151]
	v_mfma_f32_16x16x32_bf16 v[72:75], v[216:219], v[24:27], v[76:79]
	v_mfma_f32_16x16x32_bf16 v[76:79], v[220:223], v[24:27], v[200:203]
	v_mfma_f32_16x16x32_bf16 v[64:67], v[224:227], v[24:27], v[68:71]
	v_mfma_f32_16x16x32_bf16 v[68:71], v[228:231], v[24:27], v[152:155]
	v_mfma_f32_16x16x32_bf16 v[56:59], v[216:219], v[32:35], v[60:63]
	v_mfma_f32_16x16x32_bf16 v[60:63], v[220:223], v[32:35], v[204:207]
	v_mfma_f32_16x16x32_bf16 v[48:51], v[224:227], v[32:35], v[52:55]
	v_mfma_f32_16x16x32_bf16 v[52:55], v[228:231], v[32:35], v[156:159]
	v_mfma_f32_16x16x32_bf16 v[40:43], v[216:219], v[172:175], v[44:47]
	v_mfma_f32_16x16x32_bf16 v[44:47], v[220:223], v[172:175], v[208:211]
	v_mfma_f32_16x16x32_bf16 v[32:35], v[224:227], v[172:175], v[36:39]
	v_mfma_f32_16x16x32_bf16 v[36:39], v[228:231], v[172:175], v[160:163]
	v_mfma_f32_16x16x32_bf16 v[24:27], v[216:219], v[176:179], v[28:31]
	v_mfma_f32_16x16x32_bf16 v[28:31], v[220:223], v[176:179], v[212:215]
	v_mfma_f32_16x16x32_bf16 v[16:19], v[224:227], v[176:179], v[20:23]
	v_mfma_f32_16x16x32_bf16 v[20:23], v[228:231], v[176:179], v[164:167]
	v_mfma_f32_16x16x32_bf16 v[8:11], v[216:219], v[180:183], v[12:15]
	v_mfma_f32_16x16x32_bf16 v[12:15], v[220:223], v[180:183], v[138:141]
	v_mfma_f32_16x16x32_bf16 v[0:3], v[224:227], v[180:183], v[4:7]
	v_mfma_f32_16x16x32_bf16 v[4:7], v[228:231], v[180:183], v[168:171]
	s_setprio 0
	v_and_b32_e32 v128, 0xffffff80, v134
	v_add_u32_e32 v128, s42, v128
	v_or_b32_e32 v132, v128, v135
	v_lshrrev_b32_e32 v130, 1, v134
	v_lshlrev_b32_e32 v128, 6, v136
	v_and_b32_e32 v130, 24, v130
	v_ashrrev_i32_e32 v133, 31, v132
	v_readlane_b32 s2, v254, 62
	v_or3_b32 v128, v128, v130, s4
	v_lshlrev_b64 v[130:131], 11, v[132:133]
	v_readlane_b32 s3, v254, 63
	s_nop 1
	v_lshl_add_u64 v[136:137], s[2:3], 0, v[130:131]
	v_lshlrev_b64 v[130:131], 10, v[132:133]
	v_lshl_add_u64 v[134:135], s[96:97], 0, v[130:131]
	v_cmp_lt_i32_e64 s[2:3], s48, v128
	s_and_saveexec_b64 s[4:5], s[2:3]
	s_xor_b64 s[4:5], exec, s[4:5]
	s_cbranch_execz .LBB0_132
	s_cmpk_gt_u32 s33, 0x3ff
	s_mov_b64 s[42:43], -1
	s_cbranch_scc0 .LBB0_130
	v_lshl_add_u64 v[138:139], v[128:129], 1, v[136:137]
	v_lshl_add_u64 v[138:139], v[138:139], 0, s[34:35]
	s_mov_b64 s[42:43], 0

.LBB0_248:
	s_add_u32 s2, s52, 0xc550000
	s_addc_u32 s3, s53, 0
	v_writelane_b32 v255, s2, 2
	s_cmpk_lt_i32 s49, 0xe1
	v_mov_b32_e32 v0, v190
	v_writelane_b32 v255, s3, 3
	s_cselect_b64 s[2:3], -1, 0
	v_writelane_b32 v255, s2, 4
	s_cmpk_gt_i32 s49, 0xe0
	s_nop 0
	v_writelane_b32 v255, s3, 5
	s_cbranch_scc1 .LBB0_340
	v_and_b32_e32 v42, 15, v0
	v_bfe_u32 v1, v0, 4, 2
	v_ashrrev_i32_e32 v0, 1, v0
	v_and_b32_e32 v43, 0xffffffe0, v0
	v_mov_b32_e32 v19, 0
	v_lshlrev_b32_e32 v44, 2, v1
	v_or_b32_e32 v45, 16, v42
	v_lshlrev_b32_e32 v16, 4, v1
	v_and_b32_e32 v238, 1, v42
	v_lshl_or_b32 v16, v238, 6, v16
	v_mov_b32_e32 v17, v19
	v_or_b32_e32 v46, v43, v42
	s_movk_i32 s9, 0x4000
	s_mov_b32 s12, 0x12d0000
	s_mov_b32 s13, 0x12d8000
	s_mov_b32 s14, 0x8000
	s_mov_b64 s[6:7], 0x200
	s_movk_i32 s15, 0x1ff
	s_movk_i32 s16, 0x7fff
	s_mov_b32 s8, 0x3db504f3
	v_mov_b32_e32 v47, 1
	v_readlane_b32 s17, v254, 56
	s_branch .LBB0_252

.LBB0_252:
	s_min_i32 s2, s17, 0x60
	s_lshl_b32 s3, s17, 7
	s_lshl_b32 s18, s2, 5
	s_addk_i32 s3, 0xcf80
	s_cmpk_gt_i32 s17, 0x60
	s_cselect_b32 s10, s3, 0x4000
	s_and_b32 s2, s2, 0x3ffffe0
	s_cmp_eq_u32 s2, 64
	v_or_b32_e32 v20, s18, v42
	s_cselect_b64 s[2:3], -1, 0
	s_cmpk_lt_i32 s18, 0x400
	v_ashrrev_i32_e32 v21, 31, v20
	s_cselect_b64 s[4:5], -1, 0
	v_and_b32_e32 v0, -2, v20
	v_mov_b32_e32 v1, v21
	v_lshlrev_b64 v[0:1], 11, v[0:1]
	s_or_b64 s[2:3], s[4:5], s[2:3]
	v_add_u32_e32 v24, s10, v46
	v_lshl_add_u64 v[22:23], s[52:53], 0, v[0:1]
	s_mov_b64 s[4:5], -1
	s_and_b64 vcc, exec, s[2:3]
	v_ashrrev_i32_e32 v25, 31, v24
	s_cbranch_vccnz .LBB0_256
	v_and_b32_e32 v0, -2, v24
	v_mov_b32_e32 v1, v25
	v_lshlrev_b64 v[0:1], 11, v[0:1]
	v_lshl_add_u64 v[26:27], s[52:53], 0, v[0:1]
	v_mov_b32_e32 v0, 0
	s_movk_i32 s4, 0xffe0
	v_mov_b64_e32 v[28:29], v[22:23]
	v_mov_b32_e32 v1, v0
	v_mov_b32_e32 v2, v0
	v_mov_b32_e32 v3, v0
	v_mov_b32_e32 v12, v0
	v_mov_b32_e32 v13, v0
	v_mov_b32_e32 v14, v0
	v_mov_b32_e32 v15, v0
	v_mov_b32_e32 v8, v0
	v_mov_b32_e32 v9, v0
	v_mov_b32_e32 v10, v0
	v_mov_b32_e32 v11, v0
	v_mov_b32_e32 v4, v0
	v_mov_b32_e32 v5, v0
	v_mov_b32_e32 v6, v0
	v_mov_b32_e32 v7, v0
.LBB0_254:
	v_lshl_add_u64 v[34:35], v[26:27], 0, v[16:17]
	v_add_co_u32_e32 v52, vcc, s12, v34
	v_lshl_add_u64 v[56:57], v[28:29], 0, v[16:17]
	s_nop 0
	v_addc_co_u32_e32 v53, vcc, 0, v35, vcc
	v_add_co_u32_e32 v54, vcc, s13, v34
	global_load_dwordx4 v[30:33], v[52:53], off
	s_nop 0
	v_addc_co_u32_e32 v55, vcc, 0, v35, vcc
	global_load_dwordx4 v[34:37], v[54:55], off
	v_add_co_u32_e32 v58, vcc, s14, v56
	global_load_dwordx4 v[38:41], v[56:57], off
	s_nop 0
	v_addc_co_u32_e32 v59, vcc, 0, v57, vcc
	global_load_dwordx4 v[48:51], v[58:59], off
	s_addk_i32 s4, 0x80
	v_lshl_add_u64 v[28:29], v[28:29], 0, s[6:7]
	v_lshl_add_u64 v[26:27], v[26:27], 0, s[6:7]
	s_cmpk_lt_u32 s4, 0x3e0
	s_waitcnt vmcnt(0)
	v_mfma_f32_16x16x32_bf16 v[12:15], v[30:33], v[38:41], v[12:15]
	v_mfma_f32_16x16x32_bf16 v[8:11], v[30:33], v[48:51], v[8:11]
	v_mfma_f32_16x16x32_bf16 v[4:7], v[34:37], v[38:41], v[4:7]
	v_mfma_f32_16x16x32_bf16 v[0:3], v[34:37], v[48:51], v[0:3]
	global_load_dwordx4 v[30:33], v[52:53], off offset:128
	global_load_dwordx4 v[34:37], v[54:55], off offset:128
	global_load_dwordx4 v[38:41], v[56:57], off offset:128
	global_load_dwordx4 v[48:51], v[58:59], off offset:128
	s_waitcnt vmcnt(1)
	v_mfma_f32_16x16x32_bf16 v[12:15], v[30:33], v[38:41], v[12:15]
	s_waitcnt vmcnt(0)
	v_mfma_f32_16x16x32_bf16 v[8:11], v[30:33], v[48:51], v[8:11]
	v_mfma_f32_16x16x32_bf16 v[4:7], v[34:37], v[38:41], v[4:7]
	v_mfma_f32_16x16x32_bf16 v[0:3], v[34:37], v[48:51], v[0:3]
	global_load_dwordx4 v[30:33], v[52:53], off offset:256
	global_load_dwordx4 v[34:37], v[54:55], off offset:256
	global_load_dwordx4 v[38:41], v[56:57], off offset:256
	global_load_dwordx4 v[48:51], v[58:59], off offset:256
	s_waitcnt vmcnt(1)
	v_mfma_f32_16x16x32_bf16 v[12:15], v[30:33], v[38:41], v[12:15]
	s_waitcnt vmcnt(0)
	v_mfma_f32_16x16x32_bf16 v[8:11], v[30:33], v[48:51], v[8:11]
	v_mfma_f32_16x16x32_bf16 v[4:7], v[34:37], v[38:41], v[4:7]
	v_mfma_f32_16x16x32_bf16 v[0:3], v[34:37], v[48:51], v[0:3]
	global_load_dwordx4 v[30:33], v[52:53], off offset:384
	global_load_dwordx4 v[34:37], v[54:55], off offset:384
	global_load_dwordx4 v[38:41], v[56:57], off offset:384
	global_load_dwordx4 v[48:51], v[58:59], off offset:384
	s_waitcnt vmcnt(1)
	v_mfma_f32_16x16x32_bf16 v[12:15], v[30:33], v[38:41], v[12:15]
	s_waitcnt vmcnt(0)
	v_mfma_f32_16x16x32_bf16 v[8:11], v[30:33], v[48:51], v[8:11]
	v_mfma_f32_16x16x32_bf16 v[4:7], v[34:37], v[38:41], v[4:7]
	v_mfma_f32_16x16x32_bf16 v[0:3], v[34:37], v[48:51], v[0:3]
	s_cbranch_scc1 .LBB0_254
	s_mov_b64 s[4:5], 0
.LBB0_256:
	s_and_b64 vcc, exec, s[4:5]
	s_cbranch_vccz .LBB0_259
	s_nop 3
	v_and_b32_e32 v0, -2, v24
	v_mov_b32_e32 v1, v25
	v_lshlrev_b64 v[0:1], 11, v[0:1]
	v_lshl_add_u64 v[24:25], s[52:53], 0, v[0:1]
	v_mov_b32_e32 v0, 0
	s_movk_i32 s4, 0xffe0
	v_mov_b32_e32 v1, v0
	v_mov_b32_e32 v2, v0
	v_mov_b32_e32 v3, v0
	v_mov_b32_e32 v12, v0
	v_mov_b32_e32 v13, v0
	v_mov_b32_e32 v14, v0
	v_mov_b32_e32 v15, v0
	v_mov_b32_e32 v8, v0
	v_mov_b32_e32 v9, v0
	v_mov_b32_e32 v10, v0
	v_mov_b32_e32 v11, v0
	v_mov_b32_e32 v4, v0
	v_mov_b32_e32 v5, v0
	v_mov_b32_e32 v6, v0
	v_mov_b32_e32 v7, v0
.LBB0_258:
	v_lshl_add_u64 v[30:31], v[24:25], 0, v[16:17]
	v_add_co_u32_e32 v48, vcc, s12, v30
	v_lshl_add_u64 v[52:53], v[22:23], 0, v[16:17]
	s_nop 0
	v_addc_co_u32_e32 v49, vcc, 0, v31, vcc
	v_add_co_u32_e32 v50, vcc, s13, v30
	global_load_dwordx4 v[34:37], v[52:53], off
	s_nop 0
	v_addc_co_u32_e32 v51, vcc, 0, v31, vcc
	v_add_co_u32_e32 v54, vcc, s14, v52
	global_load_dwordx4 v[26:29], v[48:49], off
	global_load_dwordx4 v[30:33], v[50:51], off
	v_addc_co_u32_e32 v55, vcc, 0, v53, vcc
	global_load_dwordx4 v[38:41], v[54:55], off
	s_addk_i32 s4, 0x80
	v_lshl_add_u64 v[22:23], v[22:23], 0, s[6:7]
	v_lshl_add_u64 v[24:25], v[24:25], 0, s[6:7]
	s_cmpk_gt_u32 s4, 0x3df
	s_waitcnt vmcnt(0)
	v_mfma_f32_16x16x32_bf16 v[12:15], v[34:37], v[26:29], v[12:15]
	v_mfma_f32_16x16x32_bf16 v[8:11], v[38:41], v[26:29], v[8:11]
	v_mfma_f32_16x16x32_bf16 v[4:7], v[34:37], v[30:33], v[4:7]
	v_mfma_f32_16x16x32_bf16 v[0:3], v[38:41], v[30:33], v[0:3]
	global_load_dwordx4 v[26:29], v[48:49], off offset:128
	global_load_dwordx4 v[30:33], v[50:51], off offset:128
	global_load_dwordx4 v[34:37], v[52:53], off offset:128
	global_load_dwordx4 v[38:41], v[54:55], off offset:128
	s_waitcnt vmcnt(1)
	v_mfma_f32_16x16x32_bf16 v[12:15], v[34:37], v[26:29], v[12:15]
	s_waitcnt vmcnt(0)
	v_mfma_f32_16x16x32_bf16 v[8:11], v[38:41], v[26:29], v[8:11]
	v_mfma_f32_16x16x32_bf16 v[4:7], v[34:37], v[30:33], v[4:7]
	v_mfma_f32_16x16x32_bf16 v[0:3], v[38:41], v[30:33], v[0:3]
	global_load_dwordx4 v[26:29], v[48:49], off offset:256
	global_load_dwordx4 v[30:33], v[50:51], off offset:256
	global_load_dwordx4 v[34:37], v[52:53], off offset:256
	global_load_dwordx4 v[38:41], v[54:55], off offset:256
	s_waitcnt vmcnt(1)
	v_mfma_f32_16x16x32_bf16 v[12:15], v[34:37], v[26:29], v[12:15]
	s_waitcnt vmcnt(0)
	v_mfma_f32_16x16x32_bf16 v[8:11], v[38:41], v[26:29], v[8:11]
	v_mfma_f32_16x16x32_bf16 v[4:7], v[34:37], v[30:33], v[4:7]
	v_mfma_f32_16x16x32_bf16 v[0:3], v[38:41], v[30:33], v[0:3]
	global_load_dwordx4 v[26:29], v[48:49], off offset:384
	global_load_dwordx4 v[30:33], v[50:51], off offset:384
	global_load_dwordx4 v[34:37], v[52:53], off offset:384
	global_load_dwordx4 v[38:41], v[54:55], off offset:384
	s_waitcnt vmcnt(1)
	v_mfma_f32_16x16x32_bf16 v[12:15], v[34:37], v[26:29], v[12:15]
	s_waitcnt vmcnt(0)
	v_mfma_f32_16x16x32_bf16 v[8:11], v[38:41], v[26:29], v[8:11]
	v_mfma_f32_16x16x32_bf16 v[4:7], v[34:37], v[30:33], v[4:7]
	v_mfma_f32_16x16x32_bf16 v[0:3], v[38:41], v[30:33], v[0:3]
	s_cbranch_scc0 .LBB0_258

.LBB0_519:
	v_writelane_b32 v255, s8, 15
	s_nop 1
	v_writelane_b32 v255, s9, 16
	s_or_b64 exec, exec, s[2:3]
	v_readlane_b32 s12, v254, 56
	v_mov_b32_e32 v0, v190
	s_cmpk_gt_i32 s12, 0x2bf
	s_cbranch_scc1 .LBB0_555
	v_and_b32_e32 v20, 63, v0
	v_ashrrev_i32_e32 v21, 6, v0
	v_ashrrev_i32_e32 v22, 3, v0
	v_lshlrev_b32_e32 v0, 3, v0
	s_load_dword s6, s[0:1], 0x108
	v_and_b32_e32 v3, 56, v0
	v_bfe_u32 v0, v190, 2, 1
	v_lshlrev_b32_e32 v0, 7, v0
	v_bfe_u32 v200, v190, 3, 1
	v_lshl_or_b32 v0, v200, 6, v0
	v_and_b32_e32 v200, 3, v190
	v_lshl_or_b32 v0, v200, 4, v0
	v_mov_b32_e32 v1, 0
	v_lshl_add_u64 v[16:17], s[52:53], 0, v[0:1]
	v_lshlrev_b32_e32 v0, 2, v22
	s_movk_i32 s2, 0x104
	v_lshlrev_b32_e32 v2, 2, v20
	v_mad_u32_u24 v23, v3, s2, v0
	v_mul_lo_u32 v0, v21, s2
	s_lshl_b32 s7, s12, 6
	s_waitcnt lgkmcnt(0)
	s_lshl_b32 s8, s6, 6
	s_mov_b32 s9, 0
	s_movk_i32 s10, 0x2c00
	v_add_u32_e32 v24, v2, v0
	s_movk_i32 s11, 0x7fff
	v_mov_b32_e32 v25, 1
	s_branch .LBB0_522
.LBB0_521:
	s_or_b64 exec, exec, s[4:5]
	s_barrier
	s_waitcnt vmcnt(0)
	ds_write_b32 v24, v0
	ds_write_b32 v24, v1 offset:1040
	ds_write_b32 v24, v2 offset:2080
	ds_write_b32 v24, v3 offset:3120
	ds_write_b32 v24, v4 offset:4160
	ds_write_b32 v24, v5 offset:5200
	ds_write_b32 v24, v6 offset:6240
	ds_write_b32 v24, v7 offset:7280
	ds_write_b32 v24, v8 offset:8320
	ds_write_b32 v24, v9 offset:9360
	ds_write_b32 v24, v10 offset:10400
	ds_write_b32 v24, v11 offset:11440
	ds_write_b32 v24, v12 offset:12480
	ds_write_b32 v24, v13 offset:13520
	ds_write_b32 v24, v14 offset:14560
	ds_write_b32 v24, v15 offset:15600
	s_waitcnt lgkmcnt(0)
	s_barrier
	ds_read2_b32 v[6:7], v23 offset1:32
	ds_read2_b32 v[8:9], v23 offset0:65 offset1:97
	ds_read2_b32 v[10:11], v23 offset0:130 offset1:162
	ds_read2_b32 v[12:13], v23 offset0:195 offset1:227
	v_add_u32_e32 v30, s13, v22
	v_and_b32_e32 v30, -2, v30
	s_ashr_i32 s3, s2, 31
	v_add_u32_e32 v0, 0x400, v23
	v_ashrrev_i32_e32 v31, 31, v30
	v_lshl_add_u64 v[4:5], s[2:3], 2, v[16:17]
	ds_read2_b32 v[14:15], v0 offset0:4 offset1:36
	ds_read2_b32 v[18:19], v0 offset0:69 offset1:101
	ds_read2_b32 v[26:27], v0 offset0:134 offset1:166
	ds_read2_b32 v[28:29], v0 offset0:199 offset1:231
	v_lshlrev_b64 v[0:1], 11, v[30:31]
	v_lshl_add_u64 v[32:33], v[4:5], 0, v[0:1]
	s_waitcnt lgkmcnt(7)
	v_and_b32_sdwa v1, v6, v25 dst_sel:DWORD dst_unused:UNUSED_PAD src0_sel:WORD_1 src1_sel:DWORD
	v_add3_u32 v2, v6, v1, s11
	s_waitcnt lgkmcnt(4)
	v_and_b32_sdwa v1, v12, v25 dst_sel:DWORD dst_unused:UNUSED_PAD src0_sel:WORD_1 src1_sel:DWORD
	v_and_b32_sdwa v3, v8, v25 dst_sel:DWORD dst_unused:UNUSED_PAD src0_sel:WORD_1 src1_sel:DWORD
	v_and_b32_sdwa v0, v10, v25 dst_sel:DWORD dst_unused:UNUSED_PAD src0_sel:WORD_1 src1_sel:DWORD
	v_add3_u32 v1, v12, v1, s11
	v_add3_u32 v3, v8, v3, s11
	v_add3_u32 v0, v10, v0, s11
	v_and_b32_e32 v1, 0xffff0000, v1
	v_and_b32_e32 v3, 0xffff0000, v3
	v_or_b32_sdwa v1, v1, v0 dst_sel:DWORD dst_unused:UNUSED_PAD src0_sel:DWORD src1_sel:WORD_1
	v_or_b32_sdwa v0, v3, v2 dst_sel:DWORD dst_unused:UNUSED_PAD src0_sel:DWORD src1_sel:WORD_1
	s_waitcnt lgkmcnt(3)
	v_and_b32_sdwa v3, v14, v25 dst_sel:DWORD dst_unused:UNUSED_PAD src0_sel:WORD_1 src1_sel:DWORD
	v_add3_u32 v6, v14, v3, s11
	s_waitcnt lgkmcnt(0)
	v_and_b32_sdwa v3, v28, v25 dst_sel:DWORD dst_unused:UNUSED_PAD src0_sel:WORD_1 src1_sel:DWORD
	v_and_b32_sdwa v8, v18, v25 dst_sel:DWORD dst_unused:UNUSED_PAD src0_sel:WORD_1 src1_sel:DWORD
	v_and_b32_sdwa v2, v26, v25 dst_sel:DWORD dst_unused:UNUSED_PAD src0_sel:WORD_1 src1_sel:DWORD
	v_add3_u32 v3, v28, v3, s11
	v_add3_u32 v8, v18, v8, s11
	v_add3_u32 v2, v26, v2, s11
	v_and_b32_e32 v3, 0xffff0000, v3
	v_and_b32_e32 v8, 0xffff0000, v8
	v_or_b32_sdwa v3, v3, v2 dst_sel:DWORD dst_unused:UNUSED_PAD src0_sel:DWORD src1_sel:WORD_1
	v_or_b32_sdwa v2, v8, v6 dst_sel:DWORD dst_unused:UNUSED_PAD src0_sel:DWORD src1_sel:WORD_1
	global_store_dwordx4 v[32:33], v[0:3], off
	s_add_i32 s12, s12, s6
	s_add_i32 s7, s7, s8
	v_add_u32_e32 v0, 32, v30
	v_ashrrev_i32_e32 v1, 31, v0
	v_lshlrev_b64 v[0:1], 11, v[0:1]
	v_lshl_add_u64 v[4:5], v[4:5], 0, v[0:1]
	v_and_b32_sdwa v1, v7, v25 dst_sel:DWORD dst_unused:UNUSED_PAD src0_sel:WORD_1 src1_sel:DWORD
	v_add3_u32 v2, v7, v1, s11
	v_and_b32_sdwa v1, v13, v25 dst_sel:DWORD dst_unused:UNUSED_PAD src0_sel:WORD_1 src1_sel:DWORD
	v_and_b32_sdwa v3, v9, v25 dst_sel:DWORD dst_unused:UNUSED_PAD src0_sel:WORD_1 src1_sel:DWORD
	v_and_b32_sdwa v0, v11, v25 dst_sel:DWORD dst_unused:UNUSED_PAD src0_sel:WORD_1 src1_sel:DWORD
	v_add3_u32 v1, v13, v1, s11
	v_add3_u32 v3, v9, v3, s11
	v_add3_u32 v0, v11, v0, s11
	v_and_b32_e32 v1, 0xffff0000, v1
	v_and_b32_e32 v3, 0xffff0000, v3
	v_or_b32_sdwa v1, v1, v0 dst_sel:DWORD dst_unused:UNUSED_PAD src0_sel:DWORD src1_sel:WORD_1
	v_or_b32_sdwa v0, v3, v2 dst_sel:DWORD dst_unused:UNUSED_PAD src0_sel:DWORD src1_sel:WORD_1
	v_and_b32_sdwa v3, v15, v25 dst_sel:DWORD dst_unused:UNUSED_PAD src0_sel:WORD_1 src1_sel:DWORD
	v_add3_u32 v6, v15, v3, s11
	v_and_b32_sdwa v3, v29, v25 dst_sel:DWORD dst_unused:UNUSED_PAD src0_sel:WORD_1 src1_sel:DWORD
	v_and_b32_sdwa v7, v19, v25 dst_sel:DWORD dst_unused:UNUSED_PAD src0_sel:WORD_1 src1_sel:DWORD
	v_and_b32_sdwa v2, v27, v25 dst_sel:DWORD dst_unused:UNUSED_PAD src0_sel:WORD_1 src1_sel:DWORD
	v_add3_u32 v3, v29, v3, s11
	v_add3_u32 v7, v19, v7, s11
	v_add3_u32 v2, v27, v2, s11
	v_and_b32_e32 v3, 0xffff0000, v3
	v_and_b32_e32 v7, 0xffff0000, v7
	v_or_b32_sdwa v3, v3, v2 dst_sel:DWORD dst_unused:UNUSED_PAD src0_sel:DWORD src1_sel:WORD_1
	v_or_b32_sdwa v2, v7, v6 dst_sel:DWORD dst_unused:UNUSED_PAD src0_sel:DWORD src1_sel:WORD_1
	s_cmpk_lt_i32 s12, 0x2c0
	global_store_dwordx4 v[4:5], v[0:3], off
	s_cbranch_scc0 .LBB0_554

.LBB0_823:
	s_add_i32 s15, s14, 2
	s_mul_hi_i32 s16, s15, 0x55555556
	s_lshr_b32 s17, s16, 31
	s_add_i32 s16, s16, s17
	s_mul_i32 s16, s16, 3
	s_sub_i32 s15, s15, s16
	s_mulk_i32 s15, 0x6000
	s_mul_i32 s54, s14, 0x6000
	v_readfirstlane_b32 s55, v140
	v_lshl_add_u64 v[232:233], v[132:133], 0, s[4:5]
	v_lshl_add_u64 v[234:235], v[130:131], 0, s[4:5]
	s_add_u32 s55, s55, s15
	s_waitcnt vmcnt(6) lgkmcnt(0)
	s_barrier
	v_or_b32_e32 v128, s54, v138
	v_add3_u32 v128, v128, v139, v137
	ds_read_b128 v[174:177], v128 offset:16384
	ds_read_b128 v[178:181], v128 offset:16640
	ds_read_b128 v[182:185], v128 offset:18432
	ds_read_b128 v[186:189], v128 offset:18688
	v_add3_u32 v128, s54, v141, v137
	ds_read_b128 v[142:145], v128
	ds_read_b128 v[146:149], v128 offset:1024
	ds_read_b128 v[150:153], v128 offset:2048
	ds_read_b128 v[154:157], v128 offset:3072
	ds_read_b128 v[158:161], v128 offset:4096
	ds_read_b128 v[162:165], v128 offset:5120
	ds_read_b128 v[166:169], v128 offset:6144
	ds_read_b128 v[170:173], v128 offset:7168
	s_setprio 1
	s_waitcnt lgkmcnt(7)
	v_mfma_f32_16x16x32_bf16 v[124:127], v[174:177], v[142:145], v[124:127]
	v_mfma_f32_16x16x32_bf16 v[120:123], v[178:181], v[142:145], v[120:123]
	v_mfma_f32_16x16x32_bf16 v[116:119], v[182:185], v[142:145], v[116:119]
	v_mfma_f32_16x16x32_bf16 v[112:115], v[186:189], v[142:145], v[112:115]
	s_mov_b32 m0, s55
	s_mov_b64 s[16:17], 0xa510080
	v_lshl_add_u64 v[236:237], v[232:233], 0, s[16:17]
	global_load_lds_dwordx4 v[236:237], off
	s_waitcnt lgkmcnt(6)
	v_mfma_f32_16x16x32_bf16 v[108:111], v[174:177], v[146:149], v[108:111]
	v_mfma_f32_16x16x32_bf16 v[104:107], v[178:181], v[146:149], v[104:107]
	v_mfma_f32_16x16x32_bf16 v[100:103], v[182:185], v[146:149], v[100:103]
	v_mfma_f32_16x16x32_bf16 v[96:99], v[186:189], v[146:149], v[96:99]
	s_add_u32 m0, s55, 0x1000
	s_mov_b64 s[16:17], 0xa530080
	v_lshl_add_u64 v[236:237], v[232:233], 0, s[16:17]
	global_load_lds_dwordx4 v[236:237], off
	s_waitcnt lgkmcnt(5)
	v_mfma_f32_16x16x32_bf16 v[92:95], v[174:177], v[150:153], v[92:95]
	v_mfma_f32_16x16x32_bf16 v[88:91], v[178:181], v[150:153], v[88:91]
	v_mfma_f32_16x16x32_bf16 v[84:87], v[182:185], v[150:153], v[84:87]
	v_mfma_f32_16x16x32_bf16 v[80:83], v[186:189], v[150:153], v[80:83]
	s_add_u32 m0, s55, 0x2000
	s_mov_b64 s[16:17], 0xa550080
	v_lshl_add_u64 v[236:237], v[232:233], 0, s[16:17]
	global_load_lds_dwordx4 v[236:237], off
	s_waitcnt lgkmcnt(4)
	v_mfma_f32_16x16x32_bf16 v[76:79], v[174:177], v[154:157], v[76:79]
	v_mfma_f32_16x16x32_bf16 v[72:75], v[178:181], v[154:157], v[72:75]
	v_mfma_f32_16x16x32_bf16 v[68:71], v[182:185], v[154:157], v[68:71]
	v_mfma_f32_16x16x32_bf16 v[64:67], v[186:189], v[154:157], v[64:67]
	s_add_u32 m0, s55, 0x3000
	s_mov_b64 s[16:17], 0xa570080
	v_lshl_add_u64 v[236:237], v[232:233], 0, s[16:17]
	global_load_lds_dwordx4 v[236:237], off
	s_waitcnt lgkmcnt(3)
	v_mfma_f32_16x16x32_bf16 v[60:63], v[174:177], v[158:161], v[60:63]
	v_mfma_f32_16x16x32_bf16 v[56:59], v[178:181], v[158:161], v[56:59]
	v_mfma_f32_16x16x32_bf16 v[52:55], v[182:185], v[158:161], v[52:55]
	v_mfma_f32_16x16x32_bf16 v[48:51], v[186:189], v[158:161], v[48:51]
	s_add_u32 m0, s55, 0x4000
	s_mov_b64 s[16:17], 0xa40080
	v_lshl_add_u64 v[236:237], v[234:235], 0, s[16:17]
	global_load_lds_dwordx4 v[236:237], off
	s_waitcnt lgkmcnt(2)
	v_mfma_f32_16x16x32_bf16 v[44:47], v[174:177], v[162:165], v[44:47]
	v_mfma_f32_16x16x32_bf16 v[40:43], v[178:181], v[162:165], v[40:43]
	v_mfma_f32_16x16x32_bf16 v[36:39], v[182:185], v[162:165], v[36:39]
	v_mfma_f32_16x16x32_bf16 v[32:35], v[186:189], v[162:165], v[32:35]
	s_add_u32 m0, s55, 0x5000
	s_mov_b64 s[16:17], 0xa60080
	v_lshl_add_u64 v[236:237], v[234:235], 0, s[16:17]
	global_load_lds_dwordx4 v[236:237], off
	s_waitcnt lgkmcnt(1)
	v_mfma_f32_16x16x32_bf16 v[28:31], v[174:177], v[166:169], v[28:31]
	v_mfma_f32_16x16x32_bf16 v[24:27], v[178:181], v[166:169], v[24:27]
	v_mfma_f32_16x16x32_bf16 v[20:23], v[182:185], v[166:169], v[20:23]
	v_mfma_f32_16x16x32_bf16 v[16:19], v[186:189], v[166:169], v[16:19]
	s_waitcnt lgkmcnt(0)
	v_mfma_f32_16x16x32_bf16 v[12:15], v[174:177], v[170:173], v[12:15]
	v_mfma_f32_16x16x32_bf16 v[8:11], v[178:181], v[170:173], v[8:11]
	v_mfma_f32_16x16x32_bf16 v[4:7], v[182:185], v[170:173], v[4:7]
	v_mfma_f32_16x16x32_bf16 v[0:3], v[186:189], v[170:173], v[0:3]
	s_setprio 0
	s_add_i32 s15, s14, 1
	s_cmp_lg_u32 s14, 2
	s_cselect_b32 s14, s15, 0
	s_add_u32 s4, s4, 64
	s_addc_u32 s5, s5, 0
	s_cmpk_eq_i32 s4, 0x780
	s_cbranch_scc0 .LBB0_823
	s_waitcnt vmcnt(6) lgkmcnt(0)
	s_barrier
	v_add_u32_e32 v128, v141, v137
	ds_read_b128 v[130:133], v128
	ds_read_b128 v[140:143], v128 offset:1024
	ds_read_b128 v[144:147], v128 offset:2048
	ds_read_b128 v[148:151], v128 offset:3072
	ds_read_b128 v[152:155], v128 offset:4096
	ds_read_b128 v[156:159], v128 offset:5120
	ds_read_b128 v[160:163], v128 offset:6144
	ds_read_b128 v[164:167], v128 offset:7168
	v_add3_u32 v137, v138, v139, v137
	ds_read_b128 v[168:171], v137 offset:16384
	ds_read_b128 v[172:175], v137 offset:16640
	ds_read_b128 v[176:179], v137 offset:18432
	ds_read_b128 v[180:183], v137 offset:18688
	s_setprio 1
	s_waitcnt lgkmcnt(0)
	v_mfma_f32_16x16x32_bf16 v[124:127], v[168:171], v[130:133], v[124:127]
	v_mfma_f32_16x16x32_bf16 v[120:123], v[172:175], v[130:133], v[120:123]
	v_mfma_f32_16x16x32_bf16 v[116:119], v[176:179], v[130:133], v[116:119]
	v_mfma_f32_16x16x32_bf16 v[112:115], v[180:183], v[130:133], v[112:115]
	v_mfma_f32_16x16x32_bf16 v[108:111], v[168:171], v[140:143], v[108:111]
	v_mfma_f32_16x16x32_bf16 v[104:107], v[172:175], v[140:143], v[104:107]
	v_mfma_f32_16x16x32_bf16 v[100:103], v[176:179], v[140:143], v[100:103]
	v_mfma_f32_16x16x32_bf16 v[96:99], v[180:183], v[140:143], v[96:99]
	v_mfma_f32_16x16x32_bf16 v[92:95], v[168:171], v[144:147], v[92:95]
	v_mfma_f32_16x16x32_bf16 v[88:91], v[172:175], v[144:147], v[88:91]
	v_mfma_f32_16x16x32_bf16 v[84:87], v[176:179], v[144:147], v[84:87]
	v_mfma_f32_16x16x32_bf16 v[80:83], v[180:183], v[144:147], v[80:83]
	v_mfma_f32_16x16x32_bf16 v[76:79], v[168:171], v[148:151], v[76:79]
	v_mfma_f32_16x16x32_bf16 v[72:75], v[172:175], v[148:151], v[72:75]
	v_mfma_f32_16x16x32_bf16 v[68:71], v[176:179], v[148:151], v[68:71]
	v_mfma_f32_16x16x32_bf16 v[64:67], v[180:183], v[148:151], v[64:67]
	v_mfma_f32_16x16x32_bf16 v[60:63], v[168:171], v[152:155], v[60:63]
	v_mfma_f32_16x16x32_bf16 v[56:59], v[172:175], v[152:155], v[56:59]
	v_mfma_f32_16x16x32_bf16 v[52:55], v[176:179], v[152:155], v[52:55]
	v_mfma_f32_16x16x32_bf16 v[48:51], v[180:183], v[152:155], v[48:51]
	v_mfma_f32_16x16x32_bf16 v[44:47], v[168:171], v[156:159], v[44:47]
	v_mfma_f32_16x16x32_bf16 v[40:43], v[172:175], v[156:159], v[40:43]
	v_mfma_f32_16x16x32_bf16 v[36:39], v[176:179], v[156:159], v[36:39]
	v_mfma_f32_16x16x32_bf16 v[32:35], v[180:183], v[156:159], v[32:35]
	v_mfma_f32_16x16x32_bf16 v[28:31], v[168:171], v[160:163], v[28:31]
	v_mfma_f32_16x16x32_bf16 v[24:27], v[172:175], v[160:163], v[24:27]
	v_mfma_f32_16x16x32_bf16 v[20:23], v[176:179], v[160:163], v[20:23]
	v_mfma_f32_16x16x32_bf16 v[16:19], v[180:183], v[160:163], v[16:19]
	v_mfma_f32_16x16x32_bf16 v[12:15], v[168:171], v[164:167], v[12:15]
	v_mfma_f32_16x16x32_bf16 v[8:11], v[172:175], v[164:167], v[8:11]
	v_mfma_f32_16x16x32_bf16 v[4:7], v[176:179], v[164:167], v[4:7]
	v_mfma_f32_16x16x32_bf16 v[0:3], v[180:183], v[164:167], v[0:3]
	s_setprio 0
	s_waitcnt vmcnt(0) lgkmcnt(0)
	s_barrier
	ds_read_b128 v[130:133], v128 offset:24576
	ds_read_b128 v[138:141], v128 offset:25600
	ds_read_b128 v[142:145], v128 offset:26624
	ds_read_b128 v[146:149], v128 offset:27648
	ds_read_b128 v[150:153], v128 offset:28672
	ds_read_b128 v[154:157], v128 offset:29696
	ds_read_b128 v[158:161], v128 offset:30720
	ds_read_b128 v[162:165], v128 offset:31744
	ds_read_b128 v[166:169], v137 offset:40960
	ds_read_b128 v[170:173], v137 offset:41216
	ds_read_b128 v[174:177], v137 offset:43008
	ds_read_b128 v[178:181], v137 offset:43264
	s_setprio 1
	s_waitcnt lgkmcnt(0)
	v_mfma_f32_16x16x32_bf16 v[124:127], v[166:169], v[130:133], v[124:127]
	v_mfma_f32_16x16x32_bf16 v[120:123], v[170:173], v[130:133], v[120:123]
	v_mfma_f32_16x16x32_bf16 v[116:119], v[174:177], v[130:133], v[116:119]
	v_mfma_f32_16x16x32_bf16 v[112:115], v[178:181], v[130:133], v[112:115]
	v_mfma_f32_16x16x32_bf16 v[108:111], v[166:169], v[138:141], v[108:111]
	v_mfma_f32_16x16x32_bf16 v[104:107], v[170:173], v[138:141], v[104:107]
	v_mfma_f32_16x16x32_bf16 v[130:133], v[174:177], v[138:141], v[100:103]
	v_mfma_f32_16x16x32_bf16 v[96:99], v[178:181], v[138:141], v[96:99]
	v_mfma_f32_16x16x32_bf16 v[92:95], v[166:169], v[142:145], v[92:95]
	v_mfma_f32_16x16x32_bf16 v[88:91], v[170:173], v[142:145], v[88:91]
	v_mfma_f32_16x16x32_bf16 v[84:87], v[174:177], v[142:145], v[84:87]
	v_mfma_f32_16x16x32_bf16 v[80:83], v[178:181], v[142:145], v[80:83]
	v_mfma_f32_16x16x32_bf16 v[76:79], v[166:169], v[146:149], v[76:79]
	v_mfma_f32_16x16x32_bf16 v[72:75], v[170:173], v[146:149], v[72:75]
	v_mfma_f32_16x16x32_bf16 v[68:71], v[174:177], v[146:149], v[68:71]
	v_mfma_f32_16x16x32_bf16 v[64:67], v[178:181], v[146:149], v[64:67]
	v_mfma_f32_16x16x32_bf16 v[60:63], v[166:169], v[150:153], v[60:63]
	v_mfma_f32_16x16x32_bf16 v[56:59], v[170:173], v[150:153], v[56:59]
	v_mfma_f32_16x16x32_bf16 v[52:55], v[174:177], v[150:153], v[52:55]
	v_mfma_f32_16x16x32_bf16 v[48:51], v[178:181], v[150:153], v[48:51]
	v_mfma_f32_16x16x32_bf16 v[44:47], v[166:169], v[154:157], v[44:47]
	v_mfma_f32_16x16x32_bf16 v[40:43], v[170:173], v[154:157], v[40:43]
	v_mfma_f32_16x16x32_bf16 v[36:39], v[174:177], v[154:157], v[36:39]
	v_mfma_f32_16x16x32_bf16 v[32:35], v[178:181], v[154:157], v[32:35]
	v_mfma_f32_16x16x32_bf16 v[28:31], v[166:169], v[158:161], v[28:31]
	v_mfma_f32_16x16x32_bf16 v[24:27], v[170:173], v[158:161], v[24:27]
	v_mfma_f32_16x16x32_bf16 v[20:23], v[174:177], v[158:161], v[20:23]
	v_mfma_f32_16x16x32_bf16 v[16:19], v[178:181], v[158:161], v[16:19]
	v_mfma_f32_16x16x32_bf16 v[12:15], v[166:169], v[162:165], v[12:15]
	v_mfma_f32_16x16x32_bf16 v[8:11], v[170:173], v[162:165], v[8:11]
	v_mfma_f32_16x16x32_bf16 v[4:7], v[174:177], v[162:165], v[4:7]
	v_mfma_f32_16x16x32_bf16 v[0:3], v[178:181], v[162:165], v[0:3]
	s_setprio 0
	v_and_b32_e32 v100, 0xffffff80, v134
	v_lshrrev_b32_e32 v102, 1, v134
	v_add_u32_e32 v100, s12, v100
	v_lshlrev_b32_e32 v101, 6, v136
	v_and_b32_e32 v102, 24, v102
	v_or_b32_e32 v100, v100, v135
	v_or3_b32 v102, v101, v102, s13
	v_mov_b32_e32 v101, v129
	v_add_u32_e32 v128, 0xffffc000, v100
	v_readlane_b32 s12, v254, 2
	v_lshlrev_b64 v[138:139], 12, v[100:101]
	v_ashrrev_i32_e32 v101, 31, v100
	v_lshlrev_b64 v[134:135], 12, v[128:129]
	v_readlane_b32 s13, v254, 3
	v_readlane_b32 s14, v254, 4
	v_readlane_b32 s15, v254, 5
	v_lshlrev_b64 v[140:141], 12, v[100:101]
	v_lshl_add_u64 v[136:137], s[12:13], 0, v[140:141]
	v_lshl_add_u64 v[134:135], s[14:15], 0, v[134:135]
	v_cmp_gt_i32_e32 vcc, s10, v100
	v_ashrrev_i32_e32 v103, 31, v102
	v_lshlrev_b64 v[102:103], 2, v[102:103]
	v_cndmask_b32_e32 v135, v135, v137, vcc
	v_cndmask_b32_e32 v134, v134, v136, vcc
	v_lshl_add_u64 v[142:143], v[134:135], 0, v[102:103]
	global_load_dwordx4 v[134:137], v[142:143], off
	v_readlane_b32 s16, v254, 6
	v_readlane_b32 s17, v254, 7
	v_readlane_b32 s18, v254, 8
	v_readlane_b32 s19, v254, 9
	v_readlane_b32 s20, v254, 10
	v_readlane_b32 s21, v254, 11
	v_readlane_b32 s22, v254, 12
	v_readlane_b32 s23, v254, 13
	v_readlane_b32 s24, v254, 14
	v_readlane_b32 s25, v254, 15
	v_readlane_b32 s26, v254, 16
	v_readlane_b32 s27, v254, 17
	v_readlane_b32 s16, v254, 34
	v_cndmask_b32_e32 v139, v139, v141, vcc
	v_cndmask_b32_e32 v138, v138, v140, vcc
	v_readlane_b32 s30, v254, 48
	v_readlane_b32 s31, v254, 49
	v_add_u32_e32 v128, 0xffffc010, v100
	s_add_i32 s11, s11, s86
	v_lshl_add_u64 v[138:139], s[30:31], 0, v[138:139]
	v_lshl_add_u64 v[138:139], v[138:139], 0, v[102:103]
	s_add_i32 s6, s6, s7
	s_add_i32 s8, s8, s9
	s_cmpk_gt_i32 s11, 0x1ff
	v_readlane_b32 s17, v254, 35
	v_readlane_b32 s18, v254, 36
	v_readlane_b32 s19, v254, 37
	v_readlane_b32 s20, v254, 38
	v_readlane_b32 s21, v254, 39
	v_readlane_b32 s22, v254, 40
	v_readlane_b32 s23, v254, 41
	v_readlane_b32 s24, v254, 42
	v_readlane_b32 s25, v254, 43
	v_readlane_b32 s26, v254, 44
	v_readlane_b32 s27, v254, 45
	v_readlane_b32 s28, v254, 46
	v_readlane_b32 s29, v254, 47
	s_waitcnt vmcnt(0)
	v_pk_add_f32 v[124:125], v[124:125], v[134:135]
	v_pk_add_f32 v[126:127], v[126:127], v[136:137]
	global_store_dwordx4 v[138:139], v[124:127], off
	global_load_dwordx4 v[124:127], v[142:143], off offset:16
	s_waitcnt vmcnt(0)
	v_pk_add_f32 v[120:121], v[120:121], v[124:125]
	v_pk_add_f32 v[122:123], v[122:123], v[126:127]
	global_store_dwordx4 v[138:139], v[120:123], off offset:16
	global_load_dwordx4 v[120:123], v[142:143], off offset:128
	v_lshlrev_b64 v[124:125], 12, v[128:129]
	v_lshl_add_u64 v[124:125], s[14:15], 0, v[124:125]
	v_add_u32_e32 v128, 0xffffc020, v100
	s_waitcnt vmcnt(0)
	v_pk_add_f32 v[116:117], v[116:117], v[120:121]
	v_pk_add_f32 v[118:119], v[118:119], v[122:123]
	global_store_dwordx4 v[138:139], v[116:119], off offset:128
	global_load_dwordx4 v[116:119], v[142:143], off offset:144
	v_mov_b32_e32 v121, v129
	v_or_b32_e32 v120, 16, v100
	v_lshlrev_b64 v[122:123], 12, v[120:121]
	v_ashrrev_i32_e32 v121, 31, v120
	v_lshlrev_b64 v[126:127], 12, v[120:121]
	v_lshl_add_u64 v[134:135], s[12:13], 0, v[126:127]
	v_cmp_gt_i32_e32 vcc, s10, v120
	s_waitcnt vmcnt(0)
	v_pk_add_f32 v[112:113], v[112:113], v[116:117]
	v_cndmask_b32_e32 v125, v125, v135, vcc
	v_cndmask_b32_e32 v124, v124, v134, vcc
	v_pk_add_f32 v[114:115], v[114:115], v[118:119]
	v_lshl_add_u64 v[124:125], v[124:125], 0, v[102:103]
	global_store_dwordx4 v[138:139], v[112:115], off offset:144
	global_load_dwordx4 v[112:115], v[124:125], off
	v_cndmask_b32_e32 v121, v123, v127, vcc
	v_cndmask_b32_e32 v120, v122, v126, vcc
	v_lshl_add_u64 v[116:117], s[30:31], 0, v[120:121]
	v_lshl_add_u64 v[116:117], v[116:117], 0, v[102:103]
	s_waitcnt vmcnt(0)
	v_pk_add_f32 v[108:109], v[108:109], v[112:113]
	v_pk_add_f32 v[110:111], v[110:111], v[114:115]
	global_store_dwordx4 v[116:117], v[108:111], off
	global_load_dwordx4 v[108:111], v[124:125], off offset:16
	v_lshlrev_b64 v[114:115], 12, v[128:129]
	v_lshl_add_u64 v[114:115], s[14:15], 0, v[114:115]
	v_add_u32_e32 v128, 0xffffc030, v100
	s_waitcnt vmcnt(0)
	v_pk_add_f32 v[104:105], v[104:105], v[108:109]
	v_pk_add_f32 v[106:107], v[106:107], v[110:111]
	global_store_dwordx4 v[116:117], v[104:107], off offset:16
	global_load_dwordx4 v[104:107], v[124:125], off offset:128
	v_mov_b32_e32 v109, v129
	v_or_b32_e32 v108, 32, v100
	v_lshlrev_b64 v[110:111], 12, v[108:109]
	v_ashrrev_i32_e32 v109, 31, v108
	v_lshlrev_b64 v[112:113], 12, v[108:109]
	v_lshl_add_u64 v[118:119], s[12:13], 0, v[112:113]
	v_cmp_gt_i32_e32 vcc, s10, v108
	s_waitcnt vmcnt(0)
	v_pk_add_f32 v[104:105], v[130:131], v[104:105]
	v_pk_add_f32 v[106:107], v[132:133], v[106:107]
	global_store_dwordx4 v[116:117], v[104:107], off offset:128
	global_load_dwordx4 v[104:107], v[124:125], off offset:144
	v_cndmask_b32_e32 v115, v115, v119, vcc
	v_cndmask_b32_e32 v114, v114, v118, vcc
	v_lshl_add_u64 v[114:115], v[114:115], 0, v[102:103]
	v_cndmask_b32_e32 v109, v111, v113, vcc
	v_cndmask_b32_e32 v108, v110, v112, vcc
	s_waitcnt vmcnt(0)
	v_pk_add_f32 v[96:97], v[96:97], v[104:105]
	v_pk_add_f32 v[98:99], v[98:99], v[106:107]
	global_store_dwordx4 v[116:117], v[96:99], off offset:144
	global_load_dwordx4 v[96:99], v[114:115], off
	v_lshl_add_u64 v[104:105], s[30:31], 0, v[108:109]
	v_lshl_add_u64 v[104:105], v[104:105], 0, v[102:103]
	s_waitcnt vmcnt(0)
	v_pk_add_f32 v[92:93], v[92:93], v[96:97]
	v_pk_add_f32 v[94:95], v[94:95], v[98:99]
	global_store_dwordx4 v[104:105], v[92:95], off
	global_load_dwordx4 v[92:95], v[114:115], off offset:16
	v_lshlrev_b64 v[96:97], 12, v[128:129]
	v_lshl_add_u64 v[96:97], s[14:15], 0, v[96:97]
	v_add_u32_e32 v128, 0xffffc040, v100
	s_waitcnt vmcnt(0)
	v_pk_add_f32 v[88:89], v[88:89], v[92:93]
	v_pk_add_f32 v[90:91], v[90:91], v[94:95]
	global_store_dwordx4 v[104:105], v[88:91], off offset:16
	global_load_dwordx4 v[88:91], v[114:115], off offset:128
	s_waitcnt vmcnt(0)
	v_pk_add_f32 v[84:85], v[84:85], v[88:89]
	v_pk_add_f32 v[86:87], v[86:87], v[90:91]
	global_store_dwordx4 v[104:105], v[84:87], off offset:128
	global_load_dwordx4 v[84:87], v[114:115], off offset:144
	v_mov_b32_e32 v89, v129
	v_or_b32_e32 v88, 48, v100
	v_lshlrev_b64 v[90:91], 12, v[88:89]
	v_ashrrev_i32_e32 v89, 31, v88
	v_lshlrev_b64 v[92:93], 12, v[88:89]
	v_lshl_add_u64 v[94:95], s[12:13], 0, v[92:93]
	v_cmp_gt_i32_e32 vcc, s10, v88
	s_waitcnt vmcnt(0)
	v_pk_add_f32 v[80:81], v[80:81], v[84:85]
	v_cndmask_b32_e32 v95, v97, v95, vcc
	v_cndmask_b32_e32 v94, v96, v94, vcc
	v_pk_add_f32 v[82:83], v[82:83], v[86:87]
	v_lshl_add_u64 v[94:95], v[94:95], 0, v[102:103]
	global_store_dwordx4 v[104:105], v[80:83], off offset:144
	global_load_dwordx4 v[80:83], v[94:95], off
	v_cndmask_b32_e32 v89, v91, v93, vcc
	v_cndmask_b32_e32 v88, v90, v92, vcc
	v_lshl_add_u64 v[84:85], s[30:31], 0, v[88:89]
	v_lshl_add_u64 v[84:85], v[84:85], 0, v[102:103]
	s_waitcnt vmcnt(0)
	v_pk_add_f32 v[76:77], v[76:77], v[80:81]
	v_pk_add_f32 v[78:79], v[78:79], v[82:83]
	global_store_dwordx4 v[84:85], v[76:79], off
	global_load_dwordx4 v[76:79], v[94:95], off offset:16
	v_lshlrev_b64 v[80:81], 12, v[128:129]
	v_lshl_add_u64 v[80:81], s[14:15], 0, v[80:81]
	v_add_u32_e32 v128, 0xffffc050, v100
	s_waitcnt vmcnt(0)
	v_pk_add_f32 v[72:73], v[72:73], v[76:77]
	v_pk_add_f32 v[74:75], v[74:75], v[78:79]
	global_store_dwordx4 v[84:85], v[72:75], off offset:16
	global_load_dwordx4 v[72:75], v[94:95], off offset:128
	s_waitcnt vmcnt(0)
	v_pk_add_f32 v[68:69], v[68:69], v[72:73]
	v_pk_add_f32 v[70:71], v[70:71], v[74:75]
	global_store_dwordx4 v[84:85], v[68:71], off offset:128
	global_load_dwordx4 v[68:71], v[94:95], off offset:144
	v_mov_b32_e32 v73, v129
	v_or_b32_e32 v72, 64, v100
	v_lshlrev_b64 v[74:75], 12, v[72:73]
	v_ashrrev_i32_e32 v73, 31, v72
	v_lshlrev_b64 v[76:77], 12, v[72:73]
	v_lshl_add_u64 v[78:79], s[12:13], 0, v[76:77]
	v_cmp_gt_i32_e32 vcc, s10, v72
	s_waitcnt vmcnt(0)
	v_pk_add_f32 v[64:65], v[64:65], v[68:69]
	v_cndmask_b32_e32 v79, v81, v79, vcc
	v_cndmask_b32_e32 v78, v80, v78, vcc
	v_pk_add_f32 v[66:67], v[66:67], v[70:71]
	v_lshl_add_u64 v[78:79], v[78:79], 0, v[102:103]
	global_store_dwordx4 v[84:85], v[64:67], off offset:144
	global_load_dwordx4 v[64:67], v[78:79], off
	v_cndmask_b32_e32 v73, v75, v77, vcc
	v_cndmask_b32_e32 v72, v74, v76, vcc
	v_lshl_add_u64 v[68:69], s[30:31], 0, v[72:73]
	v_lshl_add_u64 v[68:69], v[68:69], 0, v[102:103]
	s_waitcnt vmcnt(0)
	v_pk_add_f32 v[60:61], v[60:61], v[64:65]
	v_pk_add_f32 v[62:63], v[62:63], v[66:67]
	global_store_dwordx4 v[68:69], v[60:63], off
	global_load_dwordx4 v[60:63], v[78:79], off offset:16
	v_lshlrev_b64 v[64:65], 12, v[128:129]
	v_lshl_add_u64 v[64:65], s[14:15], 0, v[64:65]
	v_add_u32_e32 v128, 0xffffc060, v100
	s_waitcnt vmcnt(0)
	v_pk_add_f32 v[56:57], v[56:57], v[60:61]
	v_pk_add_f32 v[58:59], v[58:59], v[62:63]
	global_store_dwordx4 v[68:69], v[56:59], off offset:16
	global_load_dwordx4 v[56:59], v[78:79], off offset:128
	s_waitcnt vmcnt(0)
	v_pk_add_f32 v[52:53], v[52:53], v[56:57]
	v_pk_add_f32 v[54:55], v[54:55], v[58:59]
	global_store_dwordx4 v[68:69], v[52:55], off offset:128
	global_load_dwordx4 v[52:55], v[78:79], off offset:144
	v_mov_b32_e32 v57, v129
	v_or_b32_e32 v56, 0x50, v100
	v_lshlrev_b64 v[58:59], 12, v[56:57]
	v_ashrrev_i32_e32 v57, 31, v56
	v_lshlrev_b64 v[60:61], 12, v[56:57]
	v_lshl_add_u64 v[62:63], s[12:13], 0, v[60:61]
	v_cmp_gt_i32_e32 vcc, s10, v56
	s_waitcnt vmcnt(0)
	v_pk_add_f32 v[48:49], v[48:49], v[52:53]
	v_cndmask_b32_e32 v63, v65, v63, vcc
	v_cndmask_b32_e32 v62, v64, v62, vcc
	v_pk_add_f32 v[50:51], v[50:51], v[54:55]
	v_lshl_add_u64 v[62:63], v[62:63], 0, v[102:103]
	global_store_dwordx4 v[68:69], v[48:51], off offset:144
	global_load_dwordx4 v[48:51], v[62:63], off
	v_cndmask_b32_e32 v57, v59, v61, vcc
	v_cndmask_b32_e32 v56, v58, v60, vcc
	v_lshl_add_u64 v[52:53], s[30:31], 0, v[56:57]
	v_lshl_add_u64 v[52:53], v[52:53], 0, v[102:103]
	s_waitcnt vmcnt(0)
	v_pk_add_f32 v[44:45], v[44:45], v[48:49]
	v_pk_add_f32 v[46:47], v[46:47], v[50:51]
	global_store_dwordx4 v[52:53], v[44:47], off
	global_load_dwordx4 v[44:47], v[62:63], off offset:16
	v_lshlrev_b64 v[48:49], 12, v[128:129]
	v_lshl_add_u64 v[48:49], s[14:15], 0, v[48:49]
	v_add_u32_e32 v128, 0xffffc070, v100
	s_waitcnt vmcnt(0)
	v_pk_add_f32 v[40:41], v[40:41], v[44:45]
	v_pk_add_f32 v[42:43], v[42:43], v[46:47]
	global_store_dwordx4 v[52:53], v[40:43], off offset:16
	global_load_dwordx4 v[40:43], v[62:63], off offset:128
	s_waitcnt vmcnt(0)
	v_pk_add_f32 v[36:37], v[36:37], v[40:41]
	v_pk_add_f32 v[38:39], v[38:39], v[42:43]
	global_store_dwordx4 v[52:53], v[36:39], off offset:128
	global_load_dwordx4 v[36:39], v[62:63], off offset:144
	v_mov_b32_e32 v41, v129
	v_or_b32_e32 v40, 0x60, v100
	v_lshlrev_b64 v[42:43], 12, v[40:41]
	v_ashrrev_i32_e32 v41, 31, v40
	v_lshlrev_b64 v[44:45], 12, v[40:41]
	v_lshl_add_u64 v[46:47], s[12:13], 0, v[44:45]
	v_cmp_gt_i32_e32 vcc, s10, v40
	s_waitcnt vmcnt(0)
	v_pk_add_f32 v[32:33], v[32:33], v[36:37]
	v_cndmask_b32_e32 v47, v49, v47, vcc
	v_cndmask_b32_e32 v46, v48, v46, vcc
	v_pk_add_f32 v[34:35], v[34:35], v[38:39]
	v_lshl_add_u64 v[46:47], v[46:47], 0, v[102:103]
	global_store_dwordx4 v[52:53], v[32:35], off offset:144
	global_load_dwordx4 v[32:35], v[46:47], off
	v_cndmask_b32_e32 v41, v43, v45, vcc
	v_cndmask_b32_e32 v40, v42, v44, vcc
	v_lshl_add_u64 v[36:37], s[30:31], 0, v[40:41]
	v_lshl_add_u64 v[36:37], v[36:37], 0, v[102:103]
	s_waitcnt vmcnt(0)
	v_pk_add_f32 v[28:29], v[28:29], v[32:33]
	v_pk_add_f32 v[30:31], v[30:31], v[34:35]
	global_store_dwordx4 v[36:37], v[28:31], off
	global_load_dwordx4 v[28:31], v[46:47], off offset:16
	v_lshlrev_b64 v[32:33], 12, v[128:129]
	v_lshl_add_u64 v[32:33], s[14:15], 0, v[32:33]
	s_waitcnt vmcnt(0)
	v_pk_add_f32 v[24:25], v[24:25], v[28:29]
	v_pk_add_f32 v[26:27], v[26:27], v[30:31]
	global_store_dwordx4 v[36:37], v[24:27], off offset:16
	global_load_dwordx4 v[24:27], v[46:47], off offset:128
	s_waitcnt vmcnt(0)
	v_pk_add_f32 v[20:21], v[20:21], v[24:25]
	v_pk_add_f32 v[22:23], v[22:23], v[26:27]
	global_store_dwordx4 v[36:37], v[20:23], off offset:128
	global_load_dwordx4 v[20:23], v[46:47], off offset:144
	v_mov_b32_e32 v25, v129
	v_or_b32_e32 v24, 0x70, v100
	v_lshlrev_b64 v[26:27], 12, v[24:25]
	v_ashrrev_i32_e32 v25, 31, v24
	v_lshlrev_b64 v[28:29], 12, v[24:25]
	v_lshl_add_u64 v[30:31], s[12:13], 0, v[28:29]
	v_cmp_gt_i32_e32 vcc, s10, v24
	s_waitcnt vmcnt(0)
	v_pk_add_f32 v[16:17], v[16:17], v[20:21]
	v_cndmask_b32_e32 v31, v33, v31, vcc
	v_cndmask_b32_e32 v30, v32, v30, vcc
	v_pk_add_f32 v[18:19], v[18:19], v[22:23]
	v_lshl_add_u64 v[30:31], v[30:31], 0, v[102:103]
	global_store_dwordx4 v[36:37], v[16:19], off offset:144
	global_load_dwordx4 v[16:19], v[30:31], off
	v_cndmask_b32_e32 v25, v27, v29, vcc
	v_cndmask_b32_e32 v24, v26, v28, vcc
	v_lshl_add_u64 v[20:21], s[30:31], 0, v[24:25]
	v_lshl_add_u64 v[20:21], v[20:21], 0, v[102:103]
	s_waitcnt vmcnt(0)
	v_pk_add_f32 v[12:13], v[12:13], v[16:17]
	v_pk_add_f32 v[14:15], v[14:15], v[18:19]
	global_store_dwordx4 v[20:21], v[12:15], off
	global_load_dwordx4 v[12:15], v[30:31], off offset:16
	s_waitcnt vmcnt(0)
	v_pk_add_f32 v[8:9], v[8:9], v[12:13]
	v_pk_add_f32 v[10:11], v[10:11], v[14:15]
	global_store_dwordx4 v[20:21], v[8:11], off offset:16
	global_load_dwordx4 v[8:11], v[30:31], off offset:128
	s_waitcnt vmcnt(0)
	v_pk_add_f32 v[4:5], v[4:5], v[8:9]
	v_pk_add_f32 v[6:7], v[6:7], v[10:11]
	global_store_dwordx4 v[20:21], v[4:7], off offset:128
	global_load_dwordx4 v[4:7], v[30:31], off offset:144
	s_waitcnt vmcnt(0)
	v_pk_add_f32 v[0:1], v[0:1], v[4:5]
	v_pk_add_f32 v[2:3], v[2:3], v[6:7]
	global_store_dwordx4 v[20:21], v[0:3], off offset:144
	s_cbranch_scc0 .LBB0_822
	v_readlane_b32 s11, v254, 56

.LBB0_856:
	s_or_b64 exec, exec, s[40:41]
	v_readlane_b32 s0, v254, 34
	v_readlane_b32 s14, v254, 48
	v_readlane_b32 s1, v254, 35
	v_readlane_b32 s15, v254, 49
	s_add_u32 s0, s14, 0x4000000
	v_mov_b32_e32 v0, v190
	v_mov_b32_e32 v1, v190
	s_waitcnt lgkmcnt(0)
	s_barrier
	s_addc_u32 s1, s15, 0
	v_writelane_b32 v255, s0, 39
	v_ashrrev_i32_e32 v1, 6, v1
	v_add_u32_e32 v16, s87, v1
	v_writelane_b32 v255, s1, 40
	s_movk_i32 s0, 0x4080
	v_cmp_gt_i32_e32 vcc, s0, v16
	v_readlane_b32 s2, v254, 36
	v_readlane_b32 s3, v254, 37
	v_readlane_b32 s4, v254, 38
	v_readlane_b32 s5, v254, 39
	v_readlane_b32 s6, v254, 40
	v_readlane_b32 s7, v254, 41
	v_readlane_b32 s8, v254, 42
	v_readlane_b32 s9, v254, 43
	v_readlane_b32 s10, v254, 44
	v_readlane_b32 s11, v254, 45
	v_readlane_b32 s12, v254, 46
	v_readlane_b32 s13, v254, 47
	s_and_saveexec_b64 s[0:1], vcc
	s_cbranch_execz .LBB0_859
	v_lshlrev_b32_e32 v0, 2, v0
	v_mbcnt_hi_u32_b32 v2, -1, v191
	v_and_b32_e32 v24, 0xfc, v0
	v_and_b32_e32 v0, 64, v2
	v_add_u32_e32 v3, 64, v0
	v_xor_b32_e32 v4, 32, v2
	v_cmp_lt_i32_e32 vcc, v4, v3
	v_readlane_b32 s4, v254, 2
	v_mov_b32_e32 v19, 0
	v_cndmask_b32_e32 v4, v2, v4, vcc
	v_lshlrev_b32_e32 v25, 2, v4
	v_xor_b32_e32 v4, 16, v2
	v_cmp_lt_i32_e32 vcc, v4, v3
	v_lshlrev_b32_e32 v18, 2, v24
	v_readlane_b32 s18, v254, 16
	v_cndmask_b32_e32 v4, v2, v4, vcc
	v_lshlrev_b32_e32 v26, 2, v4
	v_xor_b32_e32 v4, 8, v2
	v_cmp_lt_i32_e32 vcc, v4, v3
	v_readlane_b32 s19, v254, 17
	s_mov_b64 s[2:3], 0x1000
	v_cndmask_b32_e32 v4, v2, v4, vcc
	v_lshlrev_b32_e32 v27, 2, v4
	v_xor_b32_e32 v4, 4, v2
	v_cmp_lt_i32_e32 vcc, v4, v3
	v_lshl_add_u64 v[0:1], s[18:19], 0, v[18:19]
	v_lshl_add_u64 v[12:13], v[0:1], 0, s[2:3]
	v_cndmask_b32_e32 v4, v2, v4, vcc
	v_lshlrev_b32_e32 v28, 2, v4
	v_xor_b32_e32 v4, 2, v2
	v_cmp_lt_i32_e32 vcc, v4, v3
	s_movk_i32 s2, 0x1000
	v_readlane_b32 s6, v254, 4
	v_cndmask_b32_e32 v4, v2, v4, vcc
	v_lshlrev_b32_e32 v29, 2, v4
	v_xor_b32_e32 v4, 1, v2
	v_cmp_lt_i32_e32 vcc, v4, v3
	v_readlane_b32 s7, v254, 5
	v_readlane_b32 s8, v254, 6
	v_cndmask_b32_e32 v2, v2, v4, vcc
	v_add_co_u32_e32 v0, vcc, s2, v0
	v_lshlrev_b32_e32 v30, 2, v2
	s_nop 0
	v_addc_co_u32_e32 v1, vcc, 0, v1, vcc
	global_load_dwordx4 v[0:3], v[0:1], off
	s_nop 0
	global_load_dwordx4 v[4:7], v[12:13], off offset:1024
	global_load_dwordx4 v[8:11], v[12:13], off offset:2048
	s_nop 0
	global_load_dwordx4 v[12:15], v[12:13], off offset:3072
	v_readlane_b32 s9, v254, 7
	v_readlane_b32 s10, v254, 8
	v_readlane_b32 s11, v254, 9
	v_readlane_b32 s12, v254, 10
	v_readlane_b32 s13, v254, 11
	v_readlane_b32 s14, v254, 12
	v_readlane_b32 s15, v254, 13
	v_readlane_b32 s16, v254, 14
	v_readlane_b32 s17, v254, 15
	v_readlane_b32 s6, v255, 39
	v_readlane_b32 s8, v254, 34
	v_readlane_b32 s5, v254, 3
	v_lshlrev_b32_e32 v18, 1, v24
	v_readlane_b32 s7, v255, 40
	v_readlane_b32 s22, v254, 48
	v_readlane_b32 s23, v254, 49
	v_and_b32_e32 v200, -64, v18
	v_add_u32_e32 v200, v18, v200
	v_mov_b32_e32 v201, v19
	v_lshl_add_u64 v[20:21], s[88:89], 0, v[200:201]
	s_lshl_b32 s4, s86, 2
	s_mov_b64 s[2:3], 0
	v_mov_b32_e32 v31, s6
	v_mov_b32_e32 v32, s22
	v_lshlrev_b32_e32 v18, 2, v24
	v_mov_b32_e32 v24, 0x358637bd
	s_movk_i32 s5, 0x7fff
	v_mov_b32_e32 v33, 1
	v_readlane_b32 s9, v254, 35
	v_readlane_b32 s10, v254, 36
	v_readlane_b32 s11, v254, 37
	v_readlane_b32 s12, v254, 38
	v_readlane_b32 s13, v254, 39
	v_readlane_b32 s14, v254, 40
	v_readlane_b32 s15, v254, 41
	v_readlane_b32 s16, v254, 42
	v_readlane_b32 s17, v254, 43
	v_readlane_b32 s18, v254, 44
	v_readlane_b32 s19, v254, 45
	v_readlane_b32 s20, v254, 46
	v_readlane_b32 s21, v254, 47
	s_waitcnt vmcnt(3)
	v_mov_b32_e32 v22, v1
	v_mov_b32_e32 v23, v3
	v_mov_b32_e32 v1, v2
	s_waitcnt vmcnt(2)
	v_mov_b32_e32 v2, v5
	v_mov_b32_e32 v3, v7
	v_mov_b32_e32 v5, v6
	s_waitcnt vmcnt(1)
	v_mov_b32_e32 v6, v9
	v_mov_b32_e32 v7, v11
	v_mov_b32_e32 v9, v10
	s_waitcnt vmcnt(0)
	v_mov_b32_e32 v10, v13
	v_mov_b32_e32 v11, v15
	v_mov_b32_e32 v13, v14
	v_mov_b32_e32 v14, s7
	v_mov_b32_e32 v15, s23
.LBB0_858:
	s_movk_i32 s6, 0x4000
	v_cmp_gt_i32_e32 vcc, s6, v16
	v_add_u32_e32 v34, 0xffffc000, v16
	v_ashrrev_i32_e32 v17, 31, v16
	v_cndmask_b32_e32 v35, 0, v17, vcc
	v_cndmask_b32_e32 v34, v34, v16, vcc
	v_cndmask_b32_e32 v37, v14, v15, vcc
	v_cndmask_b32_e32 v36, v31, v32, vcc
	v_lshlrev_b64 v[34:35], 12, v[34:35]
	v_lshl_add_u64 v[34:35], v[36:37], 0, v[34:35]
	v_lshl_add_u64 v[42:43], v[34:35], 0, v[18:19]
	v_and_b32_e32 v34, -2, v16
	v_mov_b32_e32 v35, v17
	v_lshlrev_b64 v[34:35], 11, v[34:35]
	v_and_b32_e32 v200, 1, v16
	v_lshl_or_b32 v34, v200, 6, v34
	v_lshl_add_u64 v[44:45], v[20:21], 0, v[34:35]
	global_load_dwordx4 v[34:37], v[42:43], off
	global_load_dwordx4 v[38:41], v[42:43], off offset:1024
	s_mov_b32 s6, 0x800000
	v_add_u32_e32 v16, s4, v16
	s_waitcnt vmcnt(1)
	v_mov_b32_e32 v46, v34
	s_waitcnt vmcnt(0)
	v_mov_b32_e32 v50, v38
	v_mov_b32_e32 v55, v38
	v_mov_b32_e32 v38, v35
	v_mov_b32_e32 v48, v35
	v_mov_b32_e32 v54, v34
	v_pk_mul_f32 v[34:35], v[38:39], v[38:39]
	v_mov_b32_e32 v52, v39
	v_pk_fma_f32 v[34:35], v[54:55], v[54:55], v[34:35]
	v_mov_b32_e32 v38, v36
	v_mov_b32_e32 v39, v40
	v_mov_b32_e32 v51, v40
	v_pk_fma_f32 v[34:35], v[38:39], v[38:39], v[34:35]
	v_mov_b32_e32 v40, v37
	v_mov_b32_e32 v47, v36
	v_mov_b32_e32 v49, v37
	v_mov_b32_e32 v53, v41
	v_pk_fma_f32 v[54:55], v[40:41], v[40:41], v[34:35]
	global_load_dwordx4 v[34:37], v[42:43], off offset:2048
	global_load_dwordx4 v[38:41], v[42:43], off offset:3072
	v_add_f32_e32 v17, v54, v55
	s_waitcnt vmcnt(1)
	v_mov_b32_e32 v56, v34
	s_waitcnt vmcnt(0)
	v_mov_b32_e32 v42, v38
	v_mov_b32_e32 v63, v38
	v_mov_b32_e32 v38, v35
	v_mov_b32_e32 v58, v35
	v_mov_b32_e32 v62, v34
	v_pk_mul_f32 v[34:35], v[38:39], v[38:39]
	v_mov_b32_e32 v60, v39
	v_pk_fma_f32 v[34:35], v[62:63], v[62:63], v[34:35]
	v_mov_b32_e32 v38, v36
	v_mov_b32_e32 v39, v40
	v_mov_b32_e32 v43, v40
	v_pk_fma_f32 v[34:35], v[38:39], v[38:39], v[34:35]
	v_mov_b32_e32 v40, v37
	v_pk_fma_f32 v[34:35], v[40:41], v[40:41], v[34:35]
	v_mov_b32_e32 v57, v36
	v_add_f32_e32 v17, v17, v34
	v_add_f32_e32 v17, v17, v35
	ds_bpermute_b32 v34, v25, v17
	v_mov_b32_e32 v59, v37
	v_mov_b32_e32 v61, v41
	s_waitcnt lgkmcnt(0)
	v_add_f32_e32 v17, v17, v34
	ds_bpermute_b32 v34, v26, v17
	s_waitcnt lgkmcnt(0)
	v_add_f32_e32 v17, v17, v34
	ds_bpermute_b32 v34, v27, v17
	s_waitcnt lgkmcnt(0)
	v_add_f32_e32 v17, v17, v34
	ds_bpermute_b32 v34, v28, v17
	s_waitcnt lgkmcnt(0)
	v_add_f32_e32 v17, v17, v34
	ds_bpermute_b32 v34, v29, v17
	s_waitcnt lgkmcnt(0)
	v_add_f32_e32 v17, v17, v34
	ds_bpermute_b32 v34, v30, v17
	s_waitcnt lgkmcnt(0)
	v_add_f32_e32 v17, v17, v34
	v_fmamk_f32 v17, v17, 0x3a800000, v24
	v_cmp_gt_f32_e32 vcc, s6, v17
	v_mul_f32_e32 v34, 0x4b800000, v17
	s_movk_i32 s6, 0x407f
	v_cndmask_b32_e32 v17, v17, v34, vcc
	v_rsq_f32_e32 v17, v17
	s_nop 0
	v_mul_f32_e32 v34, 0x45800000, v17
	v_cndmask_b32_e32 v34, v17, v34, vcc
	v_pk_mul_f32 v[36:37], v[46:47], v[34:35] op_sel_hi:[1,0]
	v_pk_mul_f32 v[38:39], v[48:49], v[34:35] op_sel_hi:[1,0]
	v_pk_mul_f32 v[36:37], v[0:1], v[36:37]
	v_pk_mul_f32 v[38:39], v[22:23], v[38:39]
	v_and_b32_sdwa v17, v37, v33 dst_sel:DWORD dst_unused:UNUSED_PAD src0_sel:WORD_1 src1_sel:DWORD
	v_and_b32_sdwa v35, v36, v33 dst_sel:DWORD dst_unused:UNUSED_PAD src0_sel:WORD_1 src1_sel:DWORD
	v_add3_u32 v35, v36, v35, s5
	v_add3_u32 v17, v37, v17, s5
	v_and_b32_sdwa v36, v39, v33 dst_sel:DWORD dst_unused:UNUSED_PAD src0_sel:WORD_1 src1_sel:DWORD
	v_and_b32_sdwa v37, v38, v33 dst_sel:DWORD dst_unused:UNUSED_PAD src0_sel:WORD_1 src1_sel:DWORD
	v_add3_u32 v36, v39, v36, s5
	v_add3_u32 v37, v38, v37, s5
	v_and_b32_e32 v36, 0xffff0000, v36
	v_and_b32_e32 v38, 0xffff0000, v37
	v_or_b32_sdwa v37, v36, v17 dst_sel:DWORD dst_unused:UNUSED_PAD src0_sel:DWORD src1_sel:WORD_1
	v_or_b32_sdwa v36, v38, v35 dst_sel:DWORD dst_unused:UNUSED_PAD src0_sel:DWORD src1_sel:WORD_1
	global_store_dwordx2 v[44:45], v[36:37], off
	v_pk_mul_f32 v[36:37], v[50:51], v[34:35] op_sel_hi:[1,0]
	v_pk_mul_f32 v[38:39], v[52:53], v[34:35] op_sel_hi:[1,0]
	v_pk_mul_f32 v[36:37], v[4:5], v[36:37]
	v_pk_mul_f32 v[38:39], v[2:3], v[38:39]
	v_and_b32_sdwa v17, v37, v33 dst_sel:DWORD dst_unused:UNUSED_PAD src0_sel:WORD_1 src1_sel:DWORD
	v_and_b32_sdwa v35, v36, v33 dst_sel:DWORD dst_unused:UNUSED_PAD src0_sel:WORD_1 src1_sel:DWORD
	v_add3_u32 v35, v36, v35, s5
	v_add3_u32 v17, v37, v17, s5
	v_and_b32_sdwa v36, v39, v33 dst_sel:DWORD dst_unused:UNUSED_PAD src0_sel:WORD_1 src1_sel:DWORD
	v_and_b32_sdwa v37, v38, v33 dst_sel:DWORD dst_unused:UNUSED_PAD src0_sel:WORD_1 src1_sel:DWORD
	v_add3_u32 v36, v39, v36, s5
	v_add3_u32 v37, v38, v37, s5
	v_and_b32_e32 v36, 0xffff0000, v36
	v_and_b32_e32 v38, 0xffff0000, v37
	v_or_b32_sdwa v37, v36, v17 dst_sel:DWORD dst_unused:UNUSED_PAD src0_sel:DWORD src1_sel:WORD_1
	v_or_b32_sdwa v36, v38, v35 dst_sel:DWORD dst_unused:UNUSED_PAD src0_sel:DWORD src1_sel:WORD_1
	global_store_dwordx2 v[44:45], v[36:37], off offset:1024
	v_pk_mul_f32 v[36:37], v[56:57], v[34:35] op_sel_hi:[1,0]
	v_pk_mul_f32 v[38:39], v[58:59], v[34:35] op_sel_hi:[1,0]
	v_pk_mul_f32 v[36:37], v[8:9], v[36:37]
	v_pk_mul_f32 v[38:39], v[6:7], v[38:39]
	v_and_b32_sdwa v17, v37, v33 dst_sel:DWORD dst_unused:UNUSED_PAD src0_sel:WORD_1 src1_sel:DWORD
	v_and_b32_sdwa v35, v36, v33 dst_sel:DWORD dst_unused:UNUSED_PAD src0_sel:WORD_1 src1_sel:DWORD
	v_add3_u32 v35, v36, v35, s5
	v_add3_u32 v17, v37, v17, s5
	v_and_b32_sdwa v36, v39, v33 dst_sel:DWORD dst_unused:UNUSED_PAD src0_sel:WORD_1 src1_sel:DWORD
	v_and_b32_sdwa v37, v38, v33 dst_sel:DWORD dst_unused:UNUSED_PAD src0_sel:WORD_1 src1_sel:DWORD
	v_add3_u32 v36, v39, v36, s5
	v_add3_u32 v37, v38, v37, s5
	v_and_b32_e32 v36, 0xffff0000, v36
	v_and_b32_e32 v38, 0xffff0000, v37
	v_or_b32_sdwa v37, v36, v17 dst_sel:DWORD dst_unused:UNUSED_PAD src0_sel:DWORD src1_sel:WORD_1
	v_or_b32_sdwa v36, v38, v35 dst_sel:DWORD dst_unused:UNUSED_PAD src0_sel:DWORD src1_sel:WORD_1
	global_store_dwordx2 v[44:45], v[36:37], off offset:2048
	v_pk_mul_f32 v[36:37], v[42:43], v[34:35] op_sel_hi:[1,0]
	v_pk_mul_f32 v[34:35], v[60:61], v[34:35] op_sel_hi:[1,0]
	v_pk_mul_f32 v[36:37], v[12:13], v[36:37]
	v_pk_mul_f32 v[34:35], v[10:11], v[34:35]
	v_and_b32_sdwa v17, v37, v33 dst_sel:DWORD dst_unused:UNUSED_PAD src0_sel:WORD_1 src1_sel:DWORD
	v_and_b32_sdwa v38, v36, v33 dst_sel:DWORD dst_unused:UNUSED_PAD src0_sel:WORD_1 src1_sel:DWORD
	v_add3_u32 v36, v36, v38, s5
	v_add3_u32 v17, v37, v17, s5
	v_and_b32_sdwa v37, v35, v33 dst_sel:DWORD dst_unused:UNUSED_PAD src0_sel:WORD_1 src1_sel:DWORD
	v_and_b32_sdwa v38, v34, v33 dst_sel:DWORD dst_unused:UNUSED_PAD src0_sel:WORD_1 src1_sel:DWORD
	v_add3_u32 v35, v35, v37, s5
	v_add3_u32 v34, v34, v38, s5
	v_and_b32_e32 v35, 0xffff0000, v35
	v_and_b32_e32 v34, 0xffff0000, v34
	v_cmp_lt_i32_e32 vcc, s6, v16
	v_or_b32_sdwa v35, v35, v17 dst_sel:DWORD dst_unused:UNUSED_PAD src0_sel:DWORD src1_sel:WORD_1
	v_or_b32_sdwa v34, v34, v36 dst_sel:DWORD dst_unused:UNUSED_PAD src0_sel:DWORD src1_sel:WORD_1
	s_or_b64 s[2:3], vcc, s[2:3]
	global_store_dwordx2 v[44:45], v[34:35], off offset:3072
	s_andn2_b64 exec, exec, s[2:3]
	s_cbranch_execnz .LBB0_858

.LBB0_884:
	s_or_b64 exec, exec, s[40:41]
	s_add_u32 s40, s52, 0x5f68000
	s_addc_u32 s41, s53, 0
	v_readlane_b32 s16, v254, 56
	s_cmpk_gt_i32 s16, 0x57f
	s_waitcnt lgkmcnt(0)
	s_barrier
	s_cbranch_scc1 .LBB0_890
	s_movk_i32 s4, 0xf500
	s_lshl_b32 s8, s16, 1
	s_lshl_b32 s9, s86, 1
	s_lshl_b32 s10, s16, 3
	s_lshl_b32 s11, s86, 3
	v_mov_b32_e32 v129, 0
	s_mov_b64 s[0:1], 0x20000
	s_mov_b64 s[2:3], 0x20080
	s_movk_i32 s12, 0x580
	s_mov_b32 s5, -1
	s_movk_i32 s13, 0x7fff
	s_mov_b32 s14, 0xffff0000
	s_movk_i32 s15, 0xb00
.LBB0_886:
	s_lshl_b32 s6, s10, 8
	s_lshl_b32 s7, s16, 3
	s_mov_b64 s[62:63], 0x80
	v_mov_b32_e32 v134, v190
	s_and_b32 s20, s6, 0x3800
	s_bfe_u32 s6, s16, 0x30003
	s_and_b32 s7, s7, 56
	s_lshl_b32 s21, s6, 8
	v_lshlrev_b32_e32 v0, 6, v134
	s_or_b32 s6, s7, s6
	v_and_b32_e32 v141, 0xffffe3c0, v0
	v_lshlrev_b32_e32 v0, 1, v134
	v_and_b32_e32 v7, 3, v134
	v_ashrrev_i32_e32 v6, 2, v134
	v_and_b32_e32 v6, -2, v6
	v_and_or_b32 v0, v0, 24, v7
	s_lshl_b32 s17, s6, 8
	v_lshlrev_b32_e32 v139, 6, v0
	v_add_u32_e32 v0, s17, v6
	v_ashrrev_i32_e32 v1, 31, v0
	v_lshlrev_b32_e32 v140, 4, v134
	v_lshlrev_b64 v[0:1], 11, v[0:1]
	s_lshl_b32 s6, s16, 1
	v_lshl_add_u64 v[0:1], s[88:89], 0, v[0:1]
	v_and_b32_e32 v128, 0x70, v140
	s_and_b32 s18, s6, 0xffffff80
	v_readfirstlane_b32 s6, v140
	v_add_u32_e32 v8, 0x1000, v140
	v_lshl_add_u64 v[0:1], v[0:1], 0, v[128:129]
	s_waitcnt vmcnt(0)
	s_mov_b32 m0, s6
	v_readfirstlane_b32 s6, v8
	global_load_lds_dwordx4 v[0:1], off
	v_lshl_add_u64 v[4:5], v[0:1], 0, s[0:1]
	s_mov_b32 m0, s6
	s_mov_b64 s[6:7], 0x40000
	v_add_u32_e32 v8, 0x2000, v140
	global_load_lds_dwordx4 v[4:5], off
	v_lshl_add_u64 v[4:5], v[0:1], 0, s[6:7]
	v_readfirstlane_b32 s6, v8
	s_mov_b32 m0, s6
	s_mov_b64 s[6:7], 0x60000
	v_add_u32_e32 v8, 0x3000, v140
	v_add_u32_e32 v2, s18, v6
	global_load_lds_dwordx4 v[4:5], off
	v_lshl_add_u64 v[4:5], v[0:1], 0, s[6:7]
	v_readfirstlane_b32 s6, v8
	v_ashrrev_i32_e32 v3, 31, v2
	s_mov_b32 m0, s6
	v_lshlrev_b64 v[2:3], 11, v[2:3]
	global_load_lds_dwordx4 v[4:5], off
	v_add_u32_e32 v4, 0x4000, v140
	v_lshl_add_u64 v[2:3], s[52:53], 0, v[2:3]
	v_readfirstlane_b32 s6, v4
	v_add_u32_e32 v8, 0x5000, v140
	v_lshl_add_u64 v[2:3], v[2:3], 0, v[128:129]
	s_mov_b32 m0, s6
	v_readfirstlane_b32 s6, v8
	v_add_u32_e32 v8, 0x6000, v140
	global_load_lds_dwordx4 v[2:3], off
	v_lshl_add_u64 v[4:5], v[2:3], 0, s[0:1]
	s_mov_b32 m0, s6
	v_readfirstlane_b32 s6, v8
	v_add_u32_e32 v8, 0x7000, v140
	global_load_lds_dwordx4 v[4:5], off
	v_lshl_add_u64 v[4:5], v[0:1], 0, s[62:63]
	s_mov_b32 m0, s6
	v_readfirstlane_b32 s6, v8
	global_load_lds_dwordx4 v[4:5], off
	v_lshl_add_u64 v[4:5], v[0:1], 0, s[2:3]
	s_mov_b32 m0, s6
	s_mov_b64 s[6:7], 0x40080
	v_add_u32_e32 v8, 0x8000, v140
	global_load_lds_dwordx4 v[4:5], off
	v_lshl_add_u64 v[4:5], v[0:1], 0, s[6:7]
	v_readfirstlane_b32 s6, v8
	s_mov_b32 m0, s6
	s_mov_b64 s[6:7], 0x60080
	global_load_lds_dwordx4 v[4:5], off
	v_add_u32_e32 v4, 0x9000, v140
	v_lshl_add_u64 v[0:1], v[0:1], 0, s[6:7]
	v_readfirstlane_b32 s6, v4
	v_add_u32_e32 v4, 0xa000, v140
	s_mov_b32 m0, s6
	v_readfirstlane_b32 s6, v4
	global_load_lds_dwordx4 v[0:1], off
	v_lshl_add_u64 v[0:1], v[2:3], 0, s[62:63]
	s_mov_b32 m0, s6
	s_and_b32 s19, s8, 0xffffff80
	global_load_lds_dwordx4 v[0:1], off
	v_lshl_add_u64 v[0:1], v[2:3], 0, s[2:3]
	v_add_u32_e32 v2, 0xb000, v140
	v_bfe_u32 v136, v134, 6, 1
	v_readfirstlane_b32 s6, v2
	s_mov_b32 m0, s6
	v_and_b32_e32 v2, 7, v134
	v_lshlrev_b32_e32 v2, 4, v2
	global_load_lds_dwordx4 v[0:1], off
	v_add_u32_e32 v0, s19, v6
	v_ashrrev_i32_e32 v1, 31, v0
	v_lshlrev_b64 v[0:1], 11, v[0:1]
	v_or_b32_e32 v0, v0, v2
	s_or_b32 s6, s21, s20
	v_lshl_add_u64 v[130:131], s[52:53], 0, v[0:1]
	v_add_u32_e32 v0, s6, v6
	v_ashrrev_i32_e32 v1, 31, v0
	v_lshlrev_b64 v[0:1], 11, v[0:1]
	v_or_b32_e32 v0, v0, v2
	v_and_b32_e32 v135, 15, v134
	v_and_b32_e32 v137, 48, v134
	v_lshlrev_b32_e32 v138, 12, v136
	v_lshl_add_u64 v[132:133], s[52:53], 0, v[0:1]
	s_mov_b64 s[6:7], 0
	s_mov_b32 s19, 0
	v_mov_b32_e32 v0, 0
	v_mov_b32_e32 v1, v129
	v_mov_b32_e32 v2, v129
	v_mov_b32_e32 v3, v129
	v_mov_b32_e32 v4, 0
	v_mov_b32_e32 v5, v129
	v_mov_b32_e32 v6, v129
	v_mov_b32_e32 v7, v129
	v_mov_b32_e32 v8, 0
	v_mov_b32_e32 v9, v129
	v_mov_b32_e32 v10, v129
	v_mov_b32_e32 v11, v129
	v_mov_b32_e32 v12, 0
	v_mov_b32_e32 v13, v129
	v_mov_b32_e32 v14, v129
	v_mov_b32_e32 v15, v129
	v_mov_b32_e32 v16, 0
	v_mov_b32_e32 v17, v129
	v_mov_b32_e32 v18, v129
	v_mov_b32_e32 v19, v129
	v_mov_b32_e32 v20, 0
	v_mov_b32_e32 v21, v129
	v_mov_b32_e32 v22, v129
	v_mov_b32_e32 v23, v129
	v_mov_b32_e32 v24, 0
	v_mov_b32_e32 v25, v129
	v_mov_b32_e32 v26, v129
	v_mov_b32_e32 v27, v129
	v_mov_b32_e32 v28, 0
	v_mov_b32_e32 v29, v129
	v_mov_b32_e32 v30, v129
	v_mov_b32_e32 v31, v129
	v_mov_b32_e32 v32, 0
	v_mov_b32_e32 v33, v129
	v_mov_b32_e32 v34, v129
	v_mov_b32_e32 v35, v129
	v_mov_b32_e32 v36, 0
	v_mov_b32_e32 v37, v129
	v_mov_b32_e32 v38, v129
	v_mov_b32_e32 v39, v129
	v_mov_b32_e32 v40, 0
	v_mov_b32_e32 v41, v129
	v_mov_b32_e32 v42, v129
	v_mov_b32_e32 v43, v129
	v_mov_b32_e32 v44, 0
	v_mov_b32_e32 v45, v129
	v_mov_b32_e32 v46, v129
	v_mov_b32_e32 v47, v129
	v_mov_b32_e32 v48, 0
	v_mov_b32_e32 v49, v129
	v_mov_b32_e32 v50, v129
	v_mov_b32_e32 v51, v129
	v_mov_b32_e32 v52, 0
	v_mov_b32_e32 v53, v129
	v_mov_b32_e32 v54, v129
	v_mov_b32_e32 v55, v129
	v_mov_b32_e32 v56, 0
	v_mov_b32_e32 v57, v129
	v_mov_b32_e32 v58, v129
	v_mov_b32_e32 v59, v129
	v_mov_b32_e32 v60, 0
	v_mov_b32_e32 v61, v129
	v_mov_b32_e32 v62, v129
	v_mov_b32_e32 v63, v129
	v_mov_b32_e32 v64, 0
	v_mov_b32_e32 v65, v129
	v_mov_b32_e32 v66, v129
	v_mov_b32_e32 v67, v129
	v_mov_b32_e32 v68, 0
	v_mov_b32_e32 v69, v129
	v_mov_b32_e32 v70, v129
	v_mov_b32_e32 v71, v129
	v_mov_b32_e32 v72, 0
	v_mov_b32_e32 v73, v129
	v_mov_b32_e32 v74, v129
	v_mov_b32_e32 v75, v129
	v_mov_b32_e32 v76, 0
	v_mov_b32_e32 v77, v129
	v_mov_b32_e32 v78, v129
	v_mov_b32_e32 v79, v129
	v_mov_b32_e32 v80, 0
	v_mov_b32_e32 v81, v129
	v_mov_b32_e32 v82, v129
	v_mov_b32_e32 v83, v129
	v_mov_b32_e32 v84, 0
	v_mov_b32_e32 v85, v129
	v_mov_b32_e32 v86, v129
	v_mov_b32_e32 v87, v129
	v_mov_b32_e32 v88, 0
	v_mov_b32_e32 v89, v129
	v_mov_b32_e32 v90, v129
	v_mov_b32_e32 v91, v129
	v_mov_b32_e32 v92, 0
	v_mov_b32_e32 v93, v129
	v_mov_b32_e32 v94, v129
	v_mov_b32_e32 v95, v129
	v_mov_b32_e32 v96, 0
	v_mov_b32_e32 v97, v129
	v_mov_b32_e32 v98, v129
	v_mov_b32_e32 v99, v129
	v_mov_b32_e32 v100, 0
	v_mov_b32_e32 v101, v129
	v_mov_b32_e32 v102, v129
	v_mov_b32_e32 v103, v129
	v_mov_b32_e32 v104, 0
	v_mov_b32_e32 v105, v129
	v_mov_b32_e32 v106, v129
	v_mov_b32_e32 v107, v129
	v_mov_b32_e32 v108, 0
	v_mov_b32_e32 v109, v129
	v_mov_b32_e32 v110, v129
	v_mov_b32_e32 v111, v129
	v_mov_b32_e32 v112, 0
	v_mov_b32_e32 v113, v129
	v_mov_b32_e32 v114, v129
	v_mov_b32_e32 v115, v129
	v_mov_b32_e32 v116, 0
	v_mov_b32_e32 v117, v129
	v_mov_b32_e32 v118, v129
	v_mov_b32_e32 v119, v129
	v_mov_b32_e32 v120, 0
	v_mov_b32_e32 v121, v129
	v_mov_b32_e32 v122, v129
	v_mov_b32_e32 v123, v129
	v_mov_b32_e32 v124, 0
	v_mov_b32_e32 v125, v129
	v_mov_b32_e32 v126, v129
	v_mov_b32_e32 v127, v129
.LBB0_887:
	s_add_i32 s20, s19, 2
	s_mul_hi_i32 s21, s20, 0x55555556
	s_lshr_b32 s22, s21, 31
	s_add_i32 s21, s21, s22
	s_mul_i32 s21, s21, 3
	s_sub_i32 s20, s20, s21
	s_mulk_i32 s20, 0x6000
	s_mul_i32 s54, s19, 0x6000
	v_readfirstlane_b32 s55, v140
	v_lshl_add_u64 v[232:233], v[132:133], 0, s[6:7]
	v_lshl_add_u64 v[234:235], v[130:131], 0, s[6:7]
	s_add_u32 s55, s55, s20
	s_waitcnt vmcnt(6) lgkmcnt(0)
	s_barrier
	v_or_b32_e32 v128, s54, v138
	v_add3_u32 v128, v128, v139, v137
	ds_read_b128 v[174:177], v128 offset:16384
	ds_read_b128 v[178:181], v128 offset:16640
	ds_read_b128 v[182:185], v128 offset:18432
	ds_read_b128 v[186:189], v128 offset:18688
	v_add3_u32 v128, s54, v141, v137
	ds_read_b128 v[142:145], v128
	ds_read_b128 v[146:149], v128 offset:1024
	ds_read_b128 v[150:153], v128 offset:2048
	ds_read_b128 v[154:157], v128 offset:3072
	ds_read_b128 v[158:161], v128 offset:4096
	ds_read_b128 v[162:165], v128 offset:5120
	ds_read_b128 v[166:169], v128 offset:6144
	ds_read_b128 v[170:173], v128 offset:7168
	s_setprio 1
	s_waitcnt lgkmcnt(7)
	v_mfma_f32_16x16x32_bf16 v[124:127], v[174:177], v[142:145], v[124:127]
	v_mfma_f32_16x16x32_bf16 v[120:123], v[178:181], v[142:145], v[120:123]
	v_mfma_f32_16x16x32_bf16 v[116:119], v[182:185], v[142:145], v[116:119]
	v_mfma_f32_16x16x32_bf16 v[112:115], v[186:189], v[142:145], v[112:115]
	s_mov_b32 m0, s55
	s_mov_b64 s[20:21], 0x12d0100
	v_lshl_add_u64 v[236:237], v[232:233], 0, s[20:21]
	global_load_lds_dwordx4 v[236:237], off
	s_waitcnt lgkmcnt(6)
	v_mfma_f32_16x16x32_bf16 v[108:111], v[174:177], v[146:149], v[108:111]
	v_mfma_f32_16x16x32_bf16 v[104:107], v[178:181], v[146:149], v[104:107]
	v_mfma_f32_16x16x32_bf16 v[100:103], v[182:185], v[146:149], v[100:103]
	v_mfma_f32_16x16x32_bf16 v[96:99], v[186:189], v[146:149], v[96:99]
	s_add_u32 m0, s55, 0x1000
	s_mov_b64 s[20:21], 0x12f0100
	v_lshl_add_u64 v[236:237], v[232:233], 0, s[20:21]
	global_load_lds_dwordx4 v[236:237], off
	s_waitcnt lgkmcnt(5)
	v_mfma_f32_16x16x32_bf16 v[92:95], v[174:177], v[150:153], v[92:95]
	v_mfma_f32_16x16x32_bf16 v[88:91], v[178:181], v[150:153], v[88:91]
	v_mfma_f32_16x16x32_bf16 v[84:87], v[182:185], v[150:153], v[84:87]
	v_mfma_f32_16x16x32_bf16 v[80:83], v[186:189], v[150:153], v[80:83]
	s_add_u32 m0, s55, 0x2000
	s_mov_b64 s[20:21], 0x1310100
	v_lshl_add_u64 v[236:237], v[232:233], 0, s[20:21]
	global_load_lds_dwordx4 v[236:237], off
	s_waitcnt lgkmcnt(4)
	v_mfma_f32_16x16x32_bf16 v[76:79], v[174:177], v[154:157], v[76:79]
	v_mfma_f32_16x16x32_bf16 v[72:75], v[178:181], v[154:157], v[72:75]
	v_mfma_f32_16x16x32_bf16 v[68:71], v[182:185], v[154:157], v[68:71]
	v_mfma_f32_16x16x32_bf16 v[64:67], v[186:189], v[154:157], v[64:67]
	s_add_u32 m0, s55, 0x3000
	s_mov_b64 s[20:21], 0x1330100
	v_lshl_add_u64 v[236:237], v[232:233], 0, s[20:21]
	global_load_lds_dwordx4 v[236:237], off
	s_waitcnt lgkmcnt(3)
	v_mfma_f32_16x16x32_bf16 v[60:63], v[174:177], v[158:161], v[60:63]
	v_mfma_f32_16x16x32_bf16 v[56:59], v[178:181], v[158:161], v[56:59]
	v_mfma_f32_16x16x32_bf16 v[52:55], v[182:185], v[158:161], v[52:55]
	v_mfma_f32_16x16x32_bf16 v[48:51], v[186:189], v[158:161], v[48:51]
	s_add_u32 m0, s55, 0x4000
	s_mov_b64 s[20:21], 0x100
	v_lshl_add_u64 v[236:237], v[234:235], 0, s[20:21]
	global_load_lds_dwordx4 v[236:237], off
	s_waitcnt lgkmcnt(2)
	v_mfma_f32_16x16x32_bf16 v[44:47], v[174:177], v[162:165], v[44:47]
	v_mfma_f32_16x16x32_bf16 v[40:43], v[178:181], v[162:165], v[40:43]
	v_mfma_f32_16x16x32_bf16 v[36:39], v[182:185], v[162:165], v[36:39]
	v_mfma_f32_16x16x32_bf16 v[32:35], v[186:189], v[162:165], v[32:35]
	s_add_u32 m0, s55, 0x5000
	s_mov_b64 s[20:21], 0x20100
	v_lshl_add_u64 v[236:237], v[234:235], 0, s[20:21]
	global_load_lds_dwordx4 v[236:237], off
	s_waitcnt lgkmcnt(1)
	v_mfma_f32_16x16x32_bf16 v[28:31], v[174:177], v[166:169], v[28:31]
	v_mfma_f32_16x16x32_bf16 v[24:27], v[178:181], v[166:169], v[24:27]
	v_mfma_f32_16x16x32_bf16 v[20:23], v[182:185], v[166:169], v[20:23]
	v_mfma_f32_16x16x32_bf16 v[16:19], v[186:189], v[166:169], v[16:19]
	s_waitcnt lgkmcnt(0)
	v_mfma_f32_16x16x32_bf16 v[12:15], v[174:177], v[170:173], v[12:15]
	v_mfma_f32_16x16x32_bf16 v[8:11], v[178:181], v[170:173], v[8:11]
	v_mfma_f32_16x16x32_bf16 v[4:7], v[182:185], v[170:173], v[4:7]
	v_mfma_f32_16x16x32_bf16 v[0:3], v[186:189], v[170:173], v[0:3]
	s_setprio 0
	s_add_i32 s20, s19, 1
	s_cmp_lg_u32 s19, 2
	s_cselect_b32 s19, s20, 0
	s_add_u32 s6, s6, 0x80
	s_addc_u32 s7, s7, 0
	s_cmpk_lg_i32 s6, 0xf00
	s_cbranch_scc1 .LBB0_887
	s_waitcnt vmcnt(6) lgkmcnt(0)
	s_barrier
	v_add_u32_e32 v128, v141, v137
	ds_read_b128 v[130:133], v128
	ds_read_b128 v[140:143], v128 offset:1024
	ds_read_b128 v[144:147], v128 offset:2048
	ds_read_b128 v[148:151], v128 offset:3072
	ds_read_b128 v[152:155], v128 offset:4096
	ds_read_b128 v[156:159], v128 offset:5120
	ds_read_b128 v[160:163], v128 offset:6144
	ds_read_b128 v[164:167], v128 offset:7168
	v_add3_u32 v137, v138, v139, v137
	ds_read_b128 v[168:171], v137 offset:16384
	ds_read_b128 v[172:175], v137 offset:16640
	ds_read_b128 v[176:179], v137 offset:18432
	ds_read_b128 v[180:183], v137 offset:18688
	s_setprio 1
	s_waitcnt lgkmcnt(0)
	v_mfma_f32_16x16x32_bf16 v[124:127], v[168:171], v[130:133], v[124:127]
	v_mfma_f32_16x16x32_bf16 v[120:123], v[172:175], v[130:133], v[120:123]
	v_mfma_f32_16x16x32_bf16 v[116:119], v[176:179], v[130:133], v[116:119]
	v_mfma_f32_16x16x32_bf16 v[112:115], v[180:183], v[130:133], v[112:115]
	v_mfma_f32_16x16x32_bf16 v[108:111], v[168:171], v[140:143], v[108:111]
	v_mfma_f32_16x16x32_bf16 v[104:107], v[172:175], v[140:143], v[104:107]
	v_mfma_f32_16x16x32_bf16 v[100:103], v[176:179], v[140:143], v[100:103]
	v_mfma_f32_16x16x32_bf16 v[96:99], v[180:183], v[140:143], v[96:99]
	v_mfma_f32_16x16x32_bf16 v[92:95], v[168:171], v[144:147], v[92:95]
	v_mfma_f32_16x16x32_bf16 v[88:91], v[172:175], v[144:147], v[88:91]
	v_mfma_f32_16x16x32_bf16 v[84:87], v[176:179], v[144:147], v[84:87]
	v_mfma_f32_16x16x32_bf16 v[80:83], v[180:183], v[144:147], v[80:83]
	v_mfma_f32_16x16x32_bf16 v[76:79], v[168:171], v[148:151], v[76:79]
	v_mfma_f32_16x16x32_bf16 v[72:75], v[172:175], v[148:151], v[72:75]
	v_mfma_f32_16x16x32_bf16 v[68:71], v[176:179], v[148:151], v[68:71]
	v_mfma_f32_16x16x32_bf16 v[64:67], v[180:183], v[148:151], v[64:67]
	v_mfma_f32_16x16x32_bf16 v[60:63], v[168:171], v[152:155], v[60:63]
	v_mfma_f32_16x16x32_bf16 v[56:59], v[172:175], v[152:155], v[56:59]
	v_mfma_f32_16x16x32_bf16 v[52:55], v[176:179], v[152:155], v[52:55]
	v_mfma_f32_16x16x32_bf16 v[48:51], v[180:183], v[152:155], v[48:51]
	v_mfma_f32_16x16x32_bf16 v[44:47], v[168:171], v[156:159], v[44:47]
	v_mfma_f32_16x16x32_bf16 v[40:43], v[172:175], v[156:159], v[40:43]
	v_mfma_f32_16x16x32_bf16 v[36:39], v[176:179], v[156:159], v[36:39]
	v_mfma_f32_16x16x32_bf16 v[32:35], v[180:183], v[156:159], v[32:35]
	v_mfma_f32_16x16x32_bf16 v[28:31], v[168:171], v[160:163], v[28:31]
	v_mfma_f32_16x16x32_bf16 v[24:27], v[172:175], v[160:163], v[24:27]
	v_mfma_f32_16x16x32_bf16 v[20:23], v[176:179], v[160:163], v[20:23]
	v_mfma_f32_16x16x32_bf16 v[16:19], v[180:183], v[160:163], v[16:19]
	v_mfma_f32_16x16x32_bf16 v[12:15], v[168:171], v[164:167], v[12:15]
	v_mfma_f32_16x16x32_bf16 v[8:11], v[172:175], v[164:167], v[8:11]
	v_mfma_f32_16x16x32_bf16 v[4:7], v[176:179], v[164:167], v[4:7]
	v_mfma_f32_16x16x32_bf16 v[0:3], v[180:183], v[164:167], v[0:3]
	s_setprio 0
	s_waitcnt vmcnt(0) lgkmcnt(0)
	s_barrier
	ds_read_b128 v[130:133], v128 offset:24576
	ds_read_b128 v[138:141], v128 offset:25600
	ds_read_b128 v[142:145], v128 offset:26624
	ds_read_b128 v[146:149], v128 offset:27648
	ds_read_b128 v[150:153], v128 offset:28672
	ds_read_b128 v[154:157], v128 offset:29696
	ds_read_b128 v[158:161], v128 offset:30720
	ds_read_b128 v[162:165], v128 offset:31744
	ds_read_b128 v[166:169], v137 offset:40960
	ds_read_b128 v[170:173], v137 offset:41216
	ds_read_b128 v[174:177], v137 offset:43008
	ds_read_b128 v[178:181], v137 offset:43264
	s_setprio 1
	s_waitcnt lgkmcnt(0)
	v_mfma_f32_16x16x32_bf16 v[124:127], v[166:169], v[130:133], v[124:127]
	v_mfma_f32_16x16x32_bf16 v[120:123], v[170:173], v[130:133], v[120:123]
	v_mfma_f32_16x16x32_bf16 v[116:119], v[174:177], v[130:133], v[116:119]
	v_mfma_f32_16x16x32_bf16 v[112:115], v[178:181], v[130:133], v[112:115]
	v_mfma_f32_16x16x32_bf16 v[108:111], v[166:169], v[138:141], v[108:111]
	v_mfma_f32_16x16x32_bf16 v[104:107], v[170:173], v[138:141], v[104:107]
	v_mfma_f32_16x16x32_bf16 v[100:103], v[174:177], v[138:141], v[100:103]
	v_mfma_f32_16x16x32_bf16 v[96:99], v[178:181], v[138:141], v[96:99]
	v_mfma_f32_16x16x32_bf16 v[92:95], v[166:169], v[142:145], v[92:95]
	v_mfma_f32_16x16x32_bf16 v[88:91], v[170:173], v[142:145], v[88:91]
	v_mfma_f32_16x16x32_bf16 v[84:87], v[174:177], v[142:145], v[84:87]
	v_mfma_f32_16x16x32_bf16 v[80:83], v[178:181], v[142:145], v[80:83]
	v_mfma_f32_16x16x32_bf16 v[130:133], v[166:169], v[146:149], v[76:79]
	v_mfma_f32_16x16x32_bf16 v[72:75], v[170:173], v[146:149], v[72:75]
	v_mfma_f32_16x16x32_bf16 v[68:71], v[174:177], v[146:149], v[68:71]
	v_mfma_f32_16x16x32_bf16 v[64:67], v[178:181], v[146:149], v[64:67]
	v_mfma_f32_16x16x32_bf16 v[60:63], v[166:169], v[150:153], v[60:63]
	v_mfma_f32_16x16x32_bf16 v[56:59], v[170:173], v[150:153], v[56:59]
	v_mfma_f32_16x16x32_bf16 v[52:55], v[174:177], v[150:153], v[52:55]
	v_mfma_f32_16x16x32_bf16 v[48:51], v[178:181], v[150:153], v[48:51]
	v_mfma_f32_16x16x32_bf16 v[44:47], v[166:169], v[154:157], v[44:47]
	v_mfma_f32_16x16x32_bf16 v[40:43], v[170:173], v[154:157], v[40:43]
	v_mfma_f32_16x16x32_bf16 v[36:39], v[174:177], v[154:157], v[36:39]
	v_mfma_f32_16x16x32_bf16 v[32:35], v[178:181], v[154:157], v[32:35]
	v_mfma_f32_16x16x32_bf16 v[28:31], v[166:169], v[158:161], v[28:31]
	v_mfma_f32_16x16x32_bf16 v[24:27], v[170:173], v[158:161], v[24:27]
	v_mfma_f32_16x16x32_bf16 v[20:23], v[174:177], v[158:161], v[20:23]
	v_mfma_f32_16x16x32_bf16 v[16:19], v[178:181], v[158:161], v[16:19]
	v_mfma_f32_16x16x32_bf16 v[12:15], v[166:169], v[162:165], v[12:15]
	v_mfma_f32_16x16x32_bf16 v[8:11], v[170:173], v[162:165], v[8:11]
	v_mfma_f32_16x16x32_bf16 v[4:7], v[174:177], v[162:165], v[4:7]
	v_mfma_f32_16x16x32_bf16 v[0:3], v[178:181], v[162:165], v[0:3]
	s_setprio 0
	v_and_b32_e32 v76, 0xffffff80, v134
	v_add_u32_e32 v76, s17, v76
	v_lshrrev_b32_e32 v77, 1, v134
	v_or_b32_e32 v128, v76, v135
	v_lshlrev_b32_e32 v76, 6, v136
	v_and_b32_e32 v77, 24, v77
	v_or3_b32 v78, v76, v77, s18
	v_ashrrev_i32_e32 v79, 31, v78
	v_lshl_add_u64 v[76:77], v[78:79], 1, s[94:95]
	v_mov_b32_e32 v79, v129
	v_lshl_add_u64 v[134:135], v[78:79], 1, s[40:41]
	v_bfe_u32 v79, v124, 16, 1
	v_add3_u32 v79, v124, v79, s13
	v_bfe_u32 v124, v125, 16, 1
	v_lshrrev_b32_e32 v79, 16, v79
	v_add3_u32 v124, v125, v124, s13
	v_and_or_b32 v124, v124, s14, v79
	v_bfe_u32 v79, v126, 16, 1
	v_add3_u32 v79, v126, v79, s13
	v_bfe_u32 v125, v127, 16, 1
	v_lshrrev_b32_e32 v79, 16, v79
	v_add3_u32 v125, v127, v125, s13
	v_and_or_b32 v125, v125, s14, v79
	v_bfe_u32 v79, v120, 16, 1
	v_add3_u32 v79, v120, v79, s13
	v_bfe_u32 v120, v121, 16, 1
	v_lshrrev_b32_e32 v79, 16, v79
	v_add3_u32 v120, v121, v120, s13
	v_and_or_b32 v126, v120, s14, v79
	v_bfe_u32 v79, v122, 16, 1
	v_lshl_add_u64 v[134:135], v[134:135], 0, s[4:5]
	v_cmp_gt_i32_e32 vcc, s12, v78
	v_add3_u32 v79, v122, v79, s13
	v_bfe_u32 v120, v123, 16, 1
	v_cndmask_b32_e32 v77, v135, v77, vcc
	v_cndmask_b32_e32 v76, v134, v76, vcc
	v_lshrrev_b32_e32 v79, 16, v79
	v_add3_u32 v120, v123, v120, s13
	v_or_b32_e32 v78, 32, v78
	v_and_or_b32 v127, v120, s14, v79
	v_mad_i64_i32 v[120:121], s[6:7], v128, s15, v[76:77]
	v_ashrrev_i32_e32 v79, 31, v78
	global_store_dwordx4 v[120:121], v[124:127], off
	v_lshl_add_u64 v[120:121], v[78:79], 1, s[94:95]
	v_mov_b32_e32 v79, v129
	v_lshl_add_u64 v[122:123], v[78:79], 1, s[40:41]
	v_lshl_add_u64 v[122:123], v[122:123], 0, s[4:5]
	v_cmp_gt_i32_e32 vcc, s12, v78
	s_add_i32 s16, s16, s86
	s_add_i32 s8, s8, s9
	v_cndmask_b32_e32 v78, v122, v120, vcc
	v_bfe_u32 v120, v116, 16, 1
	v_add3_u32 v116, v116, v120, s13
	v_bfe_u32 v120, v117, 16, 1
	v_lshrrev_b32_e32 v116, 16, v116
	v_add3_u32 v117, v117, v120, s13
	v_and_or_b32 v116, v117, s14, v116
	v_bfe_u32 v117, v118, 16, 1
	v_add3_u32 v117, v118, v117, s13
	v_bfe_u32 v118, v119, 16, 1
	v_lshrrev_b32_e32 v117, 16, v117
	v_add3_u32 v118, v119, v118, s13
	v_and_or_b32 v117, v118, s14, v117
	v_bfe_u32 v118, v112, 16, 1
	v_add3_u32 v112, v112, v118, s13
	v_bfe_u32 v118, v113, 16, 1
	v_lshrrev_b32_e32 v112, 16, v112
	v_add3_u32 v113, v113, v118, s13
	v_and_or_b32 v118, v113, s14, v112
	v_bfe_u32 v112, v114, 16, 1
	v_add3_u32 v112, v114, v112, s13
	v_bfe_u32 v113, v115, 16, 1
	v_cndmask_b32_e32 v79, v123, v121, vcc
	v_lshrrev_b32_e32 v112, 16, v112
	v_add3_u32 v113, v115, v113, s13
	v_and_or_b32 v119, v113, s14, v112
	v_mad_i64_i32 v[112:113], s[6:7], v128, s15, v[78:79]
	global_store_dwordx4 v[112:113], v[116:119], off
	v_bfe_u32 v113, v108, 16, 1
	v_add3_u32 v108, v108, v113, s13
	v_bfe_u32 v113, v109, 16, 1
	v_lshrrev_b32_e32 v108, 16, v108
	v_add3_u32 v109, v109, v113, s13
	v_and_or_b32 v108, v109, s14, v108
	v_bfe_u32 v109, v110, 16, 1
	v_add3_u32 v109, v110, v109, s13
	v_bfe_u32 v110, v111, 16, 1
	v_lshrrev_b32_e32 v109, 16, v109
	v_add3_u32 v110, v111, v110, s13
	v_and_or_b32 v109, v110, s14, v109
	v_bfe_u32 v110, v104, 16, 1
	v_add3_u32 v104, v104, v110, s13
	v_bfe_u32 v110, v105, 16, 1
	v_lshrrev_b32_e32 v104, 16, v104
	v_add3_u32 v105, v105, v110, s13
	v_and_or_b32 v110, v105, s14, v104
	v_bfe_u32 v104, v106, 16, 1
	v_add3_u32 v104, v106, v104, s13
	v_bfe_u32 v105, v107, 16, 1
	v_or_b32_e32 v112, 16, v128
	v_lshrrev_b32_e32 v104, 16, v104
	v_add3_u32 v105, v107, v105, s13
	v_and_or_b32 v111, v105, s14, v104
	v_mad_i64_i32 v[104:105], s[6:7], v112, s15, v[76:77]
	global_store_dwordx4 v[104:105], v[108:111], off
	v_bfe_u32 v104, v100, 16, 1
	v_add3_u32 v100, v100, v104, s13
	v_bfe_u32 v104, v101, 16, 1
	v_lshrrev_b32_e32 v100, 16, v100
	v_add3_u32 v101, v101, v104, s13
	v_and_or_b32 v100, v101, s14, v100
	v_bfe_u32 v101, v102, 16, 1
	v_add3_u32 v101, v102, v101, s13
	v_bfe_u32 v102, v103, 16, 1
	v_lshrrev_b32_e32 v101, 16, v101
	v_add3_u32 v102, v103, v102, s13
	v_and_or_b32 v101, v102, s14, v101
	v_bfe_u32 v102, v96, 16, 1
	v_add3_u32 v96, v96, v102, s13
	v_bfe_u32 v102, v97, 16, 1
	v_lshrrev_b32_e32 v96, 16, v96
	v_add3_u32 v97, v97, v102, s13
	v_and_or_b32 v102, v97, s14, v96
	v_bfe_u32 v96, v98, 16, 1
	v_add3_u32 v96, v98, v96, s13
	v_bfe_u32 v97, v99, 16, 1
	v_lshrrev_b32_e32 v96, 16, v96
	v_add3_u32 v97, v99, v97, s13
	v_and_or_b32 v103, v97, s14, v96
	v_mad_i64_i32 v[96:97], s[6:7], v112, s15, v[78:79]
	global_store_dwordx4 v[96:97], v[100:103], off
	v_bfe_u32 v97, v92, 16, 1
	v_add3_u32 v92, v92, v97, s13
	v_bfe_u32 v97, v93, 16, 1
	v_lshrrev_b32_e32 v92, 16, v92
	v_add3_u32 v93, v93, v97, s13
	v_and_or_b32 v92, v93, s14, v92
	v_bfe_u32 v93, v94, 16, 1
	v_add3_u32 v93, v94, v93, s13
	v_bfe_u32 v94, v95, 16, 1
	v_lshrrev_b32_e32 v93, 16, v93
	v_add3_u32 v94, v95, v94, s13
	v_and_or_b32 v93, v94, s14, v93
	v_bfe_u32 v94, v88, 16, 1
	v_add3_u32 v88, v88, v94, s13
	v_bfe_u32 v94, v89, 16, 1
	v_lshrrev_b32_e32 v88, 16, v88
	v_add3_u32 v89, v89, v94, s13
	v_and_or_b32 v94, v89, s14, v88
	v_bfe_u32 v88, v90, 16, 1
	v_add3_u32 v88, v90, v88, s13
	v_bfe_u32 v89, v91, 16, 1
	v_or_b32_e32 v96, 32, v128
	v_lshrrev_b32_e32 v88, 16, v88
	v_add3_u32 v89, v91, v89, s13
	v_and_or_b32 v95, v89, s14, v88
	v_mad_i64_i32 v[88:89], s[6:7], v96, s15, v[76:77]
	global_store_dwordx4 v[88:89], v[92:95], off
	v_bfe_u32 v88, v84, 16, 1
	v_add3_u32 v84, v84, v88, s13
	v_bfe_u32 v88, v85, 16, 1
	v_lshrrev_b32_e32 v84, 16, v84
	v_add3_u32 v85, v85, v88, s13
	v_and_or_b32 v84, v85, s14, v84
	v_bfe_u32 v85, v86, 16, 1
	v_add3_u32 v85, v86, v85, s13
	v_bfe_u32 v86, v87, 16, 1
	v_lshrrev_b32_e32 v85, 16, v85
	v_add3_u32 v86, v87, v86, s13
	v_and_or_b32 v85, v86, s14, v85
	v_bfe_u32 v86, v80, 16, 1
	v_add3_u32 v80, v80, v86, s13
	v_bfe_u32 v86, v81, 16, 1
	v_lshrrev_b32_e32 v80, 16, v80
	v_add3_u32 v81, v81, v86, s13
	v_and_or_b32 v86, v81, s14, v80
	v_bfe_u32 v80, v82, 16, 1
	v_add3_u32 v80, v82, v80, s13
	v_bfe_u32 v81, v83, 16, 1
	v_lshrrev_b32_e32 v80, 16, v80
	v_add3_u32 v81, v83, v81, s13
	v_and_or_b32 v87, v81, s14, v80
	v_mad_i64_i32 v[80:81], s[6:7], v96, s15, v[78:79]
	global_store_dwordx4 v[80:81], v[84:87], off
	v_bfe_u32 v80, v130, 16, 1
	v_add3_u32 v80, v130, v80, s13
	v_bfe_u32 v81, v131, 16, 1
	v_lshrrev_b32_e32 v80, 16, v80
	v_add3_u32 v81, v131, v81, s13
	v_and_or_b32 v80, v81, s14, v80
	v_bfe_u32 v81, v132, 16, 1
	v_add3_u32 v81, v132, v81, s13
	v_bfe_u32 v82, v133, 16, 1
	v_lshrrev_b32_e32 v81, 16, v81
	v_add3_u32 v82, v133, v82, s13
	v_and_or_b32 v81, v82, s14, v81
	v_bfe_u32 v82, v72, 16, 1
	v_add3_u32 v72, v72, v82, s13
	v_bfe_u32 v82, v73, 16, 1
	v_lshrrev_b32_e32 v72, 16, v72
	v_add3_u32 v73, v73, v82, s13
	v_and_or_b32 v82, v73, s14, v72
	v_bfe_u32 v72, v74, 16, 1
	v_add3_u32 v72, v74, v72, s13
	v_bfe_u32 v73, v75, 16, 1
	v_or_b32_e32 v84, 48, v128
	v_lshrrev_b32_e32 v72, 16, v72
	v_add3_u32 v73, v75, v73, s13
	v_and_or_b32 v83, v73, s14, v72
	v_mad_i64_i32 v[72:73], s[6:7], v84, s15, v[76:77]
	global_store_dwordx4 v[72:73], v[80:83], off
	v_bfe_u32 v72, v68, 16, 1
	v_add3_u32 v68, v68, v72, s13
	v_bfe_u32 v72, v69, 16, 1
	v_lshrrev_b32_e32 v68, 16, v68
	v_add3_u32 v69, v69, v72, s13
	v_and_or_b32 v68, v69, s14, v68
	v_bfe_u32 v69, v70, 16, 1
	v_add3_u32 v69, v70, v69, s13
	v_bfe_u32 v70, v71, 16, 1
	v_lshrrev_b32_e32 v69, 16, v69
	v_add3_u32 v70, v71, v70, s13
	v_and_or_b32 v69, v70, s14, v69
	v_bfe_u32 v70, v64, 16, 1
	v_add3_u32 v64, v64, v70, s13
	v_bfe_u32 v70, v65, 16, 1
	v_lshrrev_b32_e32 v64, 16, v64
	v_add3_u32 v65, v65, v70, s13
	v_and_or_b32 v70, v65, s14, v64
	v_bfe_u32 v64, v66, 16, 1
	v_add3_u32 v64, v66, v64, s13
	v_bfe_u32 v65, v67, 16, 1
	v_lshrrev_b32_e32 v64, 16, v64
	v_add3_u32 v65, v67, v65, s13
	v_and_or_b32 v71, v65, s14, v64
	v_mad_i64_i32 v[64:65], s[6:7], v84, s15, v[78:79]
	global_store_dwordx4 v[64:65], v[68:71], off
	v_bfe_u32 v65, v60, 16, 1
	v_add3_u32 v60, v60, v65, s13
	v_bfe_u32 v65, v61, 16, 1
	v_lshrrev_b32_e32 v60, 16, v60
	v_add3_u32 v61, v61, v65, s13
	v_and_or_b32 v60, v61, s14, v60
	v_bfe_u32 v61, v62, 16, 1
	v_add3_u32 v61, v62, v61, s13
	v_bfe_u32 v62, v63, 16, 1
	v_lshrrev_b32_e32 v61, 16, v61
	v_add3_u32 v62, v63, v62, s13
	v_and_or_b32 v61, v62, s14, v61
	v_bfe_u32 v62, v56, 16, 1
	v_add3_u32 v56, v56, v62, s13
	v_bfe_u32 v62, v57, 16, 1
	v_lshrrev_b32_e32 v56, 16, v56
	v_add3_u32 v57, v57, v62, s13
	v_and_or_b32 v62, v57, s14, v56
	v_bfe_u32 v56, v58, 16, 1
	v_add3_u32 v56, v58, v56, s13
	v_bfe_u32 v57, v59, 16, 1
	v_or_b32_e32 v64, 64, v128
	v_lshrrev_b32_e32 v56, 16, v56
	v_add3_u32 v57, v59, v57, s13
	v_and_or_b32 v63, v57, s14, v56
	v_mad_i64_i32 v[56:57], s[6:7], v64, s15, v[76:77]
	global_store_dwordx4 v[56:57], v[60:63], off
	v_bfe_u32 v56, v52, 16, 1
	v_add3_u32 v52, v52, v56, s13
	v_bfe_u32 v56, v53, 16, 1
	v_lshrrev_b32_e32 v52, 16, v52
	v_add3_u32 v53, v53, v56, s13
	v_and_or_b32 v52, v53, s14, v52
	v_bfe_u32 v53, v54, 16, 1
	v_add3_u32 v53, v54, v53, s13
	v_bfe_u32 v54, v55, 16, 1
	v_lshrrev_b32_e32 v53, 16, v53
	v_add3_u32 v54, v55, v54, s13
	v_and_or_b32 v53, v54, s14, v53
	v_bfe_u32 v54, v48, 16, 1
	v_add3_u32 v48, v48, v54, s13
	v_bfe_u32 v54, v49, 16, 1
	v_lshrrev_b32_e32 v48, 16, v48
	v_add3_u32 v49, v49, v54, s13
	v_and_or_b32 v54, v49, s14, v48
	v_bfe_u32 v48, v50, 16, 1
	v_add3_u32 v48, v50, v48, s13
	v_bfe_u32 v49, v51, 16, 1
	v_lshrrev_b32_e32 v48, 16, v48
	v_add3_u32 v49, v51, v49, s13
	v_and_or_b32 v55, v49, s14, v48
	v_mad_i64_i32 v[48:49], s[6:7], v64, s15, v[78:79]
	global_store_dwordx4 v[48:49], v[52:55], off
	v_bfe_u32 v49, v44, 16, 1
	v_add3_u32 v44, v44, v49, s13
	v_bfe_u32 v49, v45, 16, 1
	v_lshrrev_b32_e32 v44, 16, v44
	v_add3_u32 v45, v45, v49, s13
	v_and_or_b32 v44, v45, s14, v44
	v_bfe_u32 v45, v46, 16, 1
	v_add3_u32 v45, v46, v45, s13
	v_bfe_u32 v46, v47, 16, 1
	v_lshrrev_b32_e32 v45, 16, v45
	v_add3_u32 v46, v47, v46, s13
	v_and_or_b32 v45, v46, s14, v45
	v_bfe_u32 v46, v40, 16, 1
	v_add3_u32 v40, v40, v46, s13
	v_bfe_u32 v46, v41, 16, 1
	v_lshrrev_b32_e32 v40, 16, v40
	v_add3_u32 v41, v41, v46, s13
	v_and_or_b32 v46, v41, s14, v40
	v_bfe_u32 v40, v42, 16, 1
	v_add3_u32 v40, v42, v40, s13
	v_bfe_u32 v41, v43, 16, 1
	v_or_b32_e32 v48, 0x50, v128
	v_lshrrev_b32_e32 v40, 16, v40
	v_add3_u32 v41, v43, v41, s13
	v_and_or_b32 v47, v41, s14, v40
	v_mad_i64_i32 v[40:41], s[6:7], v48, s15, v[76:77]
	global_store_dwordx4 v[40:41], v[44:47], off
	v_bfe_u32 v40, v36, 16, 1
	v_add3_u32 v36, v36, v40, s13
	v_bfe_u32 v40, v37, 16, 1
	v_lshrrev_b32_e32 v36, 16, v36
	v_add3_u32 v37, v37, v40, s13
	v_and_or_b32 v36, v37, s14, v36
	v_bfe_u32 v37, v38, 16, 1
	v_add3_u32 v37, v38, v37, s13
	v_bfe_u32 v38, v39, 16, 1
	v_lshrrev_b32_e32 v37, 16, v37
	v_add3_u32 v38, v39, v38, s13
	v_and_or_b32 v37, v38, s14, v37
	v_bfe_u32 v38, v32, 16, 1
	v_add3_u32 v32, v32, v38, s13
	v_bfe_u32 v38, v33, 16, 1
	v_lshrrev_b32_e32 v32, 16, v32
	v_add3_u32 v33, v33, v38, s13
	v_and_or_b32 v38, v33, s14, v32
	v_bfe_u32 v32, v34, 16, 1
	v_add3_u32 v32, v34, v32, s13
	v_bfe_u32 v33, v35, 16, 1
	v_lshrrev_b32_e32 v32, 16, v32
	v_add3_u32 v33, v35, v33, s13
	v_and_or_b32 v39, v33, s14, v32
	v_mad_i64_i32 v[32:33], s[6:7], v48, s15, v[78:79]
	global_store_dwordx4 v[32:33], v[36:39], off
	v_bfe_u32 v33, v28, 16, 1
	v_add3_u32 v28, v28, v33, s13
	v_bfe_u32 v33, v29, 16, 1
	v_lshrrev_b32_e32 v28, 16, v28
	v_add3_u32 v29, v29, v33, s13
	v_and_or_b32 v28, v29, s14, v28
	v_bfe_u32 v29, v30, 16, 1
	v_add3_u32 v29, v30, v29, s13
	v_bfe_u32 v30, v31, 16, 1
	v_lshrrev_b32_e32 v29, 16, v29
	v_add3_u32 v30, v31, v30, s13
	v_and_or_b32 v29, v30, s14, v29
	v_bfe_u32 v30, v24, 16, 1
	v_add3_u32 v24, v24, v30, s13
	v_bfe_u32 v30, v25, 16, 1
	v_lshrrev_b32_e32 v24, 16, v24
	v_add3_u32 v25, v25, v30, s13
	v_and_or_b32 v30, v25, s14, v24
	v_bfe_u32 v24, v26, 16, 1
	v_add3_u32 v24, v26, v24, s13
	v_bfe_u32 v25, v27, 16, 1
	v_or_b32_e32 v32, 0x60, v128
	v_lshrrev_b32_e32 v24, 16, v24
	v_add3_u32 v25, v27, v25, s13
	v_and_or_b32 v31, v25, s14, v24
	v_mad_i64_i32 v[24:25], s[6:7], v32, s15, v[76:77]
	global_store_dwordx4 v[24:25], v[28:31], off
	v_bfe_u32 v24, v20, 16, 1
	v_add3_u32 v20, v20, v24, s13
	v_bfe_u32 v24, v21, 16, 1
	v_lshrrev_b32_e32 v20, 16, v20
	v_add3_u32 v21, v21, v24, s13
	v_and_or_b32 v20, v21, s14, v20
	v_bfe_u32 v21, v22, 16, 1
	v_add3_u32 v21, v22, v21, s13
	v_bfe_u32 v22, v23, 16, 1
	v_lshrrev_b32_e32 v21, 16, v21
	v_add3_u32 v22, v23, v22, s13
	v_and_or_b32 v21, v22, s14, v21
	v_bfe_u32 v22, v16, 16, 1
	v_add3_u32 v16, v16, v22, s13
	v_bfe_u32 v22, v17, 16, 1
	v_lshrrev_b32_e32 v16, 16, v16
	v_add3_u32 v17, v17, v22, s13
	v_and_or_b32 v22, v17, s14, v16
	v_bfe_u32 v16, v18, 16, 1
	v_add3_u32 v16, v18, v16, s13
	v_bfe_u32 v17, v19, 16, 1
	v_lshrrev_b32_e32 v16, 16, v16
	v_add3_u32 v17, v19, v17, s13
	v_and_or_b32 v23, v17, s14, v16
	v_mad_i64_i32 v[16:17], s[6:7], v32, s15, v[78:79]
	global_store_dwordx4 v[16:17], v[20:23], off
	v_bfe_u32 v17, v12, 16, 1
	v_add3_u32 v12, v12, v17, s13
	v_bfe_u32 v17, v13, 16, 1
	v_lshrrev_b32_e32 v12, 16, v12
	v_add3_u32 v13, v13, v17, s13
	v_and_or_b32 v12, v13, s14, v12
	v_bfe_u32 v13, v14, 16, 1
	v_add3_u32 v13, v14, v13, s13
	v_bfe_u32 v14, v15, 16, 1
	v_lshrrev_b32_e32 v13, 16, v13
	v_add3_u32 v14, v15, v14, s13
	v_and_or_b32 v13, v14, s14, v13
	v_bfe_u32 v14, v8, 16, 1
	v_add3_u32 v8, v8, v14, s13
	v_bfe_u32 v14, v9, 16, 1
	v_lshrrev_b32_e32 v8, 16, v8
	v_add3_u32 v9, v9, v14, s13
	v_and_or_b32 v14, v9, s14, v8
	v_bfe_u32 v8, v10, 16, 1
	v_add3_u32 v8, v10, v8, s13
	v_bfe_u32 v9, v11, 16, 1
	v_or_b32_e32 v16, 0x70, v128
	v_lshrrev_b32_e32 v8, 16, v8
	v_add3_u32 v9, v11, v9, s13
	v_and_or_b32 v15, v9, s14, v8
	v_mad_i64_i32 v[8:9], s[6:7], v16, s15, v[76:77]
	global_store_dwordx4 v[8:9], v[12:15], off
	v_bfe_u32 v8, v4, 16, 1
	v_add3_u32 v4, v4, v8, s13
	v_bfe_u32 v8, v5, 16, 1
	v_lshrrev_b32_e32 v4, 16, v4
	v_add3_u32 v5, v5, v8, s13
	v_and_or_b32 v4, v5, s14, v4
	v_bfe_u32 v5, v6, 16, 1
	v_add3_u32 v5, v6, v5, s13
	v_bfe_u32 v6, v7, 16, 1
	v_lshrrev_b32_e32 v5, 16, v5
	v_add3_u32 v6, v7, v6, s13
	v_and_or_b32 v5, v6, s14, v5
	v_bfe_u32 v6, v0, 16, 1
	v_add3_u32 v0, v0, v6, s13
	v_bfe_u32 v6, v1, 16, 1
	v_lshrrev_b32_e32 v0, 16, v0
	v_add3_u32 v1, v1, v6, s13
	v_and_or_b32 v6, v1, s14, v0
	v_bfe_u32 v0, v2, 16, 1
	v_add3_u32 v0, v2, v0, s13
	v_bfe_u32 v1, v3, 16, 1
	v_lshrrev_b32_e32 v0, 16, v0
	v_add3_u32 v1, v3, v1, s13
	s_add_i32 s10, s10, s11
	v_and_or_b32 v7, v1, s14, v0
	v_mad_i64_i32 v[0:1], s[6:7], v16, s15, v[78:79]
	s_cmpk_lt_i32 s16, 0x580
	global_store_dwordx4 v[0:1], v[4:7], off
	s_cbranch_scc1 .LBB0_886
	v_readlane_b32 s16, v254, 56
.LBB0_890:
	s_cmpk_lt_i32 s16, 0x58
	v_readlane_b32 s0, v254, 18
	v_mov_b32_e32 v0, v190
	s_cselect_b64 s[66:67], -1, 0
	s_cmpk_gt_i32 s16, 0x57
	v_readlane_b32 s14, v254, 32
	v_readlane_b32 s15, v254, 33
	v_readlane_b32 s1, v254, 19
	v_readlane_b32 s2, v254, 20
	v_readlane_b32 s3, v254, 21
	v_readlane_b32 s4, v254, 22
	v_readlane_b32 s5, v254, 23
	v_readlane_b32 s6, v254, 24
	v_readlane_b32 s7, v254, 25
	v_readlane_b32 s8, v254, 26
	v_readlane_b32 s9, v254, 27
	v_readlane_b32 s10, v254, 28
	v_readlane_b32 s11, v254, 29
	v_readlane_b32 s12, v254, 30
	v_readlane_b32 s13, v254, 31
	s_cbranch_scc1 .LBB0_895
	v_and_b32_e32 v2, 15, v0
	v_bfe_u32 v3, v0, 4, 2
	v_ashrrev_i32_e32 v0, 1, v0
	s_movk_i32 s0, 0xffe0
	v_and_or_b32 v4, v0, s0, v2
	v_add_u32_e32 v0, 0x4000, v4
	v_ashrrev_i32_e32 v1, 31, v0
	s_movk_i32 s2, 0xb00
	v_add_u32_e32 v4, 0x4010, v4
	v_mad_i64_i32 v[16:17], s[0:1], v0, s2, 0
	v_mad_i64_i32 v[18:19], s[0:1], v4, s2, 0
	v_readlane_b32 s7, v254, 56
	v_and_b32_e32 v0, -2, v0
	v_lshlrev_b64 v[0:1], 11, v[0:1]
	s_movk_i32 s2, 0xf500
	v_lshlrev_b32_e32 v30, 2, v3
	v_lshlrev_b32_e32 v20, 4, v3
	v_and_b32_e32 v238, 1, v2
	v_lshl_or_b32 v20, v238, 6, v20
	v_mov_b32_e32 v21, 0
	v_lshl_or_b32 v22, s7, 5, v2
	s_lshl_b32 s4, s86, 5
	v_lshl_add_u64 v[24:25], s[52:53], 0, v[0:1]
	s_mov_b64 s[0:1], 0x200
	s_movk_i32 s5, 0x580
	s_mov_b32 s3, -1
	s_movk_i32 s6, 0x7fff
	v_mov_b32_e32 v31, 1
.LBB0_892:
	v_ashrrev_i32_e32 v23, 31, v22
	v_and_b32_e32 v0, -2, v22
	v_mov_b32_e32 v1, v23
	v_lshlrev_b64 v[0:1], 11, v[0:1]
	v_lshl_add_u64 v[26:27], s[52:53], 0, v[0:1]
	s_movk_i32 s8, 0xffe0
	v_mov_b64_e32 v[28:29], v[24:25]
	v_mov_b32_e32 v0, 0
	v_mov_b32_e32 v1, v21
	v_mov_b32_e32 v2, v21
	v_mov_b32_e32 v3, v21
	v_mov_b32_e32 v12, 0
	v_mov_b32_e32 v13, v21
	v_mov_b32_e32 v14, v21
	v_mov_b32_e32 v15, v21
	v_mov_b32_e32 v8, 0
	v_mov_b32_e32 v9, v21
	v_mov_b32_e32 v10, v21
	v_mov_b32_e32 v11, v21
	v_mov_b32_e32 v4, 0
	v_mov_b32_e32 v5, v21
	v_mov_b32_e32 v6, v21
	v_mov_b32_e32 v7, v21
.LBB0_893:
	v_lshl_add_u64 v[36:37], v[28:29], 0, v[20:21]
	s_mov_b32 s9, 0x12d0000
	v_add_co_u32_e32 v48, vcc, s9, v36
	s_mov_b32 s9, 0x12d8000
	s_nop 0
	v_addc_co_u32_e32 v49, vcc, 0, v37, vcc
	v_add_co_u32_e32 v50, vcc, s9, v36
	v_lshl_add_u64 v[52:53], v[26:27], 0, v[20:21]
	s_nop 0
	v_addc_co_u32_e32 v51, vcc, 0, v37, vcc
	s_mov_b32 s9, 0x8000
	v_add_co_u32_e32 v54, vcc, s9, v52
	global_load_dwordx4 v[40:43], v[52:53], off
	s_nop 0
	v_addc_co_u32_e32 v55, vcc, 0, v53, vcc
	global_load_dwordx4 v[44:47], v[54:55], off
	global_load_dwordx4 v[32:35], v[48:49], off
	global_load_dwordx4 v[36:39], v[50:51], off
	s_addk_i32 s8, 0x80
	v_lshl_add_u64 v[26:27], v[26:27], 0, s[0:1]
	v_lshl_add_u64 v[28:29], v[28:29], 0, s[0:1]
	s_cmpk_gt_u32 s8, 0x3df
	s_waitcnt vmcnt(0)
	v_mfma_f32_16x16x32_bf16 v[12:15], v[40:43], v[32:35], v[12:15]
	v_mfma_f32_16x16x32_bf16 v[8:11], v[44:47], v[32:35], v[8:11]
	v_mfma_f32_16x16x32_bf16 v[4:7], v[40:43], v[36:39], v[4:7]
	v_mfma_f32_16x16x32_bf16 v[0:3], v[44:47], v[36:39], v[0:3]
	global_load_dwordx4 v[32:35], v[48:49], off offset:128
	global_load_dwordx4 v[36:39], v[50:51], off offset:128
	global_load_dwordx4 v[40:43], v[52:53], off offset:128
	global_load_dwordx4 v[44:47], v[54:55], off offset:128
	s_waitcnt vmcnt(1)
	v_mfma_f32_16x16x32_bf16 v[12:15], v[40:43], v[32:35], v[12:15]
	s_waitcnt vmcnt(0)
	v_mfma_f32_16x16x32_bf16 v[8:11], v[44:47], v[32:35], v[8:11]
	v_mfma_f32_16x16x32_bf16 v[4:7], v[40:43], v[36:39], v[4:7]
	v_mfma_f32_16x16x32_bf16 v[0:3], v[44:47], v[36:39], v[0:3]
	global_load_dwordx4 v[32:35], v[48:49], off offset:256
	global_load_dwordx4 v[36:39], v[50:51], off offset:256
	global_load_dwordx4 v[40:43], v[52:53], off offset:256
	global_load_dwordx4 v[44:47], v[54:55], off offset:256
	s_waitcnt vmcnt(1)
	v_mfma_f32_16x16x32_bf16 v[12:15], v[40:43], v[32:35], v[12:15]
	s_waitcnt vmcnt(0)
	v_mfma_f32_16x16x32_bf16 v[8:11], v[44:47], v[32:35], v[8:11]
	v_mfma_f32_16x16x32_bf16 v[4:7], v[40:43], v[36:39], v[4:7]
	v_mfma_f32_16x16x32_bf16 v[0:3], v[44:47], v[36:39], v[0:3]
	global_load_dwordx4 v[32:35], v[48:49], off offset:384
	global_load_dwordx4 v[36:39], v[50:51], off offset:384
	global_load_dwordx4 v[40:43], v[52:53], off offset:384
	global_load_dwordx4 v[44:47], v[54:55], off offset:384
	s_waitcnt vmcnt(1)
	v_mfma_f32_16x16x32_bf16 v[12:15], v[40:43], v[32:35], v[12:15]
	s_waitcnt vmcnt(0)
	v_mfma_f32_16x16x32_bf16 v[8:11], v[44:47], v[32:35], v[8:11]
	v_mfma_f32_16x16x32_bf16 v[4:7], v[40:43], v[36:39], v[4:7]
	v_mfma_f32_16x16x32_bf16 v[0:3], v[44:47], v[36:39], v[0:3]
	s_cbranch_scc0 .LBB0_893
	v_lshl_or_b32 v26, s7, 5, v30
	v_ashrrev_i32_e32 v27, 31, v26
	v_lshl_add_u64 v[28:29], v[26:27], 1, s[94:95]
	v_mov_b32_e32 v27, v21
	v_lshl_add_u64 v[32:33], v[26:27], 1, s[40:41]
	v_and_b32_sdwa v23, v14, v31 dst_sel:DWORD dst_unused:UNUSED_PAD src0_sel:WORD_1 src1_sel:DWORD
	v_and_b32_sdwa v27, v12, v31 dst_sel:DWORD dst_unused:UNUSED_PAD src0_sel:WORD_1 src1_sel:DWORD
	v_add3_u32 v12, v12, v27, s6
	v_add3_u32 v14, v14, v23, s6
	v_and_b32_sdwa v23, v15, v31 dst_sel:DWORD dst_unused:UNUSED_PAD src0_sel:WORD_1 src1_sel:DWORD
	v_and_b32_sdwa v27, v13, v31 dst_sel:DWORD dst_unused:UNUSED_PAD src0_sel:WORD_1 src1_sel:DWORD
	v_lshl_add_u64 v[32:33], v[32:33], 0, s[2:3]
	v_cmp_gt_i32_e32 vcc, s5, v26
	v_add3_u32 v15, v15, v23, s6
	v_add3_u32 v13, v13, v27, s6
	v_cndmask_b32_e32 v29, v33, v29, vcc
	v_cndmask_b32_e32 v28, v32, v28, vcc
	v_and_b32_e32 v15, 0xffff0000, v15
	v_and_b32_e32 v23, 0xffff0000, v13
	v_lshl_add_u64 v[32:33], v[28:29], 0, v[16:17]
	v_or_b32_sdwa v13, v15, v14 dst_sel:DWORD dst_unused:UNUSED_PAD src0_sel:DWORD src1_sel:WORD_1
	v_or_b32_sdwa v12, v23, v12 dst_sel:DWORD dst_unused:UNUSED_PAD src0_sel:DWORD src1_sel:WORD_1
	global_store_dwordx2 v[32:33], v[12:13], off
	v_or_b32_e32 v12, 16, v26
	v_ashrrev_i32_e32 v13, 31, v12
	v_lshl_add_u64 v[14:15], v[12:13], 1, s[94:95]
	v_mov_b32_e32 v13, v21
	v_lshl_add_u64 v[26:27], v[12:13], 1, s[40:41]
	v_lshl_add_u64 v[26:27], v[26:27], 0, s[2:3]
	v_cmp_gt_i32_e32 vcc, s5, v12
	v_and_b32_sdwa v23, v10, v31 dst_sel:DWORD dst_unused:UNUSED_PAD src0_sel:WORD_1 src1_sel:DWORD
	v_add3_u32 v10, v10, v23, s6
	v_cndmask_b32_e32 v12, v26, v14, vcc
	v_and_b32_sdwa v26, v8, v31 dst_sel:DWORD dst_unused:UNUSED_PAD src0_sel:WORD_1 src1_sel:DWORD
	v_and_b32_sdwa v23, v11, v31 dst_sel:DWORD dst_unused:UNUSED_PAD src0_sel:WORD_1 src1_sel:DWORD
	v_add3_u32 v8, v8, v26, s6
	v_and_b32_sdwa v26, v9, v31 dst_sel:DWORD dst_unused:UNUSED_PAD src0_sel:WORD_1 src1_sel:DWORD
	v_add3_u32 v11, v11, v23, s6
	v_add3_u32 v9, v9, v26, s6
	v_and_b32_e32 v11, 0xffff0000, v11
	v_and_b32_e32 v23, 0xffff0000, v9
	v_or_b32_sdwa v9, v11, v10 dst_sel:DWORD dst_unused:UNUSED_PAD src0_sel:DWORD src1_sel:WORD_1
	v_and_b32_sdwa v10, v6, v31 dst_sel:DWORD dst_unused:UNUSED_PAD src0_sel:WORD_1 src1_sel:DWORD
	v_and_b32_sdwa v11, v4, v31 dst_sel:DWORD dst_unused:UNUSED_PAD src0_sel:WORD_1 src1_sel:DWORD
	v_add3_u32 v6, v6, v10, s6
	v_and_b32_sdwa v10, v7, v31 dst_sel:DWORD dst_unused:UNUSED_PAD src0_sel:WORD_1 src1_sel:DWORD
	v_add3_u32 v4, v4, v11, s6
	v_and_b32_sdwa v11, v5, v31 dst_sel:DWORD dst_unused:UNUSED_PAD src0_sel:WORD_1 src1_sel:DWORD
	v_add3_u32 v7, v7, v10, s6
	v_add3_u32 v5, v5, v11, s6
	v_and_b32_e32 v7, 0xffff0000, v7
	v_and_b32_e32 v10, 0xffff0000, v5
	v_or_b32_sdwa v5, v7, v6 dst_sel:DWORD dst_unused:UNUSED_PAD src0_sel:DWORD src1_sel:WORD_1
	v_and_b32_sdwa v6, v2, v31 dst_sel:DWORD dst_unused:UNUSED_PAD src0_sel:WORD_1 src1_sel:DWORD
	v_and_b32_sdwa v7, v0, v31 dst_sel:DWORD dst_unused:UNUSED_PAD src0_sel:WORD_1 src1_sel:DWORD
	v_cndmask_b32_e32 v13, v27, v15, vcc
	v_add3_u32 v0, v0, v7, s6
	v_add3_u32 v2, v2, v6, s6
	v_and_b32_sdwa v6, v3, v31 dst_sel:DWORD dst_unused:UNUSED_PAD src0_sel:WORD_1 src1_sel:DWORD
	v_and_b32_sdwa v7, v1, v31 dst_sel:DWORD dst_unused:UNUSED_PAD src0_sel:WORD_1 src1_sel:DWORD
	v_lshl_add_u64 v[14:15], v[12:13], 0, v[16:17]
	v_or_b32_sdwa v8, v23, v8 dst_sel:DWORD dst_unused:UNUSED_PAD src0_sel:DWORD src1_sel:WORD_1
	v_add3_u32 v3, v3, v6, s6
	v_add3_u32 v1, v1, v7, s6
	global_store_dwordx2 v[14:15], v[8:9], off
	v_lshl_add_u64 v[8:9], v[28:29], 0, v[18:19]
	v_or_b32_sdwa v4, v10, v4 dst_sel:DWORD dst_unused:UNUSED_PAD src0_sel:DWORD src1_sel:WORD_1
	v_and_b32_e32 v3, 0xffff0000, v3
	v_and_b32_e32 v6, 0xffff0000, v1
	s_add_i32 s7, s7, s86
	global_store_dwordx2 v[8:9], v[4:5], off
	v_lshl_add_u64 v[4:5], v[12:13], 0, v[18:19]
	v_or_b32_sdwa v1, v3, v2 dst_sel:DWORD dst_unused:UNUSED_PAD src0_sel:DWORD src1_sel:WORD_1
	v_or_b32_sdwa v0, v6, v0 dst_sel:DWORD dst_unused:UNUSED_PAD src0_sel:DWORD src1_sel:WORD_1
	s_cmpk_gt_i32 s7, 0x57
	v_add_u32_e32 v22, s4, v22
	global_store_dwordx2 v[4:5], v[0:1], off
	s_cbranch_scc0 .LBB0_892

.LBB0_1034:
	v_readlane_b32 s0, v254, 56
	v_mov_b32_e32 v0, v190
	s_cmpk_gt_i32 s0, 0x50f
	s_cbranch_scc1 .LBB0_1069
	v_and_b32_e32 v20, 63, v0
	v_ashrrev_i32_e32 v21, 6, v0
	v_ashrrev_i32_e32 v22, 3, v0
	v_lshlrev_b32_e32 v0, 3, v0
	v_and_b32_e32 v3, 56, v0
	v_bfe_u32 v0, v190, 2, 1
	v_lshlrev_b32_e32 v0, 7, v0
	v_bfe_u32 v200, v190, 3, 1
	v_lshl_or_b32 v0, v200, 6, v0
	v_and_b32_e32 v200, 3, v190
	v_lshl_or_b32 v0, v200, 4, v0
	v_mov_b32_e32 v1, 0
	v_lshl_add_u64 v[16:17], s[52:53], 0, v[0:1]
	v_lshlrev_b32_e32 v0, 2, v22
	s_movk_i32 s0, 0x104
	v_lshlrev_b32_e32 v2, 2, v20
	v_mad_u32_u24 v23, v3, s0, v0
	v_mul_lo_u32 v0, v21, s0
	v_readlane_b32 s9, v254, 56
	s_lshl_b32 s4, s9, 6
	s_lshl_b32 s5, s86, 6
	s_mov_b32 s6, 0
	s_movk_i32 s7, 0x5080
	v_add_u32_e32 v24, v2, v0
	s_movk_i32 s8, 0x7fff
	v_mov_b32_e32 v25, 1
	s_branch .LBB0_1037
.LBB0_1036:
	s_or_b64 exec, exec, s[2:3]
	s_barrier
	s_waitcnt vmcnt(0)
	ds_write_b32 v24, v0
	ds_write_b32 v24, v1 offset:1040
	ds_write_b32 v24, v2 offset:2080
	ds_write_b32 v24, v3 offset:3120
	ds_write_b32 v24, v4 offset:4160
	ds_write_b32 v24, v5 offset:5200
	ds_write_b32 v24, v6 offset:6240
	ds_write_b32 v24, v7 offset:7280
	ds_write_b32 v24, v8 offset:8320
	ds_write_b32 v24, v9 offset:9360
	ds_write_b32 v24, v10 offset:10400
	ds_write_b32 v24, v11 offset:11440
	ds_write_b32 v24, v12 offset:12480
	ds_write_b32 v24, v13 offset:13520
	ds_write_b32 v24, v14 offset:14560
	ds_write_b32 v24, v15 offset:15600
	s_waitcnt lgkmcnt(0)
	s_barrier
	ds_read2_b32 v[6:7], v23 offset1:32
	ds_read2_b32 v[8:9], v23 offset0:65 offset1:97
	ds_read2_b32 v[10:11], v23 offset0:130 offset1:162
	ds_read2_b32 v[12:13], v23 offset0:195 offset1:227
	v_add_u32_e32 v30, s10, v22
	v_and_b32_e32 v30, -2, v30
	s_ashr_i32 s1, s0, 31
	v_add_u32_e32 v0, 0x400, v23
	v_ashrrev_i32_e32 v31, 31, v30
	v_lshl_add_u64 v[4:5], s[0:1], 2, v[16:17]
	ds_read2_b32 v[14:15], v0 offset0:4 offset1:36
	ds_read2_b32 v[18:19], v0 offset0:69 offset1:101
	ds_read2_b32 v[26:27], v0 offset0:134 offset1:166
	ds_read2_b32 v[28:29], v0 offset0:199 offset1:231
	v_lshlrev_b64 v[0:1], 11, v[30:31]
	v_lshl_add_u64 v[32:33], v[4:5], 0, v[0:1]
	s_waitcnt lgkmcnt(7)
	v_and_b32_sdwa v1, v6, v25 dst_sel:DWORD dst_unused:UNUSED_PAD src0_sel:WORD_1 src1_sel:DWORD
	v_add3_u32 v2, v6, v1, s8
	s_waitcnt lgkmcnt(4)
	v_and_b32_sdwa v1, v12, v25 dst_sel:DWORD dst_unused:UNUSED_PAD src0_sel:WORD_1 src1_sel:DWORD
	v_and_b32_sdwa v3, v8, v25 dst_sel:DWORD dst_unused:UNUSED_PAD src0_sel:WORD_1 src1_sel:DWORD
	v_and_b32_sdwa v0, v10, v25 dst_sel:DWORD dst_unused:UNUSED_PAD src0_sel:WORD_1 src1_sel:DWORD
	v_add3_u32 v1, v12, v1, s8
	v_add3_u32 v3, v8, v3, s8
	v_add3_u32 v0, v10, v0, s8
	v_and_b32_e32 v1, 0xffff0000, v1
	v_and_b32_e32 v3, 0xffff0000, v3
	v_or_b32_sdwa v1, v1, v0 dst_sel:DWORD dst_unused:UNUSED_PAD src0_sel:DWORD src1_sel:WORD_1
	v_or_b32_sdwa v0, v3, v2 dst_sel:DWORD dst_unused:UNUSED_PAD src0_sel:DWORD src1_sel:WORD_1
	s_waitcnt lgkmcnt(3)
	v_and_b32_sdwa v3, v14, v25 dst_sel:DWORD dst_unused:UNUSED_PAD src0_sel:WORD_1 src1_sel:DWORD
	v_add3_u32 v6, v14, v3, s8
	s_waitcnt lgkmcnt(0)
	v_and_b32_sdwa v3, v28, v25 dst_sel:DWORD dst_unused:UNUSED_PAD src0_sel:WORD_1 src1_sel:DWORD
	v_and_b32_sdwa v8, v18, v25 dst_sel:DWORD dst_unused:UNUSED_PAD src0_sel:WORD_1 src1_sel:DWORD
	v_and_b32_sdwa v2, v26, v25 dst_sel:DWORD dst_unused:UNUSED_PAD src0_sel:WORD_1 src1_sel:DWORD
	v_add3_u32 v3, v28, v3, s8
	v_add3_u32 v8, v18, v8, s8
	v_add3_u32 v2, v26, v2, s8
	v_and_b32_e32 v3, 0xffff0000, v3
	v_and_b32_e32 v8, 0xffff0000, v8
	v_or_b32_sdwa v3, v3, v2 dst_sel:DWORD dst_unused:UNUSED_PAD src0_sel:DWORD src1_sel:WORD_1
	v_or_b32_sdwa v2, v8, v6 dst_sel:DWORD dst_unused:UNUSED_PAD src0_sel:DWORD src1_sel:WORD_1
	global_store_dwordx4 v[32:33], v[0:3], off
	s_add_i32 s9, s9, s86
	s_add_i32 s4, s4, s5
	v_add_u32_e32 v0, 32, v30
	v_ashrrev_i32_e32 v1, 31, v0
	v_lshlrev_b64 v[0:1], 11, v[0:1]
	v_lshl_add_u64 v[4:5], v[4:5], 0, v[0:1]
	v_and_b32_sdwa v1, v7, v25 dst_sel:DWORD dst_unused:UNUSED_PAD src0_sel:WORD_1 src1_sel:DWORD
	v_add3_u32 v2, v7, v1, s8
	v_and_b32_sdwa v1, v13, v25 dst_sel:DWORD dst_unused:UNUSED_PAD src0_sel:WORD_1 src1_sel:DWORD
	v_and_b32_sdwa v3, v9, v25 dst_sel:DWORD dst_unused:UNUSED_PAD src0_sel:WORD_1 src1_sel:DWORD
	v_and_b32_sdwa v0, v11, v25 dst_sel:DWORD dst_unused:UNUSED_PAD src0_sel:WORD_1 src1_sel:DWORD
	v_add3_u32 v1, v13, v1, s8
	v_add3_u32 v3, v9, v3, s8
	v_add3_u32 v0, v11, v0, s8
	v_and_b32_e32 v1, 0xffff0000, v1
	v_and_b32_e32 v3, 0xffff0000, v3
	v_or_b32_sdwa v1, v1, v0 dst_sel:DWORD dst_unused:UNUSED_PAD src0_sel:DWORD src1_sel:WORD_1
	v_or_b32_sdwa v0, v3, v2 dst_sel:DWORD dst_unused:UNUSED_PAD src0_sel:DWORD src1_sel:WORD_1
	v_and_b32_sdwa v3, v15, v25 dst_sel:DWORD dst_unused:UNUSED_PAD src0_sel:WORD_1 src1_sel:DWORD
	v_add3_u32 v6, v15, v3, s8
	v_and_b32_sdwa v3, v29, v25 dst_sel:DWORD dst_unused:UNUSED_PAD src0_sel:WORD_1 src1_sel:DWORD
	v_and_b32_sdwa v7, v19, v25 dst_sel:DWORD dst_unused:UNUSED_PAD src0_sel:WORD_1 src1_sel:DWORD
	v_and_b32_sdwa v2, v27, v25 dst_sel:DWORD dst_unused:UNUSED_PAD src0_sel:WORD_1 src1_sel:DWORD
	v_add3_u32 v3, v29, v3, s8
	v_add3_u32 v7, v19, v7, s8
	v_add3_u32 v2, v27, v2, s8
	v_and_b32_e32 v3, 0xffff0000, v3
	v_and_b32_e32 v7, 0xffff0000, v7
	v_or_b32_sdwa v3, v3, v2 dst_sel:DWORD dst_unused:UNUSED_PAD src0_sel:DWORD src1_sel:WORD_1
	v_or_b32_sdwa v2, v7, v6 dst_sel:DWORD dst_unused:UNUSED_PAD src0_sel:DWORD src1_sel:WORD_1
	s_cmpk_lt_i32 s9, 0x510
	global_store_dwordx4 v[4:5], v[0:3], off
	s_cbranch_scc0 .LBB0_1069

.LBB0_1259:
	s_add_i32 s16, s15, 2
	s_mul_hi_i32 s17, s16, 0x55555556
	s_lshr_b32 s18, s17, 31
	s_add_i32 s17, s17, s18
	s_mul_i32 s17, s17, 3
	s_sub_i32 s16, s16, s17
	s_mulk_i32 s16, 0x6000
	s_mul_i32 s54, s15, 0x6000
	v_readfirstlane_b32 s55, v144
	v_lshl_add_u64 v[232:233], v[136:137], 0, s[4:5]
	v_lshl_add_u64 v[234:235], v[134:135], 0, s[4:5]
	s_add_u32 s55, s55, s16
	s_waitcnt vmcnt(6) lgkmcnt(0)
	s_barrier
	v_or_b32_e32 v130, s54, v142
	v_add3_u32 v130, v130, v143, v141
	ds_read_b128 v[178:181], v130 offset:16384
	ds_read_b128 v[182:185], v130 offset:16640
	ds_read_b128 v[186:189], v130 offset:18432
	ds_read_b128 v[192:195], v130 offset:18688
	v_add3_u32 v130, s54, v145, v141
	ds_read_b128 v[146:149], v130
	ds_read_b128 v[150:153], v130 offset:1024
	ds_read_b128 v[154:157], v130 offset:2048
	ds_read_b128 v[158:161], v130 offset:3072
	ds_read_b128 v[162:165], v130 offset:4096
	ds_read_b128 v[166:169], v130 offset:5120
	ds_read_b128 v[170:173], v130 offset:6144
	ds_read_b128 v[174:177], v130 offset:7168
	s_setprio 1
	s_waitcnt lgkmcnt(7)
	v_mfma_f32_16x16x32_bf16 v[124:127], v[178:181], v[146:149], v[124:127]
	v_mfma_f32_16x16x32_bf16 v[120:123], v[182:185], v[146:149], v[120:123]
	v_mfma_f32_16x16x32_bf16 v[116:119], v[186:189], v[146:149], v[116:119]
	v_mfma_f32_16x16x32_bf16 v[112:115], v[192:195], v[146:149], v[112:115]
	s_mov_b32 m0, s55
	s_mov_b64 s[16:17], 0x8bc0080
	v_lshl_add_u64 v[236:237], v[232:233], 0, s[16:17]
	global_load_lds_dwordx4 v[236:237], off
	s_waitcnt lgkmcnt(6)
	v_mfma_f32_16x16x32_bf16 v[108:111], v[178:181], v[150:153], v[108:111]
	v_mfma_f32_16x16x32_bf16 v[104:107], v[182:185], v[150:153], v[104:107]
	v_mfma_f32_16x16x32_bf16 v[100:103], v[186:189], v[150:153], v[100:103]
	v_mfma_f32_16x16x32_bf16 v[96:99], v[192:195], v[150:153], v[96:99]
	s_add_u32 m0, s55, 0x1000
	s_mov_b64 s[16:17], 0x8bec080
	v_lshl_add_u64 v[236:237], v[232:233], 0, s[16:17]
	global_load_lds_dwordx4 v[236:237], off
	s_waitcnt lgkmcnt(5)
	v_mfma_f32_16x16x32_bf16 v[92:95], v[178:181], v[154:157], v[92:95]
	v_mfma_f32_16x16x32_bf16 v[88:91], v[182:185], v[154:157], v[88:91]
	v_mfma_f32_16x16x32_bf16 v[84:87], v[186:189], v[154:157], v[84:87]
	v_mfma_f32_16x16x32_bf16 v[80:83], v[192:195], v[154:157], v[80:83]
	s_add_u32 m0, s55, 0x2000
	s_mov_b64 s[16:17], 0x8c18080
	v_lshl_add_u64 v[236:237], v[232:233], 0, s[16:17]
	global_load_lds_dwordx4 v[236:237], off
	s_waitcnt lgkmcnt(4)
	v_mfma_f32_16x16x32_bf16 v[76:79], v[178:181], v[158:161], v[76:79]
	v_mfma_f32_16x16x32_bf16 v[72:75], v[182:185], v[158:161], v[72:75]
	v_mfma_f32_16x16x32_bf16 v[68:71], v[186:189], v[158:161], v[68:71]
	v_mfma_f32_16x16x32_bf16 v[64:67], v[192:195], v[158:161], v[64:67]
	s_add_u32 m0, s55, 0x3000
	s_mov_b64 s[16:17], 0x8c44080
	v_lshl_add_u64 v[236:237], v[232:233], 0, s[16:17]
	global_load_lds_dwordx4 v[236:237], off
	s_waitcnt lgkmcnt(3)
	v_mfma_f32_16x16x32_bf16 v[60:63], v[178:181], v[162:165], v[60:63]
	v_mfma_f32_16x16x32_bf16 v[56:59], v[182:185], v[162:165], v[56:59]
	v_mfma_f32_16x16x32_bf16 v[52:55], v[186:189], v[162:165], v[52:55]
	v_mfma_f32_16x16x32_bf16 v[48:51], v[192:195], v[162:165], v[48:51]
	s_add_u32 m0, s55, 0x4000
	s_mov_b64 s[16:17], 0xe40080
	v_lshl_add_u64 v[236:237], v[234:235], 0, s[16:17]
	global_load_lds_dwordx4 v[236:237], off
	s_waitcnt lgkmcnt(2)
	v_mfma_f32_16x16x32_bf16 v[44:47], v[178:181], v[166:169], v[44:47]
	v_mfma_f32_16x16x32_bf16 v[40:43], v[182:185], v[166:169], v[40:43]
	v_mfma_f32_16x16x32_bf16 v[36:39], v[186:189], v[166:169], v[36:39]
	v_mfma_f32_16x16x32_bf16 v[32:35], v[192:195], v[166:169], v[32:35]
	s_add_u32 m0, s55, 0x5000
	s_mov_b64 s[16:17], 0xe6c080
	v_lshl_add_u64 v[236:237], v[234:235], 0, s[16:17]
	global_load_lds_dwordx4 v[236:237], off
	s_waitcnt lgkmcnt(1)
	v_mfma_f32_16x16x32_bf16 v[28:31], v[178:181], v[170:173], v[28:31]
	v_mfma_f32_16x16x32_bf16 v[24:27], v[182:185], v[170:173], v[24:27]
	v_mfma_f32_16x16x32_bf16 v[20:23], v[186:189], v[170:173], v[20:23]
	v_mfma_f32_16x16x32_bf16 v[16:19], v[192:195], v[170:173], v[16:19]
	s_waitcnt lgkmcnt(0)
	v_mfma_f32_16x16x32_bf16 v[12:15], v[178:181], v[174:177], v[12:15]
	v_mfma_f32_16x16x32_bf16 v[8:11], v[182:185], v[174:177], v[8:11]
	v_mfma_f32_16x16x32_bf16 v[4:7], v[186:189], v[174:177], v[4:7]
	v_mfma_f32_16x16x32_bf16 v[0:3], v[192:195], v[174:177], v[0:3]
	s_setprio 0
	s_add_i32 s16, s15, 1
	s_cmp_lg_u32 s15, 2
	s_cselect_b32 s15, s16, 0
	s_add_u32 s4, s4, 64
	s_addc_u32 s5, s5, 0
	s_cmpk_eq_i32 s4, 0xa80
	s_cbranch_scc0 .LBB0_1259
	s_waitcnt vmcnt(6) lgkmcnt(0)
	s_barrier
	v_add_u32_e32 v130, v145, v141
	ds_read_b128 v[134:137], v130
	ds_read_b128 v[144:147], v130 offset:1024
	ds_read_b128 v[148:151], v130 offset:2048
	ds_read_b128 v[152:155], v130 offset:3072
	ds_read_b128 v[156:159], v130 offset:4096
	ds_read_b128 v[160:163], v130 offset:5120
	ds_read_b128 v[164:167], v130 offset:6144
	ds_read_b128 v[168:171], v130 offset:7168
	v_add3_u32 v141, v142, v143, v141
	ds_read_b128 v[172:175], v141 offset:16384
	ds_read_b128 v[176:179], v141 offset:16640
	ds_read_b128 v[180:183], v141 offset:18432
	ds_read_b128 v[184:187], v141 offset:18688
	s_setprio 1
	s_waitcnt lgkmcnt(0)
	v_mfma_f32_16x16x32_bf16 v[124:127], v[172:175], v[134:137], v[124:127]
	v_mfma_f32_16x16x32_bf16 v[120:123], v[176:179], v[134:137], v[120:123]
	v_mfma_f32_16x16x32_bf16 v[116:119], v[180:183], v[134:137], v[116:119]
	v_mfma_f32_16x16x32_bf16 v[112:115], v[184:187], v[134:137], v[112:115]
	v_mfma_f32_16x16x32_bf16 v[108:111], v[172:175], v[144:147], v[108:111]
	v_mfma_f32_16x16x32_bf16 v[104:107], v[176:179], v[144:147], v[104:107]
	v_mfma_f32_16x16x32_bf16 v[100:103], v[180:183], v[144:147], v[100:103]
	v_mfma_f32_16x16x32_bf16 v[96:99], v[184:187], v[144:147], v[96:99]
	v_mfma_f32_16x16x32_bf16 v[92:95], v[172:175], v[148:151], v[92:95]
	v_mfma_f32_16x16x32_bf16 v[88:91], v[176:179], v[148:151], v[88:91]
	v_mfma_f32_16x16x32_bf16 v[84:87], v[180:183], v[148:151], v[84:87]
	v_mfma_f32_16x16x32_bf16 v[80:83], v[184:187], v[148:151], v[80:83]
	v_mfma_f32_16x16x32_bf16 v[76:79], v[172:175], v[152:155], v[76:79]
	v_mfma_f32_16x16x32_bf16 v[72:75], v[176:179], v[152:155], v[72:75]
	v_mfma_f32_16x16x32_bf16 v[68:71], v[180:183], v[152:155], v[68:71]
	v_mfma_f32_16x16x32_bf16 v[64:67], v[184:187], v[152:155], v[64:67]
	v_mfma_f32_16x16x32_bf16 v[60:63], v[172:175], v[156:159], v[60:63]
	v_mfma_f32_16x16x32_bf16 v[56:59], v[176:179], v[156:159], v[56:59]
	v_mfma_f32_16x16x32_bf16 v[52:55], v[180:183], v[156:159], v[52:55]
	v_mfma_f32_16x16x32_bf16 v[48:51], v[184:187], v[156:159], v[48:51]
	v_mfma_f32_16x16x32_bf16 v[44:47], v[172:175], v[160:163], v[44:47]
	v_mfma_f32_16x16x32_bf16 v[40:43], v[176:179], v[160:163], v[40:43]
	v_mfma_f32_16x16x32_bf16 v[36:39], v[180:183], v[160:163], v[36:39]
	v_mfma_f32_16x16x32_bf16 v[32:35], v[184:187], v[160:163], v[32:35]
	v_mfma_f32_16x16x32_bf16 v[28:31], v[172:175], v[164:167], v[28:31]
	v_mfma_f32_16x16x32_bf16 v[24:27], v[176:179], v[164:167], v[24:27]
	v_mfma_f32_16x16x32_bf16 v[20:23], v[180:183], v[164:167], v[20:23]
	v_mfma_f32_16x16x32_bf16 v[16:19], v[184:187], v[164:167], v[16:19]
	v_mfma_f32_16x16x32_bf16 v[12:15], v[172:175], v[168:171], v[12:15]
	v_mfma_f32_16x16x32_bf16 v[8:11], v[176:179], v[168:171], v[8:11]
	v_mfma_f32_16x16x32_bf16 v[4:7], v[180:183], v[168:171], v[4:7]
	v_mfma_f32_16x16x32_bf16 v[0:3], v[184:187], v[168:171], v[0:3]
	s_setprio 0
	s_waitcnt vmcnt(0) lgkmcnt(0)
	s_barrier
	ds_read_b128 v[134:137], v130 offset:24576
	ds_read_b128 v[142:145], v130 offset:25600
	ds_read_b128 v[146:149], v130 offset:26624
	ds_read_b128 v[150:153], v130 offset:27648
	ds_read_b128 v[154:157], v130 offset:28672
	ds_read_b128 v[158:161], v130 offset:29696
	ds_read_b128 v[162:165], v130 offset:30720
	ds_read_b128 v[166:169], v130 offset:31744
	ds_read_b128 v[170:173], v141 offset:40960
	ds_read_b128 v[174:177], v141 offset:41216
	ds_read_b128 v[178:181], v141 offset:43008
	ds_read_b128 v[182:185], v141 offset:43264
	s_setprio 1
	s_waitcnt lgkmcnt(0)
	v_mfma_f32_16x16x32_bf16 v[124:127], v[170:173], v[134:137], v[124:127]
	v_mfma_f32_16x16x32_bf16 v[120:123], v[174:177], v[134:137], v[120:123]
	v_mfma_f32_16x16x32_bf16 v[116:119], v[178:181], v[134:137], v[116:119]
	v_mfma_f32_16x16x32_bf16 v[112:115], v[182:185], v[134:137], v[112:115]
	v_mfma_f32_16x16x32_bf16 v[108:111], v[170:173], v[142:145], v[108:111]
	v_mfma_f32_16x16x32_bf16 v[104:107], v[174:177], v[142:145], v[104:107]
	v_mfma_f32_16x16x32_bf16 v[134:137], v[178:181], v[142:145], v[100:103]
	v_mfma_f32_16x16x32_bf16 v[96:99], v[182:185], v[142:145], v[96:99]
	v_mfma_f32_16x16x32_bf16 v[92:95], v[170:173], v[146:149], v[92:95]
	v_mfma_f32_16x16x32_bf16 v[88:91], v[174:177], v[146:149], v[88:91]
	v_mfma_f32_16x16x32_bf16 v[84:87], v[178:181], v[146:149], v[84:87]
	v_mfma_f32_16x16x32_bf16 v[80:83], v[182:185], v[146:149], v[80:83]
	v_mfma_f32_16x16x32_bf16 v[76:79], v[170:173], v[150:153], v[76:79]
	v_mfma_f32_16x16x32_bf16 v[72:75], v[174:177], v[150:153], v[72:75]
	v_mfma_f32_16x16x32_bf16 v[68:71], v[178:181], v[150:153], v[68:71]
	v_mfma_f32_16x16x32_bf16 v[64:67], v[182:185], v[150:153], v[64:67]
	v_mfma_f32_16x16x32_bf16 v[60:63], v[170:173], v[154:157], v[60:63]
	v_mfma_f32_16x16x32_bf16 v[56:59], v[174:177], v[154:157], v[56:59]
	v_mfma_f32_16x16x32_bf16 v[52:55], v[178:181], v[154:157], v[52:55]
	v_mfma_f32_16x16x32_bf16 v[48:51], v[182:185], v[154:157], v[48:51]
	v_mfma_f32_16x16x32_bf16 v[44:47], v[170:173], v[158:161], v[44:47]
	v_mfma_f32_16x16x32_bf16 v[40:43], v[174:177], v[158:161], v[40:43]
	v_mfma_f32_16x16x32_bf16 v[36:39], v[178:181], v[158:161], v[36:39]
	v_mfma_f32_16x16x32_bf16 v[32:35], v[182:185], v[158:161], v[32:35]
	v_mfma_f32_16x16x32_bf16 v[28:31], v[170:173], v[162:165], v[28:31]
	v_mfma_f32_16x16x32_bf16 v[24:27], v[174:177], v[162:165], v[24:27]
	v_mfma_f32_16x16x32_bf16 v[20:23], v[178:181], v[162:165], v[20:23]
	v_mfma_f32_16x16x32_bf16 v[16:19], v[182:185], v[162:165], v[16:19]
	v_mfma_f32_16x16x32_bf16 v[12:15], v[170:173], v[166:169], v[12:15]
	v_mfma_f32_16x16x32_bf16 v[8:11], v[174:177], v[166:169], v[8:11]
	v_mfma_f32_16x16x32_bf16 v[4:7], v[178:181], v[166:169], v[4:7]
	v_mfma_f32_16x16x32_bf16 v[0:3], v[182:185], v[166:169], v[0:3]
	s_setprio 0
	v_and_b32_e32 v100, 0xffffff80, v138
	v_lshrrev_b32_e32 v102, 1, v138
	v_add_u32_e32 v100, s13, v100
	v_lshlrev_b32_e32 v101, 6, v140
	v_and_b32_e32 v102, 24, v102
	v_or_b32_e32 v100, v100, v139
	v_or3_b32 v102, v101, v102, s14
	v_mov_b32_e32 v101, v131
	v_add_u32_e32 v130, 0xffffc000, v100
	v_readlane_b32 s4, v255, 39
	v_lshlrev_b64 v[142:143], 12, v[100:101]
	v_ashrrev_i32_e32 v101, 31, v100
	v_readlane_b32 s16, v254, 34
	v_lshlrev_b64 v[138:139], 12, v[130:131]
	v_readlane_b32 s5, v255, 40
	v_lshlrev_b64 v[144:145], 12, v[100:101]
	v_readlane_b32 s30, v254, 48
	v_readlane_b32 s31, v254, 49
	v_lshl_add_u64 v[138:139], s[4:5], 0, v[138:139]
	v_cmp_gt_i32_e32 vcc, s11, v100
	v_lshl_add_u64 v[140:141], s[30:31], 0, v[144:145]
	v_ashrrev_i32_e32 v103, 31, v102
	v_cndmask_b32_e32 v139, v139, v141, vcc
	v_cndmask_b32_e32 v138, v138, v140, vcc
	v_lshlrev_b64 v[102:103], 2, v[102:103]
	v_lshl_add_u64 v[146:147], v[138:139], 0, v[102:103]
	global_load_dwordx4 v[138:141], v[146:147], off
	v_cndmask_b32_e32 v143, v143, v145, vcc
	v_cndmask_b32_e32 v142, v142, v144, vcc
	v_lshl_add_u64 v[142:143], s[30:31], 0, v[142:143]
	v_lshl_add_u64 v[142:143], v[142:143], 0, v[102:103]
	v_add_u32_e32 v130, 0xffffc010, v100
	s_add_i32 s12, s12, s86
	s_add_i32 s6, s6, s7
	s_add_i32 s8, s8, s9
	s_cmpk_gt_i32 s12, 0x1ff
	v_readlane_b32 s17, v254, 35
	v_readlane_b32 s18, v254, 36
	v_readlane_b32 s19, v254, 37
	v_readlane_b32 s20, v254, 38
	v_readlane_b32 s21, v254, 39
	v_readlane_b32 s22, v254, 40
	v_readlane_b32 s23, v254, 41
	v_readlane_b32 s24, v254, 42
	v_readlane_b32 s25, v254, 43
	v_readlane_b32 s26, v254, 44
	v_readlane_b32 s27, v254, 45
	v_readlane_b32 s28, v254, 46
	v_readlane_b32 s29, v254, 47
	s_waitcnt vmcnt(0)
	v_pk_add_f32 v[124:125], v[124:125], v[138:139]
	v_pk_add_f32 v[126:127], v[126:127], v[140:141]
	global_store_dwordx4 v[142:143], v[124:127], off
	global_load_dwordx4 v[124:127], v[146:147], off offset:16
	s_waitcnt vmcnt(0)
	v_pk_add_f32 v[120:121], v[120:121], v[124:125]
	v_pk_add_f32 v[122:123], v[122:123], v[126:127]
	global_store_dwordx4 v[142:143], v[120:123], off offset:16
	global_load_dwordx4 v[120:123], v[146:147], off offset:128
	v_lshlrev_b64 v[124:125], 12, v[130:131]
	v_lshl_add_u64 v[124:125], s[4:5], 0, v[124:125]
	v_add_u32_e32 v130, 0xffffc020, v100
	s_waitcnt vmcnt(0)
	v_pk_add_f32 v[116:117], v[116:117], v[120:121]
	v_pk_add_f32 v[118:119], v[118:119], v[122:123]
	global_store_dwordx4 v[142:143], v[116:119], off offset:128
	global_load_dwordx4 v[116:119], v[146:147], off offset:144
	v_mov_b32_e32 v121, v131
	v_or_b32_e32 v120, 16, v100
	v_lshlrev_b64 v[122:123], 12, v[120:121]
	v_ashrrev_i32_e32 v121, 31, v120
	v_lshlrev_b64 v[126:127], 12, v[120:121]
	v_lshl_add_u64 v[138:139], s[30:31], 0, v[126:127]
	v_cmp_gt_i32_e32 vcc, s11, v120
	s_waitcnt vmcnt(0)
	v_pk_add_f32 v[112:113], v[112:113], v[116:117]
	v_cndmask_b32_e32 v125, v125, v139, vcc
	v_cndmask_b32_e32 v124, v124, v138, vcc
	v_pk_add_f32 v[114:115], v[114:115], v[118:119]
	v_lshl_add_u64 v[124:125], v[124:125], 0, v[102:103]
	global_store_dwordx4 v[142:143], v[112:115], off offset:144
	global_load_dwordx4 v[112:115], v[124:125], off
	v_cndmask_b32_e32 v121, v123, v127, vcc
	v_cndmask_b32_e32 v120, v122, v126, vcc
	v_lshl_add_u64 v[116:117], s[30:31], 0, v[120:121]
	v_lshl_add_u64 v[116:117], v[116:117], 0, v[102:103]
	s_waitcnt vmcnt(0)
	v_pk_add_f32 v[108:109], v[108:109], v[112:113]
	v_pk_add_f32 v[110:111], v[110:111], v[114:115]
	global_store_dwordx4 v[116:117], v[108:111], off
	global_load_dwordx4 v[108:111], v[124:125], off offset:16
	v_lshlrev_b64 v[114:115], 12, v[130:131]
	v_lshl_add_u64 v[114:115], s[4:5], 0, v[114:115]
	v_add_u32_e32 v130, 0xffffc030, v100
	s_waitcnt vmcnt(0)
	v_pk_add_f32 v[104:105], v[104:105], v[108:109]
	v_pk_add_f32 v[106:107], v[106:107], v[110:111]
	global_store_dwordx4 v[116:117], v[104:107], off offset:16
	global_load_dwordx4 v[104:107], v[124:125], off offset:128
	v_mov_b32_e32 v109, v131
	v_or_b32_e32 v108, 32, v100
	v_lshlrev_b64 v[110:111], 12, v[108:109]
	v_ashrrev_i32_e32 v109, 31, v108
	v_lshlrev_b64 v[112:113], 12, v[108:109]
	v_lshl_add_u64 v[118:119], s[30:31], 0, v[112:113]
	v_cmp_gt_i32_e32 vcc, s11, v108
	s_waitcnt vmcnt(0)
	v_pk_add_f32 v[104:105], v[134:135], v[104:105]
	v_pk_add_f32 v[106:107], v[136:137], v[106:107]
	global_store_dwordx4 v[116:117], v[104:107], off offset:128
	global_load_dwordx4 v[104:107], v[124:125], off offset:144
	v_cndmask_b32_e32 v115, v115, v119, vcc
	v_cndmask_b32_e32 v114, v114, v118, vcc
	v_lshl_add_u64 v[114:115], v[114:115], 0, v[102:103]
	v_cndmask_b32_e32 v109, v111, v113, vcc
	v_cndmask_b32_e32 v108, v110, v112, vcc
	s_waitcnt vmcnt(0)
	v_pk_add_f32 v[96:97], v[96:97], v[104:105]
	v_pk_add_f32 v[98:99], v[98:99], v[106:107]
	global_store_dwordx4 v[116:117], v[96:99], off offset:144
	global_load_dwordx4 v[96:99], v[114:115], off
	v_lshl_add_u64 v[104:105], s[30:31], 0, v[108:109]
	v_lshl_add_u64 v[104:105], v[104:105], 0, v[102:103]
	s_waitcnt vmcnt(0)
	v_pk_add_f32 v[92:93], v[92:93], v[96:97]
	v_pk_add_f32 v[94:95], v[94:95], v[98:99]
	global_store_dwordx4 v[104:105], v[92:95], off
	global_load_dwordx4 v[92:95], v[114:115], off offset:16
	v_lshlrev_b64 v[96:97], 12, v[130:131]
	v_lshl_add_u64 v[96:97], s[4:5], 0, v[96:97]
	v_add_u32_e32 v130, 0xffffc040, v100
	s_waitcnt vmcnt(0)
	v_pk_add_f32 v[88:89], v[88:89], v[92:93]
	v_pk_add_f32 v[90:91], v[90:91], v[94:95]
	global_store_dwordx4 v[104:105], v[88:91], off offset:16
	global_load_dwordx4 v[88:91], v[114:115], off offset:128
	s_waitcnt vmcnt(0)
	v_pk_add_f32 v[84:85], v[84:85], v[88:89]
	v_pk_add_f32 v[86:87], v[86:87], v[90:91]
	global_store_dwordx4 v[104:105], v[84:87], off offset:128
	global_load_dwordx4 v[84:87], v[114:115], off offset:144
	v_mov_b32_e32 v89, v131
	v_or_b32_e32 v88, 48, v100
	v_lshlrev_b64 v[90:91], 12, v[88:89]
	v_ashrrev_i32_e32 v89, 31, v88
	v_lshlrev_b64 v[92:93], 12, v[88:89]
	v_lshl_add_u64 v[94:95], s[30:31], 0, v[92:93]
	v_cmp_gt_i32_e32 vcc, s11, v88
	s_waitcnt vmcnt(0)
	v_pk_add_f32 v[80:81], v[80:81], v[84:85]
	v_cndmask_b32_e32 v95, v97, v95, vcc
	v_cndmask_b32_e32 v94, v96, v94, vcc
	v_pk_add_f32 v[82:83], v[82:83], v[86:87]
	v_lshl_add_u64 v[94:95], v[94:95], 0, v[102:103]
	global_store_dwordx4 v[104:105], v[80:83], off offset:144
	global_load_dwordx4 v[80:83], v[94:95], off
	v_cndmask_b32_e32 v89, v91, v93, vcc
	v_cndmask_b32_e32 v88, v90, v92, vcc
	v_lshl_add_u64 v[84:85], s[30:31], 0, v[88:89]
	v_lshl_add_u64 v[84:85], v[84:85], 0, v[102:103]
	s_waitcnt vmcnt(0)
	v_pk_add_f32 v[76:77], v[76:77], v[80:81]
	v_pk_add_f32 v[78:79], v[78:79], v[82:83]
	global_store_dwordx4 v[84:85], v[76:79], off
	global_load_dwordx4 v[76:79], v[94:95], off offset:16
	v_lshlrev_b64 v[80:81], 12, v[130:131]
	v_lshl_add_u64 v[80:81], s[4:5], 0, v[80:81]
	v_add_u32_e32 v130, 0xffffc050, v100
	s_waitcnt vmcnt(0)
	v_pk_add_f32 v[72:73], v[72:73], v[76:77]
	v_pk_add_f32 v[74:75], v[74:75], v[78:79]
	global_store_dwordx4 v[84:85], v[72:75], off offset:16
	global_load_dwordx4 v[72:75], v[94:95], off offset:128
	s_waitcnt vmcnt(0)
	v_pk_add_f32 v[68:69], v[68:69], v[72:73]
	v_pk_add_f32 v[70:71], v[70:71], v[74:75]
	global_store_dwordx4 v[84:85], v[68:71], off offset:128
	global_load_dwordx4 v[68:71], v[94:95], off offset:144
	v_mov_b32_e32 v73, v131
	v_or_b32_e32 v72, 64, v100
	v_lshlrev_b64 v[74:75], 12, v[72:73]
	v_ashrrev_i32_e32 v73, 31, v72
	v_lshlrev_b64 v[76:77], 12, v[72:73]
	v_lshl_add_u64 v[78:79], s[30:31], 0, v[76:77]
	v_cmp_gt_i32_e32 vcc, s11, v72
	s_waitcnt vmcnt(0)
	v_pk_add_f32 v[64:65], v[64:65], v[68:69]
	v_cndmask_b32_e32 v79, v81, v79, vcc
	v_cndmask_b32_e32 v78, v80, v78, vcc
	v_pk_add_f32 v[66:67], v[66:67], v[70:71]
	v_lshl_add_u64 v[78:79], v[78:79], 0, v[102:103]
	global_store_dwordx4 v[84:85], v[64:67], off offset:144
	global_load_dwordx4 v[64:67], v[78:79], off
	v_cndmask_b32_e32 v73, v75, v77, vcc
	v_cndmask_b32_e32 v72, v74, v76, vcc
	v_lshl_add_u64 v[68:69], s[30:31], 0, v[72:73]
	v_lshl_add_u64 v[68:69], v[68:69], 0, v[102:103]
	s_waitcnt vmcnt(0)
	v_pk_add_f32 v[60:61], v[60:61], v[64:65]
	v_pk_add_f32 v[62:63], v[62:63], v[66:67]
	global_store_dwordx4 v[68:69], v[60:63], off
	global_load_dwordx4 v[60:63], v[78:79], off offset:16
	v_lshlrev_b64 v[64:65], 12, v[130:131]
	v_lshl_add_u64 v[64:65], s[4:5], 0, v[64:65]
	v_add_u32_e32 v130, 0xffffc060, v100
	s_waitcnt vmcnt(0)
	v_pk_add_f32 v[56:57], v[56:57], v[60:61]
	v_pk_add_f32 v[58:59], v[58:59], v[62:63]
	global_store_dwordx4 v[68:69], v[56:59], off offset:16
	global_load_dwordx4 v[56:59], v[78:79], off offset:128
	s_waitcnt vmcnt(0)
	v_pk_add_f32 v[52:53], v[52:53], v[56:57]
	v_pk_add_f32 v[54:55], v[54:55], v[58:59]
	global_store_dwordx4 v[68:69], v[52:55], off offset:128
	global_load_dwordx4 v[52:55], v[78:79], off offset:144
	v_mov_b32_e32 v57, v131
	v_or_b32_e32 v56, 0x50, v100
	v_lshlrev_b64 v[58:59], 12, v[56:57]
	v_ashrrev_i32_e32 v57, 31, v56
	v_lshlrev_b64 v[60:61], 12, v[56:57]
	v_lshl_add_u64 v[62:63], s[30:31], 0, v[60:61]
	v_cmp_gt_i32_e32 vcc, s11, v56
	s_waitcnt vmcnt(0)
	v_pk_add_f32 v[48:49], v[48:49], v[52:53]
	v_cndmask_b32_e32 v63, v65, v63, vcc
	v_cndmask_b32_e32 v62, v64, v62, vcc
	v_pk_add_f32 v[50:51], v[50:51], v[54:55]
	v_lshl_add_u64 v[62:63], v[62:63], 0, v[102:103]
	global_store_dwordx4 v[68:69], v[48:51], off offset:144
	global_load_dwordx4 v[48:51], v[62:63], off
	v_cndmask_b32_e32 v57, v59, v61, vcc
	v_cndmask_b32_e32 v56, v58, v60, vcc
	v_lshl_add_u64 v[52:53], s[30:31], 0, v[56:57]
	v_lshl_add_u64 v[52:53], v[52:53], 0, v[102:103]
	s_waitcnt vmcnt(0)
	v_pk_add_f32 v[44:45], v[44:45], v[48:49]
	v_pk_add_f32 v[46:47], v[46:47], v[50:51]
	global_store_dwordx4 v[52:53], v[44:47], off
	global_load_dwordx4 v[44:47], v[62:63], off offset:16
	v_lshlrev_b64 v[48:49], 12, v[130:131]
	v_lshl_add_u64 v[48:49], s[4:5], 0, v[48:49]
	v_add_u32_e32 v130, 0xffffc070, v100
	s_waitcnt vmcnt(0)
	v_pk_add_f32 v[40:41], v[40:41], v[44:45]
	v_pk_add_f32 v[42:43], v[42:43], v[46:47]
	global_store_dwordx4 v[52:53], v[40:43], off offset:16
	global_load_dwordx4 v[40:43], v[62:63], off offset:128
	s_waitcnt vmcnt(0)
	v_pk_add_f32 v[36:37], v[36:37], v[40:41]
	v_pk_add_f32 v[38:39], v[38:39], v[42:43]
	global_store_dwordx4 v[52:53], v[36:39], off offset:128
	global_load_dwordx4 v[36:39], v[62:63], off offset:144
	v_mov_b32_e32 v41, v131
	v_or_b32_e32 v40, 0x60, v100
	v_lshlrev_b64 v[42:43], 12, v[40:41]
	v_ashrrev_i32_e32 v41, 31, v40
	v_lshlrev_b64 v[44:45], 12, v[40:41]
	v_lshl_add_u64 v[46:47], s[30:31], 0, v[44:45]
	v_cmp_gt_i32_e32 vcc, s11, v40
	s_waitcnt vmcnt(0)
	v_pk_add_f32 v[32:33], v[32:33], v[36:37]
	v_cndmask_b32_e32 v47, v49, v47, vcc
	v_cndmask_b32_e32 v46, v48, v46, vcc
	v_pk_add_f32 v[34:35], v[34:35], v[38:39]
	v_lshl_add_u64 v[46:47], v[46:47], 0, v[102:103]
	global_store_dwordx4 v[52:53], v[32:35], off offset:144
	global_load_dwordx4 v[32:35], v[46:47], off
	v_cndmask_b32_e32 v41, v43, v45, vcc
	v_cndmask_b32_e32 v40, v42, v44, vcc
	v_lshl_add_u64 v[36:37], s[30:31], 0, v[40:41]
	v_lshl_add_u64 v[36:37], v[36:37], 0, v[102:103]
	s_waitcnt vmcnt(0)
	v_pk_add_f32 v[28:29], v[28:29], v[32:33]
	v_pk_add_f32 v[30:31], v[30:31], v[34:35]
	global_store_dwordx4 v[36:37], v[28:31], off
	global_load_dwordx4 v[28:31], v[46:47], off offset:16
	v_lshlrev_b64 v[32:33], 12, v[130:131]
	v_lshl_add_u64 v[32:33], s[4:5], 0, v[32:33]
	s_waitcnt vmcnt(0)
	v_pk_add_f32 v[24:25], v[24:25], v[28:29]
	v_pk_add_f32 v[26:27], v[26:27], v[30:31]
	global_store_dwordx4 v[36:37], v[24:27], off offset:16
	global_load_dwordx4 v[24:27], v[46:47], off offset:128
	s_waitcnt vmcnt(0)
	v_pk_add_f32 v[20:21], v[20:21], v[24:25]
	v_pk_add_f32 v[22:23], v[22:23], v[26:27]
	global_store_dwordx4 v[36:37], v[20:23], off offset:128
	global_load_dwordx4 v[20:23], v[46:47], off offset:144
	v_mov_b32_e32 v25, v131
	v_or_b32_e32 v24, 0x70, v100
	v_lshlrev_b64 v[26:27], 12, v[24:25]
	v_ashrrev_i32_e32 v25, 31, v24
	v_lshlrev_b64 v[28:29], 12, v[24:25]
	v_lshl_add_u64 v[30:31], s[30:31], 0, v[28:29]
	v_cmp_gt_i32_e32 vcc, s11, v24
	s_waitcnt vmcnt(0)
	v_pk_add_f32 v[16:17], v[16:17], v[20:21]
	v_cndmask_b32_e32 v31, v33, v31, vcc
	v_cndmask_b32_e32 v30, v32, v30, vcc
	v_pk_add_f32 v[18:19], v[18:19], v[22:23]
	v_lshl_add_u64 v[30:31], v[30:31], 0, v[102:103]
	global_store_dwordx4 v[36:37], v[16:19], off offset:144
	global_load_dwordx4 v[16:19], v[30:31], off
	v_cndmask_b32_e32 v25, v27, v29, vcc
	v_cndmask_b32_e32 v24, v26, v28, vcc
	v_lshl_add_u64 v[20:21], s[30:31], 0, v[24:25]
	v_lshl_add_u64 v[20:21], v[20:21], 0, v[102:103]
	s_waitcnt vmcnt(0)
	v_pk_add_f32 v[12:13], v[12:13], v[16:17]
	v_pk_add_f32 v[14:15], v[14:15], v[18:19]
	global_store_dwordx4 v[20:21], v[12:15], off
	global_load_dwordx4 v[12:15], v[30:31], off offset:16
	s_waitcnt vmcnt(0)
	v_pk_add_f32 v[8:9], v[8:9], v[12:13]
	v_pk_add_f32 v[10:11], v[10:11], v[14:15]
	global_store_dwordx4 v[20:21], v[8:11], off offset:16
	global_load_dwordx4 v[8:11], v[30:31], off offset:128
	s_waitcnt vmcnt(0)
	v_pk_add_f32 v[4:5], v[4:5], v[8:9]
	v_pk_add_f32 v[6:7], v[6:7], v[10:11]
	global_store_dwordx4 v[20:21], v[4:7], off offset:128
	global_load_dwordx4 v[4:7], v[30:31], off offset:144
	s_waitcnt vmcnt(0)
	v_pk_add_f32 v[0:1], v[0:1], v[4:5]
	v_pk_add_f32 v[2:3], v[2:3], v[6:7]
	global_store_dwordx4 v[20:21], v[0:3], off offset:144
	s_cbranch_scc0 .LBB0_1258

.LBB0_1289:
	s_or_b64 exec, exec, s[0:1]
	v_mov_b32_e32 v0, v190
	v_mov_b32_e32 v1, v190
	s_waitcnt lgkmcnt(0)
	s_barrier
	s_movk_i32 s0, 0x4080
	v_ashrrev_i32_e32 v1, 6, v1
	v_add_u32_e32 v16, s87, v1
	v_cmp_gt_i32_e32 vcc, s0, v16
	s_and_saveexec_b64 s[0:1], vcc
	s_cbranch_execz .LBB0_1292
	v_lshlrev_b32_e32 v0, 2, v0
	v_and_b32_e32 v22, 0xfc, v0
	v_readlane_b32 s4, v254, 2
	v_mov_b32_e32 v19, 0
	v_lshlrev_b32_e32 v18, 2, v22
	v_readlane_b32 s18, v254, 16
	v_readlane_b32 s19, v254, 17
	s_movk_i32 s2, 0x2000
	v_mbcnt_hi_u32_b32 v17, -1, v191
	v_lshl_add_u64 v[4:5], s[18:19], 0, v[18:19]
	v_add_co_u32_e32 v0, vcc, s2, v4
	s_mov_b64 s[2:3], 0x2000
	s_nop 0
	v_addc_co_u32_e32 v1, vcc, 0, v5, vcc
	v_lshl_add_u64 v[12:13], v[4:5], 0, s[2:3]
	global_load_dwordx4 v[0:3], v[0:1], off
	s_nop 0
	global_load_dwordx4 v[4:7], v[12:13], off offset:1024
	global_load_dwordx4 v[8:11], v[12:13], off offset:2048
	s_nop 0
	global_load_dwordx4 v[12:15], v[12:13], off offset:3072
	v_and_b32_e32 v18, 64, v17
	v_xor_b32_e32 v20, 32, v17
	v_add_u32_e32 v32, 64, v18
	v_xor_b32_e32 v21, 16, v17
	v_cmp_lt_i32_e32 vcc, v20, v32
	v_xor_b32_e32 v23, 8, v17
	v_xor_b32_e32 v29, 4, v17
	v_cndmask_b32_e32 v33, v17, v20, vcc
	v_cmp_lt_i32_e32 vcc, v21, v32
	v_xor_b32_e32 v30, 2, v17
	v_readlane_b32 s6, v254, 4
	v_cndmask_b32_e32 v34, v17, v21, vcc
	v_cmp_lt_i32_e32 vcc, v23, v32
	v_readlane_b32 s7, v254, 5
	v_readlane_b32 s8, v254, 6
	v_cndmask_b32_e32 v23, v17, v23, vcc
	v_cmp_lt_i32_e32 vcc, v29, v32
	v_readlane_b32 s9, v254, 7
	v_readlane_b32 s10, v254, 8
	v_readlane_b32 s11, v254, 9
	v_readlane_b32 s12, v254, 10
	v_readlane_b32 s13, v254, 11
	v_readlane_b32 s14, v254, 12
	v_readlane_b32 s15, v254, 13
	v_readlane_b32 s16, v254, 14
	v_readlane_b32 s17, v254, 15
	v_xor_b32_e32 v31, 1, v17
	v_cndmask_b32_e32 v35, v17, v29, vcc
	v_cmp_lt_i32_e32 vcc, v30, v32
	v_readlane_b32 s6, v255, 39
	v_readlane_b32 s8, v254, 34
	v_cndmask_b32_e32 v36, v17, v30, vcc
	v_cmp_lt_i32_e32 vcc, v31, v32
	v_readlane_b32 s5, v254, 3
	v_readlane_b32 s7, v255, 40
	v_readlane_b32 s22, v254, 48
	v_readlane_b32 s23, v254, 49
	v_lshlrev_b32_e32 v18, 1, v22
	v_cndmask_b32_e32 v17, v17, v31, vcc
	s_lshl_b32 s4, s86, 2
	s_mov_b64 s[2:3], 0
	s_movk_i32 s5, 0x4000
	v_mov_b32_e32 v24, s7
	v_mov_b32_e32 v25, s23
	v_mov_b32_e32 v26, s6
	v_mov_b32_e32 v27, s22
	v_mov_b32_e32 v28, 0x358637bd
	s_mov_b32 s6, 0x800000
	s_movk_i32 s7, 0x7fff
	s_movk_i32 s8, 0x407f
	v_and_b32_e32 v200, -64, v18
	v_add_u32_e32 v200, v18, v200
	v_mov_b32_e32 v201, v19
	v_lshl_add_u64 v[20:21], s[88:89], 0, v[200:201]
	v_lshlrev_b32_e32 v29, 2, v33
	v_lshlrev_b32_e32 v30, 2, v34
	v_lshlrev_b32_e32 v31, 2, v23
	v_lshlrev_b32_e32 v32, 2, v35
	v_lshlrev_b32_e32 v33, 2, v36
	v_lshlrev_b32_e32 v34, 2, v17
	v_lshlrev_b32_e32 v18, 2, v22
	v_readlane_b32 s9, v254, 35
	v_readlane_b32 s10, v254, 36
	v_readlane_b32 s11, v254, 37
	v_readlane_b32 s12, v254, 38
	v_readlane_b32 s13, v254, 39
	v_readlane_b32 s14, v254, 40
	v_readlane_b32 s15, v254, 41
	v_readlane_b32 s16, v254, 42
	v_readlane_b32 s17, v254, 43
	v_readlane_b32 s18, v254, 44
	v_readlane_b32 s19, v254, 45
	v_readlane_b32 s20, v254, 46
	v_readlane_b32 s21, v254, 47
	s_waitcnt vmcnt(3)
	v_mov_b32_e32 v22, v1
	v_mov_b32_e32 v23, v3
	v_mov_b32_e32 v1, v2
	s_waitcnt vmcnt(2)
	v_mov_b32_e32 v2, v5
	v_mov_b32_e32 v3, v7
	v_mov_b32_e32 v5, v6
	s_waitcnt vmcnt(1)
	v_mov_b32_e32 v6, v9
	v_mov_b32_e32 v7, v11
	v_mov_b32_e32 v9, v10
	s_waitcnt vmcnt(0)
	v_mov_b32_e32 v10, v13
	v_mov_b32_e32 v11, v15
	v_mov_b32_e32 v13, v14
	v_mov_b32_e32 v14, 1
.LBB0_1291:
	v_add_u32_e32 v15, 0xffffc000, v16
	v_ashrrev_i32_e32 v17, 31, v16
	v_cmp_gt_i32_e32 vcc, s5, v16
	v_and_b32_e32 v40, -2, v16
	v_mov_b32_e32 v41, v17
	v_lshlrev_b64 v[40:41], 11, v[40:41]
	v_and_b32_e32 v200, 1, v16
	v_lshl_or_b32 v40, v200, 6, v40
	v_lshl_add_u64 v[52:53], v[20:21], 0, v[40:41]
	v_cndmask_b32_e32 v37, 0, v17, vcc
	v_cndmask_b32_e32 v36, v15, v16, vcc
	v_cndmask_b32_e32 v39, v24, v25, vcc
	v_cndmask_b32_e32 v38, v26, v27, vcc
	v_lshlrev_b64 v[36:37], 12, v[36:37]
	v_lshl_add_u64 v[36:37], v[38:39], 0, v[36:37]
	v_lshl_add_u64 v[48:49], v[36:37], 0, v[18:19]
	global_load_dwordx4 v[36:39], v[48:49], off
	global_load_dwordx4 v[40:43], v[48:49], off offset:1024
	global_load_dwordx4 v[44:47], v[48:49], off offset:2048
	s_nop 0
	global_load_dwordx4 v[48:51], v[48:49], off offset:3072
	v_add_u32_e32 v16, s4, v16
	v_cmp_lt_i32_e32 vcc, s8, v16
	s_or_b64 s[2:3], vcc, s[2:3]
	s_waitcnt vmcnt(3)
	v_mov_b32_e32 v62, v36
	s_waitcnt vmcnt(2)
	v_mov_b32_e32 v58, v40
	v_mov_b32_e32 v63, v40
	v_mov_b32_e32 v40, v37
	v_mov_b32_e32 v60, v41
	s_waitcnt vmcnt(0)
	v_mov_b32_e32 v66, v48
	v_mov_b32_e32 v71, v48
	v_mov_b32_e32 v48, v45
	v_pk_mul_f32 v[40:41], v[40:41], v[40:41]
	v_mov_b32_e32 v54, v36
	v_mov_b32_e32 v55, v38
	v_mov_b32_e32 v56, v37
	v_mov_b32_e32 v57, v39
	v_mov_b32_e32 v59, v42
	v_mov_b32_e32 v36, v38
	v_mov_b32_e32 v37, v42
	v_mov_b32_e32 v42, v39
	v_mov_b32_e32 v38, v44
	v_mov_b32_e32 v39, v46
	v_mov_b32_e32 v64, v45
	v_mov_b32_e32 v65, v47
	v_mov_b32_e32 v67, v50
	v_mov_b32_e32 v70, v44
	v_mov_b32_e32 v44, v46
	v_mov_b32_e32 v45, v50
	v_mov_b32_e32 v50, v47
	v_pk_mul_f32 v[46:47], v[48:49], v[48:49]
	v_pk_fma_f32 v[40:41], v[62:63], v[62:63], v[40:41]
	v_pk_fma_f32 v[46:47], v[70:71], v[70:71], v[46:47]
	v_pk_fma_f32 v[36:37], v[36:37], v[36:37], v[40:41]
	v_pk_fma_f32 v[40:41], v[44:45], v[44:45], v[46:47]
	v_pk_fma_f32 v[36:37], v[42:43], v[42:43], v[36:37]
	v_pk_fma_f32 v[40:41], v[50:51], v[50:51], v[40:41]
	v_add_f32_e32 v15, v36, v37
	v_add_f32_e32 v15, v15, v40
	v_add_f32_e32 v15, v15, v41
	ds_bpermute_b32 v17, v29, v15
	v_mov_b32_e32 v61, v43
	v_mov_b32_e32 v68, v49
	v_mov_b32_e32 v69, v51
	s_waitcnt lgkmcnt(0)
	v_add_f32_e32 v15, v15, v17
	ds_bpermute_b32 v17, v30, v15
	s_waitcnt lgkmcnt(0)
	v_add_f32_e32 v15, v15, v17
	ds_bpermute_b32 v17, v31, v15
	s_waitcnt lgkmcnt(0)
	v_add_f32_e32 v15, v15, v17
	ds_bpermute_b32 v17, v32, v15
	s_waitcnt lgkmcnt(0)
	v_add_f32_e32 v15, v15, v17
	ds_bpermute_b32 v17, v33, v15
	s_waitcnt lgkmcnt(0)
	v_add_f32_e32 v15, v15, v17
	ds_bpermute_b32 v17, v34, v15
	s_waitcnt lgkmcnt(0)
	v_add_f32_e32 v15, v15, v17
	v_fmamk_f32 v15, v15, 0x3a800000, v28
	v_mul_f32_e32 v17, 0x4b800000, v15
	v_cmp_gt_f32_e32 vcc, s6, v15
	s_nop 1
	v_cndmask_b32_e32 v15, v15, v17, vcc
	v_rsq_f32_e32 v15, v15
	s_nop 0
	v_mul_f32_e32 v17, 0x45800000, v15
	v_cndmask_b32_e32 v36, v15, v17, vcc
	v_pk_mul_f32 v[40:41], v[54:55], v[36:37] op_sel_hi:[1,0]
	v_pk_mul_f32 v[42:43], v[56:57], v[36:37] op_sel_hi:[1,0]
	v_pk_mul_f32 v[44:45], v[58:59], v[36:37] op_sel_hi:[1,0]
	v_pk_mul_f32 v[46:47], v[60:61], v[36:37] op_sel_hi:[1,0]
	v_pk_mul_f32 v[38:39], v[38:39], v[36:37] op_sel_hi:[1,0]
	v_pk_mul_f32 v[48:49], v[64:65], v[36:37] op_sel_hi:[1,0]
	v_pk_mul_f32 v[50:51], v[66:67], v[36:37] op_sel_hi:[1,0]
	v_pk_mul_f32 v[36:37], v[68:69], v[36:37] op_sel_hi:[1,0]
	v_pk_mul_f32 v[40:41], v[0:1], v[40:41]
	v_pk_mul_f32 v[42:43], v[22:23], v[42:43]
	v_pk_mul_f32 v[44:45], v[4:5], v[44:45]
	v_pk_mul_f32 v[46:47], v[2:3], v[46:47]
	v_pk_mul_f32 v[38:39], v[8:9], v[38:39]
	v_pk_mul_f32 v[48:49], v[6:7], v[48:49]
	v_pk_mul_f32 v[36:37], v[10:11], v[36:37]
	v_and_b32_sdwa v17, v40, v14 dst_sel:DWORD dst_unused:UNUSED_PAD src0_sel:WORD_1 src1_sel:DWORD
	v_and_b32_sdwa v35, v43, v14 dst_sel:DWORD dst_unused:UNUSED_PAD src0_sel:WORD_1 src1_sel:DWORD
	v_and_b32_sdwa v54, v42, v14 dst_sel:DWORD dst_unused:UNUSED_PAD src0_sel:WORD_1 src1_sel:DWORD
	v_pk_mul_f32 v[50:51], v[12:13], v[50:51]
	v_and_b32_sdwa v15, v41, v14 dst_sel:DWORD dst_unused:UNUSED_PAD src0_sel:WORD_1 src1_sel:DWORD
	v_and_b32_sdwa v55, v45, v14 dst_sel:DWORD dst_unused:UNUSED_PAD src0_sel:WORD_1 src1_sel:DWORD
	v_and_b32_sdwa v56, v44, v14 dst_sel:DWORD dst_unused:UNUSED_PAD src0_sel:WORD_1 src1_sel:DWORD
	v_and_b32_sdwa v57, v47, v14 dst_sel:DWORD dst_unused:UNUSED_PAD src0_sel:WORD_1 src1_sel:DWORD
	v_and_b32_sdwa v58, v46, v14 dst_sel:DWORD dst_unused:UNUSED_PAD src0_sel:WORD_1 src1_sel:DWORD
	v_and_b32_sdwa v59, v39, v14 dst_sel:DWORD dst_unused:UNUSED_PAD src0_sel:WORD_1 src1_sel:DWORD
	v_and_b32_sdwa v60, v38, v14 dst_sel:DWORD dst_unused:UNUSED_PAD src0_sel:WORD_1 src1_sel:DWORD
	v_and_b32_sdwa v61, v49, v14 dst_sel:DWORD dst_unused:UNUSED_PAD src0_sel:WORD_1 src1_sel:DWORD
	v_and_b32_sdwa v62, v48, v14 dst_sel:DWORD dst_unused:UNUSED_PAD src0_sel:WORD_1 src1_sel:DWORD
	v_and_b32_sdwa v65, v37, v14 dst_sel:DWORD dst_unused:UNUSED_PAD src0_sel:WORD_1 src1_sel:DWORD
	v_and_b32_sdwa v66, v36, v14 dst_sel:DWORD dst_unused:UNUSED_PAD src0_sel:WORD_1 src1_sel:DWORD
	v_add3_u32 v17, v40, v17, s7
	v_add3_u32 v35, v43, v35, s7
	v_add3_u32 v40, v42, v54, s7
	v_and_b32_sdwa v63, v51, v14 dst_sel:DWORD dst_unused:UNUSED_PAD src0_sel:WORD_1 src1_sel:DWORD
	v_and_b32_sdwa v64, v50, v14 dst_sel:DWORD dst_unused:UNUSED_PAD src0_sel:WORD_1 src1_sel:DWORD
	v_add3_u32 v15, v41, v15, s7
	v_add3_u32 v41, v44, v56, s7
	v_add3_u32 v42, v45, v55, s7
	v_add3_u32 v43, v47, v57, s7
	v_add3_u32 v44, v46, v58, s7
	v_add3_u32 v45, v38, v60, s7
	v_add3_u32 v46, v39, v59, s7
	v_add3_u32 v38, v49, v61, s7
	v_add3_u32 v39, v48, v62, s7
	v_add3_u32 v37, v37, v65, s7
	v_add3_u32 v36, v36, v66, s7
	v_and_b32_e32 v35, 0xffff0000, v35
	v_and_b32_e32 v40, 0xffff0000, v40
	v_add3_u32 v47, v50, v64, s7
	v_add3_u32 v48, v51, v63, s7
	v_and_b32_e32 v43, 0xffff0000, v43
	v_and_b32_e32 v44, 0xffff0000, v44
	v_and_b32_e32 v49, 0xffff0000, v38
	v_and_b32_e32 v50, 0xffff0000, v39
	v_and_b32_e32 v51, 0xffff0000, v37
	v_and_b32_e32 v54, 0xffff0000, v36
	v_or_b32_sdwa v37, v35, v15 dst_sel:DWORD dst_unused:UNUSED_PAD src0_sel:DWORD src1_sel:WORD_1
	v_or_b32_sdwa v36, v40, v17 dst_sel:DWORD dst_unused:UNUSED_PAD src0_sel:DWORD src1_sel:WORD_1
	v_or_b32_sdwa v39, v43, v42 dst_sel:DWORD dst_unused:UNUSED_PAD src0_sel:DWORD src1_sel:WORD_1
	v_or_b32_sdwa v38, v44, v41 dst_sel:DWORD dst_unused:UNUSED_PAD src0_sel:DWORD src1_sel:WORD_1
	v_or_b32_sdwa v41, v49, v46 dst_sel:DWORD dst_unused:UNUSED_PAD src0_sel:DWORD src1_sel:WORD_1
	v_or_b32_sdwa v40, v50, v45 dst_sel:DWORD dst_unused:UNUSED_PAD src0_sel:DWORD src1_sel:WORD_1
	v_or_b32_sdwa v43, v51, v48 dst_sel:DWORD dst_unused:UNUSED_PAD src0_sel:DWORD src1_sel:WORD_1
	v_or_b32_sdwa v42, v54, v47 dst_sel:DWORD dst_unused:UNUSED_PAD src0_sel:DWORD src1_sel:WORD_1
	global_store_dwordx2 v[52:53], v[36:37], off
	global_store_dwordx2 v[52:53], v[38:39], off offset:1024
	global_store_dwordx2 v[52:53], v[40:41], off offset:2048
	global_store_dwordx2 v[52:53], v[42:43], off offset:3072
	s_andn2_b64 exec, exec, s[2:3]
	s_cbranch_execnz .LBB0_1291

.LBB0_1317:
	s_or_b64 exec, exec, s[0:1]
	s_add_u32 s40, s52, 0x7390000
	s_addc_u32 s41, s53, 0
	s_add_u32 s42, s52, 0xd894000
	s_addc_u32 s43, s53, 0
	v_readlane_b32 s34, v254, 56
	s_cmpk_gt_i32 s34, 0x9ff
	s_waitcnt lgkmcnt(0)
	s_barrier
	s_cbranch_scc1 .LBB0_1345
	s_lshl_b32 s26, s34, 1
	s_lshl_b32 s27, s86, 1
	s_lshl_b32 s28, s34, 3
	s_lshl_b32 s29, s86, 3
	v_mov_b32_e32 v129, 0
	s_mov_b64 s[0:1], 0x20000
	s_mov_b64 s[2:3], 0x40000
	s_mov_b64 s[4:5], 0x60000
	s_mov_b64 s[6:7], 0x20080
	s_mov_b64 s[8:9], 0x40080
	s_mov_b64 s[10:11], 0x60080
	s_mov_b64 s[12:13], 0x12d0100
	s_mov_b64 s[14:15], 0x12f0100
	s_mov_b64 s[16:17], 0x1310100
	s_mov_b64 s[18:19], 0x1330100
	s_mov_b64 s[20:21], 0x100
	s_mov_b64 s[22:23], 0x20100
	s_movk_i32 s30, 0xc00
	s_movk_i32 s31, 0x7fff
	s_mov_b32 s33, 0xffff0000
	v_mov_b32_e32 v134, 1
	s_branch .LBB0_1320

.LBB0_1320:
	s_lshl_b32 s24, s28, 8
	s_lshl_b32 s25, s34, 3
	s_and_b32 s36, s24, 0x3800
	s_bfe_u32 s24, s34, 0x30003
	s_and_b32 s25, s25, 56
	s_lshl_b32 s37, s24, 8
	s_or_b32 s39, s25, s24
	s_lshl_b32 s24, s34, 1
	s_and_b32 s38, s26, 0xffffff80
	s_and_b32 s35, s24, 0xffffff80
	s_cmpk_gt_i32 s35, 0x7ff
	s_mov_b64 s[24:25], -1
	s_cbranch_scc0 .LBB0_1340
	s_mov_b64 s[62:63], 0x80
	v_mov_b32_e32 v136, v190
	s_lshl_b32 s44, s39, 8
	v_ashrrev_i32_e32 v6, 2, v136
	v_and_b32_e32 v6, -2, v6
	v_lshlrev_b32_e32 v0, 6, v136
	v_and_b32_e32 v142, 0xffffe000, v0
	v_add_u32_e32 v0, s44, v6
	v_ashrrev_i32_e32 v1, 31, v0
	v_lshlrev_b32_e32 v141, 4, v136
	v_lshlrev_b64 v[0:1], 11, v[0:1]
	v_lshl_add_u64 v[0:1], s[88:89], 0, v[0:1]
	v_and_b32_e32 v128, 0x70, v141
	v_readfirstlane_b32 s24, v141
	v_add_u32_e32 v7, 0x1000, v141
	v_lshl_add_u64 v[0:1], v[0:1], 0, v[128:129]
	s_waitcnt vmcnt(0)
	s_mov_b32 m0, s24
	v_readfirstlane_b32 s24, v7
	v_add_u32_e32 v7, 0x2000, v141
	global_load_lds_dwordx4 v[0:1], off
	v_lshl_add_u64 v[4:5], v[0:1], 0, s[0:1]
	s_mov_b32 m0, s24
	v_readfirstlane_b32 s24, v7
	v_add_u32_e32 v7, 0x3000, v141
	v_add_u32_e32 v2, s35, v6
	global_load_lds_dwordx4 v[4:5], off
	v_lshl_add_u64 v[4:5], v[0:1], 0, s[2:3]
	s_mov_b32 m0, s24
	v_readfirstlane_b32 s24, v7
	v_ashrrev_i32_e32 v3, 31, v2
	global_load_lds_dwordx4 v[4:5], off
	v_lshl_add_u64 v[4:5], v[0:1], 0, s[4:5]
	s_mov_b32 m0, s24
	v_lshlrev_b64 v[2:3], 11, v[2:3]
	global_load_lds_dwordx4 v[4:5], off
	v_add_u32_e32 v4, 0x4000, v141
	v_lshl_add_u64 v[2:3], s[52:53], 0, v[2:3]
	v_readfirstlane_b32 s24, v4
	v_add_u32_e32 v7, 0x5000, v141
	v_lshl_add_u64 v[2:3], v[2:3], 0, v[128:129]
	s_mov_b32 m0, s24
	v_readfirstlane_b32 s24, v7
	v_add_u32_e32 v7, 0x6000, v141
	global_load_lds_dwordx4 v[2:3], off
	v_lshl_add_u64 v[4:5], v[2:3], 0, s[0:1]
	s_mov_b32 m0, s24
	v_readfirstlane_b32 s24, v7
	v_add_u32_e32 v7, 0x7000, v141
	global_load_lds_dwordx4 v[4:5], off
	v_lshl_add_u64 v[4:5], v[0:1], 0, s[62:63]
	s_mov_b32 m0, s24
	v_readfirstlane_b32 s24, v7
	v_add_u32_e32 v7, 0x8000, v141
	global_load_lds_dwordx4 v[4:5], off
	v_lshl_add_u64 v[4:5], v[0:1], 0, s[6:7]
	s_mov_b32 m0, s24
	v_readfirstlane_b32 s24, v7
	global_load_lds_dwordx4 v[4:5], off
	v_lshl_add_u64 v[4:5], v[0:1], 0, s[8:9]
	s_mov_b32 m0, s24
	v_lshl_add_u64 v[0:1], v[0:1], 0, s[10:11]
	global_load_lds_dwordx4 v[4:5], off
	v_add_u32_e32 v4, 0x9000, v141
	v_and_b32_e32 v135, 15, v136
	v_readfirstlane_b32 s24, v4
	v_add_u32_e32 v4, 0xa000, v141
	s_mov_b32 m0, s24
	v_readfirstlane_b32 s24, v4
	global_load_lds_dwordx4 v[0:1], off
	v_lshl_add_u64 v[0:1], v[2:3], 0, s[62:63]
	s_mov_b32 m0, s24
	v_bfe_u32 v137, v136, 6, 1
	global_load_lds_dwordx4 v[0:1], off
	v_lshl_add_u64 v[0:1], v[2:3], 0, s[6:7]
	v_add_u32_e32 v2, 0xb000, v141
	v_lshlrev_b32_e32 v138, 6, v135
	v_readfirstlane_b32 s24, v2
	s_mov_b32 m0, s24
	s_add_i32 s24, s37, s36
	global_load_lds_dwordx4 v[0:1], off
	v_add_u32_e32 v0, s38, v6
	v_ashrrev_i32_e32 v1, 31, v0
	v_lshlrev_b64 v[0:1], 11, v[0:1]
	v_or_b32_e32 v0, v0, v128
	v_lshl_add_u64 v[130:131], s[52:53], 0, v[0:1]
	v_add_u32_e32 v0, s24, v6
	v_ashrrev_i32_e32 v1, 31, v0
	v_lshlrev_b64 v[0:1], 11, v[0:1]
	v_or_b32_e32 v0, v0, v128
	v_lshl_add_u64 v[132:133], s[52:53], 0, v[0:1]
	v_mov_b32_e32 v0, 0
	v_and_b32_e32 v139, 48, v136
	v_lshlrev_b32_e32 v140, 12, v137
	s_mov_b32 s45, 0
	s_mov_b64 s[24:25], 0
	v_mov_b32_e32 v1, v0
	v_mov_b32_e32 v2, v0
	v_mov_b32_e32 v3, v0
	v_mov_b32_e32 v4, v0
	v_mov_b32_e32 v5, v0
	v_mov_b32_e32 v6, v0
	v_mov_b32_e32 v7, v0
	v_mov_b32_e32 v8, v0
	v_mov_b32_e32 v9, v0
	v_mov_b32_e32 v10, v0
	v_mov_b32_e32 v11, v0
	v_mov_b32_e32 v12, v0
	v_mov_b32_e32 v13, v0
	v_mov_b32_e32 v14, v0
	v_mov_b32_e32 v15, v0
	v_mov_b32_e32 v16, v0
	v_mov_b32_e32 v17, v0
	v_mov_b32_e32 v18, v0
	v_mov_b32_e32 v19, v0
	v_mov_b32_e32 v20, v0
	v_mov_b32_e32 v21, v0
	v_mov_b32_e32 v22, v0
	v_mov_b32_e32 v23, v0
	v_mov_b32_e32 v24, v0
	v_mov_b32_e32 v25, v0
	v_mov_b32_e32 v26, v0
	v_mov_b32_e32 v27, v0
	v_mov_b32_e32 v28, v0
	v_mov_b32_e32 v29, v0
	v_mov_b32_e32 v30, v0
	v_mov_b32_e32 v31, v0
	v_mov_b32_e32 v32, v0
	v_mov_b32_e32 v33, v0
	v_mov_b32_e32 v34, v0
	v_mov_b32_e32 v35, v0
	v_mov_b32_e32 v36, v0
	v_mov_b32_e32 v37, v0
	v_mov_b32_e32 v38, v0
	v_mov_b32_e32 v39, v0
	v_mov_b32_e32 v40, v0
	v_mov_b32_e32 v41, v0
	v_mov_b32_e32 v42, v0
	v_mov_b32_e32 v43, v0
	v_mov_b32_e32 v44, v0
	v_mov_b32_e32 v45, v0
	v_mov_b32_e32 v46, v0
	v_mov_b32_e32 v47, v0
	v_mov_b32_e32 v48, v0
	v_mov_b32_e32 v49, v0
	v_mov_b32_e32 v50, v0
	v_mov_b32_e32 v51, v0
	v_mov_b32_e32 v52, v0
	v_mov_b32_e32 v53, v0
	v_mov_b32_e32 v54, v0
	v_mov_b32_e32 v55, v0
	v_mov_b32_e32 v56, v0
	v_mov_b32_e32 v57, v0
	v_mov_b32_e32 v58, v0
	v_mov_b32_e32 v59, v0
	v_mov_b32_e32 v60, v0
	v_mov_b32_e32 v61, v0
	v_mov_b32_e32 v62, v0
	v_mov_b32_e32 v63, v0
	v_mov_b32_e32 v64, v0
	v_mov_b32_e32 v65, v0
	v_mov_b32_e32 v66, v0
	v_mov_b32_e32 v67, v0
	v_mov_b32_e32 v68, v0
	v_mov_b32_e32 v69, v0
	v_mov_b32_e32 v70, v0
	v_mov_b32_e32 v71, v0
	v_mov_b32_e32 v72, v0
	v_mov_b32_e32 v73, v0
	v_mov_b32_e32 v74, v0
	v_mov_b32_e32 v75, v0
	v_mov_b32_e32 v76, v0
	v_mov_b32_e32 v77, v0
	v_mov_b32_e32 v78, v0
	v_mov_b32_e32 v79, v0
	v_mov_b32_e32 v80, v0
	v_mov_b32_e32 v81, v0
	v_mov_b32_e32 v82, v0
	v_mov_b32_e32 v83, v0
	v_mov_b32_e32 v84, v0
	v_mov_b32_e32 v85, v0
	v_mov_b32_e32 v86, v0
	v_mov_b32_e32 v87, v0
	v_mov_b32_e32 v88, v0
	v_mov_b32_e32 v89, v0
	v_mov_b32_e32 v90, v0
	v_mov_b32_e32 v91, v0
	v_mov_b32_e32 v92, v0
	v_mov_b32_e32 v93, v0
	v_mov_b32_e32 v94, v0
	v_mov_b32_e32 v95, v0
	v_mov_b32_e32 v96, v0
	v_mov_b32_e32 v97, v0
	v_mov_b32_e32 v98, v0
	v_mov_b32_e32 v99, v0
	v_mov_b32_e32 v100, v0
	v_mov_b32_e32 v101, v0
	v_mov_b32_e32 v102, v0
	v_mov_b32_e32 v103, v0
	v_mov_b32_e32 v104, v0
	v_mov_b32_e32 v105, v0
	v_mov_b32_e32 v106, v0
	v_mov_b32_e32 v107, v0
	v_mov_b32_e32 v108, v0
	v_mov_b32_e32 v109, v0
	v_mov_b32_e32 v110, v0
	v_mov_b32_e32 v111, v0
	v_mov_b32_e32 v112, v0
	v_mov_b32_e32 v113, v0
	v_mov_b32_e32 v114, v0
	v_mov_b32_e32 v115, v0
	v_mov_b32_e32 v116, v0
	v_mov_b32_e32 v117, v0
	v_mov_b32_e32 v118, v0
	v_mov_b32_e32 v119, v0
	v_mov_b32_e32 v120, v0
	v_mov_b32_e32 v121, v0
	v_mov_b32_e32 v122, v0
	v_mov_b32_e32 v123, v0
	v_mov_b32_e32 v124, v0
	v_mov_b32_e32 v125, v0
	v_mov_b32_e32 v126, v0
	v_mov_b32_e32 v127, v0
.LBB0_1322:
	s_add_i32 s46, s45, 2
	s_mul_hi_i32 s47, s46, 0x55555556
	s_lshr_b32 s48, s47, 31
	s_add_i32 s47, s47, s48
	s_mul_i32 s47, s47, 3
	s_sub_i32 s46, s46, s47
	s_mulk_i32 s46, 0x6000
	s_mul_i32 s54, s45, 0x6000
	v_readfirstlane_b32 s55, v141
	v_lshl_add_u64 v[232:233], v[132:133], 0, s[24:25]
	v_lshl_add_u64 v[234:235], v[130:131], 0, s[24:25]
	s_add_u32 s55, s55, s46
	s_waitcnt vmcnt(6) lgkmcnt(0)
	s_barrier
	v_or_b32_e32 v128, s54, v140
	v_add3_u32 v128, v128, v138, v139
	ds_read_b128 v[176:179], v128 offset:16384
	ds_read_b128 v[180:183], v128 offset:17408
	ds_read_b128 v[184:187], v128 offset:18432
	ds_read_b128 v[192:195], v128 offset:19456
	v_add_u32_e32 v128, s54, v142
	v_add3_u32 v128, v128, v138, v139
	ds_read_b128 v[144:147], v128
	ds_read_b128 v[148:151], v128 offset:1024
	ds_read_b128 v[152:155], v128 offset:2048
	ds_read_b128 v[156:159], v128 offset:3072
	ds_read_b128 v[160:163], v128 offset:4096
	ds_read_b128 v[164:167], v128 offset:5120
	ds_read_b128 v[168:171], v128 offset:6144
	ds_read_b128 v[172:175], v128 offset:7168
	s_setprio 1
	s_waitcnt lgkmcnt(7)
	v_mfma_f32_16x16x32_bf16 v[124:127], v[144:147], v[176:179], v[124:127]
	v_mfma_f32_16x16x32_bf16 v[120:123], v[144:147], v[180:183], v[120:123]
	v_mfma_f32_16x16x32_bf16 v[116:119], v[144:147], v[184:187], v[116:119]
	v_mfma_f32_16x16x32_bf16 v[112:115], v[144:147], v[192:195], v[112:115]
	s_mov_b32 m0, s55
	v_lshl_add_u64 v[236:237], v[232:233], 0, s[12:13]
	global_load_lds_dwordx4 v[236:237], off
	s_waitcnt lgkmcnt(6)
	v_mfma_f32_16x16x32_bf16 v[108:111], v[148:151], v[176:179], v[108:111]
	v_mfma_f32_16x16x32_bf16 v[104:107], v[148:151], v[180:183], v[104:107]
	v_mfma_f32_16x16x32_bf16 v[100:103], v[148:151], v[184:187], v[100:103]
	v_mfma_f32_16x16x32_bf16 v[96:99], v[148:151], v[192:195], v[96:99]
	s_add_u32 m0, s55, 0x1000
	v_lshl_add_u64 v[236:237], v[232:233], 0, s[14:15]
	global_load_lds_dwordx4 v[236:237], off
	s_waitcnt lgkmcnt(5)
	v_mfma_f32_16x16x32_bf16 v[92:95], v[152:155], v[176:179], v[92:95]
	v_mfma_f32_16x16x32_bf16 v[88:91], v[152:155], v[180:183], v[88:91]
	v_mfma_f32_16x16x32_bf16 v[84:87], v[152:155], v[184:187], v[84:87]
	v_mfma_f32_16x16x32_bf16 v[80:83], v[152:155], v[192:195], v[80:83]
	s_add_u32 m0, s55, 0x2000
	v_lshl_add_u64 v[236:237], v[232:233], 0, s[16:17]
	global_load_lds_dwordx4 v[236:237], off
	s_waitcnt lgkmcnt(4)
	v_mfma_f32_16x16x32_bf16 v[76:79], v[156:159], v[176:179], v[76:79]
	v_mfma_f32_16x16x32_bf16 v[72:75], v[156:159], v[180:183], v[72:75]
	v_mfma_f32_16x16x32_bf16 v[68:71], v[156:159], v[184:187], v[68:71]
	v_mfma_f32_16x16x32_bf16 v[64:67], v[156:159], v[192:195], v[64:67]
	s_add_u32 m0, s55, 0x3000
	v_lshl_add_u64 v[236:237], v[232:233], 0, s[18:19]
	global_load_lds_dwordx4 v[236:237], off
	s_waitcnt lgkmcnt(3)
	v_mfma_f32_16x16x32_bf16 v[60:63], v[160:163], v[176:179], v[60:63]
	v_mfma_f32_16x16x32_bf16 v[56:59], v[160:163], v[180:183], v[56:59]
	v_mfma_f32_16x16x32_bf16 v[52:55], v[160:163], v[184:187], v[52:55]
	v_mfma_f32_16x16x32_bf16 v[48:51], v[160:163], v[192:195], v[48:51]
	s_add_u32 m0, s55, 0x4000
	v_lshl_add_u64 v[236:237], v[234:235], 0, s[20:21]
	global_load_lds_dwordx4 v[236:237], off
	s_waitcnt lgkmcnt(2)
	v_mfma_f32_16x16x32_bf16 v[44:47], v[164:167], v[176:179], v[44:47]
	v_mfma_f32_16x16x32_bf16 v[40:43], v[164:167], v[180:183], v[40:43]
	v_mfma_f32_16x16x32_bf16 v[36:39], v[164:167], v[184:187], v[36:39]
	v_mfma_f32_16x16x32_bf16 v[32:35], v[164:167], v[192:195], v[32:35]
	s_add_u32 m0, s55, 0x5000
	v_lshl_add_u64 v[236:237], v[234:235], 0, s[22:23]
	global_load_lds_dwordx4 v[236:237], off
	s_waitcnt lgkmcnt(1)
	v_mfma_f32_16x16x32_bf16 v[28:31], v[168:171], v[176:179], v[28:31]
	v_mfma_f32_16x16x32_bf16 v[24:27], v[168:171], v[180:183], v[24:27]
	v_mfma_f32_16x16x32_bf16 v[20:23], v[168:171], v[184:187], v[20:23]
	v_mfma_f32_16x16x32_bf16 v[16:19], v[168:171], v[192:195], v[16:19]
	s_waitcnt lgkmcnt(0)
	v_mfma_f32_16x16x32_bf16 v[12:15], v[172:175], v[176:179], v[12:15]
	v_mfma_f32_16x16x32_bf16 v[8:11], v[172:175], v[180:183], v[8:11]
	v_mfma_f32_16x16x32_bf16 v[4:7], v[172:175], v[184:187], v[4:7]
	v_mfma_f32_16x16x32_bf16 v[0:3], v[172:175], v[192:195], v[0:3]
	s_setprio 0
	s_add_i32 s46, s45, 1
	s_cmp_lg_u32 s45, 2
	s_cselect_b32 s45, s46, 0
	s_add_u32 s24, s24, 0x80
	s_addc_u32 s25, s25, 0
	s_cmpk_eq_i32 s24, 0xf00
	s_cbranch_scc0 .LBB0_1322
	s_waitcnt vmcnt(6) lgkmcnt(0)
	s_barrier
	v_add3_u32 v128, v142, v138, v139
	ds_read_b128 v[130:133], v128
	ds_read_b128 v[142:145], v128 offset:1024
	ds_read_b128 v[146:149], v128 offset:2048
	ds_read_b128 v[150:153], v128 offset:3072
	ds_read_b128 v[154:157], v128 offset:4096
	ds_read_b128 v[158:161], v128 offset:5120
	ds_read_b128 v[162:165], v128 offset:6144
	ds_read_b128 v[166:169], v128 offset:7168
	v_add3_u32 v182, v140, v138, v139
	ds_read_b128 v[138:141], v182 offset:16384
	ds_read_b128 v[170:173], v182 offset:17408
	ds_read_b128 v[174:177], v182 offset:18432
	ds_read_b128 v[178:181], v182 offset:19456
	s_setprio 1
	s_waitcnt lgkmcnt(0)
	v_mfma_f32_16x16x32_bf16 v[100:103], v[142:145], v[174:177], v[100:103]
	v_mfma_f32_16x16x32_bf16 v[96:99], v[142:145], v[178:181], v[96:99]
	v_mfma_f32_16x16x32_bf16 v[92:95], v[146:149], v[138:141], v[92:95]
	v_mfma_f32_16x16x32_bf16 v[88:91], v[146:149], v[170:173], v[88:91]
	v_mfma_f32_16x16x32_bf16 v[84:87], v[146:149], v[174:177], v[84:87]
	v_mfma_f32_16x16x32_bf16 v[80:83], v[146:149], v[178:181], v[80:83]
	v_mfma_f32_16x16x32_bf16 v[76:79], v[150:153], v[138:141], v[76:79]
	v_mfma_f32_16x16x32_bf16 v[72:75], v[150:153], v[170:173], v[72:75]
	v_mfma_f32_16x16x32_bf16 v[68:71], v[150:153], v[174:177], v[68:71]
	v_mfma_f32_16x16x32_bf16 v[64:67], v[150:153], v[178:181], v[64:67]
	v_mfma_f32_16x16x32_bf16 v[60:63], v[154:157], v[138:141], v[60:63]
	v_mfma_f32_16x16x32_bf16 v[56:59], v[154:157], v[170:173], v[56:59]
	v_mfma_f32_16x16x32_bf16 v[52:55], v[154:157], v[174:177], v[52:55]
	v_mfma_f32_16x16x32_bf16 v[48:51], v[154:157], v[178:181], v[48:51]
	v_mfma_f32_16x16x32_bf16 v[44:47], v[158:161], v[138:141], v[44:47]
	v_mfma_f32_16x16x32_bf16 v[40:43], v[158:161], v[170:173], v[40:43]
	v_mfma_f32_16x16x32_bf16 v[36:39], v[158:161], v[174:177], v[36:39]
	v_mfma_f32_16x16x32_bf16 v[32:35], v[158:161], v[178:181], v[32:35]
	v_mfma_f32_16x16x32_bf16 v[28:31], v[162:165], v[138:141], v[28:31]
	v_mfma_f32_16x16x32_bf16 v[24:27], v[162:165], v[170:173], v[24:27]
	v_mfma_f32_16x16x32_bf16 v[20:23], v[162:165], v[174:177], v[20:23]
	v_mfma_f32_16x16x32_bf16 v[16:19], v[162:165], v[178:181], v[16:19]
	v_mfma_f32_16x16x32_bf16 v[12:15], v[166:169], v[138:141], v[12:15]
	v_mfma_f32_16x16x32_bf16 v[8:11], v[166:169], v[170:173], v[8:11]
	v_mfma_f32_16x16x32_bf16 v[4:7], v[166:169], v[174:177], v[4:7]
	v_mfma_f32_16x16x32_bf16 v[0:3], v[166:169], v[178:181], v[0:3]
	v_mfma_f32_16x16x32_bf16 v[124:127], v[130:133], v[138:141], v[124:127]
	v_mfma_f32_16x16x32_bf16 v[120:123], v[130:133], v[170:173], v[120:123]
	v_mfma_f32_16x16x32_bf16 v[116:119], v[130:133], v[174:177], v[116:119]
	v_mfma_f32_16x16x32_bf16 v[112:115], v[130:133], v[178:181], v[112:115]
	v_mfma_f32_16x16x32_bf16 v[108:111], v[142:145], v[138:141], v[108:111]
	v_mfma_f32_16x16x32_bf16 v[104:107], v[142:145], v[170:173], v[104:107]
	s_setprio 0
	s_waitcnt vmcnt(0) lgkmcnt(0)
	s_barrier
	ds_read_b128 v[130:133], v128 offset:24576
	ds_read_b128 v[138:141], v128 offset:25600
	ds_read_b128 v[142:145], v128 offset:26624
	ds_read_b128 v[146:149], v128 offset:27648
	ds_read_b128 v[150:153], v128 offset:28672
	ds_read_b128 v[154:157], v128 offset:29696
	ds_read_b128 v[158:161], v128 offset:30720
	ds_read_b128 v[162:165], v128 offset:31744
	ds_read_b128 v[166:169], v182 offset:40960
	ds_read_b128 v[170:173], v182 offset:41984
	ds_read_b128 v[174:177], v182 offset:43008
	ds_read_b128 v[178:181], v182 offset:44032
	s_setprio 1
	s_waitcnt lgkmcnt(0)
	v_mfma_f32_16x16x32_bf16 v[72:75], v[146:149], v[170:173], v[72:75]
	v_mfma_f32_16x16x32_bf16 v[68:71], v[146:149], v[174:177], v[68:71]
	v_mfma_f32_16x16x32_bf16 v[64:67], v[146:149], v[178:181], v[64:67]
	v_mfma_f32_16x16x32_bf16 v[60:63], v[150:153], v[166:169], v[60:63]
	v_mfma_f32_16x16x32_bf16 v[56:59], v[150:153], v[170:173], v[56:59]
	v_mfma_f32_16x16x32_bf16 v[52:55], v[150:153], v[174:177], v[52:55]
	v_mfma_f32_16x16x32_bf16 v[48:51], v[150:153], v[178:181], v[48:51]
	v_mfma_f32_16x16x32_bf16 v[44:47], v[154:157], v[166:169], v[44:47]
	v_mfma_f32_16x16x32_bf16 v[40:43], v[154:157], v[170:173], v[40:43]
	v_mfma_f32_16x16x32_bf16 v[36:39], v[154:157], v[174:177], v[36:39]
	v_mfma_f32_16x16x32_bf16 v[32:35], v[154:157], v[178:181], v[32:35]
	v_mfma_f32_16x16x32_bf16 v[28:31], v[158:161], v[166:169], v[28:31]
	v_mfma_f32_16x16x32_bf16 v[24:27], v[158:161], v[170:173], v[24:27]
	v_mfma_f32_16x16x32_bf16 v[20:23], v[158:161], v[174:177], v[20:23]
	v_mfma_f32_16x16x32_bf16 v[16:19], v[158:161], v[178:181], v[16:19]
	v_mfma_f32_16x16x32_bf16 v[12:15], v[162:165], v[166:169], v[12:15]
	v_mfma_f32_16x16x32_bf16 v[8:11], v[162:165], v[170:173], v[8:11]
	v_mfma_f32_16x16x32_bf16 v[4:7], v[162:165], v[174:177], v[4:7]
	v_mfma_f32_16x16x32_bf16 v[0:3], v[162:165], v[178:181], v[0:3]
	v_mfma_f32_16x16x32_bf16 v[124:127], v[130:133], v[166:169], v[124:127]
	v_mfma_f32_16x16x32_bf16 v[120:123], v[130:133], v[170:173], v[120:123]
	v_mfma_f32_16x16x32_bf16 v[116:119], v[130:133], v[174:177], v[116:119]
	v_mfma_f32_16x16x32_bf16 v[112:115], v[130:133], v[178:181], v[112:115]
	v_mfma_f32_16x16x32_bf16 v[108:111], v[138:141], v[166:169], v[108:111]
	v_mfma_f32_16x16x32_bf16 v[104:107], v[138:141], v[170:173], v[104:107]
	v_mfma_f32_16x16x32_bf16 v[130:133], v[138:141], v[174:177], v[100:103]
	v_mfma_f32_16x16x32_bf16 v[138:141], v[138:141], v[178:181], v[96:99]
	v_mfma_f32_16x16x32_bf16 v[182:185], v[142:145], v[166:169], v[92:95]
	v_mfma_f32_16x16x32_bf16 v[186:189], v[142:145], v[170:173], v[88:91]
	v_mfma_f32_16x16x32_bf16 v[192:195], v[142:145], v[174:177], v[84:87]
	v_mfma_f32_16x16x32_bf16 v[142:145], v[142:145], v[178:181], v[80:83]
	v_mfma_f32_16x16x32_bf16 v[196:199], v[146:149], v[166:169], v[76:79]
	s_setprio 0
	s_nop 1
	v_lshrrev_b32_e32 v77, 2, v136
	v_and_b32_e32 v76, 0xffffff80, v136
	v_and_b32_e32 v101, 12, v77
	v_lshlrev_b32_e32 v77, 6, v137
	s_add_i32 s24, s35, 0xfffff800
	v_add_u32_e32 v76, s44, v76
	v_or3_b32 v84, v77, s24, v135
	v_lshlrev_b32_e32 v128, 1, v101
	v_ashrrev_i32_e32 v100, 6, v76
	v_lshl_add_u64 v[76:77], s[40:41], 0, v[128:129]
	v_mov_b32_e32 v128, v84
	v_mad_i64_i32 v[92:93], s[24:25], v100, s30, v[128:129]
	v_lshlrev_b64 v[78:79], 7, v[92:93]
	v_lshl_add_u64 v[102:103], v[76:77], 0, v[78:79]
	v_and_b32_sdwa v79, v124, v134 dst_sel:DWORD dst_unused:UNUSED_PAD src0_sel:WORD_1 src1_sel:DWORD
	v_add3_u32 v80, v124, v79, s31
	v_and_b32_sdwa v79, v127, v134 dst_sel:DWORD dst_unused:UNUSED_PAD src0_sel:WORD_1 src1_sel:DWORD
	v_and_b32_sdwa v81, v125, v134 dst_sel:DWORD dst_unused:UNUSED_PAD src0_sel:WORD_1 src1_sel:DWORD
	v_and_b32_sdwa v78, v126, v134 dst_sel:DWORD dst_unused:UNUSED_PAD src0_sel:WORD_1 src1_sel:DWORD
	v_add3_u32 v79, v127, v79, s31
	v_add3_u32 v81, v125, v81, s31
	v_add3_u32 v78, v126, v78, s31
	v_and_b32_e32 v79, 0xffff0000, v79
	v_and_b32_e32 v81, 0xffff0000, v81
	v_or_b32_sdwa v79, v79, v78 dst_sel:DWORD dst_unused:UNUSED_PAD src0_sel:DWORD src1_sel:WORD_1
	v_or_b32_sdwa v78, v81, v80 dst_sel:DWORD dst_unused:UNUSED_PAD src0_sel:DWORD src1_sel:WORD_1
	global_store_dwordx2 v[102:103], v[78:79], off
	v_or_b32_e32 v78, 16, v84
	v_mov_b32_e32 v79, v129
	v_mad_i64_i32 v[88:89], s[24:25], v100, s30, v[78:79]
	v_lshlrev_b64 v[80:81], 7, v[88:89]
	v_lshl_add_u64 v[96:97], v[76:77], 0, v[80:81]
	v_and_b32_sdwa v81, v120, v134 dst_sel:DWORD dst_unused:UNUSED_PAD src0_sel:WORD_1 src1_sel:DWORD
	v_add3_u32 v82, v120, v81, s31
	v_and_b32_sdwa v81, v123, v134 dst_sel:DWORD dst_unused:UNUSED_PAD src0_sel:WORD_1 src1_sel:DWORD
	v_and_b32_sdwa v83, v121, v134 dst_sel:DWORD dst_unused:UNUSED_PAD src0_sel:WORD_1 src1_sel:DWORD
	v_and_b32_sdwa v80, v122, v134 dst_sel:DWORD dst_unused:UNUSED_PAD src0_sel:WORD_1 src1_sel:DWORD
	v_add3_u32 v81, v123, v81, s31
	v_add3_u32 v83, v121, v83, s31
	v_add3_u32 v80, v122, v80, s31
	v_and_b32_e32 v81, 0xffff0000, v81
	v_and_b32_e32 v83, 0xffff0000, v83
	v_or_b32_sdwa v81, v81, v80 dst_sel:DWORD dst_unused:UNUSED_PAD src0_sel:DWORD src1_sel:WORD_1
	v_or_b32_sdwa v80, v83, v82 dst_sel:DWORD dst_unused:UNUSED_PAD src0_sel:DWORD src1_sel:WORD_1
	global_store_dwordx2 v[96:97], v[80:81], off
	v_or_b32_e32 v80, 32, v84
	v_mov_b32_e32 v81, v129
	v_mad_i64_i32 v[86:87], s[24:25], v100, s30, v[80:81]
	v_lshlrev_b64 v[82:83], 7, v[86:87]
	v_lshl_add_u64 v[94:95], v[76:77], 0, v[82:83]
	v_and_b32_sdwa v83, v116, v134 dst_sel:DWORD dst_unused:UNUSED_PAD src0_sel:WORD_1 src1_sel:DWORD
	v_add3_u32 v85, v116, v83, s31
	v_and_b32_sdwa v83, v119, v134 dst_sel:DWORD dst_unused:UNUSED_PAD src0_sel:WORD_1 src1_sel:DWORD
	v_and_b32_sdwa v90, v117, v134 dst_sel:DWORD dst_unused:UNUSED_PAD src0_sel:WORD_1 src1_sel:DWORD
	v_and_b32_sdwa v82, v118, v134 dst_sel:DWORD dst_unused:UNUSED_PAD src0_sel:WORD_1 src1_sel:DWORD
	v_add3_u32 v83, v119, v83, s31
	v_add3_u32 v90, v117, v90, s31
	v_add3_u32 v82, v118, v82, s31
	v_and_b32_e32 v83, 0xffff0000, v83
	v_and_b32_e32 v90, 0xffff0000, v90
	v_or_b32_sdwa v83, v83, v82 dst_sel:DWORD dst_unused:UNUSED_PAD src0_sel:DWORD src1_sel:WORD_1
	v_or_b32_sdwa v82, v90, v85 dst_sel:DWORD dst_unused:UNUSED_PAD src0_sel:DWORD src1_sel:WORD_1
	v_and_b32_sdwa v98, v114, v134 dst_sel:DWORD dst_unused:UNUSED_PAD src0_sel:WORD_1 src1_sel:DWORD
	v_and_b32_sdwa v99, v112, v134 dst_sel:DWORD dst_unused:UNUSED_PAD src0_sel:WORD_1 src1_sel:DWORD
	global_store_dwordx2 v[94:95], v[82:83], off
	v_or_b32_e32 v82, 48, v84
	v_mov_b32_e32 v83, v129
	v_add3_u32 v112, v112, v99, s31
	v_add3_u32 v98, v114, v98, s31
	v_and_b32_sdwa v99, v115, v134 dst_sel:DWORD dst_unused:UNUSED_PAD src0_sel:WORD_1 src1_sel:DWORD
	v_and_b32_sdwa v114, v113, v134 dst_sel:DWORD dst_unused:UNUSED_PAD src0_sel:WORD_1 src1_sel:DWORD
	v_mad_i64_i32 v[84:85], s[24:25], v100, s30, v[82:83]
	v_add3_u32 v99, v115, v99, s31
	v_add3_u32 v113, v113, v114, s31
	v_lshlrev_b64 v[90:91], 7, v[84:85]
	v_and_b32_e32 v99, 0xffff0000, v99
	v_and_b32_e32 v113, 0xffff0000, v113
	v_lshl_add_u64 v[90:91], v[76:77], 0, v[90:91]
	v_or_b32_sdwa v99, v99, v98 dst_sel:DWORD dst_unused:UNUSED_PAD src0_sel:DWORD src1_sel:WORD_1
	v_or_b32_sdwa v98, v113, v112 dst_sel:DWORD dst_unused:UNUSED_PAD src0_sel:DWORD src1_sel:WORD_1
	global_store_dwordx2 v[90:91], v[98:99], off
	v_and_b32_sdwa v98, v110, v134 dst_sel:DWORD dst_unused:UNUSED_PAD src0_sel:WORD_1 src1_sel:DWORD
	v_and_b32_sdwa v99, v108, v134 dst_sel:DWORD dst_unused:UNUSED_PAD src0_sel:WORD_1 src1_sel:DWORD
	v_add3_u32 v108, v108, v99, s31
	v_add3_u32 v98, v110, v98, s31
	v_and_b32_sdwa v99, v111, v134 dst_sel:DWORD dst_unused:UNUSED_PAD src0_sel:WORD_1 src1_sel:DWORD
	v_and_b32_sdwa v110, v109, v134 dst_sel:DWORD dst_unused:UNUSED_PAD src0_sel:WORD_1 src1_sel:DWORD
	v_add3_u32 v99, v111, v99, s31
	v_add3_u32 v109, v109, v110, s31
	v_and_b32_e32 v99, 0xffff0000, v99
	v_and_b32_e32 v109, 0xffff0000, v109
	v_or_b32_sdwa v99, v99, v98 dst_sel:DWORD dst_unused:UNUSED_PAD src0_sel:DWORD src1_sel:WORD_1
	v_or_b32_sdwa v98, v109, v108 dst_sel:DWORD dst_unused:UNUSED_PAD src0_sel:DWORD src1_sel:WORD_1
	global_store_dwordx2 v[102:103], v[98:99], off offset:32
	v_and_b32_sdwa v98, v106, v134 dst_sel:DWORD dst_unused:UNUSED_PAD src0_sel:WORD_1 src1_sel:DWORD
	v_and_b32_sdwa v99, v104, v134 dst_sel:DWORD dst_unused:UNUSED_PAD src0_sel:WORD_1 src1_sel:DWORD
	v_add3_u32 v104, v104, v99, s31
	v_add3_u32 v98, v106, v98, s31
	v_and_b32_sdwa v99, v107, v134 dst_sel:DWORD dst_unused:UNUSED_PAD src0_sel:WORD_1 src1_sel:DWORD
	v_and_b32_sdwa v106, v105, v134 dst_sel:DWORD dst_unused:UNUSED_PAD src0_sel:WORD_1 src1_sel:DWORD
	v_add3_u32 v99, v107, v99, s31
	v_add3_u32 v105, v105, v106, s31
	v_and_b32_e32 v99, 0xffff0000, v99
	v_and_b32_e32 v105, 0xffff0000, v105
	v_or_b32_sdwa v99, v99, v98 dst_sel:DWORD dst_unused:UNUSED_PAD src0_sel:DWORD src1_sel:WORD_1
	v_or_b32_sdwa v98, v105, v104 dst_sel:DWORD dst_unused:UNUSED_PAD src0_sel:DWORD src1_sel:WORD_1
	global_store_dwordx2 v[96:97], v[98:99], off offset:32
	v_and_b32_sdwa v99, v130, v134 dst_sel:DWORD dst_unused:UNUSED_PAD src0_sel:WORD_1 src1_sel:DWORD
	v_add3_u32 v104, v130, v99, s31
	v_and_b32_sdwa v99, v133, v134 dst_sel:DWORD dst_unused:UNUSED_PAD src0_sel:WORD_1 src1_sel:DWORD
	v_and_b32_sdwa v105, v131, v134 dst_sel:DWORD dst_unused:UNUSED_PAD src0_sel:WORD_1 src1_sel:DWORD
	v_and_b32_sdwa v98, v132, v134 dst_sel:DWORD dst_unused:UNUSED_PAD src0_sel:WORD_1 src1_sel:DWORD
	v_add3_u32 v99, v133, v99, s31
	v_add3_u32 v105, v131, v105, s31
	v_add3_u32 v98, v132, v98, s31
	v_and_b32_e32 v99, 0xffff0000, v99
	v_and_b32_e32 v105, 0xffff0000, v105
	v_or_b32_sdwa v99, v99, v98 dst_sel:DWORD dst_unused:UNUSED_PAD src0_sel:DWORD src1_sel:WORD_1
	v_or_b32_sdwa v98, v105, v104 dst_sel:DWORD dst_unused:UNUSED_PAD src0_sel:DWORD src1_sel:WORD_1
	global_store_dwordx2 v[94:95], v[98:99], off offset:32
	v_and_b32_sdwa v99, v138, v134 dst_sel:DWORD dst_unused:UNUSED_PAD src0_sel:WORD_1 src1_sel:DWORD
	v_add3_u32 v104, v138, v99, s31
	v_and_b32_sdwa v99, v141, v134 dst_sel:DWORD dst_unused:UNUSED_PAD src0_sel:WORD_1 src1_sel:DWORD
	v_and_b32_sdwa v105, v139, v134 dst_sel:DWORD dst_unused:UNUSED_PAD src0_sel:WORD_1 src1_sel:DWORD
	v_and_b32_sdwa v98, v140, v134 dst_sel:DWORD dst_unused:UNUSED_PAD src0_sel:WORD_1 src1_sel:DWORD
	v_add3_u32 v99, v141, v99, s31
	v_add3_u32 v105, v139, v105, s31
	v_add3_u32 v98, v140, v98, s31
	v_and_b32_e32 v99, 0xffff0000, v99
	v_and_b32_e32 v105, 0xffff0000, v105
	v_or_b32_sdwa v99, v99, v98 dst_sel:DWORD dst_unused:UNUSED_PAD src0_sel:DWORD src1_sel:WORD_1
	v_or_b32_sdwa v98, v105, v104 dst_sel:DWORD dst_unused:UNUSED_PAD src0_sel:DWORD src1_sel:WORD_1
	global_store_dwordx2 v[90:91], v[98:99], off offset:32
	v_and_b32_sdwa v99, v182, v134 dst_sel:DWORD dst_unused:UNUSED_PAD src0_sel:WORD_1 src1_sel:DWORD
	v_add3_u32 v104, v182, v99, s31
	v_and_b32_sdwa v99, v185, v134 dst_sel:DWORD dst_unused:UNUSED_PAD src0_sel:WORD_1 src1_sel:DWORD
	v_and_b32_sdwa v105, v183, v134 dst_sel:DWORD dst_unused:UNUSED_PAD src0_sel:WORD_1 src1_sel:DWORD
	v_and_b32_sdwa v98, v184, v134 dst_sel:DWORD dst_unused:UNUSED_PAD src0_sel:WORD_1 src1_sel:DWORD
	v_add3_u32 v99, v185, v99, s31
	v_add3_u32 v105, v183, v105, s31
	v_add3_u32 v98, v184, v98, s31
	v_and_b32_e32 v99, 0xffff0000, v99
	v_and_b32_e32 v105, 0xffff0000, v105
	v_or_b32_sdwa v99, v99, v98 dst_sel:DWORD dst_unused:UNUSED_PAD src0_sel:DWORD src1_sel:WORD_1
	v_or_b32_sdwa v98, v105, v104 dst_sel:DWORD dst_unused:UNUSED_PAD src0_sel:DWORD src1_sel:WORD_1
	global_store_dwordx2 v[102:103], v[98:99], off offset:64
	v_and_b32_sdwa v99, v186, v134 dst_sel:DWORD dst_unused:UNUSED_PAD src0_sel:WORD_1 src1_sel:DWORD
	v_add3_u32 v104, v186, v99, s31
	v_and_b32_sdwa v99, v189, v134 dst_sel:DWORD dst_unused:UNUSED_PAD src0_sel:WORD_1 src1_sel:DWORD
	v_and_b32_sdwa v105, v187, v134 dst_sel:DWORD dst_unused:UNUSED_PAD src0_sel:WORD_1 src1_sel:DWORD
	v_and_b32_sdwa v98, v188, v134 dst_sel:DWORD dst_unused:UNUSED_PAD src0_sel:WORD_1 src1_sel:DWORD
	v_add3_u32 v99, v189, v99, s31
	v_add3_u32 v105, v187, v105, s31
	v_add3_u32 v98, v188, v98, s31
	v_and_b32_e32 v99, 0xffff0000, v99
	v_and_b32_e32 v105, 0xffff0000, v105
	v_or_b32_sdwa v99, v99, v98 dst_sel:DWORD dst_unused:UNUSED_PAD src0_sel:DWORD src1_sel:WORD_1
	v_or_b32_sdwa v98, v105, v104 dst_sel:DWORD dst_unused:UNUSED_PAD src0_sel:DWORD src1_sel:WORD_1
	global_store_dwordx2 v[96:97], v[98:99], off offset:64
	v_and_b32_sdwa v99, v192, v134 dst_sel:DWORD dst_unused:UNUSED_PAD src0_sel:WORD_1 src1_sel:DWORD
	v_add3_u32 v104, v192, v99, s31
	v_and_b32_sdwa v99, v195, v134 dst_sel:DWORD dst_unused:UNUSED_PAD src0_sel:WORD_1 src1_sel:DWORD
	v_and_b32_sdwa v105, v193, v134 dst_sel:DWORD dst_unused:UNUSED_PAD src0_sel:WORD_1 src1_sel:DWORD
	v_and_b32_sdwa v98, v194, v134 dst_sel:DWORD dst_unused:UNUSED_PAD src0_sel:WORD_1 src1_sel:DWORD
	v_add3_u32 v99, v195, v99, s31
	v_add3_u32 v105, v193, v105, s31
	v_add3_u32 v98, v194, v98, s31
	v_and_b32_e32 v99, 0xffff0000, v99
	v_and_b32_e32 v105, 0xffff0000, v105
	v_or_b32_sdwa v99, v99, v98 dst_sel:DWORD dst_unused:UNUSED_PAD src0_sel:DWORD src1_sel:WORD_1
	v_or_b32_sdwa v98, v105, v104 dst_sel:DWORD dst_unused:UNUSED_PAD src0_sel:DWORD src1_sel:WORD_1
	global_store_dwordx2 v[94:95], v[98:99], off offset:64
	v_and_b32_sdwa v99, v142, v134 dst_sel:DWORD dst_unused:UNUSED_PAD src0_sel:WORD_1 src1_sel:DWORD
	v_add3_u32 v104, v142, v99, s31
	v_and_b32_sdwa v99, v145, v134 dst_sel:DWORD dst_unused:UNUSED_PAD src0_sel:WORD_1 src1_sel:DWORD
	v_and_b32_sdwa v105, v143, v134 dst_sel:DWORD dst_unused:UNUSED_PAD src0_sel:WORD_1 src1_sel:DWORD
	v_and_b32_sdwa v98, v144, v134 dst_sel:DWORD dst_unused:UNUSED_PAD src0_sel:WORD_1 src1_sel:DWORD
	v_add3_u32 v99, v145, v99, s31
	v_add3_u32 v105, v143, v105, s31
	v_add3_u32 v98, v144, v98, s31
	v_and_b32_e32 v99, 0xffff0000, v99
	v_and_b32_e32 v105, 0xffff0000, v105
	v_or_b32_sdwa v99, v99, v98 dst_sel:DWORD dst_unused:UNUSED_PAD src0_sel:DWORD src1_sel:WORD_1
	v_or_b32_sdwa v98, v105, v104 dst_sel:DWORD dst_unused:UNUSED_PAD src0_sel:DWORD src1_sel:WORD_1
	global_store_dwordx2 v[90:91], v[98:99], off offset:64
	v_and_b32_sdwa v99, v196, v134 dst_sel:DWORD dst_unused:UNUSED_PAD src0_sel:WORD_1 src1_sel:DWORD
	v_cmp_eq_u32_e32 vcc, 12, v101
	v_add3_u32 v101, v196, v99, s31
	v_and_b32_sdwa v99, v199, v134 dst_sel:DWORD dst_unused:UNUSED_PAD src0_sel:WORD_1 src1_sel:DWORD
	v_and_b32_sdwa v104, v197, v134 dst_sel:DWORD dst_unused:UNUSED_PAD src0_sel:WORD_1 src1_sel:DWORD
	v_and_b32_sdwa v98, v198, v134 dst_sel:DWORD dst_unused:UNUSED_PAD src0_sel:WORD_1 src1_sel:DWORD
	v_add3_u32 v99, v199, v99, s31
	v_add3_u32 v104, v197, v104, s31
	v_add3_u32 v98, v198, v98, s31
	v_and_b32_e32 v99, 0xffff0000, v99
	v_and_b32_e32 v104, 0xffff0000, v104
	v_or_b32_sdwa v99, v99, v98 dst_sel:DWORD dst_unused:UNUSED_PAD src0_sel:DWORD src1_sel:WORD_1
	v_or_b32_sdwa v98, v104, v101 dst_sel:DWORD dst_unused:UNUSED_PAD src0_sel:DWORD src1_sel:WORD_1
	global_store_dwordx2 v[102:103], v[98:99], off offset:96
	s_and_saveexec_b64 s[24:25], vcc
	s_cbranch_execz .LBB0_1325
	v_lshl_add_u64 v[92:93], v[92:93], 3, s[42:43]
	global_store_dwordx2 v[92:93], v[98:99], off

.LBB0_1340:
	s_and_b64 vcc, exec, s[24:25]
	s_cbranch_vccz .LBB0_1319
	s_mov_b64 s[62:63], 0x80
	v_mov_b32_e32 v135, v190
	s_lshl_b32 s39, s39, 8
	v_lshlrev_b32_e32 v0, 6, v135
	v_and_b32_e32 v142, 0xffffe3c0, v0
	v_lshlrev_b32_e32 v0, 1, v135
	v_and_b32_e32 v7, 3, v135
	v_ashrrev_i32_e32 v6, 2, v135
	v_and_b32_e32 v6, -2, v6
	v_and_or_b32 v0, v0, 24, v7
	v_lshlrev_b32_e32 v140, 6, v0
	v_add_u32_e32 v0, s39, v6
	v_ashrrev_i32_e32 v1, 31, v0
	v_lshlrev_b32_e32 v141, 4, v135
	v_lshlrev_b64 v[0:1], 11, v[0:1]
	v_lshl_add_u64 v[0:1], s[88:89], 0, v[0:1]
	v_and_b32_e32 v128, 0x70, v141
	v_readfirstlane_b32 s24, v141
	v_add_u32_e32 v8, 0x1000, v141
	v_lshl_add_u64 v[0:1], v[0:1], 0, v[128:129]
	s_waitcnt vmcnt(0)
	s_mov_b32 m0, s24
	v_readfirstlane_b32 s24, v8
	v_add_u32_e32 v8, 0x2000, v141
	global_load_lds_dwordx4 v[0:1], off
	v_lshl_add_u64 v[4:5], v[0:1], 0, s[0:1]
	s_mov_b32 m0, s24
	v_readfirstlane_b32 s24, v8
	v_add_u32_e32 v8, 0x3000, v141
	v_add_u32_e32 v2, s35, v6
	global_load_lds_dwordx4 v[4:5], off
	v_lshl_add_u64 v[4:5], v[0:1], 0, s[2:3]
	s_mov_b32 m0, s24
	v_readfirstlane_b32 s24, v8
	v_ashrrev_i32_e32 v3, 31, v2
	global_load_lds_dwordx4 v[4:5], off
	v_lshl_add_u64 v[4:5], v[0:1], 0, s[4:5]
	s_mov_b32 m0, s24
	v_lshlrev_b64 v[2:3], 11, v[2:3]
	global_load_lds_dwordx4 v[4:5], off
	v_add_u32_e32 v4, 0x4000, v141
	v_lshl_add_u64 v[2:3], s[52:53], 0, v[2:3]
	v_readfirstlane_b32 s24, v4
	v_add_u32_e32 v8, 0x5000, v141
	v_lshl_add_u64 v[2:3], v[2:3], 0, v[128:129]
	s_mov_b32 m0, s24
	v_readfirstlane_b32 s24, v8
	v_add_u32_e32 v8, 0x6000, v141
	global_load_lds_dwordx4 v[2:3], off
	v_lshl_add_u64 v[4:5], v[2:3], 0, s[0:1]
	s_mov_b32 m0, s24
	v_readfirstlane_b32 s24, v8
	v_add_u32_e32 v8, 0x7000, v141
	global_load_lds_dwordx4 v[4:5], off
	v_lshl_add_u64 v[4:5], v[0:1], 0, s[62:63]
	s_mov_b32 m0, s24
	v_readfirstlane_b32 s24, v8
	v_add_u32_e32 v8, 0x8000, v141
	global_load_lds_dwordx4 v[4:5], off
	v_lshl_add_u64 v[4:5], v[0:1], 0, s[6:7]
	s_mov_b32 m0, s24
	v_readfirstlane_b32 s24, v8
	global_load_lds_dwordx4 v[4:5], off
	v_lshl_add_u64 v[4:5], v[0:1], 0, s[8:9]
	s_mov_b32 m0, s24
	v_lshl_add_u64 v[0:1], v[0:1], 0, s[10:11]
	global_load_lds_dwordx4 v[4:5], off
	v_add_u32_e32 v4, 0x9000, v141
	s_add_i32 s37, s37, s36
	v_readfirstlane_b32 s24, v4
	v_add_u32_e32 v4, 0xa000, v141
	s_mov_b32 m0, s24
	v_readfirstlane_b32 s24, v4
	global_load_lds_dwordx4 v[0:1], off
	v_lshl_add_u64 v[0:1], v[2:3], 0, s[62:63]
	s_mov_b32 m0, s24
	v_bfe_u32 v137, v135, 6, 1
	global_load_lds_dwordx4 v[0:1], off
	v_lshl_add_u64 v[0:1], v[2:3], 0, s[6:7]
	v_add_u32_e32 v2, 0xb000, v141
	v_and_b32_e32 v136, 15, v135
	v_readfirstlane_b32 s24, v2
	s_mov_b32 m0, s24
	v_and_b32_e32 v2, 7, v135
	v_lshlrev_b32_e32 v2, 4, v2
	global_load_lds_dwordx4 v[0:1], off
	v_add_u32_e32 v0, s38, v6
	v_ashrrev_i32_e32 v1, 31, v0
	v_lshlrev_b64 v[0:1], 11, v[0:1]
	v_or_b32_e32 v0, v0, v2
	v_lshl_add_u64 v[130:131], s[52:53], 0, v[0:1]
	v_add_u32_e32 v0, s37, v6
	v_ashrrev_i32_e32 v1, 31, v0
	v_lshlrev_b64 v[0:1], 11, v[0:1]
	v_or_b32_e32 v0, v0, v2
	v_lshl_add_u64 v[132:133], s[52:53], 0, v[0:1]
	v_mov_b32_e32 v0, 0
	v_and_b32_e32 v138, 48, v135
	v_lshlrev_b32_e32 v139, 12, v137
	s_mov_b32 s36, 0
	s_mov_b64 s[24:25], 0
	v_mov_b32_e32 v1, v0
	v_mov_b32_e32 v2, v0
	v_mov_b32_e32 v3, v0
	v_mov_b32_e32 v4, v0
	v_mov_b32_e32 v5, v0
	v_mov_b32_e32 v6, v0
	v_mov_b32_e32 v7, v0
	v_mov_b32_e32 v8, v0
	v_mov_b32_e32 v9, v0
	v_mov_b32_e32 v10, v0
	v_mov_b32_e32 v11, v0
	v_mov_b32_e32 v12, v0
	v_mov_b32_e32 v13, v0
	v_mov_b32_e32 v14, v0
	v_mov_b32_e32 v15, v0
	v_mov_b32_e32 v16, v0
	v_mov_b32_e32 v17, v0
	v_mov_b32_e32 v18, v0
	v_mov_b32_e32 v19, v0
	v_mov_b32_e32 v20, v0
	v_mov_b32_e32 v21, v0
	v_mov_b32_e32 v22, v0
	v_mov_b32_e32 v23, v0
	v_mov_b32_e32 v24, v0
	v_mov_b32_e32 v25, v0
	v_mov_b32_e32 v26, v0
	v_mov_b32_e32 v27, v0
	v_mov_b32_e32 v28, v0
	v_mov_b32_e32 v29, v0
	v_mov_b32_e32 v30, v0
	v_mov_b32_e32 v31, v0
	v_mov_b32_e32 v32, v0
	v_mov_b32_e32 v33, v0
	v_mov_b32_e32 v34, v0
	v_mov_b32_e32 v35, v0
	v_mov_b32_e32 v36, v0
	v_mov_b32_e32 v37, v0
	v_mov_b32_e32 v38, v0
	v_mov_b32_e32 v39, v0
	v_mov_b32_e32 v40, v0
	v_mov_b32_e32 v41, v0
	v_mov_b32_e32 v42, v0
	v_mov_b32_e32 v43, v0
	v_mov_b32_e32 v44, v0
	v_mov_b32_e32 v45, v0
	v_mov_b32_e32 v46, v0
	v_mov_b32_e32 v47, v0
	v_mov_b32_e32 v48, v0
	v_mov_b32_e32 v49, v0
	v_mov_b32_e32 v50, v0
	v_mov_b32_e32 v51, v0
	v_mov_b32_e32 v52, v0
	v_mov_b32_e32 v53, v0
	v_mov_b32_e32 v54, v0
	v_mov_b32_e32 v55, v0
	v_mov_b32_e32 v56, v0
	v_mov_b32_e32 v57, v0
	v_mov_b32_e32 v58, v0
	v_mov_b32_e32 v59, v0
	v_mov_b32_e32 v60, v0
	v_mov_b32_e32 v61, v0
	v_mov_b32_e32 v62, v0
	v_mov_b32_e32 v63, v0
	v_mov_b32_e32 v64, v0
	v_mov_b32_e32 v65, v0
	v_mov_b32_e32 v66, v0
	v_mov_b32_e32 v67, v0
	v_mov_b32_e32 v68, v0
	v_mov_b32_e32 v69, v0
	v_mov_b32_e32 v70, v0
	v_mov_b32_e32 v71, v0
	v_mov_b32_e32 v72, v0
	v_mov_b32_e32 v73, v0
	v_mov_b32_e32 v74, v0
	v_mov_b32_e32 v75, v0
	v_mov_b32_e32 v76, v0
	v_mov_b32_e32 v77, v0
	v_mov_b32_e32 v78, v0
	v_mov_b32_e32 v79, v0
	v_mov_b32_e32 v80, v0
	v_mov_b32_e32 v81, v0
	v_mov_b32_e32 v82, v0
	v_mov_b32_e32 v83, v0
	v_mov_b32_e32 v84, v0
	v_mov_b32_e32 v85, v0
	v_mov_b32_e32 v86, v0
	v_mov_b32_e32 v87, v0
	v_mov_b32_e32 v88, v0
	v_mov_b32_e32 v89, v0
	v_mov_b32_e32 v90, v0
	v_mov_b32_e32 v91, v0
	v_mov_b32_e32 v92, v0
	v_mov_b32_e32 v93, v0
	v_mov_b32_e32 v94, v0
	v_mov_b32_e32 v95, v0
	v_mov_b32_e32 v96, v0
	v_mov_b32_e32 v97, v0
	v_mov_b32_e32 v98, v0
	v_mov_b32_e32 v99, v0
	v_mov_b32_e32 v100, v0
	v_mov_b32_e32 v101, v0
	v_mov_b32_e32 v102, v0
	v_mov_b32_e32 v103, v0
	v_mov_b32_e32 v104, v0
	v_mov_b32_e32 v105, v0
	v_mov_b32_e32 v106, v0
	v_mov_b32_e32 v107, v0
	v_mov_b32_e32 v108, v0
	v_mov_b32_e32 v109, v0
	v_mov_b32_e32 v110, v0
	v_mov_b32_e32 v111, v0
	v_mov_b32_e32 v112, v0
	v_mov_b32_e32 v113, v0
	v_mov_b32_e32 v114, v0
	v_mov_b32_e32 v115, v0
	v_mov_b32_e32 v116, v0
	v_mov_b32_e32 v117, v0
	v_mov_b32_e32 v118, v0
	v_mov_b32_e32 v119, v0
	v_mov_b32_e32 v120, v0
	v_mov_b32_e32 v121, v0
	v_mov_b32_e32 v122, v0
	v_mov_b32_e32 v123, v0
	v_mov_b32_e32 v124, v0
	v_mov_b32_e32 v125, v0
	v_mov_b32_e32 v126, v0
	v_mov_b32_e32 v127, v0
.LBB0_1342:
	s_add_i32 s37, s36, 2
	s_mul_hi_i32 s38, s37, 0x55555556
	s_lshr_b32 s44, s38, 31
	s_add_i32 s38, s38, s44
	s_mul_i32 s38, s38, 3
	s_sub_i32 s37, s37, s38
	s_mulk_i32 s37, 0x6000
	s_mul_i32 s54, s36, 0x6000
	v_readfirstlane_b32 s55, v141
	v_lshl_add_u64 v[232:233], v[132:133], 0, s[24:25]
	v_lshl_add_u64 v[234:235], v[130:131], 0, s[24:25]
	s_add_u32 s55, s55, s37
	s_waitcnt vmcnt(6) lgkmcnt(0)
	s_barrier
	v_or_b32_e32 v128, s54, v139
	v_add3_u32 v128, v128, v140, v138
	ds_read_b128 v[176:179], v128 offset:16384
	ds_read_b128 v[180:183], v128 offset:16640
	ds_read_b128 v[184:187], v128 offset:18432
	ds_read_b128 v[192:195], v128 offset:18688
	v_add3_u32 v128, s54, v142, v138
	ds_read_b128 v[144:147], v128
	ds_read_b128 v[148:151], v128 offset:1024
	ds_read_b128 v[152:155], v128 offset:2048
	ds_read_b128 v[156:159], v128 offset:3072
	ds_read_b128 v[160:163], v128 offset:4096
	ds_read_b128 v[164:167], v128 offset:5120
	ds_read_b128 v[168:171], v128 offset:6144
	ds_read_b128 v[172:175], v128 offset:7168
	s_setprio 1
	s_waitcnt lgkmcnt(7)
	v_mfma_f32_16x16x32_bf16 v[124:127], v[176:179], v[144:147], v[124:127]
	v_mfma_f32_16x16x32_bf16 v[120:123], v[180:183], v[144:147], v[120:123]
	v_mfma_f32_16x16x32_bf16 v[116:119], v[184:187], v[144:147], v[116:119]
	v_mfma_f32_16x16x32_bf16 v[112:115], v[192:195], v[144:147], v[112:115]
	s_mov_b32 m0, s55
	v_lshl_add_u64 v[236:237], v[232:233], 0, s[12:13]
	global_load_lds_dwordx4 v[236:237], off
	s_waitcnt lgkmcnt(6)
	v_mfma_f32_16x16x32_bf16 v[108:111], v[176:179], v[148:151], v[108:111]
	v_mfma_f32_16x16x32_bf16 v[104:107], v[180:183], v[148:151], v[104:107]
	v_mfma_f32_16x16x32_bf16 v[100:103], v[184:187], v[148:151], v[100:103]
	v_mfma_f32_16x16x32_bf16 v[96:99], v[192:195], v[148:151], v[96:99]
	s_add_u32 m0, s55, 0x1000
	v_lshl_add_u64 v[236:237], v[232:233], 0, s[14:15]
	global_load_lds_dwordx4 v[236:237], off
	s_waitcnt lgkmcnt(5)
	v_mfma_f32_16x16x32_bf16 v[92:95], v[176:179], v[152:155], v[92:95]
	v_mfma_f32_16x16x32_bf16 v[88:91], v[180:183], v[152:155], v[88:91]
	v_mfma_f32_16x16x32_bf16 v[84:87], v[184:187], v[152:155], v[84:87]
	v_mfma_f32_16x16x32_bf16 v[80:83], v[192:195], v[152:155], v[80:83]
	s_add_u32 m0, s55, 0x2000
	v_lshl_add_u64 v[236:237], v[232:233], 0, s[16:17]
	global_load_lds_dwordx4 v[236:237], off
	s_waitcnt lgkmcnt(4)
	v_mfma_f32_16x16x32_bf16 v[76:79], v[176:179], v[156:159], v[76:79]
	v_mfma_f32_16x16x32_bf16 v[72:75], v[180:183], v[156:159], v[72:75]
	v_mfma_f32_16x16x32_bf16 v[68:71], v[184:187], v[156:159], v[68:71]
	v_mfma_f32_16x16x32_bf16 v[64:67], v[192:195], v[156:159], v[64:67]
	s_add_u32 m0, s55, 0x3000
	v_lshl_add_u64 v[236:237], v[232:233], 0, s[18:19]
	global_load_lds_dwordx4 v[236:237], off
	s_waitcnt lgkmcnt(3)
	v_mfma_f32_16x16x32_bf16 v[60:63], v[176:179], v[160:163], v[60:63]
	v_mfma_f32_16x16x32_bf16 v[56:59], v[180:183], v[160:163], v[56:59]
	v_mfma_f32_16x16x32_bf16 v[52:55], v[184:187], v[160:163], v[52:55]
	v_mfma_f32_16x16x32_bf16 v[48:51], v[192:195], v[160:163], v[48:51]
	s_add_u32 m0, s55, 0x4000
	v_lshl_add_u64 v[236:237], v[234:235], 0, s[20:21]
	global_load_lds_dwordx4 v[236:237], off
	s_waitcnt lgkmcnt(2)
	v_mfma_f32_16x16x32_bf16 v[44:47], v[176:179], v[164:167], v[44:47]
	v_mfma_f32_16x16x32_bf16 v[40:43], v[180:183], v[164:167], v[40:43]
	v_mfma_f32_16x16x32_bf16 v[36:39], v[184:187], v[164:167], v[36:39]
	v_mfma_f32_16x16x32_bf16 v[32:35], v[192:195], v[164:167], v[32:35]
	s_add_u32 m0, s55, 0x5000
	v_lshl_add_u64 v[236:237], v[234:235], 0, s[22:23]
	global_load_lds_dwordx4 v[236:237], off
	s_waitcnt lgkmcnt(1)
	v_mfma_f32_16x16x32_bf16 v[28:31], v[176:179], v[168:171], v[28:31]
	v_mfma_f32_16x16x32_bf16 v[24:27], v[180:183], v[168:171], v[24:27]
	v_mfma_f32_16x16x32_bf16 v[20:23], v[184:187], v[168:171], v[20:23]
	v_mfma_f32_16x16x32_bf16 v[16:19], v[192:195], v[168:171], v[16:19]
	s_waitcnt lgkmcnt(0)
	v_mfma_f32_16x16x32_bf16 v[12:15], v[176:179], v[172:175], v[12:15]
	v_mfma_f32_16x16x32_bf16 v[8:11], v[180:183], v[172:175], v[8:11]
	v_mfma_f32_16x16x32_bf16 v[4:7], v[184:187], v[172:175], v[4:7]
	v_mfma_f32_16x16x32_bf16 v[0:3], v[192:195], v[172:175], v[0:3]
	s_setprio 0
	s_add_i32 s37, s36, 1
	s_cmp_lg_u32 s36, 2
	s_cselect_b32 s36, s37, 0
	s_add_u32 s24, s24, 0x80
	s_addc_u32 s25, s25, 0
	s_cmpk_lg_i32 s24, 0xf00
	s_cbranch_scc1 .LBB0_1342
	s_waitcnt vmcnt(6) lgkmcnt(0)
	s_barrier
	v_add_u32_e32 v128, v142, v138
	ds_read_b128 v[130:133], v128
	ds_read_b128 v[142:145], v128 offset:1024
	ds_read_b128 v[146:149], v128 offset:2048
	ds_read_b128 v[150:153], v128 offset:3072
	ds_read_b128 v[154:157], v128 offset:4096
	ds_read_b128 v[158:161], v128 offset:5120
	ds_read_b128 v[162:165], v128 offset:6144
	ds_read_b128 v[166:169], v128 offset:7168
	v_add3_u32 v182, v139, v140, v138
	ds_read_b128 v[138:141], v182 offset:16384
	ds_read_b128 v[170:173], v182 offset:16640
	ds_read_b128 v[174:177], v182 offset:18432
	ds_read_b128 v[178:181], v182 offset:18688
	s_setprio 1
	s_waitcnt lgkmcnt(0)
	v_mfma_f32_16x16x32_bf16 v[124:127], v[138:141], v[130:133], v[124:127]
	v_mfma_f32_16x16x32_bf16 v[120:123], v[170:173], v[130:133], v[120:123]
	v_mfma_f32_16x16x32_bf16 v[116:119], v[174:177], v[130:133], v[116:119]
	v_mfma_f32_16x16x32_bf16 v[112:115], v[178:181], v[130:133], v[112:115]
	v_mfma_f32_16x16x32_bf16 v[108:111], v[138:141], v[142:145], v[108:111]
	v_mfma_f32_16x16x32_bf16 v[104:107], v[170:173], v[142:145], v[104:107]
	v_mfma_f32_16x16x32_bf16 v[100:103], v[174:177], v[142:145], v[100:103]
	v_mfma_f32_16x16x32_bf16 v[96:99], v[178:181], v[142:145], v[96:99]
	v_mfma_f32_16x16x32_bf16 v[92:95], v[138:141], v[146:149], v[92:95]
	v_mfma_f32_16x16x32_bf16 v[88:91], v[170:173], v[146:149], v[88:91]
	v_mfma_f32_16x16x32_bf16 v[84:87], v[174:177], v[146:149], v[84:87]
	v_mfma_f32_16x16x32_bf16 v[80:83], v[178:181], v[146:149], v[80:83]
	v_mfma_f32_16x16x32_bf16 v[76:79], v[138:141], v[150:153], v[76:79]
	v_mfma_f32_16x16x32_bf16 v[72:75], v[170:173], v[150:153], v[72:75]
	v_mfma_f32_16x16x32_bf16 v[68:71], v[174:177], v[150:153], v[68:71]
	v_mfma_f32_16x16x32_bf16 v[64:67], v[178:181], v[150:153], v[64:67]
	v_mfma_f32_16x16x32_bf16 v[60:63], v[138:141], v[154:157], v[60:63]
	v_mfma_f32_16x16x32_bf16 v[56:59], v[170:173], v[154:157], v[56:59]
	v_mfma_f32_16x16x32_bf16 v[52:55], v[174:177], v[154:157], v[52:55]
	v_mfma_f32_16x16x32_bf16 v[48:51], v[178:181], v[154:157], v[48:51]
	v_mfma_f32_16x16x32_bf16 v[44:47], v[138:141], v[158:161], v[44:47]
	v_mfma_f32_16x16x32_bf16 v[40:43], v[170:173], v[158:161], v[40:43]
	v_mfma_f32_16x16x32_bf16 v[36:39], v[174:177], v[158:161], v[36:39]
	v_mfma_f32_16x16x32_bf16 v[32:35], v[178:181], v[158:161], v[32:35]
	v_mfma_f32_16x16x32_bf16 v[28:31], v[138:141], v[162:165], v[28:31]
	v_mfma_f32_16x16x32_bf16 v[24:27], v[170:173], v[162:165], v[24:27]
	v_mfma_f32_16x16x32_bf16 v[20:23], v[174:177], v[162:165], v[20:23]
	v_mfma_f32_16x16x32_bf16 v[16:19], v[178:181], v[162:165], v[16:19]
	v_mfma_f32_16x16x32_bf16 v[12:15], v[138:141], v[166:169], v[12:15]
	v_mfma_f32_16x16x32_bf16 v[8:11], v[170:173], v[166:169], v[8:11]
	v_mfma_f32_16x16x32_bf16 v[4:7], v[174:177], v[166:169], v[4:7]
	v_mfma_f32_16x16x32_bf16 v[0:3], v[178:181], v[166:169], v[0:3]
	s_setprio 0
	s_waitcnt vmcnt(0) lgkmcnt(0)
	s_barrier
	ds_read_b128 v[130:133], v128 offset:24576
	ds_read_b128 v[138:141], v128 offset:25600
	ds_read_b128 v[142:145], v128 offset:26624
	ds_read_b128 v[146:149], v128 offset:27648
	ds_read_b128 v[150:153], v128 offset:28672
	ds_read_b128 v[154:157], v128 offset:29696
	ds_read_b128 v[158:161], v128 offset:30720
	ds_read_b128 v[162:165], v128 offset:31744
	ds_read_b128 v[166:169], v182 offset:40960
	ds_read_b128 v[170:173], v182 offset:41216
	ds_read_b128 v[174:177], v182 offset:43008
	ds_read_b128 v[178:181], v182 offset:43264
	s_setprio 1
	s_waitcnt lgkmcnt(0)
	v_mfma_f32_16x16x32_bf16 v[124:127], v[166:169], v[130:133], v[124:127]
	v_mfma_f32_16x16x32_bf16 v[120:123], v[170:173], v[130:133], v[120:123]
	v_mfma_f32_16x16x32_bf16 v[116:119], v[174:177], v[130:133], v[116:119]
	v_mfma_f32_16x16x32_bf16 v[112:115], v[178:181], v[130:133], v[112:115]
	v_mfma_f32_16x16x32_bf16 v[108:111], v[166:169], v[138:141], v[108:111]
	v_mfma_f32_16x16x32_bf16 v[104:107], v[170:173], v[138:141], v[104:107]
	v_mfma_f32_16x16x32_bf16 v[100:103], v[174:177], v[138:141], v[100:103]
	v_mfma_f32_16x16x32_bf16 v[96:99], v[178:181], v[138:141], v[96:99]
	v_mfma_f32_16x16x32_bf16 v[92:95], v[166:169], v[142:145], v[92:95]
	v_mfma_f32_16x16x32_bf16 v[88:91], v[170:173], v[142:145], v[88:91]
	v_mfma_f32_16x16x32_bf16 v[84:87], v[174:177], v[142:145], v[84:87]
	v_mfma_f32_16x16x32_bf16 v[80:83], v[178:181], v[142:145], v[80:83]
	v_mfma_f32_16x16x32_bf16 v[130:133], v[166:169], v[146:149], v[76:79]
	v_mfma_f32_16x16x32_bf16 v[72:75], v[170:173], v[146:149], v[72:75]
	v_mfma_f32_16x16x32_bf16 v[68:71], v[174:177], v[146:149], v[68:71]
	v_mfma_f32_16x16x32_bf16 v[64:67], v[178:181], v[146:149], v[64:67]
	v_mfma_f32_16x16x32_bf16 v[60:63], v[166:169], v[150:153], v[60:63]
	v_mfma_f32_16x16x32_bf16 v[56:59], v[170:173], v[150:153], v[56:59]
	v_mfma_f32_16x16x32_bf16 v[52:55], v[174:177], v[150:153], v[52:55]
	v_mfma_f32_16x16x32_bf16 v[48:51], v[178:181], v[150:153], v[48:51]
	v_mfma_f32_16x16x32_bf16 v[44:47], v[166:169], v[154:157], v[44:47]
	v_mfma_f32_16x16x32_bf16 v[40:43], v[170:173], v[154:157], v[40:43]
	v_mfma_f32_16x16x32_bf16 v[36:39], v[174:177], v[154:157], v[36:39]
	v_mfma_f32_16x16x32_bf16 v[32:35], v[178:181], v[154:157], v[32:35]
	v_mfma_f32_16x16x32_bf16 v[28:31], v[166:169], v[158:161], v[28:31]
	v_mfma_f32_16x16x32_bf16 v[24:27], v[170:173], v[158:161], v[24:27]
	v_mfma_f32_16x16x32_bf16 v[20:23], v[174:177], v[158:161], v[20:23]
	v_mfma_f32_16x16x32_bf16 v[16:19], v[178:181], v[158:161], v[16:19]
	v_mfma_f32_16x16x32_bf16 v[12:15], v[166:169], v[162:165], v[12:15]
	v_mfma_f32_16x16x32_bf16 v[8:11], v[170:173], v[162:165], v[8:11]
	v_mfma_f32_16x16x32_bf16 v[4:7], v[174:177], v[162:165], v[4:7]
	v_mfma_f32_16x16x32_bf16 v[0:3], v[178:181], v[162:165], v[0:3]
	s_setprio 0
	v_and_b32_e32 v76, 0xffffff80, v135
	v_add_u32_e32 v76, s39, v76
	v_lshrrev_b32_e32 v78, 1, v135
	v_or_b32_e32 v76, v76, v136
	v_lshlrev_b32_e32 v77, 6, v137
	v_and_b32_e32 v78, 24, v78
	v_or3_b32 v78, v77, v78, s35
	v_ashrrev_i32_e32 v77, 31, v76
	v_lshlrev_b64 v[136:137], 12, v[76:77]
	v_bfe_u32 v77, v124, 16, 1
	v_add3_u32 v77, v124, v77, s31
	v_bfe_u32 v79, v125, 16, 1
	v_lshrrev_b32_e32 v77, 16, v77
	v_add3_u32 v79, v125, v79, s31
	v_and_or_b32 v124, v79, s33, v77
	v_bfe_u32 v77, v126, 16, 1
	v_add3_u32 v77, v126, v77, s31
	v_bfe_u32 v79, v127, 16, 1
	v_lshrrev_b32_e32 v77, 16, v77
	v_add3_u32 v79, v127, v79, s31
	v_and_or_b32 v125, v79, s33, v77
	v_bfe_u32 v77, v120, 16, 1
	v_add3_u32 v77, v120, v77, s31
	v_bfe_u32 v79, v121, 16, 1
	v_lshrrev_b32_e32 v77, 16, v77
	v_add3_u32 v79, v121, v79, s31
	v_and_or_b32 v126, v79, s33, v77
	v_bfe_u32 v77, v122, 16, 1
	v_add3_u32 v77, v122, v77, s31
	v_bfe_u32 v79, v123, 16, 1
	v_lshrrev_b32_e32 v77, 16, v77
	v_add3_u32 v79, v123, v79, s31
	v_and_or_b32 v127, v79, s33, v77
	v_bfe_u32 v77, v116, 16, 1
	v_add3_u32 v77, v116, v77, s31
	v_bfe_u32 v116, v117, 16, 1
	v_lshrrev_b32_e32 v77, 16, v77
	v_add3_u32 v116, v117, v116, s31
	v_and_or_b32 v116, v116, s33, v77
	v_bfe_u32 v77, v118, 16, 1
	v_add3_u32 v77, v118, v77, s31
	v_bfe_u32 v117, v119, 16, 1
	v_lshrrev_b32_e32 v77, 16, v77
	v_add3_u32 v117, v119, v117, s31
	v_and_or_b32 v117, v117, s33, v77
	v_bfe_u32 v77, v112, 16, 1
	v_add3_u32 v77, v112, v77, s31
	v_bfe_u32 v112, v113, 16, 1
	v_lshrrev_b32_e32 v77, 16, v77
	v_add3_u32 v112, v113, v112, s31
	v_and_or_b32 v118, v112, s33, v77
	v_bfe_u32 v77, v114, 16, 1
	v_add3_u32 v77, v114, v77, s31
	v_bfe_u32 v112, v115, 16, 1
	v_lshrrev_b32_e32 v77, 16, v77
	v_add3_u32 v112, v115, v112, s31
	v_and_or_b32 v119, v112, s33, v77
	v_bfe_u32 v77, v108, 16, 1
	v_add3_u32 v77, v108, v77, s31
	v_bfe_u32 v108, v109, 16, 1
	v_lshrrev_b32_e32 v77, 16, v77
	v_add3_u32 v108, v109, v108, s31
	v_and_or_b32 v108, v108, s33, v77
	v_bfe_u32 v77, v110, 16, 1
	v_add3_u32 v77, v110, v77, s31
	v_bfe_u32 v109, v111, 16, 1
	v_lshrrev_b32_e32 v77, 16, v77
	v_add3_u32 v109, v111, v109, s31
	v_and_or_b32 v109, v109, s33, v77
	v_bfe_u32 v77, v104, 16, 1
	v_add3_u32 v77, v104, v77, s31
	v_bfe_u32 v104, v105, 16, 1
	v_lshrrev_b32_e32 v77, 16, v77
	v_add3_u32 v104, v105, v104, s31
	v_and_or_b32 v110, v104, s33, v77
	v_bfe_u32 v77, v106, 16, 1
	v_add3_u32 v77, v106, v77, s31
	v_bfe_u32 v104, v107, 16, 1
	v_lshrrev_b32_e32 v77, 16, v77
	v_add3_u32 v104, v107, v104, s31
	v_and_or_b32 v111, v104, s33, v77
	v_bfe_u32 v77, v100, 16, 1
	v_add3_u32 v77, v100, v77, s31
	v_bfe_u32 v100, v101, 16, 1
	v_lshrrev_b32_e32 v77, 16, v77
	v_add3_u32 v100, v101, v100, s31
	v_and_or_b32 v100, v100, s33, v77
	v_bfe_u32 v77, v102, 16, 1
	v_add3_u32 v77, v102, v77, s31
	v_bfe_u32 v101, v103, 16, 1
	v_lshrrev_b32_e32 v77, 16, v77
	v_add3_u32 v101, v103, v101, s31
	v_and_or_b32 v101, v101, s33, v77
	v_bfe_u32 v77, v96, 16, 1
	v_add3_u32 v77, v96, v77, s31
	v_bfe_u32 v96, v97, 16, 1
	v_lshrrev_b32_e32 v77, 16, v77
	v_add3_u32 v96, v97, v96, s31
	v_and_or_b32 v102, v96, s33, v77
	v_bfe_u32 v77, v98, 16, 1
	v_add3_u32 v77, v98, v77, s31
	v_bfe_u32 v96, v99, 16, 1
	v_lshrrev_b32_e32 v77, 16, v77
	v_add3_u32 v96, v99, v96, s31
	v_and_or_b32 v103, v96, s33, v77
	v_bfe_u32 v77, v92, 16, 1
	v_add3_u32 v77, v92, v77, s31
	v_bfe_u32 v92, v93, 16, 1
	v_lshrrev_b32_e32 v77, 16, v77
	v_add3_u32 v92, v93, v92, s31
	v_and_or_b32 v92, v92, s33, v77
	v_bfe_u32 v77, v94, 16, 1
	v_add3_u32 v77, v94, v77, s31
	v_bfe_u32 v93, v95, 16, 1
	v_lshrrev_b32_e32 v77, 16, v77
	v_add3_u32 v93, v95, v93, s31
	v_and_or_b32 v93, v93, s33, v77
	v_bfe_u32 v77, v88, 16, 1
	v_add3_u32 v77, v88, v77, s31
	v_bfe_u32 v88, v89, 16, 1
	v_lshrrev_b32_e32 v77, 16, v77
	v_add3_u32 v88, v89, v88, s31
	v_and_or_b32 v94, v88, s33, v77
	v_bfe_u32 v77, v90, 16, 1
	v_add3_u32 v77, v90, v77, s31
	v_bfe_u32 v88, v91, 16, 1
	v_lshrrev_b32_e32 v77, 16, v77
	v_add3_u32 v88, v91, v88, s31
	v_and_or_b32 v95, v88, s33, v77
	v_bfe_u32 v77, v84, 16, 1
	v_add3_u32 v77, v84, v77, s31
	v_bfe_u32 v84, v85, 16, 1
	v_lshrrev_b32_e32 v77, 16, v77
	v_add3_u32 v84, v85, v84, s31
	v_and_or_b32 v84, v84, s33, v77
	v_bfe_u32 v77, v86, 16, 1
	v_add3_u32 v77, v86, v77, s31
	v_bfe_u32 v85, v87, 16, 1
	v_lshrrev_b32_e32 v77, 16, v77
	v_add3_u32 v85, v87, v85, s31
	v_and_or_b32 v85, v85, s33, v77
	v_bfe_u32 v77, v80, 16, 1
	v_add3_u32 v77, v80, v77, s31
	v_bfe_u32 v80, v81, 16, 1
	v_lshrrev_b32_e32 v77, 16, v77
	v_add3_u32 v80, v81, v80, s31
	v_and_or_b32 v86, v80, s33, v77
	v_bfe_u32 v77, v82, 16, 1
	v_or_b32_e32 v96, 32, v76
	v_add3_u32 v77, v82, v77, s31
	v_bfe_u32 v80, v83, 16, 1
	v_ashrrev_i32_e32 v97, 31, v96
	v_lshrrev_b32_e32 v77, 16, v77
	v_add3_u32 v80, v83, v80, s31
	v_ashrrev_i32_e32 v79, 31, v78
	v_lshlrev_b64 v[96:97], 12, v[96:97]
	v_and_or_b32 v87, v80, s33, v77
	v_or_b32_e32 v80, 48, v76
	v_lshlrev_b64 v[78:79], 1, v[78:79]
	v_lshl_add_u64 v[96:97], s[94:95], 0, v[96:97]
	v_ashrrev_i32_e32 v81, 31, v80
	v_lshl_add_u64 v[88:89], v[96:97], 0, v[78:79]
	v_lshlrev_b64 v[80:81], 12, v[80:81]
	v_bfe_u32 v77, v130, 16, 1
	global_store_dwordx4 v[88:89], v[84:87], off offset:64
	v_add3_u32 v77, v130, v77, s31
	v_lshrrev_b32_e32 v77, 16, v77
	v_lshl_add_u64 v[84:85], s[94:95], 0, v[80:81]
	v_bfe_u32 v80, v131, 16, 1
	v_add3_u32 v80, v131, v80, s31
	v_and_or_b32 v80, v80, s33, v77
	v_bfe_u32 v77, v132, 16, 1
	v_add3_u32 v77, v132, v77, s31
	v_bfe_u32 v81, v133, 16, 1
	v_lshrrev_b32_e32 v77, 16, v77
	v_add3_u32 v81, v133, v81, s31
	v_and_or_b32 v81, v81, s33, v77
	v_bfe_u32 v77, v72, 16, 1
	v_add3_u32 v72, v72, v77, s31
	v_bfe_u32 v77, v73, 16, 1
	v_lshrrev_b32_e32 v72, 16, v72
	v_add3_u32 v73, v73, v77, s31
	v_and_or_b32 v82, v73, s33, v72
	v_bfe_u32 v72, v74, 16, 1
	v_add3_u32 v72, v74, v72, s31
	v_bfe_u32 v74, v68, 16, 1
	v_add3_u32 v68, v68, v74, s31
	v_bfe_u32 v74, v69, 16, 1
	v_lshrrev_b32_e32 v68, 16, v68
	v_add3_u32 v69, v69, v74, s31
	v_and_or_b32 v68, v69, s33, v68
	v_bfe_u32 v69, v70, 16, 1
	v_add3_u32 v69, v70, v69, s31
	v_bfe_u32 v70, v71, 16, 1
	v_lshrrev_b32_e32 v69, 16, v69
	v_add3_u32 v70, v71, v70, s31
	v_and_or_b32 v69, v70, s33, v69
	v_bfe_u32 v70, v64, 16, 1
	v_add3_u32 v64, v64, v70, s31
	v_bfe_u32 v70, v65, 16, 1
	v_lshrrev_b32_e32 v64, 16, v64
	v_add3_u32 v65, v65, v70, s31
	v_and_or_b32 v70, v65, s33, v64
	v_bfe_u32 v64, v66, 16, 1
	v_add3_u32 v64, v66, v64, s31
	v_bfe_u32 v66, v60, 16, 1
	v_add3_u32 v60, v60, v66, s31
	v_bfe_u32 v66, v61, 16, 1
	v_lshrrev_b32_e32 v60, 16, v60
	v_add3_u32 v61, v61, v66, s31
	v_and_or_b32 v60, v61, s33, v60
	v_bfe_u32 v61, v62, 16, 1
	v_add3_u32 v61, v62, v61, s31
	v_bfe_u32 v62, v63, 16, 1
	v_lshrrev_b32_e32 v61, 16, v61
	v_add3_u32 v62, v63, v62, s31
	v_and_or_b32 v61, v62, s33, v61
	v_bfe_u32 v62, v56, 16, 1
	v_add3_u32 v56, v56, v62, s31
	v_bfe_u32 v62, v57, 16, 1
	v_lshrrev_b32_e32 v56, 16, v56
	v_add3_u32 v57, v57, v62, s31
	v_and_or_b32 v62, v57, s33, v56
	v_bfe_u32 v56, v58, 16, 1
	v_add3_u32 v56, v58, v56, s31
	v_bfe_u32 v58, v52, 16, 1
	v_add3_u32 v52, v52, v58, s31
	v_bfe_u32 v58, v53, 16, 1
	v_lshrrev_b32_e32 v52, 16, v52
	v_add3_u32 v53, v53, v58, s31
	v_and_or_b32 v52, v53, s33, v52
	v_bfe_u32 v53, v54, 16, 1
	v_add3_u32 v53, v54, v53, s31
	v_bfe_u32 v54, v55, 16, 1
	v_lshrrev_b32_e32 v53, 16, v53
	v_add3_u32 v54, v55, v54, s31
	v_and_or_b32 v53, v54, s33, v53
	v_bfe_u32 v54, v48, 16, 1
	v_add3_u32 v48, v48, v54, s31
	v_bfe_u32 v54, v49, 16, 1
	v_lshrrev_b32_e32 v48, 16, v48
	v_add3_u32 v49, v49, v54, s31
	v_and_or_b32 v54, v49, s33, v48
	v_bfe_u32 v48, v50, 16, 1
	v_add3_u32 v48, v50, v48, s31
	v_bfe_u32 v50, v44, 16, 1
	v_add3_u32 v44, v44, v50, s31
	v_bfe_u32 v50, v45, 16, 1
	v_lshrrev_b32_e32 v44, 16, v44
	v_add3_u32 v45, v45, v50, s31
	v_and_or_b32 v44, v45, s33, v44
	v_bfe_u32 v45, v46, 16, 1
	v_add3_u32 v45, v46, v45, s31
	v_bfe_u32 v46, v47, 16, 1
	v_lshrrev_b32_e32 v45, 16, v45
	v_add3_u32 v46, v47, v46, s31
	v_and_or_b32 v45, v46, s33, v45
	v_bfe_u32 v46, v40, 16, 1
	v_add3_u32 v40, v40, v46, s31
	v_bfe_u32 v46, v41, 16, 1
	v_lshrrev_b32_e32 v40, 16, v40
	v_add3_u32 v41, v41, v46, s31
	v_and_or_b32 v46, v41, s33, v40
	v_bfe_u32 v40, v42, 16, 1
	v_add3_u32 v40, v42, v40, s31
	v_bfe_u32 v42, v36, 16, 1
	v_add3_u32 v36, v36, v42, s31
	v_bfe_u32 v42, v37, 16, 1
	v_lshrrev_b32_e32 v36, 16, v36
	v_add3_u32 v37, v37, v42, s31
	v_and_or_b32 v36, v37, s33, v36
	v_bfe_u32 v37, v38, 16, 1
	v_add3_u32 v37, v38, v37, s31
	v_bfe_u32 v38, v39, 16, 1
	v_lshrrev_b32_e32 v37, 16, v37
	v_add3_u32 v38, v39, v38, s31
	v_and_or_b32 v37, v38, s33, v37
	v_bfe_u32 v38, v32, 16, 1
	v_add3_u32 v32, v32, v38, s31
	v_bfe_u32 v38, v33, 16, 1
	v_lshrrev_b32_e32 v32, 16, v32
	v_add3_u32 v33, v33, v38, s31
	v_and_or_b32 v38, v33, s33, v32
	v_bfe_u32 v32, v34, 16, 1
	v_add3_u32 v32, v34, v32, s31
	v_bfe_u32 v34, v28, 16, 1
	v_add3_u32 v28, v28, v34, s31
	v_bfe_u32 v34, v29, 16, 1
	v_lshrrev_b32_e32 v28, 16, v28
	v_add3_u32 v29, v29, v34, s31
	v_and_or_b32 v28, v29, s33, v28
	v_bfe_u32 v29, v30, 16, 1
	v_add3_u32 v29, v30, v29, s31
	v_bfe_u32 v30, v31, 16, 1
	v_lshrrev_b32_e32 v29, 16, v29
	v_add3_u32 v30, v31, v30, s31
	v_and_or_b32 v29, v30, s33, v29
	v_bfe_u32 v30, v24, 16, 1
	v_add3_u32 v24, v24, v30, s31
	v_bfe_u32 v30, v25, 16, 1
	v_lshrrev_b32_e32 v24, 16, v24
	v_add3_u32 v25, v25, v30, s31
	v_and_or_b32 v30, v25, s33, v24
	v_bfe_u32 v24, v26, 16, 1
	v_add3_u32 v24, v26, v24, s31
	v_bfe_u32 v26, v20, 16, 1
	v_add3_u32 v20, v20, v26, s31
	v_bfe_u32 v26, v21, 16, 1
	v_lshrrev_b32_e32 v20, 16, v20
	v_add3_u32 v21, v21, v26, s31
	v_and_or_b32 v20, v21, s33, v20
	v_bfe_u32 v21, v22, 16, 1
	v_add3_u32 v21, v22, v21, s31
	v_bfe_u32 v22, v23, 16, 1
	v_lshrrev_b32_e32 v21, 16, v21
	v_add3_u32 v22, v23, v22, s31
	v_and_or_b32 v21, v22, s33, v21
	v_bfe_u32 v22, v16, 16, 1
	v_add3_u32 v16, v16, v22, s31
	v_bfe_u32 v22, v17, 16, 1
	v_lshrrev_b32_e32 v16, 16, v16
	v_add3_u32 v17, v17, v22, s31
	v_and_or_b32 v22, v17, s33, v16
	v_bfe_u32 v16, v18, 16, 1
	v_add3_u32 v16, v18, v16, s31
	v_bfe_u32 v18, v12, 16, 1
	v_add3_u32 v12, v12, v18, s31
	v_bfe_u32 v18, v13, 16, 1
	v_lshrrev_b32_e32 v12, 16, v12
	v_add3_u32 v13, v13, v18, s31
	v_and_or_b32 v12, v13, s33, v12
	v_bfe_u32 v13, v14, 16, 1
	v_add3_u32 v13, v14, v13, s31
	v_bfe_u32 v14, v15, 16, 1
	v_lshrrev_b32_e32 v13, 16, v13
	v_add3_u32 v14, v15, v14, s31
	v_and_or_b32 v13, v14, s33, v13
	v_bfe_u32 v14, v8, 16, 1
	v_add3_u32 v8, v8, v14, s31
	v_bfe_u32 v14, v9, 16, 1
	v_lshrrev_b32_e32 v8, 16, v8
	v_add3_u32 v9, v9, v14, s31
	v_and_or_b32 v14, v9, s33, v8
	v_bfe_u32 v8, v10, 16, 1
	v_add3_u32 v8, v10, v8, s31
	v_bfe_u32 v10, v4, 16, 1
	v_add3_u32 v4, v4, v10, s31
	v_bfe_u32 v10, v5, 16, 1
	v_lshrrev_b32_e32 v4, 16, v4
	v_add3_u32 v5, v5, v10, s31
	v_and_or_b32 v4, v5, s33, v4
	v_bfe_u32 v5, v6, 16, 1
	v_add3_u32 v5, v6, v5, s31
	v_bfe_u32 v6, v7, 16, 1
	v_lshrrev_b32_e32 v5, 16, v5
	v_add3_u32 v6, v7, v6, s31
	v_bfe_u32 v65, v67, 16, 1
	v_bfe_u32 v49, v51, 16, 1
	v_bfe_u32 v33, v35, 16, 1
	v_bfe_u32 v17, v19, 16, 1
	v_and_or_b32 v5, v6, s33, v5
	v_bfe_u32 v6, v0, 16, 1
	v_lshrrev_b32_e32 v64, 16, v64
	v_add3_u32 v65, v67, v65, s31
	v_lshrrev_b32_e32 v48, 16, v48
	v_add3_u32 v49, v51, v49, s31
	v_lshrrev_b32_e32 v32, 16, v32
	v_add3_u32 v33, v35, v33, s31
	v_lshrrev_b32_e32 v16, 16, v16
	v_add3_u32 v17, v19, v17, s31
	v_add3_u32 v0, v0, v6, s31
	v_bfe_u32 v6, v1, 16, 1
	v_or_b32_e32 v112, 16, v76
	v_and_or_b32 v71, v65, s33, v64
	v_or_b32_e32 v64, 64, v76
	v_and_or_b32 v55, v49, s33, v48
	v_or_b32_e32 v48, 0x50, v76
	v_and_or_b32 v39, v33, s33, v32
	v_or_b32_e32 v32, 0x60, v76
	v_and_or_b32 v23, v17, s33, v16
	v_or_b32_e32 v16, 0x70, v76
	v_lshrrev_b32_e32 v0, 16, v0
	v_add3_u32 v1, v1, v6, s31
	v_ashrrev_i32_e32 v113, 31, v112
	v_ashrrev_i32_e32 v65, 31, v64
	v_ashrrev_i32_e32 v49, 31, v48
	v_ashrrev_i32_e32 v33, 31, v32
	v_ashrrev_i32_e32 v17, 31, v16
	v_and_or_b32 v6, v1, s33, v0
	v_bfe_u32 v0, v2, 16, 1
	v_lshlrev_b64 v[112:113], 12, v[112:113]
	v_bfe_u32 v73, v75, 16, 1
	v_lshlrev_b64 v[64:65], 12, v[64:65]
	v_bfe_u32 v57, v59, 16, 1
	v_lshlrev_b64 v[48:49], 12, v[48:49]
	v_bfe_u32 v41, v43, 16, 1
	v_lshlrev_b64 v[32:33], 12, v[32:33]
	v_bfe_u32 v25, v27, 16, 1
	v_lshlrev_b64 v[16:17], 12, v[16:17]
	v_bfe_u32 v9, v11, 16, 1
	v_add3_u32 v0, v2, v0, s31
	v_bfe_u32 v1, v3, 16, 1
	v_lshl_add_u64 v[136:137], s[94:95], 0, v[136:137]
	v_lshl_add_u64 v[112:113], s[94:95], 0, v[112:113]
	v_lshrrev_b32_e32 v72, 16, v72
	v_add3_u32 v73, v75, v73, s31
	v_lshl_add_u64 v[64:65], s[94:95], 0, v[64:65]
	v_lshrrev_b32_e32 v56, 16, v56
	v_add3_u32 v57, v59, v57, s31
	v_lshl_add_u64 v[48:49], s[94:95], 0, v[48:49]
	v_lshrrev_b32_e32 v40, 16, v40
	v_add3_u32 v41, v43, v41, s31
	v_lshl_add_u64 v[32:33], s[94:95], 0, v[32:33]
	v_lshrrev_b32_e32 v24, 16, v24
	v_add3_u32 v25, v27, v25, s31
	v_lshl_add_u64 v[16:17], s[94:95], 0, v[16:17]
	v_lshrrev_b32_e32 v8, 16, v8
	v_add3_u32 v9, v11, v9, s31
	v_lshrrev_b32_e32 v0, 16, v0
	v_add3_u32 v1, v3, v1, s31
	v_lshl_add_u64 v[120:121], v[136:137], 0, v[78:79]
	v_lshl_add_u64 v[104:105], v[112:113], 0, v[78:79]
	v_and_or_b32 v83, v73, s33, v72
	v_lshl_add_u64 v[72:73], v[84:85], 0, v[78:79]
	v_and_or_b32 v63, v57, s33, v56
	v_lshl_add_u64 v[56:57], v[64:65], 0, v[78:79]
	v_and_or_b32 v47, v41, s33, v40
	v_lshl_add_u64 v[40:41], v[48:49], 0, v[78:79]
	v_and_or_b32 v31, v25, s33, v24
	v_lshl_add_u64 v[24:25], v[32:33], 0, v[78:79]
	v_and_or_b32 v15, v9, s33, v8
	v_lshl_add_u64 v[8:9], v[16:17], 0, v[78:79]
	v_and_or_b32 v7, v1, s33, v0
	global_store_dwordx4 v[120:121], v[124:127], off
	global_store_dwordx4 v[120:121], v[116:119], off offset:64
	global_store_dwordx4 v[104:105], v[108:111], off
	global_store_dwordx4 v[104:105], v[100:103], off offset:64
	global_store_dwordx4 v[88:89], v[92:95], off
	global_store_dwordx4 v[72:73], v[80:83], off
	global_store_dwordx4 v[72:73], v[68:71], off offset:64
	global_store_dwordx4 v[56:57], v[60:63], off
	global_store_dwordx4 v[56:57], v[52:55], off offset:64
	global_store_dwordx4 v[40:41], v[44:47], off
	global_store_dwordx4 v[40:41], v[36:39], off offset:64
	global_store_dwordx4 v[24:25], v[28:31], off
	global_store_dwordx4 v[24:25], v[20:23], off offset:64
	global_store_dwordx4 v[8:9], v[12:15], off
	global_store_dwordx4 v[8:9], v[4:7], off offset:64
	s_branch .LBB0_1319

.LBB0_1345:
	s_add_u32 s90, s52, 0xd690000
	s_addc_u32 s91, s53, 0
	v_mov_b32_e32 v0, v190
	s_cmpk_gt_i32 s34, 0x120
	s_cbranch_scc1 .LBB0_1409
	v_and_b32_e32 v42, 15, v0
	v_bfe_u32 v1, v0, 4, 2
	v_ashrrev_i32_e32 v0, 1, v0
	v_and_b32_e32 v43, 0xffffffe0, v0
	v_mov_b32_e32 v19, 0
	v_lshlrev_b32_e32 v44, 2, v1
	v_lshlrev_b32_e32 v16, 4, v1
	v_and_b32_e32 v238, 1, v42
	v_lshl_or_b32 v16, v238, 6, v16
	v_mov_b32_e32 v17, v19
	v_or_b32_e32 v45, v43, v42
	s_movk_i32 s10, 0x4000
	s_movk_i32 s11, 0x7ff
	s_mov_b32 s12, 0x12d0000
	s_mov_b32 s13, 0x12d8000
	s_mov_b32 s14, 0x8000
	s_mov_b64 s[0:1], 0x200
	s_movk_i32 s15, 0xc00
	s_movk_i32 s16, 0x7fff
	v_mov_b32_e32 v46, 1
	v_readlane_b32 s17, v254, 56
	s_branch .LBB0_1348

.LBB0_1348:
	s_min_i32 s2, s17, 0xa0
	s_lshl_b32 s18, s2, 5
	s_lshl_b32 s2, s17, 7
	s_addk_i32 s2, 0xaf80
	v_or_b32_e32 v20, s18, v42
	s_cmpk_gt_i32 s17, 0xa0
	v_ashrrev_i32_e32 v21, 31, v20
	s_cselect_b32 s6, s2, 0x4000
	v_and_b32_e32 v0, -2, v20
	v_mov_b32_e32 v1, v21
	v_lshlrev_b64 v[0:1], 11, v[0:1]
	s_cmpk_gt_i32 s18, 0x7ff
	v_add_u32_e32 v24, s6, v45
	v_lshl_add_u64 v[22:23], s[52:53], 0, v[0:1]
	s_mov_b64 s[4:5], -1
	s_cselect_b64 s[2:3], -1, 0
	s_cmpk_lt_i32 s18, 0x800
	v_ashrrev_i32_e32 v25, 31, v24
	s_cbranch_scc1 .LBB0_1352
	v_and_b32_e32 v0, -2, v24
	v_mov_b32_e32 v1, v25
	v_lshlrev_b64 v[0:1], 11, v[0:1]
	v_lshl_add_u64 v[26:27], s[52:53], 0, v[0:1]
	v_mov_b32_e32 v0, 0
	s_movk_i32 s4, 0xffe0
	v_mov_b64_e32 v[28:29], v[22:23]
	v_mov_b32_e32 v1, v0
	v_mov_b32_e32 v2, v0
	v_mov_b32_e32 v3, v0
	v_mov_b32_e32 v12, v0
	v_mov_b32_e32 v13, v0
	v_mov_b32_e32 v14, v0
	v_mov_b32_e32 v15, v0
	v_mov_b32_e32 v8, v0
	v_mov_b32_e32 v9, v0
	v_mov_b32_e32 v10, v0
	v_mov_b32_e32 v11, v0
	v_mov_b32_e32 v4, v0
	v_mov_b32_e32 v5, v0
	v_mov_b32_e32 v6, v0
	v_mov_b32_e32 v7, v0
.LBB0_1350:
	v_lshl_add_u64 v[34:35], v[26:27], 0, v[16:17]
	v_add_co_u32_e32 v52, vcc, s12, v34
	v_lshl_add_u64 v[56:57], v[28:29], 0, v[16:17]
	s_nop 0
	v_addc_co_u32_e32 v53, vcc, 0, v35, vcc
	v_add_co_u32_e32 v54, vcc, s13, v34
	global_load_dwordx4 v[30:33], v[52:53], off
	s_nop 0
	v_addc_co_u32_e32 v55, vcc, 0, v35, vcc
	global_load_dwordx4 v[34:37], v[54:55], off
	v_add_co_u32_e32 v58, vcc, s14, v56
	global_load_dwordx4 v[38:41], v[56:57], off
	s_nop 0
	v_addc_co_u32_e32 v59, vcc, 0, v57, vcc
	global_load_dwordx4 v[48:51], v[58:59], off
	s_addk_i32 s4, 0x80
	v_lshl_add_u64 v[28:29], v[28:29], 0, s[0:1]
	v_lshl_add_u64 v[26:27], v[26:27], 0, s[0:1]
	s_cmpk_lt_u32 s4, 0x3e0
	s_waitcnt vmcnt(0)
	v_mfma_f32_16x16x32_bf16 v[12:15], v[30:33], v[38:41], v[12:15]
	v_mfma_f32_16x16x32_bf16 v[8:11], v[30:33], v[48:51], v[8:11]
	v_mfma_f32_16x16x32_bf16 v[4:7], v[34:37], v[38:41], v[4:7]
	v_mfma_f32_16x16x32_bf16 v[0:3], v[34:37], v[48:51], v[0:3]
	global_load_dwordx4 v[30:33], v[52:53], off offset:128
	global_load_dwordx4 v[34:37], v[54:55], off offset:128
	global_load_dwordx4 v[38:41], v[56:57], off offset:128
	global_load_dwordx4 v[48:51], v[58:59], off offset:128
	s_waitcnt vmcnt(1)
	v_mfma_f32_16x16x32_bf16 v[12:15], v[30:33], v[38:41], v[12:15]
	s_waitcnt vmcnt(0)
	v_mfma_f32_16x16x32_bf16 v[8:11], v[30:33], v[48:51], v[8:11]
	v_mfma_f32_16x16x32_bf16 v[4:7], v[34:37], v[38:41], v[4:7]
	v_mfma_f32_16x16x32_bf16 v[0:3], v[34:37], v[48:51], v[0:3]
	global_load_dwordx4 v[30:33], v[52:53], off offset:256
	global_load_dwordx4 v[34:37], v[54:55], off offset:256
	global_load_dwordx4 v[38:41], v[56:57], off offset:256
	global_load_dwordx4 v[48:51], v[58:59], off offset:256
	s_waitcnt vmcnt(1)
	v_mfma_f32_16x16x32_bf16 v[12:15], v[30:33], v[38:41], v[12:15]
	s_waitcnt vmcnt(0)
	v_mfma_f32_16x16x32_bf16 v[8:11], v[30:33], v[48:51], v[8:11]
	v_mfma_f32_16x16x32_bf16 v[4:7], v[34:37], v[38:41], v[4:7]
	v_mfma_f32_16x16x32_bf16 v[0:3], v[34:37], v[48:51], v[0:3]
	global_load_dwordx4 v[30:33], v[52:53], off offset:384
	global_load_dwordx4 v[34:37], v[54:55], off offset:384
	global_load_dwordx4 v[38:41], v[56:57], off offset:384
	global_load_dwordx4 v[48:51], v[58:59], off offset:384
	s_waitcnt vmcnt(1)
	v_mfma_f32_16x16x32_bf16 v[12:15], v[30:33], v[38:41], v[12:15]
	s_waitcnt vmcnt(0)
	v_mfma_f32_16x16x32_bf16 v[8:11], v[30:33], v[48:51], v[8:11]
	v_mfma_f32_16x16x32_bf16 v[4:7], v[34:37], v[38:41], v[4:7]
	v_mfma_f32_16x16x32_bf16 v[0:3], v[34:37], v[48:51], v[0:3]
	s_cbranch_scc1 .LBB0_1350
	s_mov_b64 s[4:5], 0

.LBB0_1354:
	v_lshl_add_u64 v[30:31], v[24:25], 0, v[16:17]
	v_add_co_u32_e32 v48, vcc, s12, v30
	v_lshl_add_u64 v[52:53], v[22:23], 0, v[16:17]
	s_nop 0
	v_addc_co_u32_e32 v49, vcc, 0, v31, vcc
	v_add_co_u32_e32 v50, vcc, s13, v30
	global_load_dwordx4 v[34:37], v[52:53], off
	s_nop 0
	v_addc_co_u32_e32 v51, vcc, 0, v31, vcc
	v_add_co_u32_e32 v54, vcc, s14, v52
	global_load_dwordx4 v[26:29], v[48:49], off
	global_load_dwordx4 v[30:33], v[50:51], off
	v_addc_co_u32_e32 v55, vcc, 0, v53, vcc
	global_load_dwordx4 v[38:41], v[54:55], off
	s_addk_i32 s4, 0x80
	v_lshl_add_u64 v[22:23], v[22:23], 0, s[0:1]
	v_lshl_add_u64 v[24:25], v[24:25], 0, s[0:1]
	s_cmpk_gt_u32 s4, 0x3df
	s_waitcnt vmcnt(0)
	v_mfma_f32_16x16x32_bf16 v[12:15], v[34:37], v[26:29], v[12:15]
	v_mfma_f32_16x16x32_bf16 v[8:11], v[38:41], v[26:29], v[8:11]
	v_mfma_f32_16x16x32_bf16 v[4:7], v[34:37], v[30:33], v[4:7]
	v_mfma_f32_16x16x32_bf16 v[0:3], v[38:41], v[30:33], v[0:3]
	global_load_dwordx4 v[26:29], v[48:49], off offset:128
	global_load_dwordx4 v[30:33], v[50:51], off offset:128
	global_load_dwordx4 v[34:37], v[52:53], off offset:128
	global_load_dwordx4 v[38:41], v[54:55], off offset:128
	s_waitcnt vmcnt(1)
	v_mfma_f32_16x16x32_bf16 v[12:15], v[34:37], v[26:29], v[12:15]
	s_waitcnt vmcnt(0)
	v_mfma_f32_16x16x32_bf16 v[8:11], v[38:41], v[26:29], v[8:11]
	v_mfma_f32_16x16x32_bf16 v[4:7], v[34:37], v[30:33], v[4:7]
	v_mfma_f32_16x16x32_bf16 v[0:3], v[38:41], v[30:33], v[0:3]
	global_load_dwordx4 v[26:29], v[48:49], off offset:256
	global_load_dwordx4 v[30:33], v[50:51], off offset:256
	global_load_dwordx4 v[34:37], v[52:53], off offset:256
	global_load_dwordx4 v[38:41], v[54:55], off offset:256
	s_waitcnt vmcnt(1)
	v_mfma_f32_16x16x32_bf16 v[12:15], v[34:37], v[26:29], v[12:15]
	s_waitcnt vmcnt(0)
	v_mfma_f32_16x16x32_bf16 v[8:11], v[38:41], v[26:29], v[8:11]
	v_mfma_f32_16x16x32_bf16 v[4:7], v[34:37], v[30:33], v[4:7]
	v_mfma_f32_16x16x32_bf16 v[0:3], v[38:41], v[30:33], v[0:3]
	global_load_dwordx4 v[26:29], v[48:49], off offset:384
	global_load_dwordx4 v[30:33], v[50:51], off offset:384
	global_load_dwordx4 v[34:37], v[52:53], off offset:384
	global_load_dwordx4 v[38:41], v[54:55], off offset:384
	s_waitcnt vmcnt(1)
	v_mfma_f32_16x16x32_bf16 v[12:15], v[34:37], v[26:29], v[12:15]
	s_waitcnt vmcnt(0)
	v_mfma_f32_16x16x32_bf16 v[8:11], v[38:41], v[26:29], v[8:11]
	v_mfma_f32_16x16x32_bf16 v[4:7], v[34:37], v[30:33], v[4:7]
	v_mfma_f32_16x16x32_bf16 v[0:3], v[38:41], v[30:33], v[0:3]
	s_cbranch_scc0 .LBB0_1354

.LBB0_1566:
	s_or_b64 exec, exec, s[2:3]
	v_readlane_b32 s0, v254, 50
	v_readlane_b32 s1, v254, 51
	v_mov_b32_e32 v0, v190
	s_andn2_b64 vcc, exec, s[0:1]
	s_cbranch_vccnz .LBB0_1601
	v_and_b32_e32 v20, 63, v0
	v_ashrrev_i32_e32 v21, 6, v0
	v_ashrrev_i32_e32 v22, 3, v0
	v_lshlrev_b32_e32 v0, 3, v0
	v_readlane_b32 s0, v255, 23
	v_and_b32_e32 v3, 56, v0
	v_readlane_b32 s2, v255, 25
	v_bfe_u32 v0, v190, 2, 1
	v_lshlrev_b32_e32 v0, 7, v0
	v_bfe_u32 v200, v190, 3, 1
	v_lshl_or_b32 v0, v200, 6, v0
	v_and_b32_e32 v200, 3, v190
	v_lshl_or_b32 v0, v200, 4, v0
	v_mov_b32_e32 v1, 0
	v_readlane_b32 s12, v255, 35
	s_add_u32 s0, s2, 0xc10000
	v_lshl_add_u64 v[16:17], s[52:53], 0, v[0:1]
	v_lshlrev_b32_e32 v0, 2, v22
	s_movk_i32 s2, 0x104
	v_readlane_b32 s1, v255, 24
	v_readlane_b32 s3, v255, 26
	v_readlane_b32 s6, v255, 29
	v_readlane_b32 s7, v255, 30
	v_readlane_b32 s8, v255, 31
	v_readlane_b32 s9, v255, 32
	v_readlane_b32 s10, v255, 33
	v_readlane_b32 s11, v255, 34
	v_lshlrev_b32_e32 v2, 2, v20
	v_mad_u32_u24 v23, v3, s2, v0
	v_mul_lo_u32 v0, v21, s2
	v_readlane_b32 s12, v254, 56
	s_addc_u32 s1, s3, 0
	s_lshl_b32 s6, s12, 6
	s_lshl_b32 s7, s86, 6
	s_mov_b32 s8, 0
	s_movk_i32 s9, 0xc10
	s_movk_i32 s10, 0x3040
	v_add_u32_e32 v24, v2, v0
	s_movk_i32 s11, 0x7fff
	v_mov_b32_e32 v25, 1
	v_readlane_b32 s4, v255, 27
	v_readlane_b32 s5, v255, 28
	v_readlane_b32 s13, v255, 36
	v_readlane_b32 s14, v255, 37
	v_readlane_b32 s15, v255, 38
	s_branch .LBB0_1569
.LBB0_1568:
	s_or_b64 exec, exec, s[4:5]
	s_waitcnt vmcnt(63) expcnt(7) lgkmcnt(15)
	s_barrier
	s_waitcnt vmcnt(0)
	ds_write_b32 v24, v0
	ds_write_b32 v24, v1 offset:1040
	ds_write_b32 v24, v2 offset:2080
	ds_write_b32 v24, v3 offset:3120
	ds_write_b32 v24, v4 offset:4160
	ds_write_b32 v24, v5 offset:5200
	ds_write_b32 v24, v6 offset:6240
	ds_write_b32 v24, v7 offset:7280
	ds_write_b32 v24, v8 offset:8320
	ds_write_b32 v24, v9 offset:9360
	ds_write_b32 v24, v10 offset:10400
	ds_write_b32 v24, v11 offset:11440
	ds_write_b32 v24, v12 offset:12480
	ds_write_b32 v24, v13 offset:13520
	ds_write_b32 v24, v14 offset:14560
	ds_write_b32 v24, v15 offset:15600
	s_waitcnt lgkmcnt(0)
	s_barrier
	ds_read2_b32 v[6:7], v23 offset1:32
	ds_read2_b32 v[8:9], v23 offset0:65 offset1:97
	ds_read2_b32 v[10:11], v23 offset0:130 offset1:162
	ds_read2_b32 v[12:13], v23 offset0:195 offset1:227
	v_add_u32_e32 v30, s13, v22
	v_and_b32_e32 v30, -2, v30
	s_ashr_i32 s3, s2, 31
	v_add_u32_e32 v0, 0x400, v23
	v_ashrrev_i32_e32 v31, 31, v30
	v_lshl_add_u64 v[4:5], s[2:3], 2, v[16:17]
	ds_read2_b32 v[14:15], v0 offset0:4 offset1:36
	ds_read2_b32 v[18:19], v0 offset0:69 offset1:101
	ds_read2_b32 v[26:27], v0 offset0:134 offset1:166
	ds_read2_b32 v[28:29], v0 offset0:199 offset1:231
	v_lshlrev_b64 v[0:1], 11, v[30:31]
	v_lshl_add_u64 v[32:33], v[4:5], 0, v[0:1]
	s_waitcnt lgkmcnt(7)
	v_and_b32_sdwa v1, v6, v25 dst_sel:DWORD dst_unused:UNUSED_PAD src0_sel:WORD_1 src1_sel:DWORD
	v_add3_u32 v2, v6, v1, s11
	s_waitcnt lgkmcnt(4)
	v_and_b32_sdwa v1, v12, v25 dst_sel:DWORD dst_unused:UNUSED_PAD src0_sel:WORD_1 src1_sel:DWORD
	v_and_b32_sdwa v3, v8, v25 dst_sel:DWORD dst_unused:UNUSED_PAD src0_sel:WORD_1 src1_sel:DWORD
	v_and_b32_sdwa v0, v10, v25 dst_sel:DWORD dst_unused:UNUSED_PAD src0_sel:WORD_1 src1_sel:DWORD
	v_add3_u32 v1, v12, v1, s11
	v_add3_u32 v3, v8, v3, s11
	v_add3_u32 v0, v10, v0, s11
	v_and_b32_e32 v1, 0xffff0000, v1
	v_and_b32_e32 v3, 0xffff0000, v3
	v_or_b32_sdwa v1, v1, v0 dst_sel:DWORD dst_unused:UNUSED_PAD src0_sel:DWORD src1_sel:WORD_1
	v_or_b32_sdwa v0, v3, v2 dst_sel:DWORD dst_unused:UNUSED_PAD src0_sel:DWORD src1_sel:WORD_1
	s_waitcnt lgkmcnt(3)
	v_and_b32_sdwa v3, v14, v25 dst_sel:DWORD dst_unused:UNUSED_PAD src0_sel:WORD_1 src1_sel:DWORD
	v_add3_u32 v6, v14, v3, s11
	s_waitcnt lgkmcnt(0)
	v_and_b32_sdwa v3, v28, v25 dst_sel:DWORD dst_unused:UNUSED_PAD src0_sel:WORD_1 src1_sel:DWORD
	v_and_b32_sdwa v8, v18, v25 dst_sel:DWORD dst_unused:UNUSED_PAD src0_sel:WORD_1 src1_sel:DWORD
	v_and_b32_sdwa v2, v26, v25 dst_sel:DWORD dst_unused:UNUSED_PAD src0_sel:WORD_1 src1_sel:DWORD
	v_add3_u32 v3, v28, v3, s11
	v_add3_u32 v8, v18, v8, s11
	v_add3_u32 v2, v26, v2, s11
	v_and_b32_e32 v3, 0xffff0000, v3
	v_and_b32_e32 v8, 0xffff0000, v8
	v_or_b32_sdwa v3, v3, v2 dst_sel:DWORD dst_unused:UNUSED_PAD src0_sel:DWORD src1_sel:WORD_1
	v_or_b32_sdwa v2, v8, v6 dst_sel:DWORD dst_unused:UNUSED_PAD src0_sel:DWORD src1_sel:WORD_1
	global_store_dwordx4 v[32:33], v[0:3], off
	s_add_i32 s12, s12, s86
	s_add_i32 s6, s6, s7
	v_add_u32_e32 v0, 32, v30
	v_ashrrev_i32_e32 v1, 31, v0
	v_lshlrev_b64 v[0:1], 11, v[0:1]
	v_lshl_add_u64 v[4:5], v[4:5], 0, v[0:1]
	v_and_b32_sdwa v1, v7, v25 dst_sel:DWORD dst_unused:UNUSED_PAD src0_sel:WORD_1 src1_sel:DWORD
	v_add3_u32 v2, v7, v1, s11
	v_and_b32_sdwa v1, v13, v25 dst_sel:DWORD dst_unused:UNUSED_PAD src0_sel:WORD_1 src1_sel:DWORD
	v_and_b32_sdwa v3, v9, v25 dst_sel:DWORD dst_unused:UNUSED_PAD src0_sel:WORD_1 src1_sel:DWORD
	v_and_b32_sdwa v0, v11, v25 dst_sel:DWORD dst_unused:UNUSED_PAD src0_sel:WORD_1 src1_sel:DWORD
	v_add3_u32 v1, v13, v1, s11
	v_add3_u32 v3, v9, v3, s11
	v_add3_u32 v0, v11, v0, s11
	v_and_b32_e32 v1, 0xffff0000, v1
	v_and_b32_e32 v3, 0xffff0000, v3
	v_or_b32_sdwa v1, v1, v0 dst_sel:DWORD dst_unused:UNUSED_PAD src0_sel:DWORD src1_sel:WORD_1
	v_or_b32_sdwa v0, v3, v2 dst_sel:DWORD dst_unused:UNUSED_PAD src0_sel:DWORD src1_sel:WORD_1
	v_and_b32_sdwa v3, v15, v25 dst_sel:DWORD dst_unused:UNUSED_PAD src0_sel:WORD_1 src1_sel:DWORD
	v_add3_u32 v6, v15, v3, s11
	v_and_b32_sdwa v3, v29, v25 dst_sel:DWORD dst_unused:UNUSED_PAD src0_sel:WORD_1 src1_sel:DWORD
	v_and_b32_sdwa v7, v19, v25 dst_sel:DWORD dst_unused:UNUSED_PAD src0_sel:WORD_1 src1_sel:DWORD
	v_and_b32_sdwa v2, v27, v25 dst_sel:DWORD dst_unused:UNUSED_PAD src0_sel:WORD_1 src1_sel:DWORD
	v_add3_u32 v3, v29, v3, s11
	v_add3_u32 v7, v19, v7, s11
	v_add3_u32 v2, v27, v2, s11
	v_and_b32_e32 v3, 0xffff0000, v3
	v_and_b32_e32 v7, 0xffff0000, v7
	v_or_b32_sdwa v3, v3, v2 dst_sel:DWORD dst_unused:UNUSED_PAD src0_sel:DWORD src1_sel:WORD_1
	v_or_b32_sdwa v2, v7, v6 dst_sel:DWORD dst_unused:UNUSED_PAD src0_sel:DWORD src1_sel:WORD_1
	s_cmpk_lt_i32 s12, 0x310
	global_store_dwordx4 v[4:5], v[0:3], off
	s_cbranch_scc0 .LBB0_1601

.LBB0_1874:
	s_add_i32 s29, s28, 2
	s_mul_hi_i32 s30, s29, 0x55555556
	s_lshr_b32 s31, s30, 31
	s_add_i32 s30, s30, s31
	s_mul_i32 s30, s30, 3
	s_sub_i32 s29, s29, s30
	s_mulk_i32 s29, 0x6000
	s_mul_i32 s54, s28, 0x6000
	v_readfirstlane_b32 s55, v142
	v_lshl_add_u64 v[232:233], v[132:133], 0, s[4:5]
	v_lshl_add_u64 v[234:235], v[130:131], 0, s[4:5]
	s_add_u32 s55, s55, s29
	s_waitcnt vmcnt(6) lgkmcnt(0)
	s_barrier
	v_or_b32_e32 v128, s54, v140
	v_add3_u32 v128, v128, v141, v139
	ds_read_b128 v[176:179], v128 offset:16384
	ds_read_b128 v[180:183], v128 offset:16640
	ds_read_b128 v[184:187], v128 offset:18432
	ds_read_b128 v[192:195], v128 offset:18688
	v_add3_u32 v128, s54, v143, v139
	ds_read_b128 v[144:147], v128
	ds_read_b128 v[148:151], v128 offset:1024
	ds_read_b128 v[152:155], v128 offset:2048
	ds_read_b128 v[156:159], v128 offset:3072
	ds_read_b128 v[160:163], v128 offset:4096
	ds_read_b128 v[164:167], v128 offset:5120
	ds_read_b128 v[168:171], v128 offset:6144
	ds_read_b128 v[172:175], v128 offset:7168
	s_setprio 1
	s_waitcnt lgkmcnt(7)
	v_mfma_f32_16x16x32_bf16 v[124:127], v[176:179], v[144:147], v[124:127]
	v_mfma_f32_16x16x32_bf16 v[120:123], v[180:183], v[144:147], v[120:123]
	v_mfma_f32_16x16x32_bf16 v[116:119], v[184:187], v[144:147], v[116:119]
	v_mfma_f32_16x16x32_bf16 v[112:115], v[192:195], v[144:147], v[112:115]
	s_mov_b32 m0, s55
	v_lshl_add_u64 v[236:237], v[232:233], 0, s[6:7]
	global_load_lds_dwordx4 v[236:237], off
	s_waitcnt lgkmcnt(6)
	v_mfma_f32_16x16x32_bf16 v[108:111], v[176:179], v[148:151], v[108:111]
	v_mfma_f32_16x16x32_bf16 v[104:107], v[180:183], v[148:151], v[104:107]
	v_mfma_f32_16x16x32_bf16 v[100:103], v[184:187], v[148:151], v[100:103]
	v_mfma_f32_16x16x32_bf16 v[96:99], v[192:195], v[148:151], v[96:99]
	s_add_u32 m0, s55, 0x1000
	v_lshl_add_u64 v[236:237], v[232:233], 0, s[8:9]
	global_load_lds_dwordx4 v[236:237], off
	s_waitcnt lgkmcnt(5)
	v_mfma_f32_16x16x32_bf16 v[92:95], v[176:179], v[152:155], v[92:95]
	v_mfma_f32_16x16x32_bf16 v[88:91], v[180:183], v[152:155], v[88:91]
	v_mfma_f32_16x16x32_bf16 v[84:87], v[184:187], v[152:155], v[84:87]
	v_mfma_f32_16x16x32_bf16 v[80:83], v[192:195], v[152:155], v[80:83]
	s_add_u32 m0, s55, 0x2000
	v_lshl_add_u64 v[236:237], v[232:233], 0, s[10:11]
	global_load_lds_dwordx4 v[236:237], off
	s_waitcnt lgkmcnt(4)
	v_mfma_f32_16x16x32_bf16 v[76:79], v[176:179], v[156:159], v[76:79]
	v_mfma_f32_16x16x32_bf16 v[72:75], v[180:183], v[156:159], v[72:75]
	v_mfma_f32_16x16x32_bf16 v[68:71], v[184:187], v[156:159], v[68:71]
	v_mfma_f32_16x16x32_bf16 v[64:67], v[192:195], v[156:159], v[64:67]
	s_add_u32 m0, s55, 0x3000
	v_lshl_add_u64 v[236:237], v[232:233], 0, s[12:13]
	global_load_lds_dwordx4 v[236:237], off
	s_waitcnt lgkmcnt(3)
	v_mfma_f32_16x16x32_bf16 v[60:63], v[176:179], v[160:163], v[60:63]
	v_mfma_f32_16x16x32_bf16 v[56:59], v[180:183], v[160:163], v[56:59]
	v_mfma_f32_16x16x32_bf16 v[52:55], v[184:187], v[160:163], v[52:55]
	v_mfma_f32_16x16x32_bf16 v[48:51], v[192:195], v[160:163], v[48:51]
	s_add_u32 m0, s55, 0x4000
	v_lshl_add_u64 v[236:237], v[234:235], 0, s[14:15]
	global_load_lds_dwordx4 v[236:237], off
	s_waitcnt lgkmcnt(2)
	v_mfma_f32_16x16x32_bf16 v[44:47], v[176:179], v[164:167], v[44:47]
	v_mfma_f32_16x16x32_bf16 v[40:43], v[180:183], v[164:167], v[40:43]
	v_mfma_f32_16x16x32_bf16 v[36:39], v[184:187], v[164:167], v[36:39]
	v_mfma_f32_16x16x32_bf16 v[32:35], v[192:195], v[164:167], v[32:35]
	s_add_u32 m0, s55, 0x5000
	v_lshl_add_u64 v[236:237], v[234:235], 0, s[16:17]
	global_load_lds_dwordx4 v[236:237], off
	s_waitcnt lgkmcnt(1)
	v_mfma_f32_16x16x32_bf16 v[28:31], v[176:179], v[168:171], v[28:31]
	v_mfma_f32_16x16x32_bf16 v[24:27], v[180:183], v[168:171], v[24:27]
	v_mfma_f32_16x16x32_bf16 v[20:23], v[184:187], v[168:171], v[20:23]
	v_mfma_f32_16x16x32_bf16 v[16:19], v[192:195], v[168:171], v[16:19]
	s_waitcnt lgkmcnt(0)
	v_mfma_f32_16x16x32_bf16 v[12:15], v[176:179], v[172:175], v[12:15]
	v_mfma_f32_16x16x32_bf16 v[8:11], v[180:183], v[172:175], v[8:11]
	v_mfma_f32_16x16x32_bf16 v[4:7], v[184:187], v[172:175], v[4:7]
	v_mfma_f32_16x16x32_bf16 v[0:3], v[192:195], v[172:175], v[0:3]
	s_setprio 0
	s_add_i32 s29, s28, 1
	s_cmp_lg_u32 s28, 2
	s_cselect_b32 s28, s29, 0
	s_add_u32 s4, s4, 64
	s_addc_u32 s5, s5, 0
	s_cmpk_eq_i32 s4, 0xf80
	s_cbranch_scc0 .LBB0_1874
	s_waitcnt vmcnt(6) lgkmcnt(0)
	s_barrier
	v_add_u32_e32 v128, v143, v139
	ds_read_b128 v[130:133], v128 offset:49152
	ds_read_b128 v[142:145], v128 offset:50176
	ds_read_b128 v[146:149], v128 offset:51200
	ds_read_b128 v[150:153], v128 offset:52224
	ds_read_b128 v[154:157], v128 offset:53248
	ds_read_b128 v[158:161], v128 offset:54272
	ds_read_b128 v[162:165], v128 offset:55296
	ds_read_b128 v[166:169], v128 offset:56320
	v_add3_u32 v139, v140, v141, v139
	v_add_u32_e32 v140, 0xc000, v139
	ds_read_b128 v[170:173], v140 offset:16384
	ds_read_b128 v[174:177], v140 offset:16640
	ds_read_b128 v[178:181], v140 offset:18432
	ds_read_b128 v[182:185], v140 offset:18688
	s_setprio 1
	s_waitcnt lgkmcnt(0)
	v_mfma_f32_16x16x32_bf16 v[124:127], v[170:173], v[130:133], v[124:127]
	v_mfma_f32_16x16x32_bf16 v[120:123], v[174:177], v[130:133], v[120:123]
	v_mfma_f32_16x16x32_bf16 v[116:119], v[178:181], v[130:133], v[116:119]
	v_mfma_f32_16x16x32_bf16 v[112:115], v[182:185], v[130:133], v[112:115]
	v_mfma_f32_16x16x32_bf16 v[108:111], v[170:173], v[142:145], v[108:111]
	v_mfma_f32_16x16x32_bf16 v[104:107], v[174:177], v[142:145], v[104:107]
	v_mfma_f32_16x16x32_bf16 v[100:103], v[178:181], v[142:145], v[100:103]
	v_mfma_f32_16x16x32_bf16 v[96:99], v[182:185], v[142:145], v[96:99]
	v_mfma_f32_16x16x32_bf16 v[92:95], v[170:173], v[146:149], v[92:95]
	v_mfma_f32_16x16x32_bf16 v[88:91], v[174:177], v[146:149], v[88:91]
	v_mfma_f32_16x16x32_bf16 v[84:87], v[178:181], v[146:149], v[84:87]
	v_mfma_f32_16x16x32_bf16 v[80:83], v[182:185], v[146:149], v[80:83]
	v_mfma_f32_16x16x32_bf16 v[76:79], v[170:173], v[150:153], v[76:79]
	v_mfma_f32_16x16x32_bf16 v[72:75], v[174:177], v[150:153], v[72:75]
	v_mfma_f32_16x16x32_bf16 v[68:71], v[178:181], v[150:153], v[68:71]
	v_mfma_f32_16x16x32_bf16 v[64:67], v[182:185], v[150:153], v[64:67]
	v_mfma_f32_16x16x32_bf16 v[60:63], v[170:173], v[154:157], v[60:63]
	v_mfma_f32_16x16x32_bf16 v[56:59], v[174:177], v[154:157], v[56:59]
	v_mfma_f32_16x16x32_bf16 v[52:55], v[178:181], v[154:157], v[52:55]
	v_mfma_f32_16x16x32_bf16 v[48:51], v[182:185], v[154:157], v[48:51]
	v_mfma_f32_16x16x32_bf16 v[44:47], v[170:173], v[158:161], v[44:47]
	v_mfma_f32_16x16x32_bf16 v[40:43], v[174:177], v[158:161], v[40:43]
	v_mfma_f32_16x16x32_bf16 v[36:39], v[178:181], v[158:161], v[36:39]
	v_mfma_f32_16x16x32_bf16 v[32:35], v[182:185], v[158:161], v[32:35]
	v_mfma_f32_16x16x32_bf16 v[28:31], v[170:173], v[162:165], v[28:31]
	v_mfma_f32_16x16x32_bf16 v[24:27], v[174:177], v[162:165], v[24:27]
	v_mfma_f32_16x16x32_bf16 v[20:23], v[178:181], v[162:165], v[20:23]
	v_mfma_f32_16x16x32_bf16 v[16:19], v[182:185], v[162:165], v[16:19]
	v_mfma_f32_16x16x32_bf16 v[12:15], v[170:173], v[166:169], v[12:15]
	v_mfma_f32_16x16x32_bf16 v[8:11], v[174:177], v[166:169], v[8:11]
	v_mfma_f32_16x16x32_bf16 v[4:7], v[178:181], v[166:169], v[4:7]
	v_mfma_f32_16x16x32_bf16 v[0:3], v[182:185], v[166:169], v[0:3]
	s_setprio 0
	s_waitcnt vmcnt(0) lgkmcnt(0)
	s_barrier
	ds_read_b128 v[130:133], v128
	ds_read_b128 v[140:143], v128 offset:1024
	ds_read_b128 v[144:147], v128 offset:2048
	ds_read_b128 v[148:151], v128 offset:3072
	ds_read_b128 v[152:155], v128 offset:4096
	ds_read_b128 v[156:159], v128 offset:5120
	ds_read_b128 v[160:163], v128 offset:6144
	ds_read_b128 v[164:167], v128 offset:7168
	ds_read_b128 v[168:171], v139 offset:16384
	ds_read_b128 v[172:175], v139 offset:16640
	ds_read_b128 v[176:179], v139 offset:18432
	ds_read_b128 v[180:183], v139 offset:18688
	s_setprio 1
	s_waitcnt lgkmcnt(0)
	v_mfma_f32_16x16x32_bf16 v[124:127], v[168:171], v[130:133], v[124:127]
	v_mfma_f32_16x16x32_bf16 v[120:123], v[172:175], v[130:133], v[120:123]
	v_mfma_f32_16x16x32_bf16 v[116:119], v[176:179], v[130:133], v[116:119]
	v_mfma_f32_16x16x32_bf16 v[112:115], v[180:183], v[130:133], v[112:115]
	v_mfma_f32_16x16x32_bf16 v[108:111], v[168:171], v[140:143], v[108:111]
	v_mfma_f32_16x16x32_bf16 v[104:107], v[172:175], v[140:143], v[104:107]
	v_mfma_f32_16x16x32_bf16 v[100:103], v[176:179], v[140:143], v[100:103]
	v_mfma_f32_16x16x32_bf16 v[96:99], v[180:183], v[140:143], v[96:99]
	v_mfma_f32_16x16x32_bf16 v[92:95], v[168:171], v[144:147], v[92:95]
	v_mfma_f32_16x16x32_bf16 v[88:91], v[172:175], v[144:147], v[88:91]
	v_mfma_f32_16x16x32_bf16 v[84:87], v[176:179], v[144:147], v[84:87]
	v_mfma_f32_16x16x32_bf16 v[80:83], v[180:183], v[144:147], v[80:83]
	v_mfma_f32_16x16x32_bf16 v[76:79], v[168:171], v[148:151], v[76:79]
	v_mfma_f32_16x16x32_bf16 v[72:75], v[172:175], v[148:151], v[72:75]
	v_mfma_f32_16x16x32_bf16 v[68:71], v[176:179], v[148:151], v[68:71]
	v_mfma_f32_16x16x32_bf16 v[64:67], v[180:183], v[148:151], v[64:67]
	v_mfma_f32_16x16x32_bf16 v[60:63], v[168:171], v[152:155], v[60:63]
	v_mfma_f32_16x16x32_bf16 v[56:59], v[172:175], v[152:155], v[56:59]
	v_mfma_f32_16x16x32_bf16 v[52:55], v[176:179], v[152:155], v[52:55]
	v_mfma_f32_16x16x32_bf16 v[48:51], v[180:183], v[152:155], v[48:51]
	v_mfma_f32_16x16x32_bf16 v[44:47], v[168:171], v[156:159], v[44:47]
	v_mfma_f32_16x16x32_bf16 v[40:43], v[172:175], v[156:159], v[40:43]
	v_mfma_f32_16x16x32_bf16 v[36:39], v[176:179], v[156:159], v[36:39]
	v_mfma_f32_16x16x32_bf16 v[32:35], v[180:183], v[156:159], v[32:35]
	v_mfma_f32_16x16x32_bf16 v[28:31], v[168:171], v[160:163], v[28:31]
	v_mfma_f32_16x16x32_bf16 v[24:27], v[172:175], v[160:163], v[24:27]
	v_mfma_f32_16x16x32_bf16 v[20:23], v[176:179], v[160:163], v[20:23]
	v_mfma_f32_16x16x32_bf16 v[16:19], v[180:183], v[160:163], v[16:19]
	v_mfma_f32_16x16x32_bf16 v[12:15], v[168:171], v[164:167], v[12:15]
	v_mfma_f32_16x16x32_bf16 v[8:11], v[172:175], v[164:167], v[8:11]
	v_mfma_f32_16x16x32_bf16 v[4:7], v[176:179], v[164:167], v[4:7]
	v_mfma_f32_16x16x32_bf16 v[0:3], v[180:183], v[164:167], v[0:3]
	s_setprio 0
	v_and_b32_e32 v128, 0xffffff80, v137
	v_add_u32_e32 v139, s27, v128
	v_and_or_b32 v130, v137, 63, v139
	v_cmp_gt_i32_e32 vcc, s23, v130
	v_mov_b32_e32 v140, 0x358637bd
	v_mov_b32_e32 v141, 0x358637bd
	s_and_saveexec_b64 s[4:5], vcc
	s_cbranch_execz .LBB0_1877
	v_ashrrev_i32_e32 v131, 31, v130
	v_readlane_b32 s28, v254, 18
	v_lshlrev_b64 v[132:133], 7, v[130:131]
	v_readlane_b32 s29, v254, 19
	s_nop 1
	v_lshl_add_u64 v[132:133], s[28:29], 0, v[132:133]
	global_load_dwordx4 v[142:145], v[132:133], off
	global_load_dwordx4 v[146:149], v[132:133], off offset:16
	global_load_dwordx4 v[150:153], v[132:133], off offset:32
	global_load_dwordx4 v[154:157], v[132:133], off offset:48
	global_load_dwordx4 v[158:161], v[132:133], off offset:64
	global_load_dwordx4 v[162:165], v[132:133], off offset:80
	global_load_dwordx4 v[166:169], v[132:133], off offset:96
	global_load_dwordx4 v[170:173], v[132:133], off offset:112
	s_waitcnt vmcnt(0)
	v_mov_b32_e32 v132, v142
	v_mov_b32_e32 v133, v146
	v_mov_b32_e32 v146, v143
	v_mov_b32_e32 v142, v144
	v_mov_b32_e32 v143, v148
	v_pk_add_f32 v[132:133], v[132:133], v[146:147]
	v_mov_b32_e32 v148, v145
	v_mov_b32_e32 v144, v150
	v_mov_b32_e32 v145, v154
	v_mov_b32_e32 v154, v151
	v_pk_add_f32 v[132:133], v[132:133], v[142:143]
	v_mov_b32_e32 v150, v152
	v_mov_b32_e32 v151, v156
	v_pk_add_f32 v[144:145], v[144:145], v[154:155]
	v_pk_add_f32 v[132:133], v[132:133], v[148:149]
	v_mov_b32_e32 v156, v153
	v_mov_b32_e32 v152, v158
	v_mov_b32_e32 v153, v162
	v_mov_b32_e32 v162, v159
	v_pk_add_f32 v[142:143], v[144:145], v[150:151]
	v_add_f32_e32 v128, 0, v132
	v_mov_b32_e32 v158, v160
	v_mov_b32_e32 v159, v164
	v_pk_add_f32 v[146:147], v[152:153], v[162:163]
	v_pk_add_f32 v[142:143], v[142:143], v[156:157]
	v_add_f32_e32 v128, v128, v133
	v_mov_b32_e32 v164, v161
	v_mov_b32_e32 v160, v166
	v_mov_b32_e32 v161, v170
	v_mov_b32_e32 v170, v167
	v_pk_add_f32 v[144:145], v[146:147], v[158:159]
	v_add_f32_e32 v128, v128, v142
	v_mov_b32_e32 v166, v168
	v_mov_b32_e32 v167, v172
	v_pk_add_f32 v[152:153], v[160:161], v[170:171]
	v_pk_add_f32 v[144:145], v[144:145], v[164:165]
	v_add_f32_e32 v128, v128, v143
	v_mov_b32_e32 v172, v169
	v_pk_add_f32 v[146:147], v[152:153], v[166:167]
	v_add_f32_e32 v128, v128, v144
	v_add_f32_e32 v128, v128, v145
	v_pk_add_f32 v[132:133], v[146:147], v[172:173]
	s_nop 0
	v_add_f32_e32 v128, v128, v132
	v_add_f32_e32 v128, v128, v133
	v_fmamk_f32 v141, v128, 0x3a000000, v134

.LBB0_1911:
	s_or_b64 exec, exec, s[0:1]
	v_mov_b32_e32 v0, v190
	v_mov_b32_e32 v1, v190
	s_waitcnt lgkmcnt(0)
	s_barrier
	s_movk_i32 s0, 0x4080
	v_ashrrev_i32_e32 v1, 6, v1
	v_add_u32_e32 v16, s87, v1
	v_cmp_gt_i32_e32 vcc, s0, v16
	s_and_saveexec_b64 s[0:1], vcc
	s_cbranch_execz .LBB0_1914
	v_lshlrev_b32_e32 v0, 2, v0
	v_and_b32_e32 v22, 0xfc, v0
	v_readlane_b32 s4, v254, 2
	v_mov_b32_e32 v19, 0
	v_lshlrev_b32_e32 v18, 2, v22
	v_readlane_b32 s18, v254, 16
	v_readlane_b32 s19, v254, 17
	s_movk_i32 s2, 0x3000
	v_mbcnt_hi_u32_b32 v17, -1, v191
	v_lshl_add_u64 v[4:5], s[18:19], 0, v[18:19]
	v_add_co_u32_e32 v0, vcc, s2, v4
	s_mov_b64 s[2:3], 0x3000
	s_nop 0
	v_addc_co_u32_e32 v1, vcc, 0, v5, vcc
	v_lshl_add_u64 v[12:13], v[4:5], 0, s[2:3]
	global_load_dwordx4 v[0:3], v[0:1], off
	s_nop 0
	global_load_dwordx4 v[4:7], v[12:13], off offset:1024
	global_load_dwordx4 v[8:11], v[12:13], off offset:2048
	s_nop 0
	global_load_dwordx4 v[12:15], v[12:13], off offset:3072
	v_and_b32_e32 v18, 64, v17
	v_xor_b32_e32 v20, 32, v17
	v_add_u32_e32 v32, 64, v18
	v_xor_b32_e32 v21, 16, v17
	v_cmp_lt_i32_e32 vcc, v20, v32
	v_xor_b32_e32 v23, 8, v17
	v_xor_b32_e32 v29, 4, v17
	v_cndmask_b32_e32 v33, v17, v20, vcc
	v_cmp_lt_i32_e32 vcc, v21, v32
	v_readlane_b32 s8, v254, 6
	v_readlane_b32 s9, v254, 7
	v_cndmask_b32_e32 v34, v17, v21, vcc
	v_cmp_lt_i32_e32 vcc, v23, v32
	v_readlane_b32 s10, v254, 8
	v_readlane_b32 s11, v254, 9
	v_readlane_b32 s12, v254, 10
	v_readlane_b32 s13, v254, 11
	v_readlane_b32 s14, v254, 12
	v_readlane_b32 s15, v254, 13
	v_readlane_b32 s16, v254, 14
	v_readlane_b32 s17, v254, 15
	v_xor_b32_e32 v30, 2, v17
	v_cndmask_b32_e32 v23, v17, v23, vcc
	v_cmp_lt_i32_e32 vcc, v29, v32
	v_readlane_b32 s6, v254, 4
	v_readlane_b32 s7, v254, 5
	v_readlane_b32 s8, v254, 34
	v_xor_b32_e32 v31, 1, v17
	v_cndmask_b32_e32 v35, v17, v29, vcc
	v_cmp_lt_i32_e32 vcc, v30, v32
	v_readlane_b32 s6, v255, 39
	v_readlane_b32 s14, v254, 40
	v_readlane_b32 s15, v254, 41
	v_readlane_b32 s22, v254, 48
	v_readlane_b32 s23, v254, 49
	v_cndmask_b32_e32 v36, v17, v30, vcc
	v_cmp_lt_i32_e32 vcc, v31, v32
	v_readlane_b32 s5, v254, 3
	v_readlane_b32 s7, v255, 40
	s_mov_b64 s[14:15], s[22:23]
	v_lshlrev_b32_e32 v18, 1, v22
	v_cndmask_b32_e32 v17, v17, v31, vcc
	s_lshl_b32 s4, s86, 2
	s_mov_b64 s[2:3], 0
	s_movk_i32 s5, 0x4000
	v_mov_b32_e32 v24, s7
	v_mov_b32_e32 v25, s15
	v_mov_b32_e32 v26, s6
	v_mov_b32_e32 v27, s14
	v_mov_b32_e32 v28, 0x358637bd
	s_mov_b32 s6, 0x800000
	s_movk_i32 s7, 0x7fff
	s_movk_i32 s8, 0x407f
	v_and_b32_e32 v200, -64, v18
	v_add_u32_e32 v200, v18, v200
	v_mov_b32_e32 v201, v19
	v_lshl_add_u64 v[20:21], s[88:89], 0, v[200:201]
	v_lshlrev_b32_e32 v29, 2, v33
	v_lshlrev_b32_e32 v30, 2, v34
	v_lshlrev_b32_e32 v31, 2, v23
	v_lshlrev_b32_e32 v32, 2, v35
	v_lshlrev_b32_e32 v33, 2, v36
	v_lshlrev_b32_e32 v34, 2, v17
	v_lshlrev_b32_e32 v18, 2, v22
	v_readlane_b32 s9, v254, 35
	v_readlane_b32 s10, v254, 36
	v_readlane_b32 s11, v254, 37
	v_readlane_b32 s12, v254, 38
	v_readlane_b32 s13, v254, 39
	v_readlane_b32 s16, v254, 42
	v_readlane_b32 s17, v254, 43
	v_readlane_b32 s18, v254, 44
	v_readlane_b32 s19, v254, 45
	v_readlane_b32 s20, v254, 46
	v_readlane_b32 s21, v254, 47
	s_waitcnt vmcnt(3)
	v_mov_b32_e32 v22, v1
	v_mov_b32_e32 v23, v3
	v_mov_b32_e32 v1, v2
	s_waitcnt vmcnt(2)
	v_mov_b32_e32 v2, v5
	v_mov_b32_e32 v3, v7
	v_mov_b32_e32 v5, v6
	s_waitcnt vmcnt(1)
	v_mov_b32_e32 v6, v9
	v_mov_b32_e32 v7, v11
	v_mov_b32_e32 v9, v10
	s_waitcnt vmcnt(0)
	v_mov_b32_e32 v10, v13
	v_mov_b32_e32 v11, v15
	v_mov_b32_e32 v13, v14
	v_mov_b32_e32 v14, 1

.LBB0_1939:
	s_or_b64 exec, exec, s[0:1]
	v_readlane_b32 s0, v255, 0
	v_readlane_b32 s1, v255, 1
	s_andn2_b64 vcc, exec, s[0:1]
	s_waitcnt lgkmcnt(0)
	s_barrier
	s_cbranch_vccnz .LBB0_2070
	v_readlane_b32 s49, v254, 56
	s_movk_i32 s2, 0xf000
	s_movk_i32 s34, 0xfc00
	s_movk_i32 s36, 0xf040
	s_movk_i32 s38, 0xfc40
	s_lshl_b32 s42, s49, 1
	s_lshl_b32 s43, s86, 1
	s_lshl_b32 s44, s49, 3
	s_lshl_b32 s45, s86, 3
	v_mov_b32_e32 v129, 0
	s_mov_b64 s[8:9], 0x20000
	s_mov_b64 s[10:11], 0x40000
	s_mov_b64 s[12:13], 0x60000
	s_mov_b64 s[14:15], 0x20080
	s_mov_b64 s[16:17], 0x40080
	s_mov_b64 s[18:19], 0x60080
	s_mov_b64 s[20:21], 0x12d0100
	s_mov_b64 s[22:23], 0x12f0100
	s_mov_b64 s[24:25], 0x1310100
	s_mov_b64 s[26:27], 0x1330100
	s_mov_b64 s[28:29], 0x100
	s_mov_b64 s[30:31], 0x20100
	s_movk_i32 s46, 0x7fff
	s_mov_b32 s47, 0xffff0000
	s_movk_i32 s48, 0x1ff
	s_mov_b32 s3, -1
	s_mov_b32 s35, -1
	s_mov_b32 s37, -1
	s_mov_b32 s39, -1
	v_mov_b32_e32 v142, 1
	s_branch .LBB0_1943

.LBB0_1943:
	s_lshl_b32 s0, s44, 8
	s_lshl_b32 s1, s49, 3
	s_and_b32 s5, s0, 0x3800
	s_bfe_u32 s0, s49, 0x30003
	s_and_b32 s1, s1, 56
	s_lshl_b32 s33, s49, 1
	s_and_b32 s7, s42, 0xffffff80
	s_lshl_b32 s6, s0, 8
	s_or_b32 s40, s1, s0
	s_and_b32 s4, s33, 0xffffff80
	s_cmpk_gt_i32 s4, 0x3ff
	s_cselect_b64 s[0:1], -1, 0
	s_and_b32 s41, s49, 0x3ffffe00
	s_cmpk_lg_i32 s41, 0x400
	s_cselect_b64 s[50:51], -1, 0
	s_and_b64 s[50:51], s[50:51], s[0:1]
	s_mov_b64 s[0:1], -1
	s_and_b64 vcc, exec, s[50:51]
	s_cbranch_vccz .LBB0_1947
	s_mov_b64 s[62:63], 0x80
	v_mov_b32_e32 v134, v190
	s_lshl_b32 s41, s40, 8
	v_ashrrev_i32_e32 v6, 2, v134
	v_and_b32_e32 v6, -2, v6
	v_lshlrev_b32_e32 v0, 6, v134
	v_and_b32_e32 v141, 0xffffe000, v0
	v_add_u32_e32 v0, s41, v6
	v_ashrrev_i32_e32 v1, 31, v0
	v_lshlrev_b32_e32 v140, 4, v134
	v_lshlrev_b64 v[0:1], 11, v[0:1]
	v_lshl_add_u64 v[0:1], s[88:89], 0, v[0:1]
	v_and_b32_e32 v128, 0x70, v140
	v_readfirstlane_b32 s0, v140
	v_add_u32_e32 v7, 0x1000, v140
	v_lshl_add_u64 v[0:1], v[0:1], 0, v[128:129]
	s_waitcnt vmcnt(0)
	s_mov_b32 m0, s0
	v_readfirstlane_b32 s0, v7
	v_add_u32_e32 v7, 0x2000, v140
	global_load_lds_dwordx4 v[0:1], off
	v_lshl_add_u64 v[4:5], v[0:1], 0, s[8:9]
	s_mov_b32 m0, s0
	v_readfirstlane_b32 s0, v7
	v_add_u32_e32 v7, 0x3000, v140
	v_add_u32_e32 v2, s4, v6
	global_load_lds_dwordx4 v[4:5], off
	v_lshl_add_u64 v[4:5], v[0:1], 0, s[10:11]
	s_mov_b32 m0, s0
	v_readfirstlane_b32 s0, v7
	v_ashrrev_i32_e32 v3, 31, v2
	global_load_lds_dwordx4 v[4:5], off
	v_lshl_add_u64 v[4:5], v[0:1], 0, s[12:13]
	s_mov_b32 m0, s0
	v_lshlrev_b64 v[2:3], 11, v[2:3]
	global_load_lds_dwordx4 v[4:5], off
	v_add_u32_e32 v4, 0x4000, v140
	v_lshl_add_u64 v[2:3], s[52:53], 0, v[2:3]
	v_readfirstlane_b32 s0, v4
	v_add_u32_e32 v7, 0x5000, v140
	v_lshl_add_u64 v[2:3], v[2:3], 0, v[128:129]
	s_mov_b32 m0, s0
	v_readfirstlane_b32 s0, v7
	v_add_u32_e32 v7, 0x6000, v140
	global_load_lds_dwordx4 v[2:3], off
	v_lshl_add_u64 v[4:5], v[2:3], 0, s[8:9]
	s_mov_b32 m0, s0
	v_readfirstlane_b32 s0, v7
	v_add_u32_e32 v7, 0x7000, v140
	global_load_lds_dwordx4 v[4:5], off
	v_lshl_add_u64 v[4:5], v[0:1], 0, s[62:63]
	s_mov_b32 m0, s0
	v_readfirstlane_b32 s0, v7
	v_add_u32_e32 v7, 0x8000, v140
	global_load_lds_dwordx4 v[4:5], off
	v_lshl_add_u64 v[4:5], v[0:1], 0, s[14:15]
	s_mov_b32 m0, s0
	v_readfirstlane_b32 s0, v7
	global_load_lds_dwordx4 v[4:5], off
	v_lshl_add_u64 v[4:5], v[0:1], 0, s[16:17]
	s_mov_b32 m0, s0
	v_lshl_add_u64 v[0:1], v[0:1], 0, s[18:19]
	global_load_lds_dwordx4 v[4:5], off
	v_add_u32_e32 v4, 0x9000, v140
	v_and_b32_e32 v135, 15, v134
	v_readfirstlane_b32 s0, v4
	v_add_u32_e32 v4, 0xa000, v140
	s_mov_b32 m0, s0
	v_readfirstlane_b32 s0, v4
	global_load_lds_dwordx4 v[0:1], off
	v_lshl_add_u64 v[0:1], v[2:3], 0, s[62:63]
	s_mov_b32 m0, s0
	v_bfe_u32 v136, v134, 6, 1
	global_load_lds_dwordx4 v[0:1], off
	v_lshl_add_u64 v[0:1], v[2:3], 0, s[14:15]
	v_add_u32_e32 v2, 0xb000, v140
	v_lshlrev_b32_e32 v137, 6, v135
	v_readfirstlane_b32 s0, v2
	s_mov_b32 m0, s0
	s_add_i32 s0, s6, s5
	global_load_lds_dwordx4 v[0:1], off
	v_add_u32_e32 v0, s7, v6
	v_ashrrev_i32_e32 v1, 31, v0
	v_lshlrev_b64 v[0:1], 11, v[0:1]
	v_or_b32_e32 v0, v0, v128
	v_lshl_add_u64 v[130:131], s[52:53], 0, v[0:1]
	v_add_u32_e32 v0, s0, v6
	v_ashrrev_i32_e32 v1, 31, v0
	v_lshlrev_b64 v[0:1], 11, v[0:1]
	v_or_b32_e32 v0, v0, v128
	v_lshl_add_u64 v[132:133], s[52:53], 0, v[0:1]
	v_mov_b32_e32 v0, 0
	v_and_b32_e32 v138, 48, v134
	v_lshlrev_b32_e32 v139, 12, v136
	s_mov_b32 s50, 0
	s_mov_b64 s[0:1], 0
	v_mov_b32_e32 v1, v0
	v_mov_b32_e32 v2, v0
	v_mov_b32_e32 v3, v0
	v_mov_b32_e32 v4, v0
	v_mov_b32_e32 v5, v0
	v_mov_b32_e32 v6, v0
	v_mov_b32_e32 v7, v0
	v_mov_b32_e32 v8, v0
	v_mov_b32_e32 v9, v0
	v_mov_b32_e32 v10, v0
	v_mov_b32_e32 v11, v0
	v_mov_b32_e32 v12, v0
	v_mov_b32_e32 v13, v0
	v_mov_b32_e32 v14, v0
	v_mov_b32_e32 v15, v0
	v_mov_b32_e32 v16, v0
	v_mov_b32_e32 v17, v0
	v_mov_b32_e32 v18, v0
	v_mov_b32_e32 v19, v0
	v_mov_b32_e32 v20, v0
	v_mov_b32_e32 v21, v0
	v_mov_b32_e32 v22, v0
	v_mov_b32_e32 v23, v0
	v_mov_b32_e32 v24, v0
	v_mov_b32_e32 v25, v0
	v_mov_b32_e32 v26, v0
	v_mov_b32_e32 v27, v0
	v_mov_b32_e32 v28, v0
	v_mov_b32_e32 v29, v0
	v_mov_b32_e32 v30, v0
	v_mov_b32_e32 v31, v0
	v_mov_b32_e32 v32, v0
	v_mov_b32_e32 v33, v0
	v_mov_b32_e32 v34, v0
	v_mov_b32_e32 v35, v0
	v_mov_b32_e32 v36, v0
	v_mov_b32_e32 v37, v0
	v_mov_b32_e32 v38, v0
	v_mov_b32_e32 v39, v0
	v_mov_b32_e32 v40, v0
	v_mov_b32_e32 v41, v0
	v_mov_b32_e32 v42, v0
	v_mov_b32_e32 v43, v0
	v_mov_b32_e32 v44, v0
	v_mov_b32_e32 v45, v0
	v_mov_b32_e32 v46, v0
	v_mov_b32_e32 v47, v0
	v_mov_b32_e32 v48, v0
	v_mov_b32_e32 v49, v0
	v_mov_b32_e32 v50, v0
	v_mov_b32_e32 v51, v0
	v_mov_b32_e32 v52, v0
	v_mov_b32_e32 v53, v0
	v_mov_b32_e32 v54, v0
	v_mov_b32_e32 v55, v0
	v_mov_b32_e32 v56, v0
	v_mov_b32_e32 v57, v0
	v_mov_b32_e32 v58, v0
	v_mov_b32_e32 v59, v0
	v_mov_b32_e32 v60, v0
	v_mov_b32_e32 v61, v0
	v_mov_b32_e32 v62, v0
	v_mov_b32_e32 v63, v0
	v_mov_b32_e32 v64, v0
	v_mov_b32_e32 v65, v0
	v_mov_b32_e32 v66, v0
	v_mov_b32_e32 v67, v0
	v_mov_b32_e32 v68, v0
	v_mov_b32_e32 v69, v0
	v_mov_b32_e32 v70, v0
	v_mov_b32_e32 v71, v0
	v_mov_b32_e32 v72, v0
	v_mov_b32_e32 v73, v0
	v_mov_b32_e32 v74, v0
	v_mov_b32_e32 v75, v0
	v_mov_b32_e32 v76, v0
	v_mov_b32_e32 v77, v0
	v_mov_b32_e32 v78, v0
	v_mov_b32_e32 v79, v0
	v_mov_b32_e32 v80, v0
	v_mov_b32_e32 v81, v0
	v_mov_b32_e32 v82, v0
	v_mov_b32_e32 v83, v0
	v_mov_b32_e32 v84, v0
	v_mov_b32_e32 v85, v0
	v_mov_b32_e32 v86, v0
	v_mov_b32_e32 v87, v0
	v_mov_b32_e32 v88, v0
	v_mov_b32_e32 v89, v0
	v_mov_b32_e32 v90, v0
	v_mov_b32_e32 v91, v0
	v_mov_b32_e32 v92, v0
	v_mov_b32_e32 v93, v0
	v_mov_b32_e32 v94, v0
	v_mov_b32_e32 v95, v0
	v_mov_b32_e32 v96, v0
	v_mov_b32_e32 v97, v0
	v_mov_b32_e32 v98, v0
	v_mov_b32_e32 v99, v0
	v_mov_b32_e32 v100, v0
	v_mov_b32_e32 v101, v0
	v_mov_b32_e32 v102, v0
	v_mov_b32_e32 v103, v0
	v_mov_b32_e32 v104, v0
	v_mov_b32_e32 v105, v0
	v_mov_b32_e32 v106, v0
	v_mov_b32_e32 v107, v0
	v_mov_b32_e32 v108, v0
	v_mov_b32_e32 v109, v0
	v_mov_b32_e32 v110, v0
	v_mov_b32_e32 v111, v0
	v_mov_b32_e32 v112, v0
	v_mov_b32_e32 v113, v0
	v_mov_b32_e32 v114, v0
	v_mov_b32_e32 v115, v0
	v_mov_b32_e32 v116, v0
	v_mov_b32_e32 v117, v0
	v_mov_b32_e32 v118, v0
	v_mov_b32_e32 v119, v0
	v_mov_b32_e32 v120, v0
	v_mov_b32_e32 v121, v0
	v_mov_b32_e32 v122, v0
	v_mov_b32_e32 v123, v0
	v_mov_b32_e32 v124, v0
	v_mov_b32_e32 v125, v0
	v_mov_b32_e32 v126, v0
	v_mov_b32_e32 v127, v0
.LBB0_1945:
	s_add_i32 s51, s50, 2
	s_mul_hi_i32 s52, s51, 0x55555556
	s_lshr_b32 s53, s52, 31
	s_add_i32 s52, s52, s53
	s_mul_i32 s52, s52, 3
	s_sub_i32 s51, s51, s52
	s_mulk_i32 s51, 0x6000
	s_mul_i32 s54, s50, 0x6000
	v_readfirstlane_b32 s55, v140
	v_lshl_add_u64 v[232:233], v[132:133], 0, s[0:1]
	v_lshl_add_u64 v[234:235], v[130:131], 0, s[0:1]
	s_add_u32 s55, s55, s51
	s_waitcnt vmcnt(6) lgkmcnt(0)
	s_barrier
	v_or_b32_e32 v128, s54, v139
	v_add3_u32 v128, v128, v137, v138
	ds_read_b128 v[176:179], v128 offset:16384
	ds_read_b128 v[180:183], v128 offset:17408
	ds_read_b128 v[184:187], v128 offset:18432
	ds_read_b128 v[192:195], v128 offset:19456
	v_add_u32_e32 v128, s54, v141
	v_add3_u32 v128, v128, v137, v138
	ds_read_b128 v[144:147], v128
	ds_read_b128 v[148:151], v128 offset:1024
	ds_read_b128 v[152:155], v128 offset:2048
	ds_read_b128 v[156:159], v128 offset:3072
	ds_read_b128 v[160:163], v128 offset:4096
	ds_read_b128 v[164:167], v128 offset:5120
	ds_read_b128 v[168:171], v128 offset:6144
	ds_read_b128 v[172:175], v128 offset:7168
	s_setprio 1
	s_waitcnt lgkmcnt(7)
	v_mfma_f32_16x16x32_bf16 v[124:127], v[144:147], v[176:179], v[124:127]
	v_mfma_f32_16x16x32_bf16 v[120:123], v[144:147], v[180:183], v[120:123]
	v_mfma_f32_16x16x32_bf16 v[116:119], v[144:147], v[184:187], v[116:119]
	v_mfma_f32_16x16x32_bf16 v[112:115], v[144:147], v[192:195], v[112:115]
	s_mov_b32 m0, s55
	v_lshl_add_u64 v[236:237], v[232:233], 0, s[20:21]
	global_load_lds_dwordx4 v[236:237], off
	s_waitcnt lgkmcnt(6)
	v_mfma_f32_16x16x32_bf16 v[108:111], v[148:151], v[176:179], v[108:111]
	v_mfma_f32_16x16x32_bf16 v[104:107], v[148:151], v[180:183], v[104:107]
	v_mfma_f32_16x16x32_bf16 v[100:103], v[148:151], v[184:187], v[100:103]
	v_mfma_f32_16x16x32_bf16 v[96:99], v[148:151], v[192:195], v[96:99]
	s_add_u32 m0, s55, 0x1000
	v_lshl_add_u64 v[236:237], v[232:233], 0, s[22:23]
	global_load_lds_dwordx4 v[236:237], off
	s_waitcnt lgkmcnt(5)
	v_mfma_f32_16x16x32_bf16 v[92:95], v[152:155], v[176:179], v[92:95]
	v_mfma_f32_16x16x32_bf16 v[88:91], v[152:155], v[180:183], v[88:91]
	v_mfma_f32_16x16x32_bf16 v[84:87], v[152:155], v[184:187], v[84:87]
	v_mfma_f32_16x16x32_bf16 v[80:83], v[152:155], v[192:195], v[80:83]
	s_add_u32 m0, s55, 0x2000
	v_lshl_add_u64 v[236:237], v[232:233], 0, s[24:25]
	global_load_lds_dwordx4 v[236:237], off
	s_waitcnt lgkmcnt(4)
	v_mfma_f32_16x16x32_bf16 v[76:79], v[156:159], v[176:179], v[76:79]
	v_mfma_f32_16x16x32_bf16 v[72:75], v[156:159], v[180:183], v[72:75]
	v_mfma_f32_16x16x32_bf16 v[68:71], v[156:159], v[184:187], v[68:71]
	v_mfma_f32_16x16x32_bf16 v[64:67], v[156:159], v[192:195], v[64:67]
	s_add_u32 m0, s55, 0x3000
	v_lshl_add_u64 v[236:237], v[232:233], 0, s[26:27]
	global_load_lds_dwordx4 v[236:237], off
	s_waitcnt lgkmcnt(3)
	v_mfma_f32_16x16x32_bf16 v[60:63], v[160:163], v[176:179], v[60:63]
	v_mfma_f32_16x16x32_bf16 v[56:59], v[160:163], v[180:183], v[56:59]
	v_mfma_f32_16x16x32_bf16 v[52:55], v[160:163], v[184:187], v[52:55]
	v_mfma_f32_16x16x32_bf16 v[48:51], v[160:163], v[192:195], v[48:51]
	s_add_u32 m0, s55, 0x4000
	v_lshl_add_u64 v[236:237], v[234:235], 0, s[28:29]
	global_load_lds_dwordx4 v[236:237], off
	s_waitcnt lgkmcnt(2)
	v_mfma_f32_16x16x32_bf16 v[44:47], v[164:167], v[176:179], v[44:47]
	v_mfma_f32_16x16x32_bf16 v[40:43], v[164:167], v[180:183], v[40:43]
	v_mfma_f32_16x16x32_bf16 v[36:39], v[164:167], v[184:187], v[36:39]
	v_mfma_f32_16x16x32_bf16 v[32:35], v[164:167], v[192:195], v[32:35]
	s_add_u32 m0, s55, 0x5000
	v_lshl_add_u64 v[236:237], v[234:235], 0, s[30:31]
	global_load_lds_dwordx4 v[236:237], off
	s_waitcnt lgkmcnt(1)
	v_mfma_f32_16x16x32_bf16 v[28:31], v[168:171], v[176:179], v[28:31]
	v_mfma_f32_16x16x32_bf16 v[24:27], v[168:171], v[180:183], v[24:27]
	v_mfma_f32_16x16x32_bf16 v[20:23], v[168:171], v[184:187], v[20:23]
	v_mfma_f32_16x16x32_bf16 v[16:19], v[168:171], v[192:195], v[16:19]
	s_waitcnt lgkmcnt(0)
	v_mfma_f32_16x16x32_bf16 v[12:15], v[172:175], v[176:179], v[12:15]
	v_mfma_f32_16x16x32_bf16 v[8:11], v[172:175], v[180:183], v[8:11]
	v_mfma_f32_16x16x32_bf16 v[4:7], v[172:175], v[184:187], v[4:7]
	v_mfma_f32_16x16x32_bf16 v[0:3], v[172:175], v[192:195], v[0:3]
	s_setprio 0
	s_add_i32 s51, s50, 1
	s_cmp_lg_u32 s50, 2
	s_cselect_b32 s50, s51, 0
	s_add_u32 s0, s0, 0x80
	s_addc_u32 s1, s1, 0
	s_cmpk_lg_i32 s0, 0xf00
	s_cbranch_scc1 .LBB0_1945
	s_waitcnt vmcnt(6) lgkmcnt(0)
	s_barrier
	v_add3_u32 v128, v141, v137, v138
	ds_read_b128 v[130:133], v128
	ds_read_b128 v[144:147], v128 offset:1024
	ds_read_b128 v[148:151], v128 offset:2048
	ds_read_b128 v[152:155], v128 offset:3072
	ds_read_b128 v[156:159], v128 offset:4096
	ds_read_b128 v[160:163], v128 offset:5120
	ds_read_b128 v[164:167], v128 offset:6144
	ds_read_b128 v[168:171], v128 offset:7168
	v_add3_u32 v137, v139, v137, v138
	ds_read_b128 v[138:141], v137 offset:16384
	ds_read_b128 v[172:175], v137 offset:17408
	ds_read_b128 v[176:179], v137 offset:18432
	ds_read_b128 v[180:183], v137 offset:19456
	s_setprio 1
	s_waitcnt lgkmcnt(0)
	v_mfma_f32_16x16x32_bf16 v[124:127], v[130:133], v[138:141], v[124:127]
	v_mfma_f32_16x16x32_bf16 v[120:123], v[130:133], v[172:175], v[120:123]
	v_mfma_f32_16x16x32_bf16 v[116:119], v[130:133], v[176:179], v[116:119]
	v_mfma_f32_16x16x32_bf16 v[112:115], v[130:133], v[180:183], v[112:115]
	v_mfma_f32_16x16x32_bf16 v[108:111], v[144:147], v[138:141], v[108:111]
	v_mfma_f32_16x16x32_bf16 v[104:107], v[144:147], v[172:175], v[104:107]
	v_mfma_f32_16x16x32_bf16 v[100:103], v[144:147], v[176:179], v[100:103]
	v_mfma_f32_16x16x32_bf16 v[96:99], v[144:147], v[180:183], v[96:99]
	v_mfma_f32_16x16x32_bf16 v[92:95], v[148:151], v[138:141], v[92:95]
	v_mfma_f32_16x16x32_bf16 v[88:91], v[148:151], v[172:175], v[88:91]
	v_mfma_f32_16x16x32_bf16 v[84:87], v[148:151], v[176:179], v[84:87]
	v_mfma_f32_16x16x32_bf16 v[80:83], v[148:151], v[180:183], v[80:83]
	v_mfma_f32_16x16x32_bf16 v[76:79], v[152:155], v[138:141], v[76:79]
	v_mfma_f32_16x16x32_bf16 v[72:75], v[152:155], v[172:175], v[72:75]
	v_mfma_f32_16x16x32_bf16 v[68:71], v[152:155], v[176:179], v[68:71]
	v_mfma_f32_16x16x32_bf16 v[64:67], v[152:155], v[180:183], v[64:67]
	v_mfma_f32_16x16x32_bf16 v[60:63], v[156:159], v[138:141], v[60:63]
	v_mfma_f32_16x16x32_bf16 v[56:59], v[156:159], v[172:175], v[56:59]
	v_mfma_f32_16x16x32_bf16 v[52:55], v[156:159], v[176:179], v[52:55]
	v_mfma_f32_16x16x32_bf16 v[48:51], v[156:159], v[180:183], v[48:51]
	v_mfma_f32_16x16x32_bf16 v[44:47], v[160:163], v[138:141], v[44:47]
	v_mfma_f32_16x16x32_bf16 v[40:43], v[160:163], v[172:175], v[40:43]
	v_mfma_f32_16x16x32_bf16 v[36:39], v[160:163], v[176:179], v[36:39]
	v_mfma_f32_16x16x32_bf16 v[32:35], v[160:163], v[180:183], v[32:35]
	v_mfma_f32_16x16x32_bf16 v[28:31], v[164:167], v[138:141], v[28:31]
	v_mfma_f32_16x16x32_bf16 v[24:27], v[164:167], v[172:175], v[24:27]
	v_mfma_f32_16x16x32_bf16 v[20:23], v[164:167], v[176:179], v[20:23]
	v_mfma_f32_16x16x32_bf16 v[16:19], v[164:167], v[180:183], v[16:19]
	v_mfma_f32_16x16x32_bf16 v[12:15], v[168:171], v[138:141], v[12:15]
	v_mfma_f32_16x16x32_bf16 v[8:11], v[168:171], v[172:175], v[8:11]
	v_mfma_f32_16x16x32_bf16 v[4:7], v[168:171], v[176:179], v[4:7]
	v_mfma_f32_16x16x32_bf16 v[0:3], v[168:171], v[180:183], v[0:3]
	s_setprio 0
	s_waitcnt vmcnt(0) lgkmcnt(0)
	s_barrier
	ds_read_b128 v[130:133], v128 offset:24576
	ds_read_b128 v[138:141], v128 offset:25600
	ds_read_b128 v[144:147], v128 offset:26624
	ds_read_b128 v[148:151], v128 offset:27648
	ds_read_b128 v[152:155], v128 offset:28672
	ds_read_b128 v[156:159], v128 offset:29696
	ds_read_b128 v[160:163], v128 offset:30720
	ds_read_b128 v[164:167], v128 offset:31744
	ds_read_b128 v[168:171], v137 offset:40960
	ds_read_b128 v[172:175], v137 offset:41984
	ds_read_b128 v[176:179], v137 offset:43008
	ds_read_b128 v[180:183], v137 offset:44032
	s_setprio 1
	s_waitcnt lgkmcnt(0)
	v_mfma_f32_16x16x32_bf16 v[124:127], v[130:133], v[168:171], v[124:127]
	v_mfma_f32_16x16x32_bf16 v[120:123], v[130:133], v[172:175], v[120:123]
	v_mfma_f32_16x16x32_bf16 v[116:119], v[130:133], v[176:179], v[116:119]
	v_mfma_f32_16x16x32_bf16 v[112:115], v[130:133], v[180:183], v[112:115]
	v_mfma_f32_16x16x32_bf16 v[108:111], v[138:141], v[168:171], v[108:111]
	v_mfma_f32_16x16x32_bf16 v[104:107], v[138:141], v[172:175], v[104:107]
	v_mfma_f32_16x16x32_bf16 v[100:103], v[138:141], v[176:179], v[100:103]
	v_mfma_f32_16x16x32_bf16 v[96:99], v[138:141], v[180:183], v[96:99]
	v_mfma_f32_16x16x32_bf16 v[92:95], v[144:147], v[168:171], v[92:95]
	v_mfma_f32_16x16x32_bf16 v[88:91], v[144:147], v[172:175], v[88:91]
	v_mfma_f32_16x16x32_bf16 v[84:87], v[144:147], v[176:179], v[84:87]
	v_mfma_f32_16x16x32_bf16 v[130:133], v[144:147], v[180:183], v[80:83]
	v_mfma_f32_16x16x32_bf16 v[138:141], v[148:151], v[168:171], v[76:79]
	v_mfma_f32_16x16x32_bf16 v[72:75], v[148:151], v[172:175], v[72:75]
	v_mfma_f32_16x16x32_bf16 v[68:71], v[148:151], v[176:179], v[68:71]
	v_mfma_f32_16x16x32_bf16 v[64:67], v[148:151], v[180:183], v[64:67]
	v_mfma_f32_16x16x32_bf16 v[60:63], v[152:155], v[168:171], v[60:63]
	v_mfma_f32_16x16x32_bf16 v[56:59], v[152:155], v[172:175], v[56:59]
	v_mfma_f32_16x16x32_bf16 v[52:55], v[152:155], v[176:179], v[52:55]
	v_mfma_f32_16x16x32_bf16 v[48:51], v[152:155], v[180:183], v[48:51]
	v_mfma_f32_16x16x32_bf16 v[44:47], v[156:159], v[168:171], v[44:47]
	v_mfma_f32_16x16x32_bf16 v[40:43], v[156:159], v[172:175], v[40:43]
	v_mfma_f32_16x16x32_bf16 v[36:39], v[156:159], v[176:179], v[36:39]
	v_mfma_f32_16x16x32_bf16 v[32:35], v[156:159], v[180:183], v[32:35]
	v_mfma_f32_16x16x32_bf16 v[28:31], v[160:163], v[168:171], v[28:31]
	v_mfma_f32_16x16x32_bf16 v[24:27], v[160:163], v[172:175], v[24:27]
	v_mfma_f32_16x16x32_bf16 v[20:23], v[160:163], v[176:179], v[20:23]
	v_mfma_f32_16x16x32_bf16 v[16:19], v[160:163], v[180:183], v[16:19]
	v_mfma_f32_16x16x32_bf16 v[12:15], v[164:167], v[168:171], v[12:15]
	v_mfma_f32_16x16x32_bf16 v[8:11], v[164:167], v[172:175], v[8:11]
	v_mfma_f32_16x16x32_bf16 v[4:7], v[164:167], v[176:179], v[4:7]
	v_mfma_f32_16x16x32_bf16 v[0:3], v[164:167], v[180:183], v[0:3]
	s_setprio 0
	v_and_b32_e32 v76, 0xffffff80, v134
	v_add_u32_e32 v76, s41, v76
	v_lshlrev_b32_e32 v77, 6, v136
	s_add_i32 s0, s4, 0xfffffc00
	v_ashrrev_i32_e32 v76, 6, v76
	v_or3_b32 v136, v77, s0, v135
	v_ashrrev_i32_e32 v77, 31, v76
	v_lshlrev_b64 v[78:79], 17, v[76:77]
	v_readlane_b32 s0, v254, 60
	v_lshrrev_b32_e32 v77, 1, v134
	v_and_b32_sdwa v81, v127, v142 dst_sel:DWORD dst_unused:UNUSED_PAD src0_sel:WORD_1 src1_sel:DWORD
	v_and_b32_sdwa v82, v125, v142 dst_sel:DWORD dst_unused:UNUSED_PAD src0_sel:WORD_1 src1_sel:DWORD
	v_readlane_b32 s1, v254, 61
	v_and_b32_e32 v128, 24, v77
	v_and_b32_sdwa v77, v126, v142 dst_sel:DWORD dst_unused:UNUSED_PAD src0_sel:WORD_1 src1_sel:DWORD
	v_and_b32_sdwa v80, v124, v142 dst_sel:DWORD dst_unused:UNUSED_PAD src0_sel:WORD_1 src1_sel:DWORD
	v_add3_u32 v81, v127, v81, s46
	v_add3_u32 v82, v125, v82, s46
	v_lshl_add_u64 v[78:79], s[0:1], 0, v[78:79]
	v_mov_b32_e32 v137, v129
	v_add3_u32 v80, v124, v80, s46
	v_add3_u32 v77, v126, v77, s46
	v_and_b32_e32 v81, 0xffff0000, v81
	v_and_b32_e32 v82, 0xffff0000, v82
	v_and_b32_sdwa v83, v123, v142 dst_sel:DWORD dst_unused:UNUSED_PAD src0_sel:WORD_1 src1_sel:DWORD
	v_lshl_add_u64 v[134:135], v[78:79], 0, v[128:129]
	v_lshlrev_b64 v[78:79], 7, v[136:137]
	v_or_b32_sdwa v81, v81, v77 dst_sel:DWORD dst_unused:UNUSED_PAD src0_sel:DWORD src1_sel:WORD_1
	v_or_b32_sdwa v80, v82, v80 dst_sel:DWORD dst_unused:UNUSED_PAD src0_sel:DWORD src1_sel:WORD_1
	v_and_b32_sdwa v77, v122, v142 dst_sel:DWORD dst_unused:UNUSED_PAD src0_sel:WORD_1 src1_sel:DWORD
	v_and_b32_sdwa v82, v120, v142 dst_sel:DWORD dst_unused:UNUSED_PAD src0_sel:WORD_1 src1_sel:DWORD
	v_add3_u32 v83, v123, v83, s46
	v_lshl_add_u64 v[144:145], v[134:135], 0, v[78:79]
	v_add3_u32 v82, v120, v82, s46
	v_add3_u32 v77, v122, v77, s46
	v_and_b32_sdwa v120, v121, v142 dst_sel:DWORD dst_unused:UNUSED_PAD src0_sel:WORD_1 src1_sel:DWORD
	v_and_b32_e32 v83, 0xffff0000, v83
	global_store_dwordx2 v[144:145], v[80:81], off
	v_or_b32_e32 v80, 16, v136
	v_mov_b32_e32 v81, v129
	v_add3_u32 v120, v121, v120, s46
	v_or_b32_sdwa v83, v83, v77 dst_sel:DWORD dst_unused:UNUSED_PAD src0_sel:DWORD src1_sel:WORD_1
	v_and_b32_sdwa v77, v118, v142 dst_sel:DWORD dst_unused:UNUSED_PAD src0_sel:WORD_1 src1_sel:DWORD
	v_lshlrev_b64 v[80:81], 7, v[80:81]
	v_and_b32_e32 v120, 0xffff0000, v120
	v_and_b32_sdwa v122, v116, v142 dst_sel:DWORD dst_unused:UNUSED_PAD src0_sel:WORD_1 src1_sel:DWORD
	v_add3_u32 v77, v118, v77, s46
	v_and_b32_sdwa v118, v119, v142 dst_sel:DWORD dst_unused:UNUSED_PAD src0_sel:WORD_1 src1_sel:DWORD
	v_lshl_add_u64 v[124:125], v[134:135], 0, v[80:81]
	v_or_b32_sdwa v82, v120, v82 dst_sel:DWORD dst_unused:UNUSED_PAD src0_sel:DWORD src1_sel:WORD_1
	v_add3_u32 v116, v116, v122, s46
	v_and_b32_sdwa v122, v117, v142 dst_sel:DWORD dst_unused:UNUSED_PAD src0_sel:WORD_1 src1_sel:DWORD
	v_add3_u32 v118, v119, v118, s46
	global_store_dwordx2 v[124:125], v[82:83], off
	v_or_b32_e32 v82, 32, v136
	v_mov_b32_e32 v83, v129
	v_add3_u32 v117, v117, v122, s46
	v_and_b32_e32 v118, 0xffff0000, v118
	v_lshlrev_b64 v[82:83], 7, v[82:83]
	v_and_b32_e32 v119, 0xffff0000, v117
	v_or_b32_sdwa v117, v118, v77 dst_sel:DWORD dst_unused:UNUSED_PAD src0_sel:DWORD src1_sel:WORD_1
	v_and_b32_sdwa v77, v114, v142 dst_sel:DWORD dst_unused:UNUSED_PAD src0_sel:WORD_1 src1_sel:DWORD
	v_and_b32_sdwa v122, v112, v142 dst_sel:DWORD dst_unused:UNUSED_PAD src0_sel:WORD_1 src1_sel:DWORD
	v_lshl_add_u64 v[120:121], v[134:135], 0, v[82:83]
	v_or_b32_sdwa v116, v119, v116 dst_sel:DWORD dst_unused:UNUSED_PAD src0_sel:DWORD src1_sel:WORD_1
	v_add3_u32 v112, v112, v122, s46
	v_add3_u32 v77, v114, v77, s46
	v_and_b32_sdwa v114, v115, v142 dst_sel:DWORD dst_unused:UNUSED_PAD src0_sel:WORD_1 src1_sel:DWORD
	v_and_b32_sdwa v122, v113, v142 dst_sel:DWORD dst_unused:UNUSED_PAD src0_sel:WORD_1 src1_sel:DWORD
	global_store_dwordx2 v[120:121], v[116:117], off
	v_or_b32_e32 v116, 48, v136
	v_mov_b32_e32 v117, v129
	v_add3_u32 v114, v115, v114, s46
	v_add3_u32 v113, v113, v122, s46
	v_lshlrev_b64 v[116:117], 7, v[116:117]
	v_and_b32_e32 v114, 0xffff0000, v114
	v_and_b32_e32 v115, 0xffff0000, v113
	v_lshl_add_u64 v[118:119], v[134:135], 0, v[116:117]
	v_or_b32_sdwa v113, v114, v77 dst_sel:DWORD dst_unused:UNUSED_PAD src0_sel:DWORD src1_sel:WORD_1
	v_or_b32_sdwa v112, v115, v112 dst_sel:DWORD dst_unused:UNUSED_PAD src0_sel:DWORD src1_sel:WORD_1
	global_store_dwordx2 v[118:119], v[112:113], off
	v_and_b32_sdwa v77, v110, v142 dst_sel:DWORD dst_unused:UNUSED_PAD src0_sel:WORD_1 src1_sel:DWORD
	v_and_b32_sdwa v112, v108, v142 dst_sel:DWORD dst_unused:UNUSED_PAD src0_sel:WORD_1 src1_sel:DWORD
	v_add3_u32 v108, v108, v112, s46
	v_add3_u32 v77, v110, v77, s46
	v_and_b32_sdwa v110, v111, v142 dst_sel:DWORD dst_unused:UNUSED_PAD src0_sel:WORD_1 src1_sel:DWORD
	v_and_b32_sdwa v112, v109, v142 dst_sel:DWORD dst_unused:UNUSED_PAD src0_sel:WORD_1 src1_sel:DWORD
	v_add3_u32 v110, v111, v110, s46
	v_add3_u32 v109, v109, v112, s46
	v_and_b32_e32 v110, 0xffff0000, v110
	v_and_b32_e32 v111, 0xffff0000, v109
	v_or_b32_sdwa v109, v110, v77 dst_sel:DWORD dst_unused:UNUSED_PAD src0_sel:DWORD src1_sel:WORD_1
	v_or_b32_sdwa v108, v111, v108 dst_sel:DWORD dst_unused:UNUSED_PAD src0_sel:DWORD src1_sel:WORD_1
	global_store_dwordx2 v[144:145], v[108:109], off offset:32
	v_and_b32_sdwa v77, v106, v142 dst_sel:DWORD dst_unused:UNUSED_PAD src0_sel:WORD_1 src1_sel:DWORD
	v_and_b32_sdwa v108, v104, v142 dst_sel:DWORD dst_unused:UNUSED_PAD src0_sel:WORD_1 src1_sel:DWORD
	v_add3_u32 v104, v104, v108, s46
	v_add3_u32 v77, v106, v77, s46
	v_and_b32_sdwa v106, v107, v142 dst_sel:DWORD dst_unused:UNUSED_PAD src0_sel:WORD_1 src1_sel:DWORD
	v_and_b32_sdwa v108, v105, v142 dst_sel:DWORD dst_unused:UNUSED_PAD src0_sel:WORD_1 src1_sel:DWORD
	v_add3_u32 v106, v107, v106, s46
	v_add3_u32 v105, v105, v108, s46
	v_and_b32_e32 v106, 0xffff0000, v106
	v_and_b32_e32 v107, 0xffff0000, v105
	v_or_b32_sdwa v105, v106, v77 dst_sel:DWORD dst_unused:UNUSED_PAD src0_sel:DWORD src1_sel:WORD_1
	v_or_b32_sdwa v104, v107, v104 dst_sel:DWORD dst_unused:UNUSED_PAD src0_sel:DWORD src1_sel:WORD_1
	global_store_dwordx2 v[124:125], v[104:105], off offset:32
	v_and_b32_sdwa v77, v102, v142 dst_sel:DWORD dst_unused:UNUSED_PAD src0_sel:WORD_1 src1_sel:DWORD
	v_and_b32_sdwa v104, v100, v142 dst_sel:DWORD dst_unused:UNUSED_PAD src0_sel:WORD_1 src1_sel:DWORD
	v_add3_u32 v100, v100, v104, s46
	v_add3_u32 v77, v102, v77, s46
	v_and_b32_sdwa v102, v103, v142 dst_sel:DWORD dst_unused:UNUSED_PAD src0_sel:WORD_1 src1_sel:DWORD
	v_and_b32_sdwa v104, v101, v142 dst_sel:DWORD dst_unused:UNUSED_PAD src0_sel:WORD_1 src1_sel:DWORD
	v_add3_u32 v102, v103, v102, s46
	v_add3_u32 v101, v101, v104, s46
	v_and_b32_e32 v102, 0xffff0000, v102
	v_and_b32_e32 v103, 0xffff0000, v101
	v_or_b32_sdwa v101, v102, v77 dst_sel:DWORD dst_unused:UNUSED_PAD src0_sel:DWORD src1_sel:WORD_1
	v_or_b32_sdwa v100, v103, v100 dst_sel:DWORD dst_unused:UNUSED_PAD src0_sel:DWORD src1_sel:WORD_1
	global_store_dwordx2 v[120:121], v[100:101], off offset:32
	v_and_b32_sdwa v77, v98, v142 dst_sel:DWORD dst_unused:UNUSED_PAD src0_sel:WORD_1 src1_sel:DWORD
	v_and_b32_sdwa v100, v96, v142 dst_sel:DWORD dst_unused:UNUSED_PAD src0_sel:WORD_1 src1_sel:DWORD
	v_add3_u32 v96, v96, v100, s46
	v_add3_u32 v77, v98, v77, s46
	v_and_b32_sdwa v98, v99, v142 dst_sel:DWORD dst_unused:UNUSED_PAD src0_sel:WORD_1 src1_sel:DWORD
	v_and_b32_sdwa v100, v97, v142 dst_sel:DWORD dst_unused:UNUSED_PAD src0_sel:WORD_1 src1_sel:DWORD
	v_add3_u32 v98, v99, v98, s46
	v_add3_u32 v97, v97, v100, s46
	v_and_b32_e32 v98, 0xffff0000, v98
	v_and_b32_e32 v99, 0xffff0000, v97
	v_or_b32_sdwa v97, v98, v77 dst_sel:DWORD dst_unused:UNUSED_PAD src0_sel:DWORD src1_sel:WORD_1
	v_or_b32_sdwa v96, v99, v96 dst_sel:DWORD dst_unused:UNUSED_PAD src0_sel:DWORD src1_sel:WORD_1
	global_store_dwordx2 v[118:119], v[96:97], off offset:32
	v_and_b32_sdwa v77, v94, v142 dst_sel:DWORD dst_unused:UNUSED_PAD src0_sel:WORD_1 src1_sel:DWORD
	v_and_b32_sdwa v96, v92, v142 dst_sel:DWORD dst_unused:UNUSED_PAD src0_sel:WORD_1 src1_sel:DWORD
	v_add3_u32 v92, v92, v96, s46
	v_add3_u32 v77, v94, v77, s46
	v_and_b32_sdwa v94, v95, v142 dst_sel:DWORD dst_unused:UNUSED_PAD src0_sel:WORD_1 src1_sel:DWORD
	v_and_b32_sdwa v96, v93, v142 dst_sel:DWORD dst_unused:UNUSED_PAD src0_sel:WORD_1 src1_sel:DWORD
	v_add3_u32 v94, v95, v94, s46
	v_add3_u32 v93, v93, v96, s46
	v_and_b32_e32 v94, 0xffff0000, v94
	v_and_b32_e32 v95, 0xffff0000, v93
	v_or_b32_sdwa v93, v94, v77 dst_sel:DWORD dst_unused:UNUSED_PAD src0_sel:DWORD src1_sel:WORD_1
	v_or_b32_sdwa v92, v95, v92 dst_sel:DWORD dst_unused:UNUSED_PAD src0_sel:DWORD src1_sel:WORD_1
	global_store_dwordx2 v[144:145], v[92:93], off offset:64
	v_and_b32_sdwa v77, v90, v142 dst_sel:DWORD dst_unused:UNUSED_PAD src0_sel:WORD_1 src1_sel:DWORD
	v_and_b32_sdwa v92, v88, v142 dst_sel:DWORD dst_unused:UNUSED_PAD src0_sel:WORD_1 src1_sel:DWORD
	v_add3_u32 v88, v88, v92, s46
	v_add3_u32 v77, v90, v77, s46
	v_and_b32_sdwa v90, v91, v142 dst_sel:DWORD dst_unused:UNUSED_PAD src0_sel:WORD_1 src1_sel:DWORD
	v_and_b32_sdwa v92, v89, v142 dst_sel:DWORD dst_unused:UNUSED_PAD src0_sel:WORD_1 src1_sel:DWORD
	v_add3_u32 v90, v91, v90, s46
	v_add3_u32 v89, v89, v92, s46
	v_and_b32_e32 v90, 0xffff0000, v90
	v_and_b32_e32 v91, 0xffff0000, v89
	v_or_b32_sdwa v89, v90, v77 dst_sel:DWORD dst_unused:UNUSED_PAD src0_sel:DWORD src1_sel:WORD_1
	v_or_b32_sdwa v88, v91, v88 dst_sel:DWORD dst_unused:UNUSED_PAD src0_sel:DWORD src1_sel:WORD_1
	global_store_dwordx2 v[124:125], v[88:89], off offset:64
	v_and_b32_sdwa v77, v86, v142 dst_sel:DWORD dst_unused:UNUSED_PAD src0_sel:WORD_1 src1_sel:DWORD
	v_and_b32_sdwa v88, v84, v142 dst_sel:DWORD dst_unused:UNUSED_PAD src0_sel:WORD_1 src1_sel:DWORD
	v_add3_u32 v84, v84, v88, s46
	v_add3_u32 v77, v86, v77, s46
	v_and_b32_sdwa v86, v87, v142 dst_sel:DWORD dst_unused:UNUSED_PAD src0_sel:WORD_1 src1_sel:DWORD
	v_and_b32_sdwa v88, v85, v142 dst_sel:DWORD dst_unused:UNUSED_PAD src0_sel:WORD_1 src1_sel:DWORD
	v_add3_u32 v86, v87, v86, s46
	v_add3_u32 v85, v85, v88, s46
	v_and_b32_e32 v86, 0xffff0000, v86
	v_and_b32_e32 v87, 0xffff0000, v85
	v_or_b32_sdwa v85, v86, v77 dst_sel:DWORD dst_unused:UNUSED_PAD src0_sel:DWORD src1_sel:WORD_1
	v_or_b32_sdwa v84, v87, v84 dst_sel:DWORD dst_unused:UNUSED_PAD src0_sel:DWORD src1_sel:WORD_1
	global_store_dwordx2 v[120:121], v[84:85], off offset:64
	v_and_b32_sdwa v85, v133, v142 dst_sel:DWORD dst_unused:UNUSED_PAD src0_sel:WORD_1 src1_sel:DWORD
	v_and_b32_sdwa v86, v131, v142 dst_sel:DWORD dst_unused:UNUSED_PAD src0_sel:WORD_1 src1_sel:DWORD
	v_and_b32_sdwa v77, v132, v142 dst_sel:DWORD dst_unused:UNUSED_PAD src0_sel:WORD_1 src1_sel:DWORD
	v_and_b32_sdwa v84, v130, v142 dst_sel:DWORD dst_unused:UNUSED_PAD src0_sel:WORD_1 src1_sel:DWORD
	v_add3_u32 v85, v133, v85, s46
	v_add3_u32 v86, v131, v86, s46
	v_add3_u32 v84, v130, v84, s46
	v_add3_u32 v77, v132, v77, s46
	v_and_b32_e32 v85, 0xffff0000, v85
	v_and_b32_e32 v86, 0xffff0000, v86
	v_or_b32_sdwa v85, v85, v77 dst_sel:DWORD dst_unused:UNUSED_PAD src0_sel:DWORD src1_sel:WORD_1
	v_or_b32_sdwa v84, v86, v84 dst_sel:DWORD dst_unused:UNUSED_PAD src0_sel:DWORD src1_sel:WORD_1
	global_store_dwordx2 v[118:119], v[84:85], off offset:64
	v_and_b32_sdwa v85, v141, v142 dst_sel:DWORD dst_unused:UNUSED_PAD src0_sel:WORD_1 src1_sel:DWORD
	v_and_b32_sdwa v86, v139, v142 dst_sel:DWORD dst_unused:UNUSED_PAD src0_sel:WORD_1 src1_sel:DWORD
	v_and_b32_sdwa v77, v140, v142 dst_sel:DWORD dst_unused:UNUSED_PAD src0_sel:WORD_1 src1_sel:DWORD
	v_and_b32_sdwa v84, v138, v142 dst_sel:DWORD dst_unused:UNUSED_PAD src0_sel:WORD_1 src1_sel:DWORD
	v_add3_u32 v85, v141, v85, s46
	v_add3_u32 v86, v139, v86, s46
	v_add3_u32 v84, v138, v84, s46
	v_add3_u32 v77, v140, v77, s46
	v_and_b32_e32 v85, 0xffff0000, v85
	v_and_b32_e32 v86, 0xffff0000, v86
	v_or_b32_sdwa v85, v85, v77 dst_sel:DWORD dst_unused:UNUSED_PAD src0_sel:DWORD src1_sel:WORD_1
	v_or_b32_sdwa v84, v86, v84 dst_sel:DWORD dst_unused:UNUSED_PAD src0_sel:DWORD src1_sel:WORD_1
	global_store_dwordx2 v[144:145], v[84:85], off offset:96
	v_and_b32_sdwa v77, v74, v142 dst_sel:DWORD dst_unused:UNUSED_PAD src0_sel:WORD_1 src1_sel:DWORD
	v_and_b32_sdwa v84, v72, v142 dst_sel:DWORD dst_unused:UNUSED_PAD src0_sel:WORD_1 src1_sel:DWORD
	v_add3_u32 v72, v72, v84, s46
	v_add3_u32 v74, v74, v77, s46
	v_and_b32_sdwa v77, v75, v142 dst_sel:DWORD dst_unused:UNUSED_PAD src0_sel:WORD_1 src1_sel:DWORD
	v_and_b32_sdwa v84, v73, v142 dst_sel:DWORD dst_unused:UNUSED_PAD src0_sel:WORD_1 src1_sel:DWORD
	v_add3_u32 v75, v75, v77, s46
	v_add3_u32 v73, v73, v84, s46
	v_and_b32_e32 v75, 0xffff0000, v75
	v_and_b32_e32 v77, 0xffff0000, v73
	v_or_b32_sdwa v73, v75, v74 dst_sel:DWORD dst_unused:UNUSED_PAD src0_sel:DWORD src1_sel:WORD_1
	v_or_b32_sdwa v72, v77, v72 dst_sel:DWORD dst_unused:UNUSED_PAD src0_sel:DWORD src1_sel:WORD_1
	global_store_dwordx2 v[124:125], v[72:73], off offset:96
	v_and_b32_sdwa v72, v70, v142 dst_sel:DWORD dst_unused:UNUSED_PAD src0_sel:WORD_1 src1_sel:DWORD
	v_and_b32_sdwa v73, v68, v142 dst_sel:DWORD dst_unused:UNUSED_PAD src0_sel:WORD_1 src1_sel:DWORD
	v_add3_u32 v68, v68, v73, s46
	v_add3_u32 v70, v70, v72, s46
	v_and_b32_sdwa v72, v71, v142 dst_sel:DWORD dst_unused:UNUSED_PAD src0_sel:WORD_1 src1_sel:DWORD
	v_and_b32_sdwa v73, v69, v142 dst_sel:DWORD dst_unused:UNUSED_PAD src0_sel:WORD_1 src1_sel:DWORD
	v_add3_u32 v71, v71, v72, s46
	v_add3_u32 v69, v69, v73, s46
	v_and_b32_e32 v71, 0xffff0000, v71
	v_and_b32_e32 v72, 0xffff0000, v69
	v_or_b32_sdwa v69, v71, v70 dst_sel:DWORD dst_unused:UNUSED_PAD src0_sel:DWORD src1_sel:WORD_1
	v_or_b32_sdwa v68, v72, v68 dst_sel:DWORD dst_unused:UNUSED_PAD src0_sel:DWORD src1_sel:WORD_1
	global_store_dwordx2 v[120:121], v[68:69], off offset:96
	v_and_b32_sdwa v69, v64, v142 dst_sel:DWORD dst_unused:UNUSED_PAD src0_sel:WORD_1 src1_sel:DWORD
	v_and_b32_sdwa v68, v66, v142 dst_sel:DWORD dst_unused:UNUSED_PAD src0_sel:WORD_1 src1_sel:DWORD
	v_add3_u32 v64, v64, v69, s46
	v_and_b32_sdwa v69, v65, v142 dst_sel:DWORD dst_unused:UNUSED_PAD src0_sel:WORD_1 src1_sel:DWORD
	v_add3_u32 v66, v66, v68, s46
	v_and_b32_sdwa v68, v67, v142 dst_sel:DWORD dst_unused:UNUSED_PAD src0_sel:WORD_1 src1_sel:DWORD
	v_add3_u32 v65, v65, v69, s46
	v_add3_u32 v67, v67, v68, s46
	v_and_b32_e32 v68, 0xffff0000, v65
	v_or_b32_sdwa v64, v68, v64 dst_sel:DWORD dst_unused:UNUSED_PAD src0_sel:DWORD src1_sel:WORD_1
	v_and_b32_sdwa v68, v62, v142 dst_sel:DWORD dst_unused:UNUSED_PAD src0_sel:WORD_1 src1_sel:DWORD
	v_and_b32_sdwa v69, v60, v142 dst_sel:DWORD dst_unused:UNUSED_PAD src0_sel:WORD_1 src1_sel:DWORD
	v_add3_u32 v62, v62, v68, s46
	v_and_b32_sdwa v68, v63, v142 dst_sel:DWORD dst_unused:UNUSED_PAD src0_sel:WORD_1 src1_sel:DWORD
	v_add3_u32 v60, v60, v69, s46
	v_and_b32_sdwa v69, v61, v142 dst_sel:DWORD dst_unused:UNUSED_PAD src0_sel:WORD_1 src1_sel:DWORD
	v_add3_u32 v63, v63, v68, s46
	v_add3_u32 v61, v61, v69, s46
	v_and_b32_e32 v63, 0xffff0000, v63
	v_and_b32_e32 v68, 0xffff0000, v61
	v_or_b32_sdwa v61, v63, v62 dst_sel:DWORD dst_unused:UNUSED_PAD src0_sel:DWORD src1_sel:WORD_1
	v_and_b32_sdwa v62, v58, v142 dst_sel:DWORD dst_unused:UNUSED_PAD src0_sel:WORD_1 src1_sel:DWORD
	v_and_b32_sdwa v63, v56, v142 dst_sel:DWORD dst_unused:UNUSED_PAD src0_sel:WORD_1 src1_sel:DWORD
	v_add3_u32 v58, v58, v62, s46
	v_and_b32_sdwa v62, v59, v142 dst_sel:DWORD dst_unused:UNUSED_PAD src0_sel:WORD_1 src1_sel:DWORD
	v_and_b32_e32 v67, 0xffff0000, v67
	v_add3_u32 v56, v56, v63, s46
	v_and_b32_sdwa v63, v57, v142 dst_sel:DWORD dst_unused:UNUSED_PAD src0_sel:WORD_1 src1_sel:DWORD
	v_add3_u32 v59, v59, v62, s46
	v_or_b32_sdwa v65, v67, v66 dst_sel:DWORD dst_unused:UNUSED_PAD src0_sel:DWORD src1_sel:WORD_1
	v_add3_u32 v57, v57, v63, s46
	v_and_b32_e32 v59, 0xffff0000, v59
	global_store_dwordx2 v[118:119], v[64:65], off offset:96
	v_or_b32_e32 v64, 1, v76
	v_and_b32_e32 v62, 0xffff0000, v57
	v_or_b32_sdwa v57, v59, v58 dst_sel:DWORD dst_unused:UNUSED_PAD src0_sel:DWORD src1_sel:WORD_1
	v_and_b32_sdwa v58, v54, v142 dst_sel:DWORD dst_unused:UNUSED_PAD src0_sel:WORD_1 src1_sel:DWORD
	v_ashrrev_i32_e32 v65, 31, v64
	v_and_b32_sdwa v59, v52, v142 dst_sel:DWORD dst_unused:UNUSED_PAD src0_sel:WORD_1 src1_sel:DWORD
	v_add3_u32 v54, v54, v58, s46
	v_and_b32_sdwa v58, v55, v142 dst_sel:DWORD dst_unused:UNUSED_PAD src0_sel:WORD_1 src1_sel:DWORD
	v_lshlrev_b64 v[64:65], 17, v[64:65]
	v_add3_u32 v52, v52, v59, s46
	v_and_b32_sdwa v59, v53, v142 dst_sel:DWORD dst_unused:UNUSED_PAD src0_sel:WORD_1 src1_sel:DWORD
	v_add3_u32 v55, v55, v58, s46
	v_lshl_add_u64 v[64:65], s[0:1], 0, v[64:65]
	v_add3_u32 v53, v53, v59, s46
	v_and_b32_e32 v55, 0xffff0000, v55
	v_lshl_add_u64 v[64:65], v[64:65], 0, v[128:129]
	v_and_b32_e32 v58, 0xffff0000, v53
	v_or_b32_sdwa v53, v55, v54 dst_sel:DWORD dst_unused:UNUSED_PAD src0_sel:DWORD src1_sel:WORD_1
	v_and_b32_sdwa v54, v50, v142 dst_sel:DWORD dst_unused:UNUSED_PAD src0_sel:WORD_1 src1_sel:DWORD
	v_and_b32_sdwa v55, v48, v142 dst_sel:DWORD dst_unused:UNUSED_PAD src0_sel:WORD_1 src1_sel:DWORD
	v_lshl_add_u64 v[66:67], v[64:65], 0, v[78:79]
	v_or_b32_sdwa v60, v68, v60 dst_sel:DWORD dst_unused:UNUSED_PAD src0_sel:DWORD src1_sel:WORD_1
	v_add3_u32 v48, v48, v55, s46
	v_add3_u32 v50, v50, v54, s46
	v_and_b32_sdwa v54, v51, v142 dst_sel:DWORD dst_unused:UNUSED_PAD src0_sel:WORD_1 src1_sel:DWORD
	v_and_b32_sdwa v55, v49, v142 dst_sel:DWORD dst_unused:UNUSED_PAD src0_sel:WORD_1 src1_sel:DWORD
	global_store_dwordx2 v[66:67], v[60:61], off
	v_lshl_add_u64 v[60:61], v[64:65], 0, v[80:81]
	v_or_b32_sdwa v56, v62, v56 dst_sel:DWORD dst_unused:UNUSED_PAD src0_sel:DWORD src1_sel:WORD_1
	v_add3_u32 v51, v51, v54, s46
	v_add3_u32 v49, v49, v55, s46
	global_store_dwordx2 v[60:61], v[56:57], off
	v_lshl_add_u64 v[56:57], v[64:65], 0, v[82:83]
	v_or_b32_sdwa v52, v58, v52 dst_sel:DWORD dst_unused:UNUSED_PAD src0_sel:DWORD src1_sel:WORD_1
	v_and_b32_e32 v51, 0xffff0000, v51
	v_and_b32_e32 v54, 0xffff0000, v49
	global_store_dwordx2 v[56:57], v[52:53], off
	v_lshl_add_u64 v[52:53], v[64:65], 0, v[116:117]
	v_or_b32_sdwa v49, v51, v50 dst_sel:DWORD dst_unused:UNUSED_PAD src0_sel:DWORD src1_sel:WORD_1
	v_or_b32_sdwa v48, v54, v48 dst_sel:DWORD dst_unused:UNUSED_PAD src0_sel:DWORD src1_sel:WORD_1
	global_store_dwordx2 v[52:53], v[48:49], off
	v_and_b32_sdwa v48, v46, v142 dst_sel:DWORD dst_unused:UNUSED_PAD src0_sel:WORD_1 src1_sel:DWORD
	v_and_b32_sdwa v49, v44, v142 dst_sel:DWORD dst_unused:UNUSED_PAD src0_sel:WORD_1 src1_sel:DWORD
	v_add3_u32 v44, v44, v49, s46
	v_add3_u32 v46, v46, v48, s46
	v_and_b32_sdwa v48, v47, v142 dst_sel:DWORD dst_unused:UNUSED_PAD src0_sel:WORD_1 src1_sel:DWORD
	v_and_b32_sdwa v49, v45, v142 dst_sel:DWORD dst_unused:UNUSED_PAD src0_sel:WORD_1 src1_sel:DWORD
	v_add3_u32 v47, v47, v48, s46
	v_add3_u32 v45, v45, v49, s46
	v_and_b32_e32 v47, 0xffff0000, v47
	v_and_b32_e32 v48, 0xffff0000, v45
	v_or_b32_sdwa v45, v47, v46 dst_sel:DWORD dst_unused:UNUSED_PAD src0_sel:DWORD src1_sel:WORD_1
	v_or_b32_sdwa v44, v48, v44 dst_sel:DWORD dst_unused:UNUSED_PAD src0_sel:DWORD src1_sel:WORD_1
	global_store_dwordx2 v[66:67], v[44:45], off offset:32
	v_and_b32_sdwa v44, v42, v142 dst_sel:DWORD dst_unused:UNUSED_PAD src0_sel:WORD_1 src1_sel:DWORD
	v_and_b32_sdwa v45, v40, v142 dst_sel:DWORD dst_unused:UNUSED_PAD src0_sel:WORD_1 src1_sel:DWORD
	v_add3_u32 v40, v40, v45, s46
	v_add3_u32 v42, v42, v44, s46
	v_and_b32_sdwa v44, v43, v142 dst_sel:DWORD dst_unused:UNUSED_PAD src0_sel:WORD_1 src1_sel:DWORD
	v_and_b32_sdwa v45, v41, v142 dst_sel:DWORD dst_unused:UNUSED_PAD src0_sel:WORD_1 src1_sel:DWORD
	v_add3_u32 v43, v43, v44, s46
	v_add3_u32 v41, v41, v45, s46
	v_and_b32_e32 v43, 0xffff0000, v43
	v_and_b32_e32 v44, 0xffff0000, v41
	v_or_b32_sdwa v41, v43, v42 dst_sel:DWORD dst_unused:UNUSED_PAD src0_sel:DWORD src1_sel:WORD_1
	v_or_b32_sdwa v40, v44, v40 dst_sel:DWORD dst_unused:UNUSED_PAD src0_sel:DWORD src1_sel:WORD_1
	global_store_dwordx2 v[60:61], v[40:41], off offset:32
	v_and_b32_sdwa v40, v38, v142 dst_sel:DWORD dst_unused:UNUSED_PAD src0_sel:WORD_1 src1_sel:DWORD
	v_and_b32_sdwa v41, v36, v142 dst_sel:DWORD dst_unused:UNUSED_PAD src0_sel:WORD_1 src1_sel:DWORD
	v_add3_u32 v36, v36, v41, s46
	v_add3_u32 v38, v38, v40, s46
	v_and_b32_sdwa v40, v39, v142 dst_sel:DWORD dst_unused:UNUSED_PAD src0_sel:WORD_1 src1_sel:DWORD
	v_and_b32_sdwa v41, v37, v142 dst_sel:DWORD dst_unused:UNUSED_PAD src0_sel:WORD_1 src1_sel:DWORD
	v_add3_u32 v39, v39, v40, s46
	v_add3_u32 v37, v37, v41, s46
	v_and_b32_e32 v39, 0xffff0000, v39
	v_and_b32_e32 v40, 0xffff0000, v37
	v_or_b32_sdwa v37, v39, v38 dst_sel:DWORD dst_unused:UNUSED_PAD src0_sel:DWORD src1_sel:WORD_1
	v_or_b32_sdwa v36, v40, v36 dst_sel:DWORD dst_unused:UNUSED_PAD src0_sel:DWORD src1_sel:WORD_1
	global_store_dwordx2 v[56:57], v[36:37], off offset:32
	v_and_b32_sdwa v36, v34, v142 dst_sel:DWORD dst_unused:UNUSED_PAD src0_sel:WORD_1 src1_sel:DWORD
	v_and_b32_sdwa v37, v32, v142 dst_sel:DWORD dst_unused:UNUSED_PAD src0_sel:WORD_1 src1_sel:DWORD
	v_add3_u32 v32, v32, v37, s46
	v_add3_u32 v34, v34, v36, s46
	v_and_b32_sdwa v36, v35, v142 dst_sel:DWORD dst_unused:UNUSED_PAD src0_sel:WORD_1 src1_sel:DWORD
	v_and_b32_sdwa v37, v33, v142 dst_sel:DWORD dst_unused:UNUSED_PAD src0_sel:WORD_1 src1_sel:DWORD
	v_add3_u32 v35, v35, v36, s46
	v_add3_u32 v33, v33, v37, s46
	v_and_b32_e32 v35, 0xffff0000, v35
	v_and_b32_e32 v36, 0xffff0000, v33
	v_or_b32_sdwa v33, v35, v34 dst_sel:DWORD dst_unused:UNUSED_PAD src0_sel:DWORD src1_sel:WORD_1
	v_or_b32_sdwa v32, v36, v32 dst_sel:DWORD dst_unused:UNUSED_PAD src0_sel:DWORD src1_sel:WORD_1
	global_store_dwordx2 v[52:53], v[32:33], off offset:32
	v_and_b32_sdwa v32, v30, v142 dst_sel:DWORD dst_unused:UNUSED_PAD src0_sel:WORD_1 src1_sel:DWORD
	v_and_b32_sdwa v33, v28, v142 dst_sel:DWORD dst_unused:UNUSED_PAD src0_sel:WORD_1 src1_sel:DWORD
	v_add3_u32 v28, v28, v33, s46
	v_add3_u32 v30, v30, v32, s46
	v_and_b32_sdwa v32, v31, v142 dst_sel:DWORD dst_unused:UNUSED_PAD src0_sel:WORD_1 src1_sel:DWORD
	v_and_b32_sdwa v33, v29, v142 dst_sel:DWORD dst_unused:UNUSED_PAD src0_sel:WORD_1 src1_sel:DWORD
	v_add3_u32 v31, v31, v32, s46
	v_add3_u32 v29, v29, v33, s46
	v_and_b32_e32 v31, 0xffff0000, v31
	v_and_b32_e32 v32, 0xffff0000, v29
	v_or_b32_sdwa v29, v31, v30 dst_sel:DWORD dst_unused:UNUSED_PAD src0_sel:DWORD src1_sel:WORD_1
	v_or_b32_sdwa v28, v32, v28 dst_sel:DWORD dst_unused:UNUSED_PAD src0_sel:DWORD src1_sel:WORD_1
	global_store_dwordx2 v[66:67], v[28:29], off offset:64
	v_and_b32_sdwa v28, v26, v142 dst_sel:DWORD dst_unused:UNUSED_PAD src0_sel:WORD_1 src1_sel:DWORD
	v_and_b32_sdwa v29, v24, v142 dst_sel:DWORD dst_unused:UNUSED_PAD src0_sel:WORD_1 src1_sel:DWORD
	v_add3_u32 v24, v24, v29, s46
	v_add3_u32 v26, v26, v28, s46
	v_and_b32_sdwa v28, v27, v142 dst_sel:DWORD dst_unused:UNUSED_PAD src0_sel:WORD_1 src1_sel:DWORD
	v_and_b32_sdwa v29, v25, v142 dst_sel:DWORD dst_unused:UNUSED_PAD src0_sel:WORD_1 src1_sel:DWORD
	v_add3_u32 v27, v27, v28, s46
	v_add3_u32 v25, v25, v29, s46
	v_and_b32_e32 v27, 0xffff0000, v27
	v_and_b32_e32 v28, 0xffff0000, v25
	v_or_b32_sdwa v25, v27, v26 dst_sel:DWORD dst_unused:UNUSED_PAD src0_sel:DWORD src1_sel:WORD_1
	v_or_b32_sdwa v24, v28, v24 dst_sel:DWORD dst_unused:UNUSED_PAD src0_sel:DWORD src1_sel:WORD_1
	global_store_dwordx2 v[60:61], v[24:25], off offset:64
	v_and_b32_sdwa v24, v22, v142 dst_sel:DWORD dst_unused:UNUSED_PAD src0_sel:WORD_1 src1_sel:DWORD
	v_and_b32_sdwa v25, v20, v142 dst_sel:DWORD dst_unused:UNUSED_PAD src0_sel:WORD_1 src1_sel:DWORD
	v_add3_u32 v20, v20, v25, s46
	v_add3_u32 v22, v22, v24, s46
	v_and_b32_sdwa v24, v23, v142 dst_sel:DWORD dst_unused:UNUSED_PAD src0_sel:WORD_1 src1_sel:DWORD
	v_and_b32_sdwa v25, v21, v142 dst_sel:DWORD dst_unused:UNUSED_PAD src0_sel:WORD_1 src1_sel:DWORD
	v_add3_u32 v23, v23, v24, s46
	v_add3_u32 v21, v21, v25, s46
	v_and_b32_e32 v23, 0xffff0000, v23
	v_and_b32_e32 v24, 0xffff0000, v21
	v_or_b32_sdwa v21, v23, v22 dst_sel:DWORD dst_unused:UNUSED_PAD src0_sel:DWORD src1_sel:WORD_1
	v_or_b32_sdwa v20, v24, v20 dst_sel:DWORD dst_unused:UNUSED_PAD src0_sel:DWORD src1_sel:WORD_1
	global_store_dwordx2 v[56:57], v[20:21], off offset:64
	v_and_b32_sdwa v20, v18, v142 dst_sel:DWORD dst_unused:UNUSED_PAD src0_sel:WORD_1 src1_sel:DWORD
	v_and_b32_sdwa v21, v16, v142 dst_sel:DWORD dst_unused:UNUSED_PAD src0_sel:WORD_1 src1_sel:DWORD
	v_add3_u32 v16, v16, v21, s46
	v_add3_u32 v18, v18, v20, s46
	v_and_b32_sdwa v20, v19, v142 dst_sel:DWORD dst_unused:UNUSED_PAD src0_sel:WORD_1 src1_sel:DWORD
	v_and_b32_sdwa v21, v17, v142 dst_sel:DWORD dst_unused:UNUSED_PAD src0_sel:WORD_1 src1_sel:DWORD
	v_add3_u32 v19, v19, v20, s46
	v_add3_u32 v17, v17, v21, s46
	v_and_b32_e32 v19, 0xffff0000, v19
	v_and_b32_e32 v20, 0xffff0000, v17
	v_or_b32_sdwa v17, v19, v18 dst_sel:DWORD dst_unused:UNUSED_PAD src0_sel:DWORD src1_sel:WORD_1
	v_or_b32_sdwa v16, v20, v16 dst_sel:DWORD dst_unused:UNUSED_PAD src0_sel:DWORD src1_sel:WORD_1
	global_store_dwordx2 v[52:53], v[16:17], off offset:64
	v_and_b32_sdwa v16, v14, v142 dst_sel:DWORD dst_unused:UNUSED_PAD src0_sel:WORD_1 src1_sel:DWORD
	v_and_b32_sdwa v17, v12, v142 dst_sel:DWORD dst_unused:UNUSED_PAD src0_sel:WORD_1 src1_sel:DWORD
	v_add3_u32 v12, v12, v17, s46
	v_add3_u32 v14, v14, v16, s46
	v_and_b32_sdwa v16, v15, v142 dst_sel:DWORD dst_unused:UNUSED_PAD src0_sel:WORD_1 src1_sel:DWORD
	v_and_b32_sdwa v17, v13, v142 dst_sel:DWORD dst_unused:UNUSED_PAD src0_sel:WORD_1 src1_sel:DWORD
	v_add3_u32 v15, v15, v16, s46
	v_add3_u32 v13, v13, v17, s46
	v_and_b32_e32 v15, 0xffff0000, v15
	v_and_b32_e32 v16, 0xffff0000, v13
	v_or_b32_sdwa v13, v15, v14 dst_sel:DWORD dst_unused:UNUSED_PAD src0_sel:DWORD src1_sel:WORD_1
	v_or_b32_sdwa v12, v16, v12 dst_sel:DWORD dst_unused:UNUSED_PAD src0_sel:DWORD src1_sel:WORD_1
	global_store_dwordx2 v[66:67], v[12:13], off offset:96
	v_and_b32_sdwa v12, v10, v142 dst_sel:DWORD dst_unused:UNUSED_PAD src0_sel:WORD_1 src1_sel:DWORD
	v_and_b32_sdwa v13, v8, v142 dst_sel:DWORD dst_unused:UNUSED_PAD src0_sel:WORD_1 src1_sel:DWORD
	v_add3_u32 v8, v8, v13, s46
	v_add3_u32 v10, v10, v12, s46
	v_and_b32_sdwa v12, v11, v142 dst_sel:DWORD dst_unused:UNUSED_PAD src0_sel:WORD_1 src1_sel:DWORD
	v_and_b32_sdwa v13, v9, v142 dst_sel:DWORD dst_unused:UNUSED_PAD src0_sel:WORD_1 src1_sel:DWORD
	v_add3_u32 v11, v11, v12, s46
	v_add3_u32 v9, v9, v13, s46
	v_and_b32_e32 v11, 0xffff0000, v11
	v_and_b32_e32 v12, 0xffff0000, v9
	v_or_b32_sdwa v9, v11, v10 dst_sel:DWORD dst_unused:UNUSED_PAD src0_sel:DWORD src1_sel:WORD_1
	v_or_b32_sdwa v8, v12, v8 dst_sel:DWORD dst_unused:UNUSED_PAD src0_sel:DWORD src1_sel:WORD_1
	global_store_dwordx2 v[60:61], v[8:9], off offset:96
	v_and_b32_sdwa v8, v6, v142 dst_sel:DWORD dst_unused:UNUSED_PAD src0_sel:WORD_1 src1_sel:DWORD
	v_and_b32_sdwa v9, v4, v142 dst_sel:DWORD dst_unused:UNUSED_PAD src0_sel:WORD_1 src1_sel:DWORD
	v_add3_u32 v4, v4, v9, s46
	v_add3_u32 v6, v6, v8, s46
	v_and_b32_sdwa v8, v7, v142 dst_sel:DWORD dst_unused:UNUSED_PAD src0_sel:WORD_1 src1_sel:DWORD
	v_and_b32_sdwa v9, v5, v142 dst_sel:DWORD dst_unused:UNUSED_PAD src0_sel:WORD_1 src1_sel:DWORD
	v_add3_u32 v7, v7, v8, s46
	v_add3_u32 v5, v5, v9, s46
	v_and_b32_e32 v7, 0xffff0000, v7
	v_and_b32_e32 v8, 0xffff0000, v5
	v_or_b32_sdwa v5, v7, v6 dst_sel:DWORD dst_unused:UNUSED_PAD src0_sel:DWORD src1_sel:WORD_1
	v_or_b32_sdwa v4, v8, v4 dst_sel:DWORD dst_unused:UNUSED_PAD src0_sel:DWORD src1_sel:WORD_1
	global_store_dwordx2 v[56:57], v[4:5], off offset:96
	v_and_b32_sdwa v4, v2, v142 dst_sel:DWORD dst_unused:UNUSED_PAD src0_sel:WORD_1 src1_sel:DWORD
	v_and_b32_sdwa v5, v0, v142 dst_sel:DWORD dst_unused:UNUSED_PAD src0_sel:WORD_1 src1_sel:DWORD
	v_add3_u32 v0, v0, v5, s46
	v_add3_u32 v2, v2, v4, s46
	v_and_b32_sdwa v4, v3, v142 dst_sel:DWORD dst_unused:UNUSED_PAD src0_sel:WORD_1 src1_sel:DWORD
	v_and_b32_sdwa v5, v1, v142 dst_sel:DWORD dst_unused:UNUSED_PAD src0_sel:WORD_1 src1_sel:DWORD
	v_add3_u32 v3, v3, v4, s46
	v_add3_u32 v1, v1, v5, s46
	v_and_b32_e32 v3, 0xffff0000, v3
	v_and_b32_e32 v4, 0xffff0000, v1
	v_readlane_b32 s52, v254, 58
	v_or_b32_sdwa v1, v3, v2 dst_sel:DWORD dst_unused:UNUSED_PAD src0_sel:DWORD src1_sel:WORD_1
	v_or_b32_sdwa v0, v4, v0 dst_sel:DWORD dst_unused:UNUSED_PAD src0_sel:DWORD src1_sel:WORD_1
	s_mov_b64 s[0:1], 0
	v_readlane_b32 s53, v254, 59
	global_store_dwordx2 v[52:53], v[0:1], off offset:96
.LBB0_1947:
	s_and_b64 vcc, exec, s[0:1]
	s_cbranch_vccz .LBB0_1942
	s_mov_b64 s[62:63], 0x80
	v_mov_b32_e32 v134, v190
	s_lshl_b32 s40, s40, 8
	v_lshlrev_b32_e32 v0, 6, v134
	v_and_b32_e32 v141, 0xffffe3c0, v0
	v_lshlrev_b32_e32 v0, 1, v134
	v_and_b32_e32 v7, 3, v134
	v_ashrrev_i32_e32 v6, 2, v134
	v_and_b32_e32 v6, -2, v6
	v_and_or_b32 v0, v0, 24, v7
	v_lshlrev_b32_e32 v139, 6, v0
	v_add_u32_e32 v0, s40, v6
	v_ashrrev_i32_e32 v1, 31, v0
	v_lshlrev_b32_e32 v140, 4, v134
	v_lshlrev_b64 v[0:1], 11, v[0:1]
	v_lshl_add_u64 v[0:1], s[88:89], 0, v[0:1]
	v_and_b32_e32 v128, 0x70, v140
	v_readfirstlane_b32 s0, v140
	v_add_u32_e32 v8, 0x1000, v140
	v_lshl_add_u64 v[0:1], v[0:1], 0, v[128:129]
	s_waitcnt vmcnt(0)
	s_mov_b32 m0, s0
	v_readfirstlane_b32 s0, v8
	v_add_u32_e32 v8, 0x2000, v140
	global_load_lds_dwordx4 v[0:1], off
	v_lshl_add_u64 v[4:5], v[0:1], 0, s[8:9]
	s_mov_b32 m0, s0
	v_readfirstlane_b32 s0, v8
	v_add_u32_e32 v8, 0x3000, v140
	v_add_u32_e32 v2, s4, v6
	global_load_lds_dwordx4 v[4:5], off
	v_lshl_add_u64 v[4:5], v[0:1], 0, s[10:11]
	s_mov_b32 m0, s0
	v_readfirstlane_b32 s0, v8
	v_ashrrev_i32_e32 v3, 31, v2
	global_load_lds_dwordx4 v[4:5], off
	v_lshl_add_u64 v[4:5], v[0:1], 0, s[12:13]
	s_mov_b32 m0, s0
	v_lshlrev_b64 v[2:3], 11, v[2:3]
	global_load_lds_dwordx4 v[4:5], off
	v_add_u32_e32 v4, 0x4000, v140
	v_lshl_add_u64 v[2:3], s[52:53], 0, v[2:3]
	v_readfirstlane_b32 s0, v4
	v_add_u32_e32 v8, 0x5000, v140
	v_lshl_add_u64 v[2:3], v[2:3], 0, v[128:129]
	s_mov_b32 m0, s0
	v_readfirstlane_b32 s0, v8
	v_add_u32_e32 v8, 0x6000, v140
	global_load_lds_dwordx4 v[2:3], off
	v_lshl_add_u64 v[4:5], v[2:3], 0, s[8:9]
	s_mov_b32 m0, s0
	v_readfirstlane_b32 s0, v8
	v_add_u32_e32 v8, 0x7000, v140
	global_load_lds_dwordx4 v[4:5], off
	v_lshl_add_u64 v[4:5], v[0:1], 0, s[62:63]
	s_mov_b32 m0, s0
	v_readfirstlane_b32 s0, v8
	v_add_u32_e32 v8, 0x8000, v140
	global_load_lds_dwordx4 v[4:5], off
	v_lshl_add_u64 v[4:5], v[0:1], 0, s[14:15]
	s_mov_b32 m0, s0
	v_readfirstlane_b32 s0, v8
	global_load_lds_dwordx4 v[4:5], off
	v_lshl_add_u64 v[4:5], v[0:1], 0, s[16:17]
	s_mov_b32 m0, s0
	v_lshl_add_u64 v[0:1], v[0:1], 0, s[18:19]
	global_load_lds_dwordx4 v[4:5], off
	v_add_u32_e32 v4, 0x9000, v140
	s_add_i32 s6, s6, s5
	v_readfirstlane_b32 s0, v4
	v_add_u32_e32 v4, 0xa000, v140
	s_mov_b32 m0, s0
	v_readfirstlane_b32 s0, v4
	global_load_lds_dwordx4 v[0:1], off
	v_lshl_add_u64 v[0:1], v[2:3], 0, s[62:63]
	s_mov_b32 m0, s0
	v_bfe_u32 v136, v134, 6, 1
	global_load_lds_dwordx4 v[0:1], off
	v_lshl_add_u64 v[0:1], v[2:3], 0, s[14:15]
	v_add_u32_e32 v2, 0xb000, v140
	v_and_b32_e32 v135, 15, v134
	v_readfirstlane_b32 s0, v2
	s_mov_b32 m0, s0
	v_and_b32_e32 v2, 7, v134
	v_lshlrev_b32_e32 v2, 4, v2
	global_load_lds_dwordx4 v[0:1], off
	v_add_u32_e32 v0, s7, v6
	v_ashrrev_i32_e32 v1, 31, v0
	v_lshlrev_b64 v[0:1], 11, v[0:1]
	v_or_b32_e32 v0, v0, v2
	v_lshl_add_u64 v[130:131], s[52:53], 0, v[0:1]
	v_add_u32_e32 v0, s6, v6
	v_ashrrev_i32_e32 v1, 31, v0
	v_lshlrev_b64 v[0:1], 11, v[0:1]
	v_or_b32_e32 v0, v0, v2
	v_lshl_add_u64 v[132:133], s[52:53], 0, v[0:1]
	v_mov_b32_e32 v0, 0
	v_and_b32_e32 v137, 48, v134
	v_lshlrev_b32_e32 v138, 12, v136
	s_mov_b32 s5, 0
	s_mov_b64 s[0:1], 0
	v_mov_b32_e32 v1, v0
	v_mov_b32_e32 v2, v0
	v_mov_b32_e32 v3, v0
	v_mov_b32_e32 v4, v0
	v_mov_b32_e32 v5, v0
	v_mov_b32_e32 v6, v0
	v_mov_b32_e32 v7, v0
	v_mov_b32_e32 v8, v0
	v_mov_b32_e32 v9, v0
	v_mov_b32_e32 v10, v0
	v_mov_b32_e32 v11, v0
	v_mov_b32_e32 v12, v0
	v_mov_b32_e32 v13, v0
	v_mov_b32_e32 v14, v0
	v_mov_b32_e32 v15, v0
	v_mov_b32_e32 v16, v0
	v_mov_b32_e32 v17, v0
	v_mov_b32_e32 v18, v0
	v_mov_b32_e32 v19, v0
	v_mov_b32_e32 v20, v0
	v_mov_b32_e32 v21, v0
	v_mov_b32_e32 v22, v0
	v_mov_b32_e32 v23, v0
	v_mov_b32_e32 v24, v0
	v_mov_b32_e32 v25, v0
	v_mov_b32_e32 v26, v0
	v_mov_b32_e32 v27, v0
	v_mov_b32_e32 v28, v0
	v_mov_b32_e32 v29, v0
	v_mov_b32_e32 v30, v0
	v_mov_b32_e32 v31, v0
	v_mov_b32_e32 v32, v0
	v_mov_b32_e32 v33, v0
	v_mov_b32_e32 v34, v0
	v_mov_b32_e32 v35, v0
	v_mov_b32_e32 v36, v0
	v_mov_b32_e32 v37, v0
	v_mov_b32_e32 v38, v0
	v_mov_b32_e32 v39, v0
	v_mov_b32_e32 v40, v0
	v_mov_b32_e32 v41, v0
	v_mov_b32_e32 v42, v0
	v_mov_b32_e32 v43, v0
	v_mov_b32_e32 v44, v0
	v_mov_b32_e32 v45, v0
	v_mov_b32_e32 v46, v0
	v_mov_b32_e32 v47, v0
	v_mov_b32_e32 v48, v0
	v_mov_b32_e32 v49, v0
	v_mov_b32_e32 v50, v0
	v_mov_b32_e32 v51, v0
	v_mov_b32_e32 v52, v0
	v_mov_b32_e32 v53, v0
	v_mov_b32_e32 v54, v0
	v_mov_b32_e32 v55, v0
	v_mov_b32_e32 v56, v0
	v_mov_b32_e32 v57, v0
	v_mov_b32_e32 v58, v0
	v_mov_b32_e32 v59, v0
	v_mov_b32_e32 v60, v0
	v_mov_b32_e32 v61, v0
	v_mov_b32_e32 v62, v0
	v_mov_b32_e32 v63, v0
	v_mov_b32_e32 v64, v0
	v_mov_b32_e32 v65, v0
	v_mov_b32_e32 v66, v0
	v_mov_b32_e32 v67, v0
	v_mov_b32_e32 v68, v0
	v_mov_b32_e32 v69, v0
	v_mov_b32_e32 v70, v0
	v_mov_b32_e32 v71, v0
	v_mov_b32_e32 v72, v0
	v_mov_b32_e32 v73, v0
	v_mov_b32_e32 v74, v0
	v_mov_b32_e32 v75, v0
	v_mov_b32_e32 v76, v0
	v_mov_b32_e32 v77, v0
	v_mov_b32_e32 v78, v0
	v_mov_b32_e32 v79, v0
	v_mov_b32_e32 v80, v0
	v_mov_b32_e32 v81, v0
	v_mov_b32_e32 v82, v0
	v_mov_b32_e32 v83, v0
	v_mov_b32_e32 v84, v0
	v_mov_b32_e32 v85, v0
	v_mov_b32_e32 v86, v0
	v_mov_b32_e32 v87, v0
	v_mov_b32_e32 v88, v0
	v_mov_b32_e32 v89, v0
	v_mov_b32_e32 v90, v0
	v_mov_b32_e32 v91, v0
	v_mov_b32_e32 v92, v0
	v_mov_b32_e32 v93, v0
	v_mov_b32_e32 v94, v0
	v_mov_b32_e32 v95, v0
	v_mov_b32_e32 v96, v0
	v_mov_b32_e32 v97, v0
	v_mov_b32_e32 v98, v0
	v_mov_b32_e32 v99, v0
	v_mov_b32_e32 v100, v0
	v_mov_b32_e32 v101, v0
	v_mov_b32_e32 v102, v0
	v_mov_b32_e32 v103, v0
	v_mov_b32_e32 v104, v0
	v_mov_b32_e32 v105, v0
	v_mov_b32_e32 v106, v0
	v_mov_b32_e32 v107, v0
	v_mov_b32_e32 v108, v0
	v_mov_b32_e32 v109, v0
	v_mov_b32_e32 v110, v0
	v_mov_b32_e32 v111, v0
	v_mov_b32_e32 v112, v0
	v_mov_b32_e32 v113, v0
	v_mov_b32_e32 v114, v0
	v_mov_b32_e32 v115, v0
	v_mov_b32_e32 v116, v0
	v_mov_b32_e32 v117, v0
	v_mov_b32_e32 v118, v0
	v_mov_b32_e32 v119, v0
	v_mov_b32_e32 v120, v0
	v_mov_b32_e32 v121, v0
	v_mov_b32_e32 v122, v0
	v_mov_b32_e32 v123, v0
	v_mov_b32_e32 v124, v0
	v_mov_b32_e32 v125, v0
	v_mov_b32_e32 v126, v0
	v_mov_b32_e32 v127, v0
.LBB0_1949:
	s_add_i32 s6, s5, 2
	s_mul_hi_i32 s7, s6, 0x55555556
	s_lshr_b32 s41, s7, 31
	s_add_i32 s7, s7, s41
	s_mul_i32 s7, s7, 3
	s_sub_i32 s6, s6, s7
	s_mulk_i32 s6, 0x6000
	s_mul_i32 s54, s5, 0x6000
	v_readfirstlane_b32 s55, v140
	v_lshl_add_u64 v[232:233], v[132:133], 0, s[0:1]
	v_lshl_add_u64 v[234:235], v[130:131], 0, s[0:1]
	s_add_u32 s55, s55, s6
	s_waitcnt vmcnt(6) lgkmcnt(0)
	s_barrier
	v_or_b32_e32 v128, s54, v138
	v_add3_u32 v128, v128, v139, v137
	ds_read_b128 v[176:179], v128 offset:16384
	ds_read_b128 v[180:183], v128 offset:16640
	ds_read_b128 v[184:187], v128 offset:18432
	ds_read_b128 v[192:195], v128 offset:18688
	v_add3_u32 v128, s54, v141, v137
	ds_read_b128 v[144:147], v128
	ds_read_b128 v[148:151], v128 offset:1024
	ds_read_b128 v[152:155], v128 offset:2048
	ds_read_b128 v[156:159], v128 offset:3072
	ds_read_b128 v[160:163], v128 offset:4096
	ds_read_b128 v[164:167], v128 offset:5120
	ds_read_b128 v[168:171], v128 offset:6144
	ds_read_b128 v[172:175], v128 offset:7168
	s_setprio 1
	s_waitcnt lgkmcnt(7)
	v_mfma_f32_16x16x32_bf16 v[124:127], v[176:179], v[144:147], v[124:127]
	v_mfma_f32_16x16x32_bf16 v[120:123], v[180:183], v[144:147], v[120:123]
	v_mfma_f32_16x16x32_bf16 v[116:119], v[184:187], v[144:147], v[116:119]
	v_mfma_f32_16x16x32_bf16 v[112:115], v[192:195], v[144:147], v[112:115]
	s_mov_b32 m0, s55
	v_lshl_add_u64 v[236:237], v[232:233], 0, s[20:21]
	global_load_lds_dwordx4 v[236:237], off
	s_waitcnt lgkmcnt(6)
	v_mfma_f32_16x16x32_bf16 v[108:111], v[176:179], v[148:151], v[108:111]
	v_mfma_f32_16x16x32_bf16 v[104:107], v[180:183], v[148:151], v[104:107]
	v_mfma_f32_16x16x32_bf16 v[100:103], v[184:187], v[148:151], v[100:103]
	v_mfma_f32_16x16x32_bf16 v[96:99], v[192:195], v[148:151], v[96:99]
	s_add_u32 m0, s55, 0x1000
	v_lshl_add_u64 v[236:237], v[232:233], 0, s[22:23]
	global_load_lds_dwordx4 v[236:237], off
	s_waitcnt lgkmcnt(5)
	v_mfma_f32_16x16x32_bf16 v[92:95], v[176:179], v[152:155], v[92:95]
	v_mfma_f32_16x16x32_bf16 v[88:91], v[180:183], v[152:155], v[88:91]
	v_mfma_f32_16x16x32_bf16 v[84:87], v[184:187], v[152:155], v[84:87]
	v_mfma_f32_16x16x32_bf16 v[80:83], v[192:195], v[152:155], v[80:83]
	s_add_u32 m0, s55, 0x2000
	v_lshl_add_u64 v[236:237], v[232:233], 0, s[24:25]
	global_load_lds_dwordx4 v[236:237], off
	s_waitcnt lgkmcnt(4)
	v_mfma_f32_16x16x32_bf16 v[76:79], v[176:179], v[156:159], v[76:79]
	v_mfma_f32_16x16x32_bf16 v[72:75], v[180:183], v[156:159], v[72:75]
	v_mfma_f32_16x16x32_bf16 v[68:71], v[184:187], v[156:159], v[68:71]
	v_mfma_f32_16x16x32_bf16 v[64:67], v[192:195], v[156:159], v[64:67]
	s_add_u32 m0, s55, 0x3000
	v_lshl_add_u64 v[236:237], v[232:233], 0, s[26:27]
	global_load_lds_dwordx4 v[236:237], off
	s_waitcnt lgkmcnt(3)
	v_mfma_f32_16x16x32_bf16 v[60:63], v[176:179], v[160:163], v[60:63]
	v_mfma_f32_16x16x32_bf16 v[56:59], v[180:183], v[160:163], v[56:59]
	v_mfma_f32_16x16x32_bf16 v[52:55], v[184:187], v[160:163], v[52:55]
	v_mfma_f32_16x16x32_bf16 v[48:51], v[192:195], v[160:163], v[48:51]
	s_add_u32 m0, s55, 0x4000
	v_lshl_add_u64 v[236:237], v[234:235], 0, s[28:29]
	global_load_lds_dwordx4 v[236:237], off
	s_waitcnt lgkmcnt(2)
	v_mfma_f32_16x16x32_bf16 v[44:47], v[176:179], v[164:167], v[44:47]
	v_mfma_f32_16x16x32_bf16 v[40:43], v[180:183], v[164:167], v[40:43]
	v_mfma_f32_16x16x32_bf16 v[36:39], v[184:187], v[164:167], v[36:39]
	v_mfma_f32_16x16x32_bf16 v[32:35], v[192:195], v[164:167], v[32:35]
	s_add_u32 m0, s55, 0x5000
	v_lshl_add_u64 v[236:237], v[234:235], 0, s[30:31]
	global_load_lds_dwordx4 v[236:237], off
	s_waitcnt lgkmcnt(1)
	v_mfma_f32_16x16x32_bf16 v[28:31], v[176:179], v[168:171], v[28:31]
	v_mfma_f32_16x16x32_bf16 v[24:27], v[180:183], v[168:171], v[24:27]
	v_mfma_f32_16x16x32_bf16 v[20:23], v[184:187], v[168:171], v[20:23]
	v_mfma_f32_16x16x32_bf16 v[16:19], v[192:195], v[168:171], v[16:19]
	s_waitcnt lgkmcnt(0)
	v_mfma_f32_16x16x32_bf16 v[12:15], v[176:179], v[172:175], v[12:15]
	v_mfma_f32_16x16x32_bf16 v[8:11], v[180:183], v[172:175], v[8:11]
	v_mfma_f32_16x16x32_bf16 v[4:7], v[184:187], v[172:175], v[4:7]
	v_mfma_f32_16x16x32_bf16 v[0:3], v[192:195], v[172:175], v[0:3]
	s_setprio 0
	s_add_i32 s6, s5, 1
	s_cmp_lg_u32 s5, 2
	s_cselect_b32 s5, s6, 0
	s_add_u32 s0, s0, 0x80
	s_addc_u32 s1, s1, 0
	s_cmpk_eq_i32 s0, 0xf00
	s_cbranch_scc0 .LBB0_1949
	s_waitcnt vmcnt(6) lgkmcnt(0)
	s_barrier
	v_add_u32_e32 v128, v141, v137
	ds_read_b128 v[130:133], v128
	ds_read_b128 v[144:147], v128 offset:1024
	ds_read_b128 v[148:151], v128 offset:2048
	ds_read_b128 v[152:155], v128 offset:3072
	ds_read_b128 v[156:159], v128 offset:4096
	ds_read_b128 v[160:163], v128 offset:5120
	ds_read_b128 v[164:167], v128 offset:6144
	ds_read_b128 v[168:171], v128 offset:7168
	v_add3_u32 v137, v138, v139, v137
	ds_read_b128 v[138:141], v137 offset:16384
	ds_read_b128 v[172:175], v137 offset:16640
	ds_read_b128 v[176:179], v137 offset:18432
	ds_read_b128 v[180:183], v137 offset:18688
	s_setprio 1
	s_waitcnt lgkmcnt(0)
	v_mfma_f32_16x16x32_bf16 v[124:127], v[138:141], v[130:133], v[124:127]
	v_mfma_f32_16x16x32_bf16 v[184:187], v[172:175], v[130:133], v[120:123]
	v_mfma_f32_16x16x32_bf16 v[116:119], v[176:179], v[130:133], v[116:119]
	v_mfma_f32_16x16x32_bf16 v[130:133], v[180:183], v[130:133], v[112:115]
	v_mfma_f32_16x16x32_bf16 v[108:111], v[138:141], v[144:147], v[108:111]
	v_mfma_f32_16x16x32_bf16 v[100:103], v[176:179], v[144:147], v[100:103]
	v_mfma_f32_16x16x32_bf16 v[92:95], v[138:141], v[148:151], v[92:95]
	v_mfma_f32_16x16x32_bf16 v[84:87], v[176:179], v[148:151], v[84:87]
	v_mfma_f32_16x16x32_bf16 v[76:79], v[138:141], v[152:155], v[76:79]
	v_mfma_f32_16x16x32_bf16 v[68:71], v[176:179], v[152:155], v[68:71]
	v_mfma_f32_16x16x32_bf16 v[60:63], v[138:141], v[156:159], v[60:63]
	v_mfma_f32_16x16x32_bf16 v[52:55], v[176:179], v[156:159], v[52:55]
	v_mfma_f32_16x16x32_bf16 v[44:47], v[138:141], v[160:163], v[44:47]
	v_mfma_f32_16x16x32_bf16 v[36:39], v[176:179], v[160:163], v[36:39]
	v_mfma_f32_16x16x32_bf16 v[28:31], v[138:141], v[164:167], v[28:31]
	v_mfma_f32_16x16x32_bf16 v[20:23], v[176:179], v[164:167], v[20:23]
	v_mfma_f32_16x16x32_bf16 v[12:15], v[138:141], v[168:171], v[12:15]
	v_mfma_f32_16x16x32_bf16 v[138:141], v[172:175], v[168:171], v[8:11]
	v_mfma_f32_16x16x32_bf16 v[4:7], v[176:179], v[168:171], v[4:7]
	v_mfma_f32_16x16x32_bf16 v[192:195], v[172:175], v[144:147], v[104:107]
	v_mfma_f32_16x16x32_bf16 v[144:147], v[180:183], v[144:147], v[96:99]
	v_mfma_f32_16x16x32_bf16 v[196:199], v[172:175], v[148:151], v[88:91]
	v_mfma_f32_16x16x32_bf16 v[148:151], v[180:183], v[148:151], v[80:83]
	v_mfma_f32_16x16x32_bf16 v[200:203], v[172:175], v[152:155], v[72:75]
	v_mfma_f32_16x16x32_bf16 v[152:155], v[180:183], v[152:155], v[64:67]
	v_mfma_f32_16x16x32_bf16 v[204:207], v[172:175], v[156:159], v[56:59]
	v_mfma_f32_16x16x32_bf16 v[156:159], v[180:183], v[156:159], v[48:51]
	v_mfma_f32_16x16x32_bf16 v[208:211], v[172:175], v[160:163], v[40:43]
	v_mfma_f32_16x16x32_bf16 v[160:163], v[180:183], v[160:163], v[32:35]
	v_mfma_f32_16x16x32_bf16 v[212:215], v[172:175], v[164:167], v[24:27]
	v_mfma_f32_16x16x32_bf16 v[164:167], v[180:183], v[164:167], v[16:19]
	v_mfma_f32_16x16x32_bf16 v[168:171], v[180:183], v[168:171], v[0:3]
	s_setprio 0
	s_waitcnt vmcnt(0) lgkmcnt(0)
	s_barrier
	s_nop 1
	ds_read_b128 v[0:3], v128 offset:24576
	ds_read_b128 v[8:11], v128 offset:25600
	ds_read_b128 v[16:19], v128 offset:26624
	ds_read_b128 v[24:27], v128 offset:27648
	ds_read_b128 v[32:35], v128 offset:28672
	ds_read_b128 v[172:175], v128 offset:29696
	ds_read_b128 v[176:179], v128 offset:30720
	ds_read_b128 v[180:183], v128 offset:31744
	ds_read_b128 v[216:219], v137 offset:40960
	ds_read_b128 v[220:223], v137 offset:41216
	ds_read_b128 v[224:227], v137 offset:43008
	ds_read_b128 v[228:231], v137 offset:43264
	s_setprio 1
	s_waitcnt lgkmcnt(0)
	v_mfma_f32_16x16x32_bf16 v[120:123], v[216:219], v[0:3], v[124:127]
	v_mfma_f32_16x16x32_bf16 v[124:127], v[220:223], v[0:3], v[184:187]
	v_mfma_f32_16x16x32_bf16 v[112:115], v[224:227], v[0:3], v[116:119]
	v_mfma_f32_16x16x32_bf16 v[116:119], v[228:231], v[0:3], v[130:133]
	v_mfma_f32_16x16x32_bf16 v[104:107], v[216:219], v[8:11], v[108:111]
	v_mfma_f32_16x16x32_bf16 v[108:111], v[220:223], v[8:11], v[192:195]
	v_mfma_f32_16x16x32_bf16 v[96:99], v[224:227], v[8:11], v[100:103]
	v_mfma_f32_16x16x32_bf16 v[100:103], v[228:231], v[8:11], v[144:147]
	v_mfma_f32_16x16x32_bf16 v[88:91], v[216:219], v[16:19], v[92:95]
	v_mfma_f32_16x16x32_bf16 v[92:95], v[220:223], v[16:19], v[196:199]
	v_mfma_f32_16x16x32_bf16 v[80:83], v[224:227], v[16:19], v[84:87]
	v_mfma_f32_16x16x32_bf16 v[84:87], v[228:231], v[16:19], v[148:151]
	v_mfma_f32_16x16x32_bf16 v[72:75], v[216:219], v[24:27], v[76:79]
	v_mfma_f32_16x16x32_bf16 v[76:79], v[220:223], v[24:27], v[200:203]
	v_mfma_f32_16x16x32_bf16 v[64:67], v[224:227], v[24:27], v[68:71]
	v_mfma_f32_16x16x32_bf16 v[68:71], v[228:231], v[24:27], v[152:155]
	v_mfma_f32_16x16x32_bf16 v[56:59], v[216:219], v[32:35], v[60:63]
	v_mfma_f32_16x16x32_bf16 v[60:63], v[220:223], v[32:35], v[204:207]
	v_mfma_f32_16x16x32_bf16 v[48:51], v[224:227], v[32:35], v[52:55]
	v_mfma_f32_16x16x32_bf16 v[52:55], v[228:231], v[32:35], v[156:159]
	v_mfma_f32_16x16x32_bf16 v[40:43], v[216:219], v[172:175], v[44:47]
	v_mfma_f32_16x16x32_bf16 v[44:47], v[220:223], v[172:175], v[208:211]
	v_mfma_f32_16x16x32_bf16 v[32:35], v[224:227], v[172:175], v[36:39]
	v_mfma_f32_16x16x32_bf16 v[36:39], v[228:231], v[172:175], v[160:163]
	v_mfma_f32_16x16x32_bf16 v[24:27], v[216:219], v[176:179], v[28:31]
	v_mfma_f32_16x16x32_bf16 v[28:31], v[220:223], v[176:179], v[212:215]
	v_mfma_f32_16x16x32_bf16 v[16:19], v[224:227], v[176:179], v[20:23]
	v_mfma_f32_16x16x32_bf16 v[20:23], v[228:231], v[176:179], v[164:167]
	v_mfma_f32_16x16x32_bf16 v[8:11], v[216:219], v[180:183], v[12:15]
	v_mfma_f32_16x16x32_bf16 v[12:15], v[220:223], v[180:183], v[138:141]
	v_mfma_f32_16x16x32_bf16 v[0:3], v[224:227], v[180:183], v[4:7]
	v_mfma_f32_16x16x32_bf16 v[4:7], v[228:231], v[180:183], v[168:171]
	s_setprio 0
	v_and_b32_e32 v128, 0xffffff80, v134
	v_add_u32_e32 v128, s40, v128
	v_or_b32_e32 v132, v128, v135
	v_lshrrev_b32_e32 v130, 1, v134
	v_lshlrev_b32_e32 v128, 6, v136
	v_and_b32_e32 v130, 24, v130
	v_ashrrev_i32_e32 v133, 31, v132
	v_readlane_b32 s0, v254, 62
	v_or3_b32 v128, v128, v130, s4
	v_lshlrev_b64 v[130:131], 11, v[132:133]
	v_readlane_b32 s1, v254, 63
	v_cmp_lt_i32_e64 s[4:5], s48, v128
	s_nop 0
	v_lshl_add_u64 v[136:137], s[0:1], 0, v[130:131]
	v_lshlrev_b64 v[130:131], 10, v[132:133]
	v_lshl_add_u64 v[134:135], s[96:97], 0, v[130:131]
	s_and_saveexec_b64 s[0:1], s[4:5]
	s_xor_b64 s[0:1], exec, s[0:1]
	s_cbranch_execz .LBB0_1955
	s_cmpk_gt_u32 s33, 0x3ff
	s_mov_b64 s[6:7], -1
	s_cbranch_scc0 .LBB0_1953
	v_lshl_add_u64 v[138:139], v[128:129], 1, v[136:137]
	v_lshl_add_u64 v[138:139], v[138:139], 0, s[2:3]
	s_mov_b64 s[6:7], 0

.LBB0_2070:
	v_readlane_b32 s0, v255, 4
	v_readlane_b32 s1, v255, 5
	v_mov_b32_e32 v0, v190
	s_andn2_b64 vcc, exec, s[0:1]
	v_readlane_b32 s64, v254, 56
	s_cbranch_vccnz .LBB0_2162
	v_and_b32_e32 v42, 15, v0
	v_bfe_u32 v1, v0, 4, 2
	v_ashrrev_i32_e32 v0, 1, v0
	v_and_b32_e32 v43, 0xffffffe0, v0
	v_mov_b32_e32 v19, 0
	v_lshlrev_b32_e32 v44, 2, v1
	v_or_b32_e32 v45, 16, v42
	v_lshlrev_b32_e32 v16, 4, v1
	v_and_b32_e32 v238, 1, v42
	v_lshl_or_b32 v16, v238, 6, v16
	v_mov_b32_e32 v17, v19
	v_or_b32_e32 v46, v43, v42
	s_movk_i32 s3, 0x4000
	s_mov_b32 s10, 0x12d0000
	s_mov_b32 s11, 0x12d8000
	s_mov_b32 s12, 0x8000
	s_mov_b64 s[0:1], 0x200
	s_movk_i32 s13, 0x1ff
	s_movk_i32 s14, 0x7fff
	s_mov_b32 s2, 0x3db504f3
	v_mov_b32_e32 v47, 1
	s_mov_b32 s15, s64
	s_branch .LBB0_2074

.LBB0_2074:
	s_min_i32 s4, s15, 0x60
	s_lshl_b32 s5, s15, 7
	s_lshl_b32 s16, s4, 5
	s_addk_i32 s5, 0xcf80
	s_cmpk_gt_i32 s15, 0x60
	s_cselect_b32 s8, s5, 0x4000
	s_and_b32 s4, s4, 0x3ffffe0
	s_cmp_eq_u32 s4, 64
	v_or_b32_e32 v20, s16, v42
	s_cselect_b64 s[4:5], -1, 0
	s_cmpk_lt_i32 s16, 0x400
	v_ashrrev_i32_e32 v21, 31, v20
	s_cselect_b64 s[6:7], -1, 0
	v_and_b32_e32 v0, -2, v20
	v_mov_b32_e32 v1, v21
	v_lshlrev_b64 v[0:1], 11, v[0:1]
	s_or_b64 s[4:5], s[6:7], s[4:5]
	v_add_u32_e32 v24, s8, v46
	v_lshl_add_u64 v[22:23], s[52:53], 0, v[0:1]
	s_mov_b64 s[6:7], -1
	s_and_b64 vcc, exec, s[4:5]
	v_ashrrev_i32_e32 v25, 31, v24
	s_cbranch_vccnz .LBB0_2078
	v_and_b32_e32 v0, -2, v24
	v_mov_b32_e32 v1, v25
	v_lshlrev_b64 v[0:1], 11, v[0:1]
	v_lshl_add_u64 v[26:27], s[52:53], 0, v[0:1]
	v_mov_b32_e32 v0, 0
	s_movk_i32 s6, 0xffe0
	v_mov_b64_e32 v[28:29], v[22:23]
	v_mov_b32_e32 v1, v0
	v_mov_b32_e32 v2, v0
	v_mov_b32_e32 v3, v0
	v_mov_b32_e32 v12, v0
	v_mov_b32_e32 v13, v0
	v_mov_b32_e32 v14, v0
	v_mov_b32_e32 v15, v0
	v_mov_b32_e32 v8, v0
	v_mov_b32_e32 v9, v0
	v_mov_b32_e32 v10, v0
	v_mov_b32_e32 v11, v0
	v_mov_b32_e32 v4, v0
	v_mov_b32_e32 v5, v0
	v_mov_b32_e32 v6, v0
	v_mov_b32_e32 v7, v0
.LBB0_2076:
	v_lshl_add_u64 v[30:31], v[26:27], 0, v[16:17]
	v_add_co_u32_e32 v66, vcc, s10, v30
	v_lshl_add_u64 v[64:65], v[28:29], 0, v[16:17]
	s_nop 0
	v_addc_co_u32_e32 v67, vcc, 0, v31, vcc
	v_add_co_u32_e32 v68, vcc, s11, v30
	s_addk_i32 s6, 0x80
	s_nop 0
	v_addc_co_u32_e32 v69, vcc, 0, v31, vcc
	v_add_co_u32_e32 v70, vcc, s12, v64
	v_lshl_add_u64 v[28:29], v[28:29], 0, s[0:1]
	s_nop 0
	v_addc_co_u32_e32 v71, vcc, 0, v65, vcc
	global_load_dwordx4 v[30:33], v[64:65], off
	global_load_dwordx4 v[34:37], v[64:65], off offset:128
	global_load_dwordx4 v[38:41], v[66:67], off
	global_load_dwordx4 v[48:51], v[70:71], off
	global_load_dwordx4 v[52:55], v[66:67], off offset:128
	global_load_dwordx4 v[56:59], v[68:69], off
	global_load_dwordx4 v[60:63], v[70:71], off offset:128
	s_cmpk_lt_u32 s6, 0x3e0
	v_lshl_add_u64 v[26:27], v[26:27], 0, s[0:1]
	s_waitcnt vmcnt(0)
	v_mfma_f32_16x16x32_bf16 v[12:15], v[38:41], v[30:33], v[12:15]
	v_mfma_f32_16x16x32_bf16 v[8:11], v[38:41], v[48:51], v[8:11]
	global_load_dwordx4 v[38:41], v[68:69], off offset:128
	v_mfma_f32_16x16x32_bf16 v[4:7], v[56:59], v[30:33], v[4:7]
	v_mfma_f32_16x16x32_bf16 v[0:3], v[56:59], v[48:51], v[0:3]
	global_load_dwordx4 v[30:33], v[64:65], off offset:256
	global_load_dwordx4 v[48:51], v[64:65], off offset:384
	v_mfma_f32_16x16x32_bf16 v[12:15], v[52:55], v[34:37], v[12:15]
	v_mfma_f32_16x16x32_bf16 v[8:11], v[52:55], v[60:63], v[8:11]
	s_waitcnt vmcnt(2)
	v_mfma_f32_16x16x32_bf16 v[4:7], v[38:41], v[34:37], v[4:7]
	global_load_dwordx4 v[34:37], v[66:67], off offset:256
	v_mfma_f32_16x16x32_bf16 v[0:3], v[38:41], v[60:63], v[0:3]
	global_load_dwordx4 v[38:41], v[70:71], off offset:256
	global_load_dwordx4 v[52:55], v[66:67], off offset:384
	global_load_dwordx4 v[56:59], v[68:69], off offset:256
	global_load_dwordx4 v[60:63], v[70:71], off offset:384
	s_waitcnt vmcnt(1)
	v_mfma_f32_16x16x32_bf16 v[4:7], v[56:59], v[30:33], v[4:7]
	v_mfma_f32_16x16x32_bf16 v[12:15], v[34:37], v[30:33], v[12:15]
	v_mfma_f32_16x16x32_bf16 v[8:11], v[34:37], v[38:41], v[8:11]
	global_load_dwordx4 v[34:37], v[68:69], off offset:384
	v_mfma_f32_16x16x32_bf16 v[0:3], v[56:59], v[38:41], v[0:3]
	v_mfma_f32_16x16x32_bf16 v[12:15], v[52:55], v[48:51], v[12:15]
	s_waitcnt vmcnt(1)
	v_mfma_f32_16x16x32_bf16 v[8:11], v[52:55], v[60:63], v[8:11]
	s_waitcnt vmcnt(0)
	v_mfma_f32_16x16x32_bf16 v[4:7], v[34:37], v[48:51], v[4:7]
	v_mfma_f32_16x16x32_bf16 v[0:3], v[34:37], v[60:63], v[0:3]
	s_cbranch_scc1 .LBB0_2076
	s_mov_b64 s[6:7], 0
.LBB0_2078:
	s_and_b64 vcc, exec, s[6:7]
	s_cbranch_vccz .LBB0_2081
	s_nop 3
	v_and_b32_e32 v0, -2, v24
	v_mov_b32_e32 v1, v25
	v_lshlrev_b64 v[0:1], 11, v[0:1]
	v_lshl_add_u64 v[24:25], s[52:53], 0, v[0:1]
	v_mov_b32_e32 v0, 0
	s_movk_i32 s6, 0xffe0
	v_mov_b32_e32 v1, v0
	v_mov_b32_e32 v2, v0
	v_mov_b32_e32 v3, v0
	v_mov_b32_e32 v12, v0
	v_mov_b32_e32 v13, v0
	v_mov_b32_e32 v14, v0
	v_mov_b32_e32 v15, v0
	v_mov_b32_e32 v8, v0
	v_mov_b32_e32 v9, v0
	v_mov_b32_e32 v10, v0
	v_mov_b32_e32 v11, v0
	v_mov_b32_e32 v4, v0
	v_mov_b32_e32 v5, v0
	v_mov_b32_e32 v6, v0
	v_mov_b32_e32 v7, v0
.LBB0_2080:
	v_lshl_add_u64 v[26:27], v[24:25], 0, v[16:17]
	v_add_co_u32_e32 v62, vcc, s10, v26
	v_lshl_add_u64 v[60:61], v[22:23], 0, v[16:17]
	s_nop 0
	v_addc_co_u32_e32 v63, vcc, 0, v27, vcc
	v_add_co_u32_e32 v64, vcc, s11, v26
	s_addk_i32 s6, 0x80
	s_nop 0
	v_addc_co_u32_e32 v65, vcc, 0, v27, vcc
	global_load_dwordx4 v[26:29], v[60:61], off
	global_load_dwordx4 v[30:33], v[60:61], off offset:128
	global_load_dwordx4 v[34:37], v[62:63], off
	global_load_dwordx4 v[38:41], v[64:65], off
	global_load_dwordx4 v[48:51], v[62:63], off offset:128
	v_add_co_u32_e32 v66, vcc, s12, v60
	v_lshl_add_u64 v[22:23], v[22:23], 0, s[0:1]
	s_nop 0
	v_addc_co_u32_e32 v67, vcc, 0, v61, vcc
	global_load_dwordx4 v[52:55], v[66:67], off
	global_load_dwordx4 v[56:59], v[64:65], off offset:128
	s_cmpk_gt_u32 s6, 0x3df
	v_lshl_add_u64 v[24:25], v[24:25], 0, s[0:1]
	s_waitcnt vmcnt(0)
	v_mfma_f32_16x16x32_bf16 v[8:11], v[52:55], v[34:37], v[8:11]
	v_mfma_f32_16x16x32_bf16 v[12:15], v[26:29], v[34:37], v[12:15]
	v_mfma_f32_16x16x32_bf16 v[4:7], v[26:29], v[38:41], v[4:7]
	global_load_dwordx4 v[26:29], v[66:67], off offset:128
	v_mfma_f32_16x16x32_bf16 v[0:3], v[52:55], v[38:41], v[0:3]
	v_mfma_f32_16x16x32_bf16 v[12:15], v[30:33], v[48:51], v[12:15]
	v_mfma_f32_16x16x32_bf16 v[4:7], v[30:33], v[56:59], v[4:7]
	global_load_dwordx4 v[30:33], v[60:61], off offset:256
	global_load_dwordx4 v[34:37], v[60:61], off offset:384
	global_load_dwordx4 v[38:41], v[62:63], off offset:256
	s_waitcnt vmcnt(3)
	v_mfma_f32_16x16x32_bf16 v[8:11], v[26:29], v[48:51], v[8:11]
	v_mfma_f32_16x16x32_bf16 v[0:3], v[26:29], v[56:59], v[0:3]
	global_load_dwordx4 v[26:29], v[64:65], off offset:256
	global_load_dwordx4 v[48:51], v[62:63], off offset:384
	global_load_dwordx4 v[52:55], v[66:67], off offset:256
	global_load_dwordx4 v[56:59], v[64:65], off offset:384
	s_waitcnt vmcnt(4)
	v_mfma_f32_16x16x32_bf16 v[12:15], v[30:33], v[38:41], v[12:15]
	s_waitcnt vmcnt(3)
	v_mfma_f32_16x16x32_bf16 v[4:7], v[30:33], v[26:29], v[4:7]
	global_load_dwordx4 v[30:33], v[66:67], off offset:384
	s_waitcnt vmcnt(2)
	v_mfma_f32_16x16x32_bf16 v[8:11], v[52:55], v[38:41], v[8:11]
	v_mfma_f32_16x16x32_bf16 v[0:3], v[52:55], v[26:29], v[0:3]
	v_mfma_f32_16x16x32_bf16 v[12:15], v[34:37], v[48:51], v[12:15]
	s_waitcnt vmcnt(1)
	v_mfma_f32_16x16x32_bf16 v[4:7], v[34:37], v[56:59], v[4:7]
	s_waitcnt vmcnt(0)
	v_mfma_f32_16x16x32_bf16 v[8:11], v[30:33], v[48:51], v[8:11]
	v_mfma_f32_16x16x32_bf16 v[0:3], v[30:33], v[56:59], v[0:3]
	s_cbranch_scc0 .LBB0_2080

.LBB0_2563:
	s_add_i32 s36, s35, 2
	s_mul_hi_i32 s37, s36, 0x55555556
	s_lshr_b32 s38, s37, 31
	s_add_i32 s37, s37, s38
	s_mul_i32 s37, s37, 3
	s_sub_i32 s36, s36, s37
	s_mulk_i32 s36, 0x6000
	s_mul_i32 s54, s35, 0x6000
	v_readfirstlane_b32 s55, v140
	v_lshl_add_u64 v[232:233], v[132:133], 0, s[24:25]
	v_lshl_add_u64 v[234:235], v[130:131], 0, s[24:25]
	s_add_u32 s55, s55, s36
	s_waitcnt vmcnt(6) lgkmcnt(0)
	s_barrier
	v_or_b32_e32 v128, s54, v138
	v_add3_u32 v128, v128, v139, v137
	ds_read_b128 v[174:177], v128 offset:16384
	ds_read_b128 v[178:181], v128 offset:16640
	ds_read_b128 v[182:185], v128 offset:18432
	ds_read_b128 v[186:189], v128 offset:18688
	v_add3_u32 v128, s54, v141, v137
	ds_read_b128 v[142:145], v128
	ds_read_b128 v[146:149], v128 offset:1024
	ds_read_b128 v[150:153], v128 offset:2048
	ds_read_b128 v[154:157], v128 offset:3072
	ds_read_b128 v[158:161], v128 offset:4096
	ds_read_b128 v[162:165], v128 offset:5120
	ds_read_b128 v[166:169], v128 offset:6144
	ds_read_b128 v[170:173], v128 offset:7168
	s_setprio 1
	s_waitcnt lgkmcnt(7)
	v_mfma_f32_16x16x32_bf16 v[124:127], v[174:177], v[142:145], v[124:127]
	v_mfma_f32_16x16x32_bf16 v[120:123], v[178:181], v[142:145], v[120:123]
	v_mfma_f32_16x16x32_bf16 v[116:119], v[182:185], v[142:145], v[116:119]
	v_mfma_f32_16x16x32_bf16 v[112:115], v[186:189], v[142:145], v[112:115]
	s_mov_b32 m0, s55
	v_lshl_add_u64 v[236:237], v[232:233], 0, s[12:13]
	global_load_lds_dwordx4 v[236:237], off
	s_waitcnt lgkmcnt(6)
	v_mfma_f32_16x16x32_bf16 v[108:111], v[174:177], v[146:149], v[108:111]
	v_mfma_f32_16x16x32_bf16 v[104:107], v[178:181], v[146:149], v[104:107]
	v_mfma_f32_16x16x32_bf16 v[100:103], v[182:185], v[146:149], v[100:103]
	v_mfma_f32_16x16x32_bf16 v[96:99], v[186:189], v[146:149], v[96:99]
	s_add_u32 m0, s55, 0x1000
	v_lshl_add_u64 v[236:237], v[232:233], 0, s[14:15]
	global_load_lds_dwordx4 v[236:237], off
	s_waitcnt lgkmcnt(5)
	v_mfma_f32_16x16x32_bf16 v[92:95], v[174:177], v[150:153], v[92:95]
	v_mfma_f32_16x16x32_bf16 v[88:91], v[178:181], v[150:153], v[88:91]
	v_mfma_f32_16x16x32_bf16 v[84:87], v[182:185], v[150:153], v[84:87]
	v_mfma_f32_16x16x32_bf16 v[80:83], v[186:189], v[150:153], v[80:83]
	s_add_u32 m0, s55, 0x2000
	v_lshl_add_u64 v[236:237], v[232:233], 0, s[16:17]
	global_load_lds_dwordx4 v[236:237], off
	s_waitcnt lgkmcnt(4)
	v_mfma_f32_16x16x32_bf16 v[76:79], v[174:177], v[154:157], v[76:79]
	v_mfma_f32_16x16x32_bf16 v[72:75], v[178:181], v[154:157], v[72:75]
	v_mfma_f32_16x16x32_bf16 v[68:71], v[182:185], v[154:157], v[68:71]
	v_mfma_f32_16x16x32_bf16 v[64:67], v[186:189], v[154:157], v[64:67]
	s_add_u32 m0, s55, 0x3000
	v_lshl_add_u64 v[236:237], v[232:233], 0, s[18:19]
	global_load_lds_dwordx4 v[236:237], off
	s_waitcnt lgkmcnt(3)
	v_mfma_f32_16x16x32_bf16 v[60:63], v[174:177], v[158:161], v[60:63]
	v_mfma_f32_16x16x32_bf16 v[56:59], v[178:181], v[158:161], v[56:59]
	v_mfma_f32_16x16x32_bf16 v[52:55], v[182:185], v[158:161], v[52:55]
	v_mfma_f32_16x16x32_bf16 v[48:51], v[186:189], v[158:161], v[48:51]
	s_add_u32 m0, s55, 0x4000
	v_lshl_add_u64 v[236:237], v[234:235], 0, s[20:21]
	global_load_lds_dwordx4 v[236:237], off
	s_waitcnt lgkmcnt(2)
	v_mfma_f32_16x16x32_bf16 v[44:47], v[174:177], v[162:165], v[44:47]
	v_mfma_f32_16x16x32_bf16 v[40:43], v[178:181], v[162:165], v[40:43]
	v_mfma_f32_16x16x32_bf16 v[36:39], v[182:185], v[162:165], v[36:39]
	v_mfma_f32_16x16x32_bf16 v[32:35], v[186:189], v[162:165], v[32:35]
	s_add_u32 m0, s55, 0x5000
	v_lshl_add_u64 v[236:237], v[234:235], 0, s[22:23]
	global_load_lds_dwordx4 v[236:237], off
	s_waitcnt lgkmcnt(1)
	v_mfma_f32_16x16x32_bf16 v[28:31], v[174:177], v[166:169], v[28:31]
	v_mfma_f32_16x16x32_bf16 v[24:27], v[178:181], v[166:169], v[24:27]
	v_mfma_f32_16x16x32_bf16 v[20:23], v[182:185], v[166:169], v[20:23]
	v_mfma_f32_16x16x32_bf16 v[16:19], v[186:189], v[166:169], v[16:19]
	s_waitcnt lgkmcnt(0)
	v_mfma_f32_16x16x32_bf16 v[12:15], v[174:177], v[170:173], v[12:15]
	v_mfma_f32_16x16x32_bf16 v[8:11], v[178:181], v[170:173], v[8:11]
	v_mfma_f32_16x16x32_bf16 v[4:7], v[182:185], v[170:173], v[4:7]
	v_mfma_f32_16x16x32_bf16 v[0:3], v[186:189], v[170:173], v[0:3]
	s_setprio 0
	s_add_i32 s36, s35, 1
	s_cmp_lg_u32 s35, 2
	s_cselect_b32 s35, s36, 0
	s_add_u32 s24, s24, 64
	s_addc_u32 s25, s25, 0
	s_cmpk_eq_i32 s24, 0x780
	s_cbranch_scc0 .LBB0_2563
	s_waitcnt vmcnt(6) lgkmcnt(0)
	s_barrier
	v_add_u32_e32 v128, v141, v137
	ds_read_b128 v[130:133], v128
	ds_read_b128 v[140:143], v128 offset:1024
	ds_read_b128 v[144:147], v128 offset:2048
	ds_read_b128 v[148:151], v128 offset:3072
	ds_read_b128 v[152:155], v128 offset:4096
	ds_read_b128 v[156:159], v128 offset:5120
	ds_read_b128 v[160:163], v128 offset:6144
	ds_read_b128 v[164:167], v128 offset:7168
	v_add3_u32 v137, v138, v139, v137
	ds_read_b128 v[168:171], v137 offset:16384
	ds_read_b128 v[172:175], v137 offset:16640
	ds_read_b128 v[176:179], v137 offset:18432
	ds_read_b128 v[180:183], v137 offset:18688
	s_setprio 1
	s_waitcnt lgkmcnt(0)
	v_mfma_f32_16x16x32_bf16 v[124:127], v[168:171], v[130:133], v[124:127]
	v_mfma_f32_16x16x32_bf16 v[120:123], v[172:175], v[130:133], v[120:123]
	v_mfma_f32_16x16x32_bf16 v[116:119], v[176:179], v[130:133], v[116:119]
	v_mfma_f32_16x16x32_bf16 v[112:115], v[180:183], v[130:133], v[112:115]
	v_mfma_f32_16x16x32_bf16 v[108:111], v[168:171], v[140:143], v[108:111]
	v_mfma_f32_16x16x32_bf16 v[104:107], v[172:175], v[140:143], v[104:107]
	v_mfma_f32_16x16x32_bf16 v[100:103], v[176:179], v[140:143], v[100:103]
	v_mfma_f32_16x16x32_bf16 v[96:99], v[180:183], v[140:143], v[96:99]
	v_mfma_f32_16x16x32_bf16 v[92:95], v[168:171], v[144:147], v[92:95]
	v_mfma_f32_16x16x32_bf16 v[88:91], v[172:175], v[144:147], v[88:91]
	v_mfma_f32_16x16x32_bf16 v[84:87], v[176:179], v[144:147], v[84:87]
	v_mfma_f32_16x16x32_bf16 v[80:83], v[180:183], v[144:147], v[80:83]
	v_mfma_f32_16x16x32_bf16 v[76:79], v[168:171], v[148:151], v[76:79]
	v_mfma_f32_16x16x32_bf16 v[72:75], v[172:175], v[148:151], v[72:75]
	v_mfma_f32_16x16x32_bf16 v[68:71], v[176:179], v[148:151], v[68:71]
	v_mfma_f32_16x16x32_bf16 v[64:67], v[180:183], v[148:151], v[64:67]
	v_mfma_f32_16x16x32_bf16 v[60:63], v[168:171], v[152:155], v[60:63]
	v_mfma_f32_16x16x32_bf16 v[56:59], v[172:175], v[152:155], v[56:59]
	v_mfma_f32_16x16x32_bf16 v[52:55], v[176:179], v[152:155], v[52:55]
	v_mfma_f32_16x16x32_bf16 v[48:51], v[180:183], v[152:155], v[48:51]
	v_mfma_f32_16x16x32_bf16 v[44:47], v[168:171], v[156:159], v[44:47]
	v_mfma_f32_16x16x32_bf16 v[40:43], v[172:175], v[156:159], v[40:43]
	v_mfma_f32_16x16x32_bf16 v[36:39], v[176:179], v[156:159], v[36:39]
	v_mfma_f32_16x16x32_bf16 v[32:35], v[180:183], v[156:159], v[32:35]
	v_mfma_f32_16x16x32_bf16 v[28:31], v[168:171], v[160:163], v[28:31]
	v_mfma_f32_16x16x32_bf16 v[24:27], v[172:175], v[160:163], v[24:27]
	v_mfma_f32_16x16x32_bf16 v[20:23], v[176:179], v[160:163], v[20:23]
	v_mfma_f32_16x16x32_bf16 v[16:19], v[180:183], v[160:163], v[16:19]
	v_mfma_f32_16x16x32_bf16 v[12:15], v[168:171], v[164:167], v[12:15]
	v_mfma_f32_16x16x32_bf16 v[8:11], v[172:175], v[164:167], v[8:11]
	v_mfma_f32_16x16x32_bf16 v[4:7], v[176:179], v[164:167], v[4:7]
	v_mfma_f32_16x16x32_bf16 v[0:3], v[180:183], v[164:167], v[0:3]
	s_setprio 0
	s_waitcnt vmcnt(0) lgkmcnt(0)
	s_barrier
	ds_read_b128 v[130:133], v128 offset:24576
	ds_read_b128 v[138:141], v128 offset:25600
	ds_read_b128 v[142:145], v128 offset:26624
	ds_read_b128 v[146:149], v128 offset:27648
	ds_read_b128 v[150:153], v128 offset:28672
	ds_read_b128 v[154:157], v128 offset:29696
	ds_read_b128 v[158:161], v128 offset:30720
	ds_read_b128 v[162:165], v128 offset:31744
	ds_read_b128 v[166:169], v137 offset:40960
	ds_read_b128 v[170:173], v137 offset:41216
	ds_read_b128 v[174:177], v137 offset:43008
	ds_read_b128 v[178:181], v137 offset:43264
	s_setprio 1
	s_waitcnt lgkmcnt(0)
	v_mfma_f32_16x16x32_bf16 v[124:127], v[166:169], v[130:133], v[124:127]
	v_mfma_f32_16x16x32_bf16 v[120:123], v[170:173], v[130:133], v[120:123]
	v_mfma_f32_16x16x32_bf16 v[116:119], v[174:177], v[130:133], v[116:119]
	v_mfma_f32_16x16x32_bf16 v[112:115], v[178:181], v[130:133], v[112:115]
	v_mfma_f32_16x16x32_bf16 v[108:111], v[166:169], v[138:141], v[108:111]
	v_mfma_f32_16x16x32_bf16 v[104:107], v[170:173], v[138:141], v[104:107]
	v_mfma_f32_16x16x32_bf16 v[100:103], v[174:177], v[138:141], v[100:103]
	v_mfma_f32_16x16x32_bf16 v[130:133], v[178:181], v[138:141], v[96:99]
	v_mfma_f32_16x16x32_bf16 v[92:95], v[166:169], v[142:145], v[92:95]
	v_mfma_f32_16x16x32_bf16 v[88:91], v[170:173], v[142:145], v[88:91]
	v_mfma_f32_16x16x32_bf16 v[84:87], v[174:177], v[142:145], v[84:87]
	v_mfma_f32_16x16x32_bf16 v[80:83], v[178:181], v[142:145], v[80:83]
	v_mfma_f32_16x16x32_bf16 v[76:79], v[166:169], v[146:149], v[76:79]
	v_mfma_f32_16x16x32_bf16 v[72:75], v[170:173], v[146:149], v[72:75]
	v_mfma_f32_16x16x32_bf16 v[68:71], v[174:177], v[146:149], v[68:71]
	v_mfma_f32_16x16x32_bf16 v[64:67], v[178:181], v[146:149], v[64:67]
	v_mfma_f32_16x16x32_bf16 v[60:63], v[166:169], v[150:153], v[60:63]
	v_mfma_f32_16x16x32_bf16 v[56:59], v[170:173], v[150:153], v[56:59]
	v_mfma_f32_16x16x32_bf16 v[52:55], v[174:177], v[150:153], v[52:55]
	v_mfma_f32_16x16x32_bf16 v[48:51], v[178:181], v[150:153], v[48:51]
	v_mfma_f32_16x16x32_bf16 v[44:47], v[166:169], v[154:157], v[44:47]
	v_mfma_f32_16x16x32_bf16 v[40:43], v[170:173], v[154:157], v[40:43]
	v_mfma_f32_16x16x32_bf16 v[36:39], v[174:177], v[154:157], v[36:39]
	v_mfma_f32_16x16x32_bf16 v[32:35], v[178:181], v[154:157], v[32:35]
	v_mfma_f32_16x16x32_bf16 v[28:31], v[166:169], v[158:161], v[28:31]
	v_mfma_f32_16x16x32_bf16 v[24:27], v[170:173], v[158:161], v[24:27]
	v_mfma_f32_16x16x32_bf16 v[20:23], v[174:177], v[158:161], v[20:23]
	v_mfma_f32_16x16x32_bf16 v[16:19], v[178:181], v[158:161], v[16:19]
	v_mfma_f32_16x16x32_bf16 v[12:15], v[166:169], v[162:165], v[12:15]
	v_mfma_f32_16x16x32_bf16 v[8:11], v[170:173], v[162:165], v[8:11]
	v_mfma_f32_16x16x32_bf16 v[4:7], v[174:177], v[162:165], v[4:7]
	v_mfma_f32_16x16x32_bf16 v[0:3], v[178:181], v[162:165], v[0:3]
	s_setprio 0
	v_and_b32_e32 v96, 0xffffff80, v134
	v_lshrrev_b32_e32 v98, 1, v134
	v_add_u32_e32 v96, s33, v96
	v_lshlrev_b32_e32 v97, 6, v136
	v_and_b32_e32 v98, 24, v98
	v_or_b32_e32 v96, v96, v135
	v_or3_b32 v98, v97, v98, s34
	v_mov_b32_e32 v97, v129
	v_add_u32_e32 v128, 0xffffc000, v96
	v_readlane_b32 s24, v255, 39
	v_lshlrev_b64 v[138:139], 12, v[96:97]
	v_ashrrev_i32_e32 v97, 31, v96
	v_readlane_b32 s36, v254, 34
	v_lshlrev_b64 v[134:135], 12, v[128:129]
	v_readlane_b32 s25, v255, 40
	v_lshlrev_b64 v[140:141], 12, v[96:97]
	v_readlane_b32 s50, v254, 48
	v_readlane_b32 s51, v254, 49
	v_lshl_add_u64 v[134:135], s[24:25], 0, v[134:135]
	v_cmp_gt_i32_e32 vcc, s30, v96
	v_lshl_add_u64 v[136:137], s[50:51], 0, v[140:141]
	v_ashrrev_i32_e32 v99, 31, v98
	v_cndmask_b32_e32 v135, v135, v137, vcc
	v_cndmask_b32_e32 v134, v134, v136, vcc
	v_lshlrev_b64 v[98:99], 2, v[98:99]
	v_lshl_add_u64 v[142:143], v[134:135], 0, v[98:99]
	global_load_dwordx4 v[134:137], v[142:143], off
	v_cndmask_b32_e32 v139, v139, v141, vcc
	v_cndmask_b32_e32 v138, v138, v140, vcc
	v_lshl_add_u64 v[138:139], s[50:51], 0, v[138:139]
	v_lshl_add_u64 v[138:139], v[138:139], 0, v[98:99]
	v_add_u32_e32 v128, 0xffffc010, v96
	s_add_i32 s31, s31, s86
	s_add_i32 s26, s26, s27
	s_add_i32 s28, s28, s29
	s_cmpk_gt_i32 s31, 0x1ff
	v_readlane_b32 s37, v254, 35
	v_readlane_b32 s38, v254, 36
	v_readlane_b32 s39, v254, 37
	v_readlane_b32 s40, v254, 38
	v_readlane_b32 s41, v254, 39
	v_readlane_b32 s42, v254, 40
	v_readlane_b32 s43, v254, 41
	v_readlane_b32 s44, v254, 42
	v_readlane_b32 s45, v254, 43
	v_readlane_b32 s46, v254, 44
	v_readlane_b32 s47, v254, 45
	v_readlane_b32 s48, v254, 46
	v_readlane_b32 s49, v254, 47
	s_waitcnt vmcnt(0)
	v_pk_add_f32 v[124:125], v[124:125], v[134:135]
	v_pk_add_f32 v[126:127], v[126:127], v[136:137]
	global_store_dwordx4 v[138:139], v[124:127], off
	global_load_dwordx4 v[124:127], v[142:143], off offset:16
	s_waitcnt vmcnt(0)
	v_pk_add_f32 v[120:121], v[120:121], v[124:125]
	v_pk_add_f32 v[122:123], v[122:123], v[126:127]
	global_store_dwordx4 v[138:139], v[120:123], off offset:16
	global_load_dwordx4 v[120:123], v[142:143], off offset:128
	v_lshlrev_b64 v[124:125], 12, v[128:129]
	v_lshl_add_u64 v[124:125], s[24:25], 0, v[124:125]
	v_add_u32_e32 v128, 0xffffc020, v96
	s_waitcnt vmcnt(0)
	v_pk_add_f32 v[116:117], v[116:117], v[120:121]
	v_pk_add_f32 v[118:119], v[118:119], v[122:123]
	global_store_dwordx4 v[138:139], v[116:119], off offset:128
	global_load_dwordx4 v[116:119], v[142:143], off offset:144
	v_mov_b32_e32 v121, v129
	v_or_b32_e32 v120, 16, v96
	v_lshlrev_b64 v[122:123], 12, v[120:121]
	v_ashrrev_i32_e32 v121, 31, v120
	v_lshlrev_b64 v[126:127], 12, v[120:121]
	v_lshl_add_u64 v[134:135], s[50:51], 0, v[126:127]
	v_cmp_gt_i32_e32 vcc, s30, v120
	s_waitcnt vmcnt(0)
	v_pk_add_f32 v[112:113], v[112:113], v[116:117]
	v_cndmask_b32_e32 v125, v125, v135, vcc
	v_cndmask_b32_e32 v124, v124, v134, vcc
	v_pk_add_f32 v[114:115], v[114:115], v[118:119]
	v_lshl_add_u64 v[124:125], v[124:125], 0, v[98:99]
	global_store_dwordx4 v[138:139], v[112:115], off offset:144
	global_load_dwordx4 v[112:115], v[124:125], off
	v_cndmask_b32_e32 v121, v123, v127, vcc
	v_cndmask_b32_e32 v120, v122, v126, vcc
	v_lshl_add_u64 v[116:117], s[50:51], 0, v[120:121]
	v_lshl_add_u64 v[116:117], v[116:117], 0, v[98:99]
	s_waitcnt vmcnt(0)
	v_pk_add_f32 v[108:109], v[108:109], v[112:113]
	v_pk_add_f32 v[110:111], v[110:111], v[114:115]
	global_store_dwordx4 v[116:117], v[108:111], off
	global_load_dwordx4 v[108:111], v[124:125], off offset:16
	s_waitcnt vmcnt(0)
	v_pk_add_f32 v[104:105], v[104:105], v[108:109]
	v_pk_add_f32 v[106:107], v[106:107], v[110:111]
	global_store_dwordx4 v[116:117], v[104:107], off offset:16
	global_load_dwordx4 v[104:107], v[124:125], off offset:128
	v_lshlrev_b64 v[110:111], 12, v[128:129]
	v_lshl_add_u64 v[110:111], s[24:25], 0, v[110:111]
	v_add_u32_e32 v128, 0xffffc030, v96
	s_waitcnt vmcnt(0)
	v_pk_add_f32 v[100:101], v[100:101], v[104:105]
	v_pk_add_f32 v[102:103], v[102:103], v[106:107]
	global_store_dwordx4 v[116:117], v[100:103], off offset:128
	global_load_dwordx4 v[100:103], v[124:125], off offset:144
	v_mov_b32_e32 v105, v129
	v_or_b32_e32 v104, 32, v96
	v_lshlrev_b64 v[106:107], 12, v[104:105]
	v_ashrrev_i32_e32 v105, 31, v104
	v_lshlrev_b64 v[108:109], 12, v[104:105]
	v_lshl_add_u64 v[112:113], s[50:51], 0, v[108:109]
	v_cmp_gt_i32_e32 vcc, s30, v104
	s_waitcnt vmcnt(0)
	v_pk_add_f32 v[100:101], v[130:131], v[100:101]
	v_cndmask_b32_e32 v111, v111, v113, vcc
	v_cndmask_b32_e32 v110, v110, v112, vcc
	v_pk_add_f32 v[102:103], v[132:133], v[102:103]
	v_lshl_add_u64 v[110:111], v[110:111], 0, v[98:99]
	global_store_dwordx4 v[116:117], v[100:103], off offset:144
	global_load_dwordx4 v[100:103], v[110:111], off
	v_cndmask_b32_e32 v105, v107, v109, vcc
	v_cndmask_b32_e32 v104, v106, v108, vcc
	v_lshl_add_u64 v[104:105], s[50:51], 0, v[104:105]
	v_lshl_add_u64 v[104:105], v[104:105], 0, v[98:99]
	s_waitcnt vmcnt(0)
	v_pk_add_f32 v[92:93], v[92:93], v[100:101]
	v_pk_add_f32 v[94:95], v[94:95], v[102:103]
	global_store_dwordx4 v[104:105], v[92:95], off
	global_load_dwordx4 v[92:95], v[110:111], off offset:16
	v_lshlrev_b64 v[100:101], 12, v[128:129]
	v_lshl_add_u64 v[100:101], s[24:25], 0, v[100:101]
	v_add_u32_e32 v128, 0xffffc040, v96
	s_waitcnt vmcnt(0)
	v_pk_add_f32 v[88:89], v[88:89], v[92:93]
	v_pk_add_f32 v[90:91], v[90:91], v[94:95]
	global_store_dwordx4 v[104:105], v[88:91], off offset:16
	global_load_dwordx4 v[88:91], v[110:111], off offset:128
	s_waitcnt vmcnt(0)
	v_pk_add_f32 v[84:85], v[84:85], v[88:89]
	v_pk_add_f32 v[86:87], v[86:87], v[90:91]
	global_store_dwordx4 v[104:105], v[84:87], off offset:128
	global_load_dwordx4 v[84:87], v[110:111], off offset:144
	v_mov_b32_e32 v89, v129
	v_or_b32_e32 v88, 48, v96
	v_lshlrev_b64 v[90:91], 12, v[88:89]
	v_ashrrev_i32_e32 v89, 31, v88
	v_lshlrev_b64 v[92:93], 12, v[88:89]
	v_lshl_add_u64 v[94:95], s[50:51], 0, v[92:93]
	v_cmp_gt_i32_e32 vcc, s30, v88
	s_waitcnt vmcnt(0)
	v_pk_add_f32 v[80:81], v[80:81], v[84:85]
	v_cndmask_b32_e32 v95, v101, v95, vcc
	v_cndmask_b32_e32 v94, v100, v94, vcc
	v_pk_add_f32 v[82:83], v[82:83], v[86:87]
	v_lshl_add_u64 v[94:95], v[94:95], 0, v[98:99]
	global_store_dwordx4 v[104:105], v[80:83], off offset:144
	global_load_dwordx4 v[80:83], v[94:95], off
	v_cndmask_b32_e32 v89, v91, v93, vcc
	v_cndmask_b32_e32 v88, v90, v92, vcc
	v_lshl_add_u64 v[84:85], s[50:51], 0, v[88:89]
	v_lshl_add_u64 v[84:85], v[84:85], 0, v[98:99]
	s_waitcnt vmcnt(0)
	v_pk_add_f32 v[76:77], v[76:77], v[80:81]
	v_pk_add_f32 v[78:79], v[78:79], v[82:83]
	global_store_dwordx4 v[84:85], v[76:79], off
	global_load_dwordx4 v[76:79], v[94:95], off offset:16
	v_lshlrev_b64 v[80:81], 12, v[128:129]
	v_lshl_add_u64 v[80:81], s[24:25], 0, v[80:81]
	v_add_u32_e32 v128, 0xffffc050, v96
	s_waitcnt vmcnt(0)
	v_pk_add_f32 v[72:73], v[72:73], v[76:77]
	v_pk_add_f32 v[74:75], v[74:75], v[78:79]
	global_store_dwordx4 v[84:85], v[72:75], off offset:16
	global_load_dwordx4 v[72:75], v[94:95], off offset:128
	s_waitcnt vmcnt(0)
	v_pk_add_f32 v[68:69], v[68:69], v[72:73]
	v_pk_add_f32 v[70:71], v[70:71], v[74:75]
	global_store_dwordx4 v[84:85], v[68:71], off offset:128
	global_load_dwordx4 v[68:71], v[94:95], off offset:144
	v_mov_b32_e32 v73, v129
	v_or_b32_e32 v72, 64, v96
	v_lshlrev_b64 v[74:75], 12, v[72:73]
	v_ashrrev_i32_e32 v73, 31, v72
	v_lshlrev_b64 v[76:77], 12, v[72:73]
	v_lshl_add_u64 v[78:79], s[50:51], 0, v[76:77]
	v_cmp_gt_i32_e32 vcc, s30, v72
	s_waitcnt vmcnt(0)
	v_pk_add_f32 v[64:65], v[64:65], v[68:69]
	v_cndmask_b32_e32 v79, v81, v79, vcc
	v_cndmask_b32_e32 v78, v80, v78, vcc
	v_pk_add_f32 v[66:67], v[66:67], v[70:71]
	v_lshl_add_u64 v[78:79], v[78:79], 0, v[98:99]
	global_store_dwordx4 v[84:85], v[64:67], off offset:144
	global_load_dwordx4 v[64:67], v[78:79], off
	v_cndmask_b32_e32 v73, v75, v77, vcc
	v_cndmask_b32_e32 v72, v74, v76, vcc
	v_lshl_add_u64 v[68:69], s[50:51], 0, v[72:73]
	v_lshl_add_u64 v[68:69], v[68:69], 0, v[98:99]
	s_waitcnt vmcnt(0)
	v_pk_add_f32 v[60:61], v[60:61], v[64:65]
	v_pk_add_f32 v[62:63], v[62:63], v[66:67]
	global_store_dwordx4 v[68:69], v[60:63], off
	global_load_dwordx4 v[60:63], v[78:79], off offset:16
	v_lshlrev_b64 v[64:65], 12, v[128:129]
	v_lshl_add_u64 v[64:65], s[24:25], 0, v[64:65]
	v_add_u32_e32 v128, 0xffffc060, v96
	s_waitcnt vmcnt(0)
	v_pk_add_f32 v[56:57], v[56:57], v[60:61]
	v_pk_add_f32 v[58:59], v[58:59], v[62:63]
	global_store_dwordx4 v[68:69], v[56:59], off offset:16
	global_load_dwordx4 v[56:59], v[78:79], off offset:128
	s_waitcnt vmcnt(0)
	v_pk_add_f32 v[52:53], v[52:53], v[56:57]
	v_pk_add_f32 v[54:55], v[54:55], v[58:59]
	global_store_dwordx4 v[68:69], v[52:55], off offset:128
	global_load_dwordx4 v[52:55], v[78:79], off offset:144
	v_mov_b32_e32 v57, v129
	v_or_b32_e32 v56, 0x50, v96
	v_lshlrev_b64 v[58:59], 12, v[56:57]
	v_ashrrev_i32_e32 v57, 31, v56
	v_lshlrev_b64 v[60:61], 12, v[56:57]
	v_lshl_add_u64 v[62:63], s[50:51], 0, v[60:61]
	v_cmp_gt_i32_e32 vcc, s30, v56
	s_waitcnt vmcnt(0)
	v_pk_add_f32 v[48:49], v[48:49], v[52:53]
	v_cndmask_b32_e32 v63, v65, v63, vcc
	v_cndmask_b32_e32 v62, v64, v62, vcc
	v_pk_add_f32 v[50:51], v[50:51], v[54:55]
	v_lshl_add_u64 v[62:63], v[62:63], 0, v[98:99]
	global_store_dwordx4 v[68:69], v[48:51], off offset:144
	global_load_dwordx4 v[48:51], v[62:63], off
	v_cndmask_b32_e32 v57, v59, v61, vcc
	v_cndmask_b32_e32 v56, v58, v60, vcc
	v_lshl_add_u64 v[52:53], s[50:51], 0, v[56:57]
	v_lshl_add_u64 v[52:53], v[52:53], 0, v[98:99]
	s_waitcnt vmcnt(0)
	v_pk_add_f32 v[44:45], v[44:45], v[48:49]
	v_pk_add_f32 v[46:47], v[46:47], v[50:51]
	global_store_dwordx4 v[52:53], v[44:47], off
	global_load_dwordx4 v[44:47], v[62:63], off offset:16
	v_lshlrev_b64 v[48:49], 12, v[128:129]
	v_lshl_add_u64 v[48:49], s[24:25], 0, v[48:49]
	v_add_u32_e32 v128, 0xffffc070, v96
	s_waitcnt vmcnt(0)
	v_pk_add_f32 v[40:41], v[40:41], v[44:45]
	v_pk_add_f32 v[42:43], v[42:43], v[46:47]
	global_store_dwordx4 v[52:53], v[40:43], off offset:16
	global_load_dwordx4 v[40:43], v[62:63], off offset:128
	s_waitcnt vmcnt(0)
	v_pk_add_f32 v[36:37], v[36:37], v[40:41]
	v_pk_add_f32 v[38:39], v[38:39], v[42:43]
	global_store_dwordx4 v[52:53], v[36:39], off offset:128
	global_load_dwordx4 v[36:39], v[62:63], off offset:144
	v_mov_b32_e32 v41, v129
	v_or_b32_e32 v40, 0x60, v96
	v_lshlrev_b64 v[42:43], 12, v[40:41]
	v_ashrrev_i32_e32 v41, 31, v40
	v_lshlrev_b64 v[44:45], 12, v[40:41]
	v_lshl_add_u64 v[46:47], s[50:51], 0, v[44:45]
	v_cmp_gt_i32_e32 vcc, s30, v40
	s_waitcnt vmcnt(0)
	v_pk_add_f32 v[32:33], v[32:33], v[36:37]
	v_cndmask_b32_e32 v47, v49, v47, vcc
	v_cndmask_b32_e32 v46, v48, v46, vcc
	v_pk_add_f32 v[34:35], v[34:35], v[38:39]
	v_lshl_add_u64 v[46:47], v[46:47], 0, v[98:99]
	global_store_dwordx4 v[52:53], v[32:35], off offset:144
	global_load_dwordx4 v[32:35], v[46:47], off
	v_cndmask_b32_e32 v41, v43, v45, vcc
	v_cndmask_b32_e32 v40, v42, v44, vcc
	v_lshl_add_u64 v[36:37], s[50:51], 0, v[40:41]
	v_lshl_add_u64 v[36:37], v[36:37], 0, v[98:99]
	s_waitcnt vmcnt(0)
	v_pk_add_f32 v[28:29], v[28:29], v[32:33]
	v_pk_add_f32 v[30:31], v[30:31], v[34:35]
	global_store_dwordx4 v[36:37], v[28:31], off
	global_load_dwordx4 v[28:31], v[46:47], off offset:16
	v_lshlrev_b64 v[32:33], 12, v[128:129]
	v_lshl_add_u64 v[32:33], s[24:25], 0, v[32:33]
	s_waitcnt vmcnt(0)
	v_pk_add_f32 v[24:25], v[24:25], v[28:29]
	v_pk_add_f32 v[26:27], v[26:27], v[30:31]
	global_store_dwordx4 v[36:37], v[24:27], off offset:16
	global_load_dwordx4 v[24:27], v[46:47], off offset:128
	s_waitcnt vmcnt(0)
	v_pk_add_f32 v[20:21], v[20:21], v[24:25]
	v_pk_add_f32 v[22:23], v[22:23], v[26:27]
	global_store_dwordx4 v[36:37], v[20:23], off offset:128
	global_load_dwordx4 v[20:23], v[46:47], off offset:144
	v_mov_b32_e32 v25, v129
	v_or_b32_e32 v24, 0x70, v96
	v_lshlrev_b64 v[26:27], 12, v[24:25]
	v_ashrrev_i32_e32 v25, 31, v24
	v_lshlrev_b64 v[28:29], 12, v[24:25]
	v_lshl_add_u64 v[30:31], s[50:51], 0, v[28:29]
	v_cmp_gt_i32_e32 vcc, s30, v24
	s_waitcnt vmcnt(0)
	v_pk_add_f32 v[16:17], v[16:17], v[20:21]
	v_cndmask_b32_e32 v31, v33, v31, vcc
	v_cndmask_b32_e32 v30, v32, v30, vcc
	v_pk_add_f32 v[18:19], v[18:19], v[22:23]
	v_lshl_add_u64 v[30:31], v[30:31], 0, v[98:99]
	global_store_dwordx4 v[36:37], v[16:19], off offset:144
	global_load_dwordx4 v[16:19], v[30:31], off
	v_cndmask_b32_e32 v25, v27, v29, vcc
	v_cndmask_b32_e32 v24, v26, v28, vcc
	v_lshl_add_u64 v[20:21], s[50:51], 0, v[24:25]
	v_lshl_add_u64 v[20:21], v[20:21], 0, v[98:99]
	s_waitcnt vmcnt(0)
	v_pk_add_f32 v[12:13], v[12:13], v[16:17]
	v_pk_add_f32 v[14:15], v[14:15], v[18:19]
	global_store_dwordx4 v[20:21], v[12:15], off
	global_load_dwordx4 v[12:15], v[30:31], off offset:16
	s_waitcnt vmcnt(0)
	v_pk_add_f32 v[8:9], v[8:9], v[12:13]
	v_pk_add_f32 v[10:11], v[10:11], v[14:15]
	global_store_dwordx4 v[20:21], v[8:11], off offset:16
	global_load_dwordx4 v[8:11], v[30:31], off offset:128
	s_waitcnt vmcnt(0)
	v_pk_add_f32 v[4:5], v[4:5], v[8:9]
	v_pk_add_f32 v[6:7], v[6:7], v[10:11]
	global_store_dwordx4 v[20:21], v[4:7], off offset:128
	global_load_dwordx4 v[4:7], v[30:31], off offset:144
	s_waitcnt vmcnt(0)
	v_pk_add_f32 v[0:1], v[0:1], v[4:5]
	v_pk_add_f32 v[2:3], v[2:3], v[6:7]
	global_store_dwordx4 v[20:21], v[0:3], off offset:144
	s_cbranch_scc0 .LBB0_2562
